# GEMM phases without provably redundant s_waitcnt lgkmcnt(0) (104), on top of the no-setprio loops
# speedup vs baseline: 1.0038x; 1.0023x over previous
.LBB0_271:
	s_ashr_i32 s37, s36, 31
	s_lshl_b64 s[38:39], s[36:37], 19
	s_add_u32 s38, s58, s38
	s_addc_u32 s39, s59, s39
	s_and_b64 s[40:41], s[4:5], exec
	s_cselect_b32 s37, s39, s61
	s_cselect_b32 s43, s38, s60
	s_ashr_i32 s35, s34, 31
	s_lshl_b64 s[40:41], s[34:35], 19
	s_add_u32 s40, s66, s40
	s_addc_u32 s41, s67, s41
	s_and_b64 s[64:65], s[4:5], exec
	s_cselect_b32 s35, s41, s63
	s_cselect_b32 s55, s40, s62
	s_add_u32 s60, s60, 0x40080
	s_addc_u32 s61, s61, 0
	s_add_u32 s84, s62, 0x100
	s_addc_u32 s85, s63, 0
	s_mov_b32 s86, -2
	ds_read_b128 v[146:149], v153
	ds_read_b128 v[156:159], v153 offset:1024
	ds_read_b128 v[160:163], v153 offset:2048
	ds_read_b128 v[164:167], v153 offset:3072
	ds_read_b128 v[168:171], v154
	ds_read_b128 v[172:175], v154 offset:1024
	ds_read_b128 v[176:179], v154 offset:2048
	ds_read_b128 v[180:183], v154 offset:3072
	s_add_u32 s62, s60, 0xfffc0080
	s_addc_u32 s63, s61, -1
	s_cmp_eq_u32 s86, 12
	s_cselect_b32 s65, s37, s63
	s_cselect_b32 s64, s43, s62
	s_cselect_b32 s63, s35, s85
	s_cselect_b32 s62, s55, s84
	s_add_i32 m0, s69, 0xc000
	ds_read_b128 v[184:187], v155
	ds_read_b128 v[192:195], v155 offset:1024
	ds_read_b128 v[196:199], v155 offset:2048
	ds_read_b128 v[200:203], v155 offset:3072
	ds_read_b128 v[204:207], v155 offset:4096
	ds_read_b128 v[208:211], v155 offset:5120
	ds_read_b128 v[212:215], v155 offset:6144
	ds_read_b128 v[216:219], v155 offset:7168
	global_load_lds_dwordx4 v138, s[60:61]
	v_lshl_add_u64 v[188:189], s[60:61], 0, v[140:141]
	s_add_i32 m0, s69, 0xe000
	s_nop 0
	global_load_lds_dwordx4 v[188:189], off
	s_waitcnt vmcnt(8)
	s_waitcnt lgkmcnt(0)
	s_barrier
	v_mfma_f32_16x16x32_bf16 v[124:127], v[146:149], v[184:187], 0
	v_mfma_f32_16x16x32_bf16 v[120:123], v[160:163], v[184:187], 0
	v_mfma_f32_16x16x32_bf16 v[116:119], v[146:149], v[196:199], 0
	v_mfma_f32_16x16x32_bf16 v[108:111], v[160:163], v[196:199], 0
	v_mfma_f32_16x16x32_bf16 v[100:103], v[146:149], v[204:207], 0
	v_mfma_f32_16x16x32_bf16 v[92:95], v[160:163], v[204:207], 0
	v_mfma_f32_16x16x32_bf16 v[84:87], v[146:149], v[212:215], 0
	v_mfma_f32_16x16x32_bf16 v[76:79], v[160:163], v[212:215], 0
	v_mfma_f32_16x16x32_bf16 v[124:127], v[156:159], v[192:195], v[124:127]
	v_mfma_f32_16x16x32_bf16 v[120:123], v[164:167], v[192:195], v[120:123]
	v_mfma_f32_16x16x32_bf16 v[116:119], v[156:159], v[200:203], v[116:119]
	v_mfma_f32_16x16x32_bf16 v[108:111], v[164:167], v[200:203], v[108:111]
	v_mfma_f32_16x16x32_bf16 v[100:103], v[156:159], v[208:211], v[100:103]
	v_mfma_f32_16x16x32_bf16 v[92:95], v[164:167], v[208:211], v[92:95]
	v_mfma_f32_16x16x32_bf16 v[84:87], v[156:159], v[216:219], v[84:87]
	v_mfma_f32_16x16x32_bf16 v[76:79], v[164:167], v[216:219], v[76:79]
	v_mfma_f32_16x16x32_bf16 v[112:115], v[168:171], v[184:187], 0
	v_mfma_f32_16x16x32_bf16 v[104:107], v[176:179], v[184:187], 0
	v_mfma_f32_16x16x32_bf16 v[96:99], v[168:171], v[196:199], 0
	v_mfma_f32_16x16x32_bf16 v[88:91], v[176:179], v[196:199], 0
	v_mfma_f32_16x16x32_bf16 v[80:83], v[168:171], v[204:207], 0
	v_mfma_f32_16x16x32_bf16 v[72:75], v[176:179], v[204:207], 0
	v_mfma_f32_16x16x32_bf16 v[68:71], v[168:171], v[212:215], 0
	v_mfma_f32_16x16x32_bf16 v[64:67], v[176:179], v[212:215], 0
	v_mfma_f32_16x16x32_bf16 v[112:115], v[172:175], v[192:195], v[112:115]
	v_mfma_f32_16x16x32_bf16 v[104:107], v[180:183], v[192:195], v[104:107]
	v_mfma_f32_16x16x32_bf16 v[96:99], v[172:175], v[200:203], v[96:99]
	v_mfma_f32_16x16x32_bf16 v[88:91], v[180:183], v[200:203], v[88:91]
	v_mfma_f32_16x16x32_bf16 v[80:83], v[172:175], v[208:211], v[80:83]
	v_mfma_f32_16x16x32_bf16 v[72:75], v[180:183], v[208:211], v[72:75]
	v_mfma_f32_16x16x32_bf16 v[68:71], v[172:175], v[216:219], v[68:71]
	v_mfma_f32_16x16x32_bf16 v[64:67], v[180:183], v[216:219], v[64:67]
	s_barrier
	s_add_i32 s87, s76, s68
	v_lshl_add_u64 v[188:189], s[62:63], 0, v[132:133]
	s_mov_b32 m0, s87
	ds_read_b128 v[184:187], v155 offset:16384
	ds_read_b128 v[192:195], v155 offset:17408
	ds_read_b128 v[196:199], v155 offset:18432
	ds_read_b128 v[200:203], v155 offset:19456
	ds_read_b128 v[204:207], v155 offset:20480
	ds_read_b128 v[208:211], v155 offset:21504
	ds_read_b128 v[212:215], v155 offset:22528
	ds_read_b128 v[216:219], v155 offset:23552
	global_load_lds_dwordx4 v[188:189], off
	s_add_i32 m0, s87, 0x2000
	s_add_u32 s88, s62, 0x40000
	v_lshl_add_u64 v[220:221], s[62:63], 0, v[128:129]
	s_addc_u32 s89, s63, 0
	s_add_i32 s87, s77, s68
	global_load_lds_dwordx4 v[220:221], off
	s_mov_b32 m0, s87
	v_lshl_add_u64 v[224:225], s[64:65], 0, v[130:131]
	global_load_lds_dwordx4 v132, s[88:89]
	s_add_i32 m0, s87, 0x2000
	s_nop 0
	global_load_lds_dwordx4 v128, s[88:89]
	v_lshl_add_u64 v[222:223], s[64:65], 0, v[134:135]
	s_mov_b32 m0, s69
	s_nop 0
	global_load_lds_dwordx4 v[222:223], off
	s_mov_b32 m0, s70
	s_nop 0
	global_load_lds_dwordx4 v[224:225], off
	s_waitcnt vmcnt(8)
	s_waitcnt lgkmcnt(0)
	s_barrier
	v_mfma_f32_16x16x32_bf16 v[60:63], v[146:149], v[184:187], 0
	v_mfma_f32_16x16x32_bf16 v[56:59], v[160:163], v[184:187], 0
	v_mfma_f32_16x16x32_bf16 v[52:55], v[146:149], v[196:199], 0
	v_mfma_f32_16x16x32_bf16 v[44:47], v[160:163], v[196:199], 0
	v_mfma_f32_16x16x32_bf16 v[36:39], v[146:149], v[204:207], 0
	v_mfma_f32_16x16x32_bf16 v[28:31], v[160:163], v[204:207], 0
	v_mfma_f32_16x16x32_bf16 v[20:23], v[146:149], v[212:215], 0
	v_mfma_f32_16x16x32_bf16 v[12:15], v[160:163], v[212:215], 0
	v_mfma_f32_16x16x32_bf16 v[60:63], v[156:159], v[192:195], v[60:63]
	v_mfma_f32_16x16x32_bf16 v[56:59], v[164:167], v[192:195], v[56:59]
	v_mfma_f32_16x16x32_bf16 v[52:55], v[156:159], v[200:203], v[52:55]
	v_mfma_f32_16x16x32_bf16 v[44:47], v[164:167], v[200:203], v[44:47]
	v_mfma_f32_16x16x32_bf16 v[36:39], v[156:159], v[208:211], v[36:39]
	v_mfma_f32_16x16x32_bf16 v[28:31], v[164:167], v[208:211], v[28:31]
	v_mfma_f32_16x16x32_bf16 v[20:23], v[156:159], v[216:219], v[20:23]
	v_mfma_f32_16x16x32_bf16 v[12:15], v[164:167], v[216:219], v[12:15]
	v_mfma_f32_16x16x32_bf16 v[48:51], v[168:171], v[184:187], 0
	v_mfma_f32_16x16x32_bf16 v[40:43], v[176:179], v[184:187], 0
	v_mfma_f32_16x16x32_bf16 v[32:35], v[168:171], v[196:199], 0
	v_mfma_f32_16x16x32_bf16 v[24:27], v[176:179], v[196:199], 0
	v_mfma_f32_16x16x32_bf16 v[16:19], v[168:171], v[204:207], 0
	v_mfma_f32_16x16x32_bf16 v[8:11], v[176:179], v[204:207], 0
	v_mfma_f32_16x16x32_bf16 v[4:7], v[168:171], v[212:215], 0
	v_mfma_f32_16x16x32_bf16 v[0:3], v[176:179], v[212:215], 0
	v_mfma_f32_16x16x32_bf16 v[48:51], v[172:175], v[192:195], v[48:51]
	v_mfma_f32_16x16x32_bf16 v[40:43], v[180:183], v[192:195], v[40:43]
	v_mfma_f32_16x16x32_bf16 v[32:35], v[172:175], v[200:203], v[32:35]
	v_mfma_f32_16x16x32_bf16 v[24:27], v[180:183], v[200:203], v[24:27]
	v_mfma_f32_16x16x32_bf16 v[16:19], v[172:175], v[208:211], v[16:19]
	v_mfma_f32_16x16x32_bf16 v[8:11], v[180:183], v[208:211], v[8:11]
	v_mfma_f32_16x16x32_bf16 v[4:7], v[172:175], v[216:219], v[4:7]
	v_mfma_f32_16x16x32_bf16 v[0:3], v[180:183], v[216:219], v[0:3]
	s_barrier
	s_add_i32 s87, 0, 0x18000
	s_add_i32 s88, 0, 0x1c000
	v_add_u32_e32 v164, s87, v151
	v_add_u32_e32 v180, s88, v151
	ds_read_b128 v[146:149], v164
	ds_read_b128 v[156:159], v164 offset:1024
	ds_read_b128 v[160:163], v164 offset:2048
	ds_read_b128 v[164:167], v164 offset:3072
	ds_read_b128 v[168:171], v180
	ds_read_b128 v[172:175], v180 offset:1024
	ds_read_b128 v[176:179], v180 offset:2048
	ds_read_b128 v[180:183], v180 offset:3072
	s_add_u32 s64, s64, 0x40000
	s_addc_u32 s65, s65, 0
	s_mov_b32 m0, s71
	ds_read_b128 v[184:187], v155 offset:32768
	ds_read_b128 v[192:195], v155 offset:33792
	ds_read_b128 v[196:199], v155 offset:34816
	ds_read_b128 v[200:203], v155 offset:35840
	ds_read_b128 v[204:207], v155 offset:36864
	ds_read_b128 v[208:211], v155 offset:37888
	ds_read_b128 v[212:215], v155 offset:38912
	ds_read_b128 v[216:219], v155 offset:39936
	global_load_lds_dwordx4 v134, s[64:65]
	s_mov_b32 m0, s72
	s_nop 0
	global_load_lds_dwordx4 v130, s[64:65]
	s_waitcnt vmcnt(8)
	s_waitcnt lgkmcnt(0)
	s_barrier
	v_mfma_f32_16x16x32_bf16 v[124:127], v[146:149], v[184:187], v[124:127]
	v_mfma_f32_16x16x32_bf16 v[120:123], v[160:163], v[184:187], v[120:123]
	v_mfma_f32_16x16x32_bf16 v[116:119], v[146:149], v[196:199], v[116:119]
	v_mfma_f32_16x16x32_bf16 v[108:111], v[160:163], v[196:199], v[108:111]
	v_mfma_f32_16x16x32_bf16 v[100:103], v[146:149], v[204:207], v[100:103]
	v_mfma_f32_16x16x32_bf16 v[92:95], v[160:163], v[204:207], v[92:95]
	v_mfma_f32_16x16x32_bf16 v[84:87], v[146:149], v[212:215], v[84:87]
	v_mfma_f32_16x16x32_bf16 v[76:79], v[160:163], v[212:215], v[76:79]
	v_mfma_f32_16x16x32_bf16 v[124:127], v[156:159], v[192:195], v[124:127]
	v_mfma_f32_16x16x32_bf16 v[120:123], v[164:167], v[192:195], v[120:123]
	v_mfma_f32_16x16x32_bf16 v[116:119], v[156:159], v[200:203], v[116:119]
	v_mfma_f32_16x16x32_bf16 v[108:111], v[164:167], v[200:203], v[108:111]
	v_mfma_f32_16x16x32_bf16 v[100:103], v[156:159], v[208:211], v[100:103]
	v_mfma_f32_16x16x32_bf16 v[92:95], v[164:167], v[208:211], v[92:95]
	v_mfma_f32_16x16x32_bf16 v[84:87], v[156:159], v[216:219], v[84:87]
	v_mfma_f32_16x16x32_bf16 v[76:79], v[164:167], v[216:219], v[76:79]
	v_mfma_f32_16x16x32_bf16 v[112:115], v[168:171], v[184:187], v[112:115]
	v_mfma_f32_16x16x32_bf16 v[104:107], v[176:179], v[184:187], v[104:107]
	v_mfma_f32_16x16x32_bf16 v[96:99], v[168:171], v[196:199], v[96:99]
	v_mfma_f32_16x16x32_bf16 v[88:91], v[176:179], v[196:199], v[88:91]
	v_mfma_f32_16x16x32_bf16 v[80:83], v[168:171], v[204:207], v[80:83]
	v_mfma_f32_16x16x32_bf16 v[72:75], v[176:179], v[204:207], v[72:75]
	v_mfma_f32_16x16x32_bf16 v[68:71], v[168:171], v[212:215], v[68:71]
	v_mfma_f32_16x16x32_bf16 v[64:67], v[176:179], v[212:215], v[64:67]
	v_mfma_f32_16x16x32_bf16 v[112:115], v[172:175], v[192:195], v[112:115]
	v_mfma_f32_16x16x32_bf16 v[104:107], v[180:183], v[192:195], v[104:107]
	v_mfma_f32_16x16x32_bf16 v[96:99], v[172:175], v[200:203], v[96:99]
	v_mfma_f32_16x16x32_bf16 v[88:91], v[180:183], v[200:203], v[88:91]
	v_mfma_f32_16x16x32_bf16 v[80:83], v[172:175], v[208:211], v[80:83]
	v_mfma_f32_16x16x32_bf16 v[72:75], v[180:183], v[208:211], v[72:75]
	v_mfma_f32_16x16x32_bf16 v[68:71], v[172:175], v[216:219], v[68:71]
	v_mfma_f32_16x16x32_bf16 v[64:67], v[180:183], v[216:219], v[64:67]
	s_barrier
	s_add_i32 s64, s87, s68
	v_lshl_add_u64 v[188:189], v[188:189], 0, s[10:11]
	s_mov_b32 m0, s64
	ds_read_b128 v[184:187], v155 offset:49152
	ds_read_b128 v[192:195], v155 offset:50176
	ds_read_b128 v[196:199], v155 offset:51200
	ds_read_b128 v[200:203], v155 offset:52224
	ds_read_b128 v[204:207], v155 offset:53248
	ds_read_b128 v[208:211], v155 offset:54272
	ds_read_b128 v[212:215], v155 offset:55296
	ds_read_b128 v[216:219], v155 offset:56320
	global_load_lds_dwordx4 v[188:189], off
	s_add_i32 m0, s64, 0x2000
	s_add_u32 s62, s62, 0x40080
	v_lshl_add_u64 v[188:189], v[220:221], 0, s[10:11]
	s_addc_u32 s63, s63, 0
	s_add_i32 s64, s88, s68
	global_load_lds_dwordx4 v[188:189], off
	s_mov_b32 m0, s64
	s_nop 0
	global_load_lds_dwordx4 v132, s[62:63]
	s_add_i32 m0, s64, 0x2000
	s_nop 0
	global_load_lds_dwordx4 v128, s[62:63]
	v_lshl_add_u64 v[188:189], v[222:223], 0, s[10:11]
	s_mov_b32 m0, s33
	s_nop 0
	global_load_lds_dwordx4 v[188:189], off
	v_lshl_add_u64 v[188:189], v[224:225], 0, s[10:11]
	s_mov_b32 m0, s74
	s_nop 0
	global_load_lds_dwordx4 v[188:189], off
	s_waitcnt vmcnt(8)
	s_waitcnt lgkmcnt(0)
	s_barrier
	v_mfma_f32_16x16x32_bf16 v[60:63], v[146:149], v[184:187], v[60:63]
	v_mfma_f32_16x16x32_bf16 v[56:59], v[160:163], v[184:187], v[56:59]
	v_mfma_f32_16x16x32_bf16 v[52:55], v[146:149], v[196:199], v[52:55]
	v_mfma_f32_16x16x32_bf16 v[44:47], v[160:163], v[196:199], v[44:47]
	v_mfma_f32_16x16x32_bf16 v[36:39], v[146:149], v[204:207], v[36:39]
	v_mfma_f32_16x16x32_bf16 v[28:31], v[160:163], v[204:207], v[28:31]
	v_mfma_f32_16x16x32_bf16 v[20:23], v[146:149], v[212:215], v[20:23]
	v_mfma_f32_16x16x32_bf16 v[12:15], v[160:163], v[212:215], v[12:15]
	v_mfma_f32_16x16x32_bf16 v[60:63], v[156:159], v[192:195], v[60:63]
	v_mfma_f32_16x16x32_bf16 v[56:59], v[164:167], v[192:195], v[56:59]
	v_mfma_f32_16x16x32_bf16 v[52:55], v[156:159], v[200:203], v[52:55]
	v_mfma_f32_16x16x32_bf16 v[44:47], v[164:167], v[200:203], v[44:47]
	v_mfma_f32_16x16x32_bf16 v[36:39], v[156:159], v[208:211], v[36:39]
	v_mfma_f32_16x16x32_bf16 v[28:31], v[164:167], v[208:211], v[28:31]
	v_mfma_f32_16x16x32_bf16 v[20:23], v[156:159], v[216:219], v[20:23]
	v_mfma_f32_16x16x32_bf16 v[12:15], v[164:167], v[216:219], v[12:15]
	v_mfma_f32_16x16x32_bf16 v[48:51], v[168:171], v[184:187], v[48:51]
	v_mfma_f32_16x16x32_bf16 v[40:43], v[176:179], v[184:187], v[40:43]
	v_mfma_f32_16x16x32_bf16 v[32:35], v[168:171], v[196:199], v[32:35]
	v_mfma_f32_16x16x32_bf16 v[24:27], v[176:179], v[196:199], v[24:27]
	v_mfma_f32_16x16x32_bf16 v[16:19], v[168:171], v[204:207], v[16:19]
	v_mfma_f32_16x16x32_bf16 v[8:11], v[176:179], v[204:207], v[8:11]
	v_mfma_f32_16x16x32_bf16 v[4:7], v[168:171], v[212:215], v[4:7]
	v_mfma_f32_16x16x32_bf16 v[0:3], v[176:179], v[212:215], v[0:3]
	v_mfma_f32_16x16x32_bf16 v[48:51], v[172:175], v[192:195], v[48:51]
	v_mfma_f32_16x16x32_bf16 v[40:43], v[180:183], v[192:195], v[40:43]
	v_mfma_f32_16x16x32_bf16 v[32:35], v[172:175], v[200:203], v[32:35]
	v_mfma_f32_16x16x32_bf16 v[24:27], v[180:183], v[200:203], v[24:27]
	v_mfma_f32_16x16x32_bf16 v[16:19], v[172:175], v[208:211], v[16:19]
	v_mfma_f32_16x16x32_bf16 v[8:11], v[180:183], v[208:211], v[8:11]
	v_mfma_f32_16x16x32_bf16 v[4:7], v[172:175], v[216:219], v[4:7]
	v_mfma_f32_16x16x32_bf16 v[0:3], v[180:183], v[216:219], v[0:3]
	s_barrier
	s_add_i32 s86, s86, 2
	s_add_u32 s60, s60, 0x100
	s_addc_u32 s61, s61, 0
	s_add_u32 s84, s84, 0x100
	s_addc_u32 s85, s85, 0
	s_cmp_gt_u32 s86, 13
	s_cbranch_scc0 .LBB0_272
	s_branch .Lpeel_exit0
.LBB0_272:
	ds_read_b128 v[146:149], v153
	ds_read_b128 v[156:159], v153 offset:1024
	ds_read_b128 v[160:163], v153 offset:2048
	ds_read_b128 v[164:167], v153 offset:3072
	ds_read_b128 v[168:171], v154
	ds_read_b128 v[172:175], v154 offset:1024
	ds_read_b128 v[176:179], v154 offset:2048
	ds_read_b128 v[180:183], v154 offset:3072
	s_add_u32 s62, s60, 0xfffc0080
	s_addc_u32 s63, s61, -1
	s_cmp_eq_u32 s86, 12
	s_cselect_b32 s65, s37, s63
	s_cselect_b32 s64, s43, s62
	s_cselect_b32 s63, s35, s85
	s_cselect_b32 s62, s55, s84
	s_add_i32 m0, s69, 0xc000
	ds_read_b128 v[184:187], v155
	ds_read_b128 v[192:195], v155 offset:1024
	ds_read_b128 v[196:199], v155 offset:2048
	ds_read_b128 v[200:203], v155 offset:3072
	ds_read_b128 v[204:207], v155 offset:4096
	ds_read_b128 v[208:211], v155 offset:5120
	ds_read_b128 v[212:215], v155 offset:6144
	ds_read_b128 v[216:219], v155 offset:7168
	global_load_lds_dwordx4 v138, s[60:61]
	v_lshl_add_u64 v[188:189], s[60:61], 0, v[140:141]
	s_add_i32 m0, s69, 0xe000
	s_nop 0
	global_load_lds_dwordx4 v[188:189], off
	s_waitcnt vmcnt(8)
	s_waitcnt lgkmcnt(0)
	s_barrier
	v_mfma_f32_16x16x32_bf16 v[124:127], v[146:149], v[184:187], v[124:127]
	v_mfma_f32_16x16x32_bf16 v[120:123], v[160:163], v[184:187], v[120:123]
	v_mfma_f32_16x16x32_bf16 v[116:119], v[146:149], v[196:199], v[116:119]
	v_mfma_f32_16x16x32_bf16 v[108:111], v[160:163], v[196:199], v[108:111]
	v_mfma_f32_16x16x32_bf16 v[100:103], v[146:149], v[204:207], v[100:103]
	v_mfma_f32_16x16x32_bf16 v[92:95], v[160:163], v[204:207], v[92:95]
	v_mfma_f32_16x16x32_bf16 v[84:87], v[146:149], v[212:215], v[84:87]
	v_mfma_f32_16x16x32_bf16 v[76:79], v[160:163], v[212:215], v[76:79]
	v_mfma_f32_16x16x32_bf16 v[124:127], v[156:159], v[192:195], v[124:127]
	v_mfma_f32_16x16x32_bf16 v[120:123], v[164:167], v[192:195], v[120:123]
	v_mfma_f32_16x16x32_bf16 v[116:119], v[156:159], v[200:203], v[116:119]
	v_mfma_f32_16x16x32_bf16 v[108:111], v[164:167], v[200:203], v[108:111]
	v_mfma_f32_16x16x32_bf16 v[100:103], v[156:159], v[208:211], v[100:103]
	v_mfma_f32_16x16x32_bf16 v[92:95], v[164:167], v[208:211], v[92:95]
	v_mfma_f32_16x16x32_bf16 v[84:87], v[156:159], v[216:219], v[84:87]
	v_mfma_f32_16x16x32_bf16 v[76:79], v[164:167], v[216:219], v[76:79]
	v_mfma_f32_16x16x32_bf16 v[112:115], v[168:171], v[184:187], v[112:115]
	v_mfma_f32_16x16x32_bf16 v[104:107], v[176:179], v[184:187], v[104:107]
	v_mfma_f32_16x16x32_bf16 v[96:99], v[168:171], v[196:199], v[96:99]
	v_mfma_f32_16x16x32_bf16 v[88:91], v[176:179], v[196:199], v[88:91]
	v_mfma_f32_16x16x32_bf16 v[80:83], v[168:171], v[204:207], v[80:83]
	v_mfma_f32_16x16x32_bf16 v[72:75], v[176:179], v[204:207], v[72:75]
	v_mfma_f32_16x16x32_bf16 v[68:71], v[168:171], v[212:215], v[68:71]
	v_mfma_f32_16x16x32_bf16 v[64:67], v[176:179], v[212:215], v[64:67]
	v_mfma_f32_16x16x32_bf16 v[112:115], v[172:175], v[192:195], v[112:115]
	v_mfma_f32_16x16x32_bf16 v[104:107], v[180:183], v[192:195], v[104:107]
	v_mfma_f32_16x16x32_bf16 v[96:99], v[172:175], v[200:203], v[96:99]
	v_mfma_f32_16x16x32_bf16 v[88:91], v[180:183], v[200:203], v[88:91]
	v_mfma_f32_16x16x32_bf16 v[80:83], v[172:175], v[208:211], v[80:83]
	v_mfma_f32_16x16x32_bf16 v[72:75], v[180:183], v[208:211], v[72:75]
	v_mfma_f32_16x16x32_bf16 v[68:71], v[172:175], v[216:219], v[68:71]
	v_mfma_f32_16x16x32_bf16 v[64:67], v[180:183], v[216:219], v[64:67]
	s_barrier
	s_add_i32 s87, s76, s68
	v_lshl_add_u64 v[188:189], s[62:63], 0, v[132:133]
	s_mov_b32 m0, s87
	ds_read_b128 v[184:187], v155 offset:16384
	ds_read_b128 v[192:195], v155 offset:17408
	ds_read_b128 v[196:199], v155 offset:18432
	ds_read_b128 v[200:203], v155 offset:19456
	ds_read_b128 v[204:207], v155 offset:20480
	ds_read_b128 v[208:211], v155 offset:21504
	ds_read_b128 v[212:215], v155 offset:22528
	ds_read_b128 v[216:219], v155 offset:23552
	global_load_lds_dwordx4 v[188:189], off
	s_add_i32 m0, s87, 0x2000
	s_add_u32 s88, s62, 0x40000
	v_lshl_add_u64 v[220:221], s[62:63], 0, v[128:129]
	s_addc_u32 s89, s63, 0
	s_add_i32 s87, s77, s68
	global_load_lds_dwordx4 v[220:221], off
	s_mov_b32 m0, s87
	v_lshl_add_u64 v[224:225], s[64:65], 0, v[130:131]
	global_load_lds_dwordx4 v132, s[88:89]
	s_add_i32 m0, s87, 0x2000
	s_nop 0
	global_load_lds_dwordx4 v128, s[88:89]
	v_lshl_add_u64 v[222:223], s[64:65], 0, v[134:135]
	s_mov_b32 m0, s69
	s_nop 0
	global_load_lds_dwordx4 v[222:223], off
	s_mov_b32 m0, s70
	s_nop 0
	global_load_lds_dwordx4 v[224:225], off
	s_waitcnt vmcnt(8)
	s_waitcnt lgkmcnt(0)
	s_barrier
	v_mfma_f32_16x16x32_bf16 v[60:63], v[146:149], v[184:187], v[60:63]
	v_mfma_f32_16x16x32_bf16 v[56:59], v[160:163], v[184:187], v[56:59]
	v_mfma_f32_16x16x32_bf16 v[52:55], v[146:149], v[196:199], v[52:55]
	v_mfma_f32_16x16x32_bf16 v[44:47], v[160:163], v[196:199], v[44:47]
	v_mfma_f32_16x16x32_bf16 v[36:39], v[146:149], v[204:207], v[36:39]
	v_mfma_f32_16x16x32_bf16 v[28:31], v[160:163], v[204:207], v[28:31]
	v_mfma_f32_16x16x32_bf16 v[20:23], v[146:149], v[212:215], v[20:23]
	v_mfma_f32_16x16x32_bf16 v[12:15], v[160:163], v[212:215], v[12:15]
	v_mfma_f32_16x16x32_bf16 v[60:63], v[156:159], v[192:195], v[60:63]
	v_mfma_f32_16x16x32_bf16 v[56:59], v[164:167], v[192:195], v[56:59]
	v_mfma_f32_16x16x32_bf16 v[52:55], v[156:159], v[200:203], v[52:55]
	v_mfma_f32_16x16x32_bf16 v[44:47], v[164:167], v[200:203], v[44:47]
	v_mfma_f32_16x16x32_bf16 v[36:39], v[156:159], v[208:211], v[36:39]
	v_mfma_f32_16x16x32_bf16 v[28:31], v[164:167], v[208:211], v[28:31]
	v_mfma_f32_16x16x32_bf16 v[20:23], v[156:159], v[216:219], v[20:23]
	v_mfma_f32_16x16x32_bf16 v[12:15], v[164:167], v[216:219], v[12:15]
	v_mfma_f32_16x16x32_bf16 v[48:51], v[168:171], v[184:187], v[48:51]
	v_mfma_f32_16x16x32_bf16 v[40:43], v[176:179], v[184:187], v[40:43]
	v_mfma_f32_16x16x32_bf16 v[32:35], v[168:171], v[196:199], v[32:35]
	v_mfma_f32_16x16x32_bf16 v[24:27], v[176:179], v[196:199], v[24:27]
	v_mfma_f32_16x16x32_bf16 v[16:19], v[168:171], v[204:207], v[16:19]
	v_mfma_f32_16x16x32_bf16 v[8:11], v[176:179], v[204:207], v[8:11]
	v_mfma_f32_16x16x32_bf16 v[4:7], v[168:171], v[212:215], v[4:7]
	v_mfma_f32_16x16x32_bf16 v[0:3], v[176:179], v[212:215], v[0:3]
	v_mfma_f32_16x16x32_bf16 v[48:51], v[172:175], v[192:195], v[48:51]
	v_mfma_f32_16x16x32_bf16 v[40:43], v[180:183], v[192:195], v[40:43]
	v_mfma_f32_16x16x32_bf16 v[32:35], v[172:175], v[200:203], v[32:35]
	v_mfma_f32_16x16x32_bf16 v[24:27], v[180:183], v[200:203], v[24:27]
	v_mfma_f32_16x16x32_bf16 v[16:19], v[172:175], v[208:211], v[16:19]
	v_mfma_f32_16x16x32_bf16 v[8:11], v[180:183], v[208:211], v[8:11]
	v_mfma_f32_16x16x32_bf16 v[4:7], v[172:175], v[216:219], v[4:7]
	v_mfma_f32_16x16x32_bf16 v[0:3], v[180:183], v[216:219], v[0:3]
	s_barrier
	s_add_i32 s87, 0, 0x18000
	s_add_i32 s88, 0, 0x1c000
	v_add_u32_e32 v164, s87, v151
	v_add_u32_e32 v180, s88, v151
	ds_read_b128 v[146:149], v164
	ds_read_b128 v[156:159], v164 offset:1024
	ds_read_b128 v[160:163], v164 offset:2048
	ds_read_b128 v[164:167], v164 offset:3072
	ds_read_b128 v[168:171], v180
	ds_read_b128 v[172:175], v180 offset:1024
	ds_read_b128 v[176:179], v180 offset:2048
	ds_read_b128 v[180:183], v180 offset:3072
	s_add_u32 s64, s64, 0x40000
	s_addc_u32 s65, s65, 0
	s_mov_b32 m0, s71
	ds_read_b128 v[184:187], v155 offset:32768
	ds_read_b128 v[192:195], v155 offset:33792
	ds_read_b128 v[196:199], v155 offset:34816
	ds_read_b128 v[200:203], v155 offset:35840
	ds_read_b128 v[204:207], v155 offset:36864
	ds_read_b128 v[208:211], v155 offset:37888
	ds_read_b128 v[212:215], v155 offset:38912
	ds_read_b128 v[216:219], v155 offset:39936
	global_load_lds_dwordx4 v134, s[64:65]
	s_mov_b32 m0, s72
	s_nop 0
	global_load_lds_dwordx4 v130, s[64:65]
	s_waitcnt vmcnt(8)
	s_waitcnt lgkmcnt(0)
	s_barrier
	v_mfma_f32_16x16x32_bf16 v[124:127], v[146:149], v[184:187], v[124:127]
	v_mfma_f32_16x16x32_bf16 v[120:123], v[160:163], v[184:187], v[120:123]
	v_mfma_f32_16x16x32_bf16 v[116:119], v[146:149], v[196:199], v[116:119]
	v_mfma_f32_16x16x32_bf16 v[108:111], v[160:163], v[196:199], v[108:111]
	v_mfma_f32_16x16x32_bf16 v[100:103], v[146:149], v[204:207], v[100:103]
	v_mfma_f32_16x16x32_bf16 v[92:95], v[160:163], v[204:207], v[92:95]
	v_mfma_f32_16x16x32_bf16 v[84:87], v[146:149], v[212:215], v[84:87]
	v_mfma_f32_16x16x32_bf16 v[76:79], v[160:163], v[212:215], v[76:79]
	v_mfma_f32_16x16x32_bf16 v[124:127], v[156:159], v[192:195], v[124:127]
	v_mfma_f32_16x16x32_bf16 v[120:123], v[164:167], v[192:195], v[120:123]
	v_mfma_f32_16x16x32_bf16 v[116:119], v[156:159], v[200:203], v[116:119]
	v_mfma_f32_16x16x32_bf16 v[108:111], v[164:167], v[200:203], v[108:111]
	v_mfma_f32_16x16x32_bf16 v[100:103], v[156:159], v[208:211], v[100:103]
	v_mfma_f32_16x16x32_bf16 v[92:95], v[164:167], v[208:211], v[92:95]
	v_mfma_f32_16x16x32_bf16 v[84:87], v[156:159], v[216:219], v[84:87]
	v_mfma_f32_16x16x32_bf16 v[76:79], v[164:167], v[216:219], v[76:79]
	v_mfma_f32_16x16x32_bf16 v[112:115], v[168:171], v[184:187], v[112:115]
	v_mfma_f32_16x16x32_bf16 v[104:107], v[176:179], v[184:187], v[104:107]
	v_mfma_f32_16x16x32_bf16 v[96:99], v[168:171], v[196:199], v[96:99]
	v_mfma_f32_16x16x32_bf16 v[88:91], v[176:179], v[196:199], v[88:91]
	v_mfma_f32_16x16x32_bf16 v[80:83], v[168:171], v[204:207], v[80:83]
	v_mfma_f32_16x16x32_bf16 v[72:75], v[176:179], v[204:207], v[72:75]
	v_mfma_f32_16x16x32_bf16 v[68:71], v[168:171], v[212:215], v[68:71]
	v_mfma_f32_16x16x32_bf16 v[64:67], v[176:179], v[212:215], v[64:67]
	v_mfma_f32_16x16x32_bf16 v[112:115], v[172:175], v[192:195], v[112:115]
	v_mfma_f32_16x16x32_bf16 v[104:107], v[180:183], v[192:195], v[104:107]
	v_mfma_f32_16x16x32_bf16 v[96:99], v[172:175], v[200:203], v[96:99]
	v_mfma_f32_16x16x32_bf16 v[88:91], v[180:183], v[200:203], v[88:91]
	v_mfma_f32_16x16x32_bf16 v[80:83], v[172:175], v[208:211], v[80:83]
	v_mfma_f32_16x16x32_bf16 v[72:75], v[180:183], v[208:211], v[72:75]
	v_mfma_f32_16x16x32_bf16 v[68:71], v[172:175], v[216:219], v[68:71]
	v_mfma_f32_16x16x32_bf16 v[64:67], v[180:183], v[216:219], v[64:67]
	s_barrier
	s_add_i32 s64, s87, s68
	v_lshl_add_u64 v[188:189], v[188:189], 0, s[10:11]
	s_mov_b32 m0, s64
	ds_read_b128 v[184:187], v155 offset:49152
	ds_read_b128 v[192:195], v155 offset:50176
	ds_read_b128 v[196:199], v155 offset:51200
	ds_read_b128 v[200:203], v155 offset:52224
	ds_read_b128 v[204:207], v155 offset:53248
	ds_read_b128 v[208:211], v155 offset:54272
	ds_read_b128 v[212:215], v155 offset:55296
	ds_read_b128 v[216:219], v155 offset:56320
	global_load_lds_dwordx4 v[188:189], off
	s_add_i32 m0, s64, 0x2000
	s_add_u32 s62, s62, 0x40080
	v_lshl_add_u64 v[188:189], v[220:221], 0, s[10:11]
	s_addc_u32 s63, s63, 0
	s_add_i32 s64, s88, s68
	global_load_lds_dwordx4 v[188:189], off
	s_mov_b32 m0, s64
	s_nop 0
	global_load_lds_dwordx4 v132, s[62:63]
	s_add_i32 m0, s64, 0x2000
	s_nop 0
	global_load_lds_dwordx4 v128, s[62:63]
	v_lshl_add_u64 v[188:189], v[222:223], 0, s[10:11]
	s_mov_b32 m0, s33
	s_nop 0
	global_load_lds_dwordx4 v[188:189], off
	v_lshl_add_u64 v[188:189], v[224:225], 0, s[10:11]
	s_mov_b32 m0, s74
	s_nop 0
	global_load_lds_dwordx4 v[188:189], off
	s_waitcnt vmcnt(8)
	s_waitcnt lgkmcnt(0)
	s_barrier
	v_mfma_f32_16x16x32_bf16 v[60:63], v[146:149], v[184:187], v[60:63]
	v_mfma_f32_16x16x32_bf16 v[56:59], v[160:163], v[184:187], v[56:59]
	v_mfma_f32_16x16x32_bf16 v[52:55], v[146:149], v[196:199], v[52:55]
	v_mfma_f32_16x16x32_bf16 v[44:47], v[160:163], v[196:199], v[44:47]
	v_mfma_f32_16x16x32_bf16 v[36:39], v[146:149], v[204:207], v[36:39]
	v_mfma_f32_16x16x32_bf16 v[28:31], v[160:163], v[204:207], v[28:31]
	v_mfma_f32_16x16x32_bf16 v[20:23], v[146:149], v[212:215], v[20:23]
	v_mfma_f32_16x16x32_bf16 v[12:15], v[160:163], v[212:215], v[12:15]
	v_mfma_f32_16x16x32_bf16 v[60:63], v[156:159], v[192:195], v[60:63]
	v_mfma_f32_16x16x32_bf16 v[56:59], v[164:167], v[192:195], v[56:59]
	v_mfma_f32_16x16x32_bf16 v[52:55], v[156:159], v[200:203], v[52:55]
	v_mfma_f32_16x16x32_bf16 v[44:47], v[164:167], v[200:203], v[44:47]
	v_mfma_f32_16x16x32_bf16 v[36:39], v[156:159], v[208:211], v[36:39]
	v_mfma_f32_16x16x32_bf16 v[28:31], v[164:167], v[208:211], v[28:31]
	v_mfma_f32_16x16x32_bf16 v[20:23], v[156:159], v[216:219], v[20:23]
	v_mfma_f32_16x16x32_bf16 v[12:15], v[164:167], v[216:219], v[12:15]
	v_mfma_f32_16x16x32_bf16 v[48:51], v[168:171], v[184:187], v[48:51]
	v_mfma_f32_16x16x32_bf16 v[40:43], v[176:179], v[184:187], v[40:43]
	v_mfma_f32_16x16x32_bf16 v[32:35], v[168:171], v[196:199], v[32:35]
	v_mfma_f32_16x16x32_bf16 v[24:27], v[176:179], v[196:199], v[24:27]
	v_mfma_f32_16x16x32_bf16 v[16:19], v[168:171], v[204:207], v[16:19]
	v_mfma_f32_16x16x32_bf16 v[8:11], v[176:179], v[204:207], v[8:11]
	v_mfma_f32_16x16x32_bf16 v[4:7], v[168:171], v[212:215], v[4:7]
	v_mfma_f32_16x16x32_bf16 v[0:3], v[176:179], v[212:215], v[0:3]
	v_mfma_f32_16x16x32_bf16 v[48:51], v[172:175], v[192:195], v[48:51]
	v_mfma_f32_16x16x32_bf16 v[40:43], v[180:183], v[192:195], v[40:43]
	v_mfma_f32_16x16x32_bf16 v[32:35], v[172:175], v[200:203], v[32:35]
	v_mfma_f32_16x16x32_bf16 v[24:27], v[180:183], v[200:203], v[24:27]
	v_mfma_f32_16x16x32_bf16 v[16:19], v[172:175], v[208:211], v[16:19]
	v_mfma_f32_16x16x32_bf16 v[8:11], v[180:183], v[208:211], v[8:11]
	v_mfma_f32_16x16x32_bf16 v[4:7], v[172:175], v[216:219], v[4:7]
	v_mfma_f32_16x16x32_bf16 v[0:3], v[180:183], v[216:219], v[0:3]
	s_barrier
	s_add_i32 s86, s86, 2
	s_add_u32 s60, s60, 0x100
	s_addc_u32 s61, s61, 0
	s_add_u32 s84, s84, 0x100
	s_addc_u32 s85, s85, 0
	s_cmp_gt_u32 s86, 13
	s_cbranch_scc0 .LBB0_272

.LBB0_301:
	s_ashr_i32 s27, s26, 31
	s_lshl_b64 s[28:29], s[26:27], 19
	s_add_u32 s28, s43, s28
	s_addc_u32 s29, s52, s29
	s_and_b64 s[30:31], s[4:5], exec
	s_cselect_b32 s27, s29, s37
	s_cselect_b32 s55, s28, s36
	s_ashr_i32 s25, s24, 31
	s_lshl_b64 s[30:31], s[24:25], 19
	s_add_u32 s30, s58, s30
	s_addc_u32 s31, s59, s31
	s_and_b64 s[40:41], s[4:5], exec
	s_cselect_b32 s25, s31, s39
	s_cselect_b32 s72, s30, s38
	s_add_u32 s36, s36, 0x40080
	s_addc_u32 s37, s37, 0
	s_add_u32 s73, s38, 0x100
	s_addc_u32 s74, s39, 0
	s_mov_b32 s75, -2
	ds_read_b128 v[152:155], v149
	ds_read_b128 v[156:159], v149 offset:1024
	ds_read_b128 v[160:163], v149 offset:2048
	ds_read_b128 v[164:167], v149 offset:3072
	ds_read_b128 v[168:171], v150
	ds_read_b128 v[172:175], v150 offset:1024
	ds_read_b128 v[176:179], v150 offset:2048
	ds_read_b128 v[180:183], v150 offset:3072
	s_add_u32 s38, s36, 0xfffc0080
	s_addc_u32 s39, s37, -1
	s_cmp_eq_u32 s75, 12
	s_cselect_b32 s41, s27, s39
	s_cselect_b32 s40, s55, s38
	s_cselect_b32 s39, s25, s74
	s_cselect_b32 s38, s72, s73
	v_lshl_add_u64 v[144:145], s[36:37], 0, v[136:137]
	s_add_i32 m0, s35, 0xc000
	ds_read_b128 v[184:187], v151
	ds_read_b128 v[192:195], v151 offset:1024
	ds_read_b128 v[196:199], v151 offset:2048
	ds_read_b128 v[200:203], v151 offset:3072
	ds_read_b128 v[204:207], v151 offset:4096
	ds_read_b128 v[208:211], v151 offset:5120
	ds_read_b128 v[212:215], v151 offset:6144
	ds_read_b128 v[216:219], v151 offset:7168
	global_load_lds_dwordx4 v[144:145], off
	s_add_i32 m0, s35, 0xe000
	s_nop 0
	global_load_lds_dwordx4 v138, s[36:37]
	s_waitcnt vmcnt(8)
	s_waitcnt lgkmcnt(0)
	s_barrier
	v_mfma_f32_16x16x32_bf16 v[124:127], v[152:155], v[184:187], 0
	v_mfma_f32_16x16x32_bf16 v[120:123], v[160:163], v[184:187], 0
	v_mfma_f32_16x16x32_bf16 v[116:119], v[152:155], v[196:199], 0
	v_mfma_f32_16x16x32_bf16 v[108:111], v[160:163], v[196:199], 0
	v_mfma_f32_16x16x32_bf16 v[100:103], v[152:155], v[204:207], 0
	v_mfma_f32_16x16x32_bf16 v[92:95], v[160:163], v[204:207], 0
	v_mfma_f32_16x16x32_bf16 v[84:87], v[152:155], v[212:215], 0
	v_mfma_f32_16x16x32_bf16 v[76:79], v[160:163], v[212:215], 0
	v_mfma_f32_16x16x32_bf16 v[124:127], v[156:159], v[192:195], v[124:127]
	v_mfma_f32_16x16x32_bf16 v[120:123], v[164:167], v[192:195], v[120:123]
	v_mfma_f32_16x16x32_bf16 v[116:119], v[156:159], v[200:203], v[116:119]
	v_mfma_f32_16x16x32_bf16 v[108:111], v[164:167], v[200:203], v[108:111]
	v_mfma_f32_16x16x32_bf16 v[100:103], v[156:159], v[208:211], v[100:103]
	v_mfma_f32_16x16x32_bf16 v[92:95], v[164:167], v[208:211], v[92:95]
	v_mfma_f32_16x16x32_bf16 v[84:87], v[156:159], v[216:219], v[84:87]
	v_mfma_f32_16x16x32_bf16 v[76:79], v[164:167], v[216:219], v[76:79]
	v_mfma_f32_16x16x32_bf16 v[112:115], v[168:171], v[184:187], 0
	v_mfma_f32_16x16x32_bf16 v[104:107], v[176:179], v[184:187], 0
	v_mfma_f32_16x16x32_bf16 v[96:99], v[168:171], v[196:199], 0
	v_mfma_f32_16x16x32_bf16 v[88:91], v[176:179], v[196:199], 0
	v_mfma_f32_16x16x32_bf16 v[80:83], v[168:171], v[204:207], 0
	v_mfma_f32_16x16x32_bf16 v[72:75], v[176:179], v[204:207], 0
	v_mfma_f32_16x16x32_bf16 v[68:71], v[168:171], v[212:215], 0
	v_mfma_f32_16x16x32_bf16 v[64:67], v[176:179], v[212:215], 0
	v_mfma_f32_16x16x32_bf16 v[112:115], v[172:175], v[192:195], v[112:115]
	v_mfma_f32_16x16x32_bf16 v[104:107], v[180:183], v[192:195], v[104:107]
	v_mfma_f32_16x16x32_bf16 v[96:99], v[172:175], v[200:203], v[96:99]
	v_mfma_f32_16x16x32_bf16 v[88:91], v[180:183], v[200:203], v[88:91]
	v_mfma_f32_16x16x32_bf16 v[80:83], v[172:175], v[208:211], v[80:83]
	v_mfma_f32_16x16x32_bf16 v[72:75], v[180:183], v[208:211], v[72:75]
	v_mfma_f32_16x16x32_bf16 v[68:71], v[172:175], v[216:219], v[68:71]
	v_mfma_f32_16x16x32_bf16 v[64:67], v[180:183], v[216:219], v[64:67]
	s_barrier
	s_add_i32 s76, s66, s53
	v_lshl_add_u64 v[144:145], s[38:39], 0, v[130:131]
	s_mov_b32 m0, s76
	ds_read_b128 v[184:187], v151 offset:16384
	ds_read_b128 v[192:195], v151 offset:17408
	ds_read_b128 v[196:199], v151 offset:18432
	ds_read_b128 v[200:203], v151 offset:19456
	ds_read_b128 v[204:207], v151 offset:20480
	ds_read_b128 v[208:211], v151 offset:21504
	ds_read_b128 v[212:215], v151 offset:22528
	ds_read_b128 v[216:219], v151 offset:23552
	global_load_lds_dwordx4 v[144:145], off
	s_add_i32 m0, s76, 0x2000
	s_add_u32 s76, s38, 0x40000
	v_lshl_add_u64 v[188:189], s[38:39], 0, v[134:135]
	s_addc_u32 s77, s39, 0
	s_add_i32 s80, s67, s53
	global_load_lds_dwordx4 v[188:189], off
	s_mov_b32 m0, s80
	v_lshl_add_u64 v[222:223], s[40:41], 0, v[132:133]
	global_load_lds_dwordx4 v130, s[76:77]
	s_add_i32 m0, s80, 0x2000
	s_nop 0
	global_load_lds_dwordx4 v134, s[76:77]
	v_lshl_add_u64 v[220:221], s[40:41], 0, v[128:129]
	s_mov_b32 m0, s35
	s_nop 0
	global_load_lds_dwordx4 v[220:221], off
	s_mov_b32 m0, s33
	s_nop 0
	global_load_lds_dwordx4 v[222:223], off
	s_waitcnt vmcnt(8)
	s_waitcnt lgkmcnt(0)
	s_barrier
	v_mfma_f32_16x16x32_bf16 v[60:63], v[152:155], v[184:187], 0
	v_mfma_f32_16x16x32_bf16 v[56:59], v[160:163], v[184:187], 0
	v_mfma_f32_16x16x32_bf16 v[52:55], v[152:155], v[196:199], 0
	v_mfma_f32_16x16x32_bf16 v[44:47], v[160:163], v[196:199], 0
	v_mfma_f32_16x16x32_bf16 v[36:39], v[152:155], v[204:207], 0
	v_mfma_f32_16x16x32_bf16 v[28:31], v[160:163], v[204:207], 0
	v_mfma_f32_16x16x32_bf16 v[20:23], v[152:155], v[212:215], 0
	v_mfma_f32_16x16x32_bf16 v[12:15], v[160:163], v[212:215], 0
	v_mfma_f32_16x16x32_bf16 v[60:63], v[156:159], v[192:195], v[60:63]
	v_mfma_f32_16x16x32_bf16 v[56:59], v[164:167], v[192:195], v[56:59]
	v_mfma_f32_16x16x32_bf16 v[52:55], v[156:159], v[200:203], v[52:55]
	v_mfma_f32_16x16x32_bf16 v[44:47], v[164:167], v[200:203], v[44:47]
	v_mfma_f32_16x16x32_bf16 v[36:39], v[156:159], v[208:211], v[36:39]
	v_mfma_f32_16x16x32_bf16 v[28:31], v[164:167], v[208:211], v[28:31]
	v_mfma_f32_16x16x32_bf16 v[20:23], v[156:159], v[216:219], v[20:23]
	v_mfma_f32_16x16x32_bf16 v[12:15], v[164:167], v[216:219], v[12:15]
	v_mfma_f32_16x16x32_bf16 v[48:51], v[168:171], v[184:187], 0
	v_mfma_f32_16x16x32_bf16 v[40:43], v[176:179], v[184:187], 0
	v_mfma_f32_16x16x32_bf16 v[32:35], v[168:171], v[196:199], 0
	v_mfma_f32_16x16x32_bf16 v[24:27], v[176:179], v[196:199], 0
	v_mfma_f32_16x16x32_bf16 v[16:19], v[168:171], v[204:207], 0
	v_mfma_f32_16x16x32_bf16 v[8:11], v[176:179], v[204:207], 0
	v_mfma_f32_16x16x32_bf16 v[4:7], v[168:171], v[212:215], 0
	v_mfma_f32_16x16x32_bf16 v[0:3], v[176:179], v[212:215], 0
	v_mfma_f32_16x16x32_bf16 v[48:51], v[172:175], v[192:195], v[48:51]
	v_mfma_f32_16x16x32_bf16 v[40:43], v[180:183], v[192:195], v[40:43]
	v_mfma_f32_16x16x32_bf16 v[32:35], v[172:175], v[200:203], v[32:35]
	v_mfma_f32_16x16x32_bf16 v[24:27], v[180:183], v[200:203], v[24:27]
	v_mfma_f32_16x16x32_bf16 v[16:19], v[172:175], v[208:211], v[16:19]
	v_mfma_f32_16x16x32_bf16 v[8:11], v[180:183], v[208:211], v[8:11]
	v_mfma_f32_16x16x32_bf16 v[4:7], v[172:175], v[216:219], v[4:7]
	v_mfma_f32_16x16x32_bf16 v[0:3], v[180:183], v[216:219], v[0:3]
	s_barrier
	s_add_i32 s76, 0, 0x18000
	s_add_i32 s77, 0, 0x1c000
	v_add_u32_e32 v164, s76, v147
	v_add_u32_e32 v180, s77, v147
	ds_read_b128 v[152:155], v164
	ds_read_b128 v[156:159], v164 offset:1024
	ds_read_b128 v[160:163], v164 offset:2048
	ds_read_b128 v[164:167], v164 offset:3072
	ds_read_b128 v[168:171], v180
	ds_read_b128 v[172:175], v180 offset:1024
	ds_read_b128 v[176:179], v180 offset:2048
	ds_read_b128 v[180:183], v180 offset:3072
	s_add_u32 s40, s40, 0x40000
	s_addc_u32 s41, s41, 0
	s_mov_b32 m0, s60
	ds_read_b128 v[184:187], v151 offset:32768
	ds_read_b128 v[192:195], v151 offset:33792
	ds_read_b128 v[196:199], v151 offset:34816
	ds_read_b128 v[200:203], v151 offset:35840
	ds_read_b128 v[204:207], v151 offset:36864
	ds_read_b128 v[208:211], v151 offset:37888
	ds_read_b128 v[212:215], v151 offset:38912
	ds_read_b128 v[216:219], v151 offset:39936
	global_load_lds_dwordx4 v128, s[40:41]
	s_mov_b32 m0, s61
	s_nop 0
	global_load_lds_dwordx4 v132, s[40:41]
	s_waitcnt vmcnt(8)
	s_waitcnt lgkmcnt(0)
	s_barrier
	v_mfma_f32_16x16x32_bf16 v[124:127], v[152:155], v[184:187], v[124:127]
	v_mfma_f32_16x16x32_bf16 v[120:123], v[160:163], v[184:187], v[120:123]
	v_mfma_f32_16x16x32_bf16 v[116:119], v[152:155], v[196:199], v[116:119]
	v_mfma_f32_16x16x32_bf16 v[108:111], v[160:163], v[196:199], v[108:111]
	v_mfma_f32_16x16x32_bf16 v[100:103], v[152:155], v[204:207], v[100:103]
	v_mfma_f32_16x16x32_bf16 v[92:95], v[160:163], v[204:207], v[92:95]
	v_mfma_f32_16x16x32_bf16 v[84:87], v[152:155], v[212:215], v[84:87]
	v_mfma_f32_16x16x32_bf16 v[76:79], v[160:163], v[212:215], v[76:79]
	v_mfma_f32_16x16x32_bf16 v[124:127], v[156:159], v[192:195], v[124:127]
	v_mfma_f32_16x16x32_bf16 v[120:123], v[164:167], v[192:195], v[120:123]
	v_mfma_f32_16x16x32_bf16 v[116:119], v[156:159], v[200:203], v[116:119]
	v_mfma_f32_16x16x32_bf16 v[108:111], v[164:167], v[200:203], v[108:111]
	v_mfma_f32_16x16x32_bf16 v[100:103], v[156:159], v[208:211], v[100:103]
	v_mfma_f32_16x16x32_bf16 v[92:95], v[164:167], v[208:211], v[92:95]
	v_mfma_f32_16x16x32_bf16 v[84:87], v[156:159], v[216:219], v[84:87]
	v_mfma_f32_16x16x32_bf16 v[76:79], v[164:167], v[216:219], v[76:79]
	v_mfma_f32_16x16x32_bf16 v[112:115], v[168:171], v[184:187], v[112:115]
	v_mfma_f32_16x16x32_bf16 v[104:107], v[176:179], v[184:187], v[104:107]
	v_mfma_f32_16x16x32_bf16 v[96:99], v[168:171], v[196:199], v[96:99]
	v_mfma_f32_16x16x32_bf16 v[88:91], v[176:179], v[196:199], v[88:91]
	v_mfma_f32_16x16x32_bf16 v[80:83], v[168:171], v[204:207], v[80:83]
	v_mfma_f32_16x16x32_bf16 v[72:75], v[176:179], v[204:207], v[72:75]
	v_mfma_f32_16x16x32_bf16 v[68:71], v[168:171], v[212:215], v[68:71]
	v_mfma_f32_16x16x32_bf16 v[64:67], v[176:179], v[212:215], v[64:67]
	v_mfma_f32_16x16x32_bf16 v[112:115], v[172:175], v[192:195], v[112:115]
	v_mfma_f32_16x16x32_bf16 v[104:107], v[180:183], v[192:195], v[104:107]
	v_mfma_f32_16x16x32_bf16 v[96:99], v[172:175], v[200:203], v[96:99]
	v_mfma_f32_16x16x32_bf16 v[88:91], v[180:183], v[200:203], v[88:91]
	v_mfma_f32_16x16x32_bf16 v[80:83], v[172:175], v[208:211], v[80:83]
	v_mfma_f32_16x16x32_bf16 v[72:75], v[180:183], v[208:211], v[72:75]
	v_mfma_f32_16x16x32_bf16 v[68:71], v[172:175], v[216:219], v[68:71]
	v_mfma_f32_16x16x32_bf16 v[64:67], v[180:183], v[216:219], v[64:67]
	s_barrier
	s_add_i32 s40, s76, s53
	v_lshl_add_u64 v[144:145], v[144:145], 0, s[12:13]
	s_mov_b32 m0, s40
	ds_read_b128 v[184:187], v151 offset:49152
	ds_read_b128 v[192:195], v151 offset:50176
	ds_read_b128 v[196:199], v151 offset:51200
	ds_read_b128 v[200:203], v151 offset:52224
	ds_read_b128 v[204:207], v151 offset:53248
	ds_read_b128 v[208:211], v151 offset:54272
	ds_read_b128 v[212:215], v151 offset:55296
	ds_read_b128 v[216:219], v151 offset:56320
	global_load_lds_dwordx4 v[144:145], off
	s_add_i32 m0, s40, 0x2000
	s_add_u32 s38, s38, 0x40080
	v_lshl_add_u64 v[144:145], v[188:189], 0, s[12:13]
	s_addc_u32 s39, s39, 0
	s_add_i32 s40, s77, s53
	global_load_lds_dwordx4 v[144:145], off
	s_mov_b32 m0, s40
	s_nop 0
	global_load_lds_dwordx4 v130, s[38:39]
	s_add_i32 m0, s40, 0x2000
	s_nop 0
	global_load_lds_dwordx4 v134, s[38:39]
	v_lshl_add_u64 v[144:145], v[220:221], 0, s[12:13]
	s_mov_b32 m0, s63
	s_nop 0
	global_load_lds_dwordx4 v[144:145], off
	v_lshl_add_u64 v[144:145], v[222:223], 0, s[12:13]
	s_mov_b32 m0, s64
	s_nop 0
	global_load_lds_dwordx4 v[144:145], off
	s_waitcnt vmcnt(8)
	s_waitcnt lgkmcnt(0)
	s_barrier
	v_mfma_f32_16x16x32_bf16 v[60:63], v[152:155], v[184:187], v[60:63]
	v_mfma_f32_16x16x32_bf16 v[56:59], v[160:163], v[184:187], v[56:59]
	v_mfma_f32_16x16x32_bf16 v[52:55], v[152:155], v[196:199], v[52:55]
	v_mfma_f32_16x16x32_bf16 v[44:47], v[160:163], v[196:199], v[44:47]
	v_mfma_f32_16x16x32_bf16 v[36:39], v[152:155], v[204:207], v[36:39]
	v_mfma_f32_16x16x32_bf16 v[28:31], v[160:163], v[204:207], v[28:31]
	v_mfma_f32_16x16x32_bf16 v[20:23], v[152:155], v[212:215], v[20:23]
	v_mfma_f32_16x16x32_bf16 v[12:15], v[160:163], v[212:215], v[12:15]
	v_mfma_f32_16x16x32_bf16 v[60:63], v[156:159], v[192:195], v[60:63]
	v_mfma_f32_16x16x32_bf16 v[56:59], v[164:167], v[192:195], v[56:59]
	v_mfma_f32_16x16x32_bf16 v[52:55], v[156:159], v[200:203], v[52:55]
	v_mfma_f32_16x16x32_bf16 v[44:47], v[164:167], v[200:203], v[44:47]
	v_mfma_f32_16x16x32_bf16 v[36:39], v[156:159], v[208:211], v[36:39]
	v_mfma_f32_16x16x32_bf16 v[28:31], v[164:167], v[208:211], v[28:31]
	v_mfma_f32_16x16x32_bf16 v[20:23], v[156:159], v[216:219], v[20:23]
	v_mfma_f32_16x16x32_bf16 v[12:15], v[164:167], v[216:219], v[12:15]
	v_mfma_f32_16x16x32_bf16 v[48:51], v[168:171], v[184:187], v[48:51]
	v_mfma_f32_16x16x32_bf16 v[40:43], v[176:179], v[184:187], v[40:43]
	v_mfma_f32_16x16x32_bf16 v[32:35], v[168:171], v[196:199], v[32:35]
	v_mfma_f32_16x16x32_bf16 v[24:27], v[176:179], v[196:199], v[24:27]
	v_mfma_f32_16x16x32_bf16 v[16:19], v[168:171], v[204:207], v[16:19]
	v_mfma_f32_16x16x32_bf16 v[8:11], v[176:179], v[204:207], v[8:11]
	v_mfma_f32_16x16x32_bf16 v[4:7], v[168:171], v[212:215], v[4:7]
	v_mfma_f32_16x16x32_bf16 v[0:3], v[176:179], v[212:215], v[0:3]
	v_mfma_f32_16x16x32_bf16 v[48:51], v[172:175], v[192:195], v[48:51]
	v_mfma_f32_16x16x32_bf16 v[40:43], v[180:183], v[192:195], v[40:43]
	v_mfma_f32_16x16x32_bf16 v[32:35], v[172:175], v[200:203], v[32:35]
	v_mfma_f32_16x16x32_bf16 v[24:27], v[180:183], v[200:203], v[24:27]
	v_mfma_f32_16x16x32_bf16 v[16:19], v[172:175], v[208:211], v[16:19]
	v_mfma_f32_16x16x32_bf16 v[8:11], v[180:183], v[208:211], v[8:11]
	v_mfma_f32_16x16x32_bf16 v[4:7], v[172:175], v[216:219], v[4:7]
	v_mfma_f32_16x16x32_bf16 v[0:3], v[180:183], v[216:219], v[0:3]
	s_barrier
	s_add_i32 s75, s75, 2
	s_add_u32 s36, s36, 0x100
	s_addc_u32 s37, s37, 0
	s_add_u32 s73, s73, 0x100
	s_addc_u32 s74, s74, 0
	s_cmp_gt_u32 s75, 13
	s_cbranch_scc0 .LBB0_302
	s_branch .Lpeel_exit1
.LBB0_302:
	ds_read_b128 v[152:155], v149
	ds_read_b128 v[156:159], v149 offset:1024
	ds_read_b128 v[160:163], v149 offset:2048
	ds_read_b128 v[164:167], v149 offset:3072
	ds_read_b128 v[168:171], v150
	ds_read_b128 v[172:175], v150 offset:1024
	ds_read_b128 v[176:179], v150 offset:2048
	ds_read_b128 v[180:183], v150 offset:3072
	s_add_u32 s38, s36, 0xfffc0080
	s_addc_u32 s39, s37, -1
	s_cmp_eq_u32 s75, 12
	s_cselect_b32 s41, s27, s39
	s_cselect_b32 s40, s55, s38
	s_cselect_b32 s39, s25, s74
	s_cselect_b32 s38, s72, s73
	v_lshl_add_u64 v[144:145], s[36:37], 0, v[136:137]
	s_add_i32 m0, s35, 0xc000
	ds_read_b128 v[184:187], v151
	ds_read_b128 v[192:195], v151 offset:1024
	ds_read_b128 v[196:199], v151 offset:2048
	ds_read_b128 v[200:203], v151 offset:3072
	ds_read_b128 v[204:207], v151 offset:4096
	ds_read_b128 v[208:211], v151 offset:5120
	ds_read_b128 v[212:215], v151 offset:6144
	ds_read_b128 v[216:219], v151 offset:7168
	global_load_lds_dwordx4 v[144:145], off
	s_add_i32 m0, s35, 0xe000
	s_nop 0
	global_load_lds_dwordx4 v138, s[36:37]
	s_waitcnt vmcnt(8)
	s_waitcnt lgkmcnt(0)
	s_barrier
	v_mfma_f32_16x16x32_bf16 v[124:127], v[152:155], v[184:187], v[124:127]
	v_mfma_f32_16x16x32_bf16 v[120:123], v[160:163], v[184:187], v[120:123]
	v_mfma_f32_16x16x32_bf16 v[116:119], v[152:155], v[196:199], v[116:119]
	v_mfma_f32_16x16x32_bf16 v[108:111], v[160:163], v[196:199], v[108:111]
	v_mfma_f32_16x16x32_bf16 v[100:103], v[152:155], v[204:207], v[100:103]
	v_mfma_f32_16x16x32_bf16 v[92:95], v[160:163], v[204:207], v[92:95]
	v_mfma_f32_16x16x32_bf16 v[84:87], v[152:155], v[212:215], v[84:87]
	v_mfma_f32_16x16x32_bf16 v[76:79], v[160:163], v[212:215], v[76:79]
	v_mfma_f32_16x16x32_bf16 v[124:127], v[156:159], v[192:195], v[124:127]
	v_mfma_f32_16x16x32_bf16 v[120:123], v[164:167], v[192:195], v[120:123]
	v_mfma_f32_16x16x32_bf16 v[116:119], v[156:159], v[200:203], v[116:119]
	v_mfma_f32_16x16x32_bf16 v[108:111], v[164:167], v[200:203], v[108:111]
	v_mfma_f32_16x16x32_bf16 v[100:103], v[156:159], v[208:211], v[100:103]
	v_mfma_f32_16x16x32_bf16 v[92:95], v[164:167], v[208:211], v[92:95]
	v_mfma_f32_16x16x32_bf16 v[84:87], v[156:159], v[216:219], v[84:87]
	v_mfma_f32_16x16x32_bf16 v[76:79], v[164:167], v[216:219], v[76:79]
	v_mfma_f32_16x16x32_bf16 v[112:115], v[168:171], v[184:187], v[112:115]
	v_mfma_f32_16x16x32_bf16 v[104:107], v[176:179], v[184:187], v[104:107]
	v_mfma_f32_16x16x32_bf16 v[96:99], v[168:171], v[196:199], v[96:99]
	v_mfma_f32_16x16x32_bf16 v[88:91], v[176:179], v[196:199], v[88:91]
	v_mfma_f32_16x16x32_bf16 v[80:83], v[168:171], v[204:207], v[80:83]
	v_mfma_f32_16x16x32_bf16 v[72:75], v[176:179], v[204:207], v[72:75]
	v_mfma_f32_16x16x32_bf16 v[68:71], v[168:171], v[212:215], v[68:71]
	v_mfma_f32_16x16x32_bf16 v[64:67], v[176:179], v[212:215], v[64:67]
	v_mfma_f32_16x16x32_bf16 v[112:115], v[172:175], v[192:195], v[112:115]
	v_mfma_f32_16x16x32_bf16 v[104:107], v[180:183], v[192:195], v[104:107]
	v_mfma_f32_16x16x32_bf16 v[96:99], v[172:175], v[200:203], v[96:99]
	v_mfma_f32_16x16x32_bf16 v[88:91], v[180:183], v[200:203], v[88:91]
	v_mfma_f32_16x16x32_bf16 v[80:83], v[172:175], v[208:211], v[80:83]
	v_mfma_f32_16x16x32_bf16 v[72:75], v[180:183], v[208:211], v[72:75]
	v_mfma_f32_16x16x32_bf16 v[68:71], v[172:175], v[216:219], v[68:71]
	v_mfma_f32_16x16x32_bf16 v[64:67], v[180:183], v[216:219], v[64:67]
	s_barrier
	s_add_i32 s76, s66, s53
	v_lshl_add_u64 v[144:145], s[38:39], 0, v[130:131]
	s_mov_b32 m0, s76
	ds_read_b128 v[184:187], v151 offset:16384
	ds_read_b128 v[192:195], v151 offset:17408
	ds_read_b128 v[196:199], v151 offset:18432
	ds_read_b128 v[200:203], v151 offset:19456
	ds_read_b128 v[204:207], v151 offset:20480
	ds_read_b128 v[208:211], v151 offset:21504
	ds_read_b128 v[212:215], v151 offset:22528
	ds_read_b128 v[216:219], v151 offset:23552
	global_load_lds_dwordx4 v[144:145], off
	s_add_i32 m0, s76, 0x2000
	s_add_u32 s76, s38, 0x40000
	v_lshl_add_u64 v[188:189], s[38:39], 0, v[134:135]
	s_addc_u32 s77, s39, 0
	s_add_i32 s80, s67, s53
	global_load_lds_dwordx4 v[188:189], off
	s_mov_b32 m0, s80
	v_lshl_add_u64 v[222:223], s[40:41], 0, v[132:133]
	global_load_lds_dwordx4 v130, s[76:77]
	s_add_i32 m0, s80, 0x2000
	s_nop 0
	global_load_lds_dwordx4 v134, s[76:77]
	v_lshl_add_u64 v[220:221], s[40:41], 0, v[128:129]
	s_mov_b32 m0, s35
	s_nop 0
	global_load_lds_dwordx4 v[220:221], off
	s_mov_b32 m0, s33
	s_nop 0
	global_load_lds_dwordx4 v[222:223], off
	s_waitcnt vmcnt(8)
	s_waitcnt lgkmcnt(0)
	s_barrier
	v_mfma_f32_16x16x32_bf16 v[60:63], v[152:155], v[184:187], v[60:63]
	v_mfma_f32_16x16x32_bf16 v[56:59], v[160:163], v[184:187], v[56:59]
	v_mfma_f32_16x16x32_bf16 v[52:55], v[152:155], v[196:199], v[52:55]
	v_mfma_f32_16x16x32_bf16 v[44:47], v[160:163], v[196:199], v[44:47]
	v_mfma_f32_16x16x32_bf16 v[36:39], v[152:155], v[204:207], v[36:39]
	v_mfma_f32_16x16x32_bf16 v[28:31], v[160:163], v[204:207], v[28:31]
	v_mfma_f32_16x16x32_bf16 v[20:23], v[152:155], v[212:215], v[20:23]
	v_mfma_f32_16x16x32_bf16 v[12:15], v[160:163], v[212:215], v[12:15]
	v_mfma_f32_16x16x32_bf16 v[60:63], v[156:159], v[192:195], v[60:63]
	v_mfma_f32_16x16x32_bf16 v[56:59], v[164:167], v[192:195], v[56:59]
	v_mfma_f32_16x16x32_bf16 v[52:55], v[156:159], v[200:203], v[52:55]
	v_mfma_f32_16x16x32_bf16 v[44:47], v[164:167], v[200:203], v[44:47]
	v_mfma_f32_16x16x32_bf16 v[36:39], v[156:159], v[208:211], v[36:39]
	v_mfma_f32_16x16x32_bf16 v[28:31], v[164:167], v[208:211], v[28:31]
	v_mfma_f32_16x16x32_bf16 v[20:23], v[156:159], v[216:219], v[20:23]
	v_mfma_f32_16x16x32_bf16 v[12:15], v[164:167], v[216:219], v[12:15]
	v_mfma_f32_16x16x32_bf16 v[48:51], v[168:171], v[184:187], v[48:51]
	v_mfma_f32_16x16x32_bf16 v[40:43], v[176:179], v[184:187], v[40:43]
	v_mfma_f32_16x16x32_bf16 v[32:35], v[168:171], v[196:199], v[32:35]
	v_mfma_f32_16x16x32_bf16 v[24:27], v[176:179], v[196:199], v[24:27]
	v_mfma_f32_16x16x32_bf16 v[16:19], v[168:171], v[204:207], v[16:19]
	v_mfma_f32_16x16x32_bf16 v[8:11], v[176:179], v[204:207], v[8:11]
	v_mfma_f32_16x16x32_bf16 v[4:7], v[168:171], v[212:215], v[4:7]
	v_mfma_f32_16x16x32_bf16 v[0:3], v[176:179], v[212:215], v[0:3]
	v_mfma_f32_16x16x32_bf16 v[48:51], v[172:175], v[192:195], v[48:51]
	v_mfma_f32_16x16x32_bf16 v[40:43], v[180:183], v[192:195], v[40:43]
	v_mfma_f32_16x16x32_bf16 v[32:35], v[172:175], v[200:203], v[32:35]
	v_mfma_f32_16x16x32_bf16 v[24:27], v[180:183], v[200:203], v[24:27]
	v_mfma_f32_16x16x32_bf16 v[16:19], v[172:175], v[208:211], v[16:19]
	v_mfma_f32_16x16x32_bf16 v[8:11], v[180:183], v[208:211], v[8:11]
	v_mfma_f32_16x16x32_bf16 v[4:7], v[172:175], v[216:219], v[4:7]
	v_mfma_f32_16x16x32_bf16 v[0:3], v[180:183], v[216:219], v[0:3]
	s_barrier
	s_add_i32 s76, 0, 0x18000
	s_add_i32 s77, 0, 0x1c000
	v_add_u32_e32 v164, s76, v147
	v_add_u32_e32 v180, s77, v147
	ds_read_b128 v[152:155], v164
	ds_read_b128 v[156:159], v164 offset:1024
	ds_read_b128 v[160:163], v164 offset:2048
	ds_read_b128 v[164:167], v164 offset:3072
	ds_read_b128 v[168:171], v180
	ds_read_b128 v[172:175], v180 offset:1024
	ds_read_b128 v[176:179], v180 offset:2048
	ds_read_b128 v[180:183], v180 offset:3072
	s_add_u32 s40, s40, 0x40000
	s_addc_u32 s41, s41, 0
	s_mov_b32 m0, s60
	ds_read_b128 v[184:187], v151 offset:32768
	ds_read_b128 v[192:195], v151 offset:33792
	ds_read_b128 v[196:199], v151 offset:34816
	ds_read_b128 v[200:203], v151 offset:35840
	ds_read_b128 v[204:207], v151 offset:36864
	ds_read_b128 v[208:211], v151 offset:37888
	ds_read_b128 v[212:215], v151 offset:38912
	ds_read_b128 v[216:219], v151 offset:39936
	global_load_lds_dwordx4 v128, s[40:41]
	s_mov_b32 m0, s61
	s_nop 0
	global_load_lds_dwordx4 v132, s[40:41]
	s_waitcnt vmcnt(8)
	s_waitcnt lgkmcnt(0)
	s_barrier
	v_mfma_f32_16x16x32_bf16 v[124:127], v[152:155], v[184:187], v[124:127]
	v_mfma_f32_16x16x32_bf16 v[120:123], v[160:163], v[184:187], v[120:123]
	v_mfma_f32_16x16x32_bf16 v[116:119], v[152:155], v[196:199], v[116:119]
	v_mfma_f32_16x16x32_bf16 v[108:111], v[160:163], v[196:199], v[108:111]
	v_mfma_f32_16x16x32_bf16 v[100:103], v[152:155], v[204:207], v[100:103]
	v_mfma_f32_16x16x32_bf16 v[92:95], v[160:163], v[204:207], v[92:95]
	v_mfma_f32_16x16x32_bf16 v[84:87], v[152:155], v[212:215], v[84:87]
	v_mfma_f32_16x16x32_bf16 v[76:79], v[160:163], v[212:215], v[76:79]
	v_mfma_f32_16x16x32_bf16 v[124:127], v[156:159], v[192:195], v[124:127]
	v_mfma_f32_16x16x32_bf16 v[120:123], v[164:167], v[192:195], v[120:123]
	v_mfma_f32_16x16x32_bf16 v[116:119], v[156:159], v[200:203], v[116:119]
	v_mfma_f32_16x16x32_bf16 v[108:111], v[164:167], v[200:203], v[108:111]
	v_mfma_f32_16x16x32_bf16 v[100:103], v[156:159], v[208:211], v[100:103]
	v_mfma_f32_16x16x32_bf16 v[92:95], v[164:167], v[208:211], v[92:95]
	v_mfma_f32_16x16x32_bf16 v[84:87], v[156:159], v[216:219], v[84:87]
	v_mfma_f32_16x16x32_bf16 v[76:79], v[164:167], v[216:219], v[76:79]
	v_mfma_f32_16x16x32_bf16 v[112:115], v[168:171], v[184:187], v[112:115]
	v_mfma_f32_16x16x32_bf16 v[104:107], v[176:179], v[184:187], v[104:107]
	v_mfma_f32_16x16x32_bf16 v[96:99], v[168:171], v[196:199], v[96:99]
	v_mfma_f32_16x16x32_bf16 v[88:91], v[176:179], v[196:199], v[88:91]
	v_mfma_f32_16x16x32_bf16 v[80:83], v[168:171], v[204:207], v[80:83]
	v_mfma_f32_16x16x32_bf16 v[72:75], v[176:179], v[204:207], v[72:75]
	v_mfma_f32_16x16x32_bf16 v[68:71], v[168:171], v[212:215], v[68:71]
	v_mfma_f32_16x16x32_bf16 v[64:67], v[176:179], v[212:215], v[64:67]
	v_mfma_f32_16x16x32_bf16 v[112:115], v[172:175], v[192:195], v[112:115]
	v_mfma_f32_16x16x32_bf16 v[104:107], v[180:183], v[192:195], v[104:107]
	v_mfma_f32_16x16x32_bf16 v[96:99], v[172:175], v[200:203], v[96:99]
	v_mfma_f32_16x16x32_bf16 v[88:91], v[180:183], v[200:203], v[88:91]
	v_mfma_f32_16x16x32_bf16 v[80:83], v[172:175], v[208:211], v[80:83]
	v_mfma_f32_16x16x32_bf16 v[72:75], v[180:183], v[208:211], v[72:75]
	v_mfma_f32_16x16x32_bf16 v[68:71], v[172:175], v[216:219], v[68:71]
	v_mfma_f32_16x16x32_bf16 v[64:67], v[180:183], v[216:219], v[64:67]
	s_barrier
	s_add_i32 s40, s76, s53
	v_lshl_add_u64 v[144:145], v[144:145], 0, s[12:13]
	s_mov_b32 m0, s40
	ds_read_b128 v[184:187], v151 offset:49152
	ds_read_b128 v[192:195], v151 offset:50176
	ds_read_b128 v[196:199], v151 offset:51200
	ds_read_b128 v[200:203], v151 offset:52224
	ds_read_b128 v[204:207], v151 offset:53248
	ds_read_b128 v[208:211], v151 offset:54272
	ds_read_b128 v[212:215], v151 offset:55296
	ds_read_b128 v[216:219], v151 offset:56320
	global_load_lds_dwordx4 v[144:145], off
	s_add_i32 m0, s40, 0x2000
	s_add_u32 s38, s38, 0x40080
	v_lshl_add_u64 v[144:145], v[188:189], 0, s[12:13]
	s_addc_u32 s39, s39, 0
	s_add_i32 s40, s77, s53
	global_load_lds_dwordx4 v[144:145], off
	s_mov_b32 m0, s40
	s_nop 0
	global_load_lds_dwordx4 v130, s[38:39]
	s_add_i32 m0, s40, 0x2000
	s_nop 0
	global_load_lds_dwordx4 v134, s[38:39]
	v_lshl_add_u64 v[144:145], v[220:221], 0, s[12:13]
	s_mov_b32 m0, s63
	s_nop 0
	global_load_lds_dwordx4 v[144:145], off
	v_lshl_add_u64 v[144:145], v[222:223], 0, s[12:13]
	s_mov_b32 m0, s64
	s_nop 0
	global_load_lds_dwordx4 v[144:145], off
	s_waitcnt vmcnt(8)
	s_waitcnt lgkmcnt(0)
	s_barrier
	v_mfma_f32_16x16x32_bf16 v[60:63], v[152:155], v[184:187], v[60:63]
	v_mfma_f32_16x16x32_bf16 v[56:59], v[160:163], v[184:187], v[56:59]
	v_mfma_f32_16x16x32_bf16 v[52:55], v[152:155], v[196:199], v[52:55]
	v_mfma_f32_16x16x32_bf16 v[44:47], v[160:163], v[196:199], v[44:47]
	v_mfma_f32_16x16x32_bf16 v[36:39], v[152:155], v[204:207], v[36:39]
	v_mfma_f32_16x16x32_bf16 v[28:31], v[160:163], v[204:207], v[28:31]
	v_mfma_f32_16x16x32_bf16 v[20:23], v[152:155], v[212:215], v[20:23]
	v_mfma_f32_16x16x32_bf16 v[12:15], v[160:163], v[212:215], v[12:15]
	v_mfma_f32_16x16x32_bf16 v[60:63], v[156:159], v[192:195], v[60:63]
	v_mfma_f32_16x16x32_bf16 v[56:59], v[164:167], v[192:195], v[56:59]
	v_mfma_f32_16x16x32_bf16 v[52:55], v[156:159], v[200:203], v[52:55]
	v_mfma_f32_16x16x32_bf16 v[44:47], v[164:167], v[200:203], v[44:47]
	v_mfma_f32_16x16x32_bf16 v[36:39], v[156:159], v[208:211], v[36:39]
	v_mfma_f32_16x16x32_bf16 v[28:31], v[164:167], v[208:211], v[28:31]
	v_mfma_f32_16x16x32_bf16 v[20:23], v[156:159], v[216:219], v[20:23]
	v_mfma_f32_16x16x32_bf16 v[12:15], v[164:167], v[216:219], v[12:15]
	v_mfma_f32_16x16x32_bf16 v[48:51], v[168:171], v[184:187], v[48:51]
	v_mfma_f32_16x16x32_bf16 v[40:43], v[176:179], v[184:187], v[40:43]
	v_mfma_f32_16x16x32_bf16 v[32:35], v[168:171], v[196:199], v[32:35]
	v_mfma_f32_16x16x32_bf16 v[24:27], v[176:179], v[196:199], v[24:27]
	v_mfma_f32_16x16x32_bf16 v[16:19], v[168:171], v[204:207], v[16:19]
	v_mfma_f32_16x16x32_bf16 v[8:11], v[176:179], v[204:207], v[8:11]
	v_mfma_f32_16x16x32_bf16 v[4:7], v[168:171], v[212:215], v[4:7]
	v_mfma_f32_16x16x32_bf16 v[0:3], v[176:179], v[212:215], v[0:3]
	v_mfma_f32_16x16x32_bf16 v[48:51], v[172:175], v[192:195], v[48:51]
	v_mfma_f32_16x16x32_bf16 v[40:43], v[180:183], v[192:195], v[40:43]
	v_mfma_f32_16x16x32_bf16 v[32:35], v[172:175], v[200:203], v[32:35]
	v_mfma_f32_16x16x32_bf16 v[24:27], v[180:183], v[200:203], v[24:27]
	v_mfma_f32_16x16x32_bf16 v[16:19], v[172:175], v[208:211], v[16:19]
	v_mfma_f32_16x16x32_bf16 v[8:11], v[180:183], v[208:211], v[8:11]
	v_mfma_f32_16x16x32_bf16 v[4:7], v[172:175], v[216:219], v[4:7]
	v_mfma_f32_16x16x32_bf16 v[0:3], v[180:183], v[216:219], v[0:3]
	s_barrier
	s_add_i32 s75, s75, 2
	s_add_u32 s36, s36, 0x100
	s_addc_u32 s37, s37, 0
	s_add_u32 s73, s73, 0x100
	s_addc_u32 s74, s74, 0
	s_cmp_gt_u32 s75, 13
	s_cbranch_scc0 .LBB0_302

.LBB0_699:
	s_ashr_i32 s25, s24, 31
	s_lshl_b64 s[26:27], s[24:25], 19
	s_add_u32 s26, s58, s26
	s_addc_u32 s27, s59, s27
	s_and_b64 s[28:29], s[4:5], exec
	s_cselect_b32 s25, s27, s35
	s_cselect_b32 s55, s26, s34
	s_ashr_i32 s23, s22, 31
	s_lshl_b64 s[28:29], s[22:23], 19
	s_add_u32 s28, s43, s28
	s_addc_u32 s29, s52, s29
	s_and_b64 s[40:41], s[4:5], exec
	s_cselect_b32 s23, s29, s39
	s_cselect_b32 s72, s28, s38
	s_add_u32 s34, s34, 0x40080
	s_addc_u32 s35, s35, 0
	s_add_u32 s73, s38, 0x100
	s_addc_u32 s74, s39, 0
	s_mov_b32 s75, -2
	ds_read_b128 v[152:155], v149
	ds_read_b128 v[156:159], v149 offset:1024
	ds_read_b128 v[160:163], v149 offset:2048
	ds_read_b128 v[164:167], v149 offset:3072
	ds_read_b128 v[168:171], v150
	ds_read_b128 v[172:175], v150 offset:1024
	ds_read_b128 v[176:179], v150 offset:2048
	ds_read_b128 v[180:183], v150 offset:3072
	s_add_u32 s38, s34, 0xfffc0080
	s_addc_u32 s39, s35, -1
	s_cmp_eq_u32 s75, 12
	s_cselect_b32 s41, s25, s39
	s_cselect_b32 s40, s55, s38
	s_cselect_b32 s39, s23, s74
	s_cselect_b32 s38, s72, s73
	s_add_i32 m0, s31, 0xc000
	ds_read_b128 v[184:187], v151
	ds_read_b128 v[192:195], v151 offset:1024
	ds_read_b128 v[196:199], v151 offset:2048
	ds_read_b128 v[200:203], v151 offset:3072
	ds_read_b128 v[204:207], v151 offset:4096
	ds_read_b128 v[208:211], v151 offset:5120
	ds_read_b128 v[212:215], v151 offset:6144
	ds_read_b128 v[216:219], v151 offset:7168
	global_load_lds_dwordx4 v136, s[34:35]
	s_add_i32 m0, s31, 0xe000
	s_nop 0
	global_load_lds_dwordx4 v138, s[34:35]
	s_waitcnt vmcnt(8)
	s_waitcnt lgkmcnt(0)
	s_barrier
	v_mfma_f32_16x16x32_bf16 v[124:127], v[152:155], v[184:187], 0
	v_mfma_f32_16x16x32_bf16 v[120:123], v[160:163], v[184:187], 0
	v_mfma_f32_16x16x32_bf16 v[116:119], v[152:155], v[196:199], 0
	v_mfma_f32_16x16x32_bf16 v[108:111], v[160:163], v[196:199], 0
	v_mfma_f32_16x16x32_bf16 v[100:103], v[152:155], v[204:207], 0
	v_mfma_f32_16x16x32_bf16 v[92:95], v[160:163], v[204:207], 0
	v_mfma_f32_16x16x32_bf16 v[84:87], v[152:155], v[212:215], 0
	v_mfma_f32_16x16x32_bf16 v[76:79], v[160:163], v[212:215], 0
	v_mfma_f32_16x16x32_bf16 v[124:127], v[156:159], v[192:195], v[124:127]
	v_mfma_f32_16x16x32_bf16 v[120:123], v[164:167], v[192:195], v[120:123]
	v_mfma_f32_16x16x32_bf16 v[116:119], v[156:159], v[200:203], v[116:119]
	v_mfma_f32_16x16x32_bf16 v[108:111], v[164:167], v[200:203], v[108:111]
	v_mfma_f32_16x16x32_bf16 v[100:103], v[156:159], v[208:211], v[100:103]
	v_mfma_f32_16x16x32_bf16 v[92:95], v[164:167], v[208:211], v[92:95]
	v_mfma_f32_16x16x32_bf16 v[84:87], v[156:159], v[216:219], v[84:87]
	v_mfma_f32_16x16x32_bf16 v[76:79], v[164:167], v[216:219], v[76:79]
	v_mfma_f32_16x16x32_bf16 v[112:115], v[168:171], v[184:187], 0
	v_mfma_f32_16x16x32_bf16 v[104:107], v[176:179], v[184:187], 0
	v_mfma_f32_16x16x32_bf16 v[96:99], v[168:171], v[196:199], 0
	v_mfma_f32_16x16x32_bf16 v[88:91], v[176:179], v[196:199], 0
	v_mfma_f32_16x16x32_bf16 v[80:83], v[168:171], v[204:207], 0
	v_mfma_f32_16x16x32_bf16 v[72:75], v[176:179], v[204:207], 0
	v_mfma_f32_16x16x32_bf16 v[68:71], v[168:171], v[212:215], 0
	v_mfma_f32_16x16x32_bf16 v[64:67], v[176:179], v[212:215], 0
	v_mfma_f32_16x16x32_bf16 v[112:115], v[172:175], v[192:195], v[112:115]
	v_mfma_f32_16x16x32_bf16 v[104:107], v[180:183], v[192:195], v[104:107]
	v_mfma_f32_16x16x32_bf16 v[96:99], v[172:175], v[200:203], v[96:99]
	v_mfma_f32_16x16x32_bf16 v[88:91], v[180:183], v[200:203], v[88:91]
	v_mfma_f32_16x16x32_bf16 v[80:83], v[172:175], v[208:211], v[80:83]
	v_mfma_f32_16x16x32_bf16 v[72:75], v[180:183], v[208:211], v[72:75]
	v_mfma_f32_16x16x32_bf16 v[68:71], v[172:175], v[216:219], v[68:71]
	v_mfma_f32_16x16x32_bf16 v[64:67], v[180:183], v[216:219], v[64:67]
	s_barrier
	s_add_i32 s76, s66, s53
	v_lshl_add_u64 v[144:145], s[38:39], 0, v[130:131]
	s_mov_b32 m0, s76
	ds_read_b128 v[184:187], v151 offset:16384
	ds_read_b128 v[192:195], v151 offset:17408
	ds_read_b128 v[196:199], v151 offset:18432
	ds_read_b128 v[200:203], v151 offset:19456
	ds_read_b128 v[204:207], v151 offset:20480
	ds_read_b128 v[208:211], v151 offset:21504
	ds_read_b128 v[212:215], v151 offset:22528
	ds_read_b128 v[216:219], v151 offset:23552
	global_load_lds_dwordx4 v[144:145], off
	s_add_i32 m0, s76, 0x2000
	s_add_u32 s76, s38, 0x40000
	v_lshl_add_u64 v[188:189], s[38:39], 0, v[134:135]
	s_addc_u32 s77, s39, 0
	s_add_i32 s79, s67, s53
	global_load_lds_dwordx4 v[188:189], off
	s_mov_b32 m0, s79
	v_lshl_add_u64 v[222:223], s[40:41], 0, v[132:133]
	global_load_lds_dwordx4 v130, s[76:77]
	s_add_i32 m0, s79, 0x2000
	s_nop 0
	global_load_lds_dwordx4 v134, s[76:77]
	v_lshl_add_u64 v[220:221], s[40:41], 0, v[128:129]
	s_mov_b32 m0, s31
	s_nop 0
	global_load_lds_dwordx4 v[220:221], off
	s_mov_b32 m0, s33
	s_nop 0
	global_load_lds_dwordx4 v[222:223], off
	s_waitcnt vmcnt(8)
	s_waitcnt lgkmcnt(0)
	s_barrier
	v_mfma_f32_16x16x32_bf16 v[60:63], v[152:155], v[184:187], 0
	v_mfma_f32_16x16x32_bf16 v[56:59], v[160:163], v[184:187], 0
	v_mfma_f32_16x16x32_bf16 v[52:55], v[152:155], v[196:199], 0
	v_mfma_f32_16x16x32_bf16 v[44:47], v[160:163], v[196:199], 0
	v_mfma_f32_16x16x32_bf16 v[36:39], v[152:155], v[204:207], 0
	v_mfma_f32_16x16x32_bf16 v[28:31], v[160:163], v[204:207], 0
	v_mfma_f32_16x16x32_bf16 v[20:23], v[152:155], v[212:215], 0
	v_mfma_f32_16x16x32_bf16 v[12:15], v[160:163], v[212:215], 0
	v_mfma_f32_16x16x32_bf16 v[60:63], v[156:159], v[192:195], v[60:63]
	v_mfma_f32_16x16x32_bf16 v[56:59], v[164:167], v[192:195], v[56:59]
	v_mfma_f32_16x16x32_bf16 v[52:55], v[156:159], v[200:203], v[52:55]
	v_mfma_f32_16x16x32_bf16 v[44:47], v[164:167], v[200:203], v[44:47]
	v_mfma_f32_16x16x32_bf16 v[36:39], v[156:159], v[208:211], v[36:39]
	v_mfma_f32_16x16x32_bf16 v[28:31], v[164:167], v[208:211], v[28:31]
	v_mfma_f32_16x16x32_bf16 v[20:23], v[156:159], v[216:219], v[20:23]
	v_mfma_f32_16x16x32_bf16 v[12:15], v[164:167], v[216:219], v[12:15]
	v_mfma_f32_16x16x32_bf16 v[48:51], v[168:171], v[184:187], 0
	v_mfma_f32_16x16x32_bf16 v[40:43], v[176:179], v[184:187], 0
	v_mfma_f32_16x16x32_bf16 v[32:35], v[168:171], v[196:199], 0
	v_mfma_f32_16x16x32_bf16 v[24:27], v[176:179], v[196:199], 0
	v_mfma_f32_16x16x32_bf16 v[16:19], v[168:171], v[204:207], 0
	v_mfma_f32_16x16x32_bf16 v[8:11], v[176:179], v[204:207], 0
	v_mfma_f32_16x16x32_bf16 v[4:7], v[168:171], v[212:215], 0
	v_mfma_f32_16x16x32_bf16 v[0:3], v[176:179], v[212:215], 0
	v_mfma_f32_16x16x32_bf16 v[48:51], v[172:175], v[192:195], v[48:51]
	v_mfma_f32_16x16x32_bf16 v[40:43], v[180:183], v[192:195], v[40:43]
	v_mfma_f32_16x16x32_bf16 v[32:35], v[172:175], v[200:203], v[32:35]
	v_mfma_f32_16x16x32_bf16 v[24:27], v[180:183], v[200:203], v[24:27]
	v_mfma_f32_16x16x32_bf16 v[16:19], v[172:175], v[208:211], v[16:19]
	v_mfma_f32_16x16x32_bf16 v[8:11], v[180:183], v[208:211], v[8:11]
	v_mfma_f32_16x16x32_bf16 v[4:7], v[172:175], v[216:219], v[4:7]
	v_mfma_f32_16x16x32_bf16 v[0:3], v[180:183], v[216:219], v[0:3]
	s_barrier
	s_add_i32 s76, 0, 0x18000
	s_add_i32 s77, 0, 0x1c000
	v_add_u32_e32 v164, s76, v147
	v_add_u32_e32 v180, s77, v147
	ds_read_b128 v[152:155], v164
	ds_read_b128 v[156:159], v164 offset:1024
	ds_read_b128 v[160:163], v164 offset:2048
	ds_read_b128 v[164:167], v164 offset:3072
	ds_read_b128 v[168:171], v180
	ds_read_b128 v[172:175], v180 offset:1024
	ds_read_b128 v[176:179], v180 offset:2048
	ds_read_b128 v[180:183], v180 offset:3072
	s_add_u32 s40, s40, 0x40000
	s_addc_u32 s41, s41, 0
	s_mov_b32 m0, s60
	ds_read_b128 v[184:187], v151 offset:32768
	ds_read_b128 v[192:195], v151 offset:33792
	ds_read_b128 v[196:199], v151 offset:34816
	ds_read_b128 v[200:203], v151 offset:35840
	ds_read_b128 v[204:207], v151 offset:36864
	ds_read_b128 v[208:211], v151 offset:37888
	ds_read_b128 v[212:215], v151 offset:38912
	ds_read_b128 v[216:219], v151 offset:39936
	global_load_lds_dwordx4 v128, s[40:41]
	s_mov_b32 m0, s61
	s_nop 0
	global_load_lds_dwordx4 v132, s[40:41]
	s_waitcnt vmcnt(8)
	s_waitcnt lgkmcnt(0)
	s_barrier
	v_mfma_f32_16x16x32_bf16 v[124:127], v[152:155], v[184:187], v[124:127]
	v_mfma_f32_16x16x32_bf16 v[120:123], v[160:163], v[184:187], v[120:123]
	v_mfma_f32_16x16x32_bf16 v[116:119], v[152:155], v[196:199], v[116:119]
	v_mfma_f32_16x16x32_bf16 v[108:111], v[160:163], v[196:199], v[108:111]
	v_mfma_f32_16x16x32_bf16 v[100:103], v[152:155], v[204:207], v[100:103]
	v_mfma_f32_16x16x32_bf16 v[92:95], v[160:163], v[204:207], v[92:95]
	v_mfma_f32_16x16x32_bf16 v[84:87], v[152:155], v[212:215], v[84:87]
	v_mfma_f32_16x16x32_bf16 v[76:79], v[160:163], v[212:215], v[76:79]
	v_mfma_f32_16x16x32_bf16 v[124:127], v[156:159], v[192:195], v[124:127]
	v_mfma_f32_16x16x32_bf16 v[120:123], v[164:167], v[192:195], v[120:123]
	v_mfma_f32_16x16x32_bf16 v[116:119], v[156:159], v[200:203], v[116:119]
	v_mfma_f32_16x16x32_bf16 v[108:111], v[164:167], v[200:203], v[108:111]
	v_mfma_f32_16x16x32_bf16 v[100:103], v[156:159], v[208:211], v[100:103]
	v_mfma_f32_16x16x32_bf16 v[92:95], v[164:167], v[208:211], v[92:95]
	v_mfma_f32_16x16x32_bf16 v[84:87], v[156:159], v[216:219], v[84:87]
	v_mfma_f32_16x16x32_bf16 v[76:79], v[164:167], v[216:219], v[76:79]
	v_mfma_f32_16x16x32_bf16 v[112:115], v[168:171], v[184:187], v[112:115]
	v_mfma_f32_16x16x32_bf16 v[104:107], v[176:179], v[184:187], v[104:107]
	v_mfma_f32_16x16x32_bf16 v[96:99], v[168:171], v[196:199], v[96:99]
	v_mfma_f32_16x16x32_bf16 v[88:91], v[176:179], v[196:199], v[88:91]
	v_mfma_f32_16x16x32_bf16 v[80:83], v[168:171], v[204:207], v[80:83]
	v_mfma_f32_16x16x32_bf16 v[72:75], v[176:179], v[204:207], v[72:75]
	v_mfma_f32_16x16x32_bf16 v[68:71], v[168:171], v[212:215], v[68:71]
	v_mfma_f32_16x16x32_bf16 v[64:67], v[176:179], v[212:215], v[64:67]
	v_mfma_f32_16x16x32_bf16 v[112:115], v[172:175], v[192:195], v[112:115]
	v_mfma_f32_16x16x32_bf16 v[104:107], v[180:183], v[192:195], v[104:107]
	v_mfma_f32_16x16x32_bf16 v[96:99], v[172:175], v[200:203], v[96:99]
	v_mfma_f32_16x16x32_bf16 v[88:91], v[180:183], v[200:203], v[88:91]
	v_mfma_f32_16x16x32_bf16 v[80:83], v[172:175], v[208:211], v[80:83]
	v_mfma_f32_16x16x32_bf16 v[72:75], v[180:183], v[208:211], v[72:75]
	v_mfma_f32_16x16x32_bf16 v[68:71], v[172:175], v[216:219], v[68:71]
	v_mfma_f32_16x16x32_bf16 v[64:67], v[180:183], v[216:219], v[64:67]
	s_barrier
	s_add_i32 s40, s76, s53
	v_lshl_add_u64 v[144:145], v[144:145], 0, s[12:13]
	s_mov_b32 m0, s40
	ds_read_b128 v[184:187], v151 offset:49152
	ds_read_b128 v[192:195], v151 offset:50176
	ds_read_b128 v[196:199], v151 offset:51200
	ds_read_b128 v[200:203], v151 offset:52224
	ds_read_b128 v[204:207], v151 offset:53248
	ds_read_b128 v[208:211], v151 offset:54272
	ds_read_b128 v[212:215], v151 offset:55296
	ds_read_b128 v[216:219], v151 offset:56320
	global_load_lds_dwordx4 v[144:145], off
	s_add_i32 m0, s40, 0x2000
	s_add_u32 s38, s38, 0x40080
	v_lshl_add_u64 v[144:145], v[188:189], 0, s[12:13]
	s_addc_u32 s39, s39, 0
	s_add_i32 s40, s77, s53
	global_load_lds_dwordx4 v[144:145], off
	s_mov_b32 m0, s40
	s_nop 0
	global_load_lds_dwordx4 v130, s[38:39]
	s_add_i32 m0, s40, 0x2000
	s_nop 0
	global_load_lds_dwordx4 v134, s[38:39]
	v_lshl_add_u64 v[144:145], v[220:221], 0, s[12:13]
	s_mov_b32 m0, s63
	s_nop 0
	global_load_lds_dwordx4 v[144:145], off
	v_lshl_add_u64 v[144:145], v[222:223], 0, s[12:13]
	s_mov_b32 m0, s64
	s_nop 0
	global_load_lds_dwordx4 v[144:145], off
	s_waitcnt vmcnt(8)
	s_waitcnt lgkmcnt(0)
	s_barrier
	v_mfma_f32_16x16x32_bf16 v[60:63], v[152:155], v[184:187], v[60:63]
	v_mfma_f32_16x16x32_bf16 v[56:59], v[160:163], v[184:187], v[56:59]
	v_mfma_f32_16x16x32_bf16 v[52:55], v[152:155], v[196:199], v[52:55]
	v_mfma_f32_16x16x32_bf16 v[44:47], v[160:163], v[196:199], v[44:47]
	v_mfma_f32_16x16x32_bf16 v[36:39], v[152:155], v[204:207], v[36:39]
	v_mfma_f32_16x16x32_bf16 v[28:31], v[160:163], v[204:207], v[28:31]
	v_mfma_f32_16x16x32_bf16 v[20:23], v[152:155], v[212:215], v[20:23]
	v_mfma_f32_16x16x32_bf16 v[12:15], v[160:163], v[212:215], v[12:15]
	v_mfma_f32_16x16x32_bf16 v[60:63], v[156:159], v[192:195], v[60:63]
	v_mfma_f32_16x16x32_bf16 v[56:59], v[164:167], v[192:195], v[56:59]
	v_mfma_f32_16x16x32_bf16 v[52:55], v[156:159], v[200:203], v[52:55]
	v_mfma_f32_16x16x32_bf16 v[44:47], v[164:167], v[200:203], v[44:47]
	v_mfma_f32_16x16x32_bf16 v[36:39], v[156:159], v[208:211], v[36:39]
	v_mfma_f32_16x16x32_bf16 v[28:31], v[164:167], v[208:211], v[28:31]
	v_mfma_f32_16x16x32_bf16 v[20:23], v[156:159], v[216:219], v[20:23]
	v_mfma_f32_16x16x32_bf16 v[12:15], v[164:167], v[216:219], v[12:15]
	v_mfma_f32_16x16x32_bf16 v[48:51], v[168:171], v[184:187], v[48:51]
	v_mfma_f32_16x16x32_bf16 v[40:43], v[176:179], v[184:187], v[40:43]
	v_mfma_f32_16x16x32_bf16 v[32:35], v[168:171], v[196:199], v[32:35]
	v_mfma_f32_16x16x32_bf16 v[24:27], v[176:179], v[196:199], v[24:27]
	v_mfma_f32_16x16x32_bf16 v[16:19], v[168:171], v[204:207], v[16:19]
	v_mfma_f32_16x16x32_bf16 v[8:11], v[176:179], v[204:207], v[8:11]
	v_mfma_f32_16x16x32_bf16 v[4:7], v[168:171], v[212:215], v[4:7]
	v_mfma_f32_16x16x32_bf16 v[0:3], v[176:179], v[212:215], v[0:3]
	v_mfma_f32_16x16x32_bf16 v[48:51], v[172:175], v[192:195], v[48:51]
	v_mfma_f32_16x16x32_bf16 v[40:43], v[180:183], v[192:195], v[40:43]
	v_mfma_f32_16x16x32_bf16 v[32:35], v[172:175], v[200:203], v[32:35]
	v_mfma_f32_16x16x32_bf16 v[24:27], v[180:183], v[200:203], v[24:27]
	v_mfma_f32_16x16x32_bf16 v[16:19], v[172:175], v[208:211], v[16:19]
	v_mfma_f32_16x16x32_bf16 v[8:11], v[180:183], v[208:211], v[8:11]
	v_mfma_f32_16x16x32_bf16 v[4:7], v[172:175], v[216:219], v[4:7]
	v_mfma_f32_16x16x32_bf16 v[0:3], v[180:183], v[216:219], v[0:3]
	s_barrier
	s_add_i32 s75, s75, 2
	s_add_u32 s34, s34, 0x100
	s_addc_u32 s35, s35, 0
	s_add_u32 s73, s73, 0x100
	s_addc_u32 s74, s74, 0
	s_cmp_gt_u32 s75, 13
	s_cbranch_scc0 .LBB0_700
	s_branch .Lpeel_exit2
.LBB0_700:
	ds_read_b128 v[152:155], v149
	ds_read_b128 v[156:159], v149 offset:1024
	ds_read_b128 v[160:163], v149 offset:2048
	ds_read_b128 v[164:167], v149 offset:3072
	ds_read_b128 v[168:171], v150
	ds_read_b128 v[172:175], v150 offset:1024
	ds_read_b128 v[176:179], v150 offset:2048
	ds_read_b128 v[180:183], v150 offset:3072
	s_add_u32 s38, s34, 0xfffc0080
	s_addc_u32 s39, s35, -1
	s_cmp_eq_u32 s75, 12
	s_cselect_b32 s41, s25, s39
	s_cselect_b32 s40, s55, s38
	s_cselect_b32 s39, s23, s74
	s_cselect_b32 s38, s72, s73
	s_add_i32 m0, s31, 0xc000
	ds_read_b128 v[184:187], v151
	ds_read_b128 v[192:195], v151 offset:1024
	ds_read_b128 v[196:199], v151 offset:2048
	ds_read_b128 v[200:203], v151 offset:3072
	ds_read_b128 v[204:207], v151 offset:4096
	ds_read_b128 v[208:211], v151 offset:5120
	ds_read_b128 v[212:215], v151 offset:6144
	ds_read_b128 v[216:219], v151 offset:7168
	global_load_lds_dwordx4 v136, s[34:35]
	s_add_i32 m0, s31, 0xe000
	s_nop 0
	global_load_lds_dwordx4 v138, s[34:35]
	s_waitcnt vmcnt(8)
	s_waitcnt lgkmcnt(0)
	s_barrier
	v_mfma_f32_16x16x32_bf16 v[124:127], v[152:155], v[184:187], v[124:127]
	v_mfma_f32_16x16x32_bf16 v[120:123], v[160:163], v[184:187], v[120:123]
	v_mfma_f32_16x16x32_bf16 v[116:119], v[152:155], v[196:199], v[116:119]
	v_mfma_f32_16x16x32_bf16 v[108:111], v[160:163], v[196:199], v[108:111]
	v_mfma_f32_16x16x32_bf16 v[100:103], v[152:155], v[204:207], v[100:103]
	v_mfma_f32_16x16x32_bf16 v[92:95], v[160:163], v[204:207], v[92:95]
	v_mfma_f32_16x16x32_bf16 v[84:87], v[152:155], v[212:215], v[84:87]
	v_mfma_f32_16x16x32_bf16 v[76:79], v[160:163], v[212:215], v[76:79]
	v_mfma_f32_16x16x32_bf16 v[124:127], v[156:159], v[192:195], v[124:127]
	v_mfma_f32_16x16x32_bf16 v[120:123], v[164:167], v[192:195], v[120:123]
	v_mfma_f32_16x16x32_bf16 v[116:119], v[156:159], v[200:203], v[116:119]
	v_mfma_f32_16x16x32_bf16 v[108:111], v[164:167], v[200:203], v[108:111]
	v_mfma_f32_16x16x32_bf16 v[100:103], v[156:159], v[208:211], v[100:103]
	v_mfma_f32_16x16x32_bf16 v[92:95], v[164:167], v[208:211], v[92:95]
	v_mfma_f32_16x16x32_bf16 v[84:87], v[156:159], v[216:219], v[84:87]
	v_mfma_f32_16x16x32_bf16 v[76:79], v[164:167], v[216:219], v[76:79]
	v_mfma_f32_16x16x32_bf16 v[112:115], v[168:171], v[184:187], v[112:115]
	v_mfma_f32_16x16x32_bf16 v[104:107], v[176:179], v[184:187], v[104:107]
	v_mfma_f32_16x16x32_bf16 v[96:99], v[168:171], v[196:199], v[96:99]
	v_mfma_f32_16x16x32_bf16 v[88:91], v[176:179], v[196:199], v[88:91]
	v_mfma_f32_16x16x32_bf16 v[80:83], v[168:171], v[204:207], v[80:83]
	v_mfma_f32_16x16x32_bf16 v[72:75], v[176:179], v[204:207], v[72:75]
	v_mfma_f32_16x16x32_bf16 v[68:71], v[168:171], v[212:215], v[68:71]
	v_mfma_f32_16x16x32_bf16 v[64:67], v[176:179], v[212:215], v[64:67]
	v_mfma_f32_16x16x32_bf16 v[112:115], v[172:175], v[192:195], v[112:115]
	v_mfma_f32_16x16x32_bf16 v[104:107], v[180:183], v[192:195], v[104:107]
	v_mfma_f32_16x16x32_bf16 v[96:99], v[172:175], v[200:203], v[96:99]
	v_mfma_f32_16x16x32_bf16 v[88:91], v[180:183], v[200:203], v[88:91]
	v_mfma_f32_16x16x32_bf16 v[80:83], v[172:175], v[208:211], v[80:83]
	v_mfma_f32_16x16x32_bf16 v[72:75], v[180:183], v[208:211], v[72:75]
	v_mfma_f32_16x16x32_bf16 v[68:71], v[172:175], v[216:219], v[68:71]
	v_mfma_f32_16x16x32_bf16 v[64:67], v[180:183], v[216:219], v[64:67]
	s_barrier
	s_add_i32 s76, s66, s53
	v_lshl_add_u64 v[144:145], s[38:39], 0, v[130:131]
	s_mov_b32 m0, s76
	ds_read_b128 v[184:187], v151 offset:16384
	ds_read_b128 v[192:195], v151 offset:17408
	ds_read_b128 v[196:199], v151 offset:18432
	ds_read_b128 v[200:203], v151 offset:19456
	ds_read_b128 v[204:207], v151 offset:20480
	ds_read_b128 v[208:211], v151 offset:21504
	ds_read_b128 v[212:215], v151 offset:22528
	ds_read_b128 v[216:219], v151 offset:23552
	global_load_lds_dwordx4 v[144:145], off
	s_add_i32 m0, s76, 0x2000
	s_add_u32 s76, s38, 0x40000
	v_lshl_add_u64 v[188:189], s[38:39], 0, v[134:135]
	s_addc_u32 s77, s39, 0
	s_add_i32 s79, s67, s53
	global_load_lds_dwordx4 v[188:189], off
	s_mov_b32 m0, s79
	v_lshl_add_u64 v[222:223], s[40:41], 0, v[132:133]
	global_load_lds_dwordx4 v130, s[76:77]
	s_add_i32 m0, s79, 0x2000
	s_nop 0
	global_load_lds_dwordx4 v134, s[76:77]
	v_lshl_add_u64 v[220:221], s[40:41], 0, v[128:129]
	s_mov_b32 m0, s31
	s_nop 0
	global_load_lds_dwordx4 v[220:221], off
	s_mov_b32 m0, s33
	s_nop 0
	global_load_lds_dwordx4 v[222:223], off
	s_waitcnt vmcnt(8)
	s_waitcnt lgkmcnt(0)
	s_barrier
	v_mfma_f32_16x16x32_bf16 v[60:63], v[152:155], v[184:187], v[60:63]
	v_mfma_f32_16x16x32_bf16 v[56:59], v[160:163], v[184:187], v[56:59]
	v_mfma_f32_16x16x32_bf16 v[52:55], v[152:155], v[196:199], v[52:55]
	v_mfma_f32_16x16x32_bf16 v[44:47], v[160:163], v[196:199], v[44:47]
	v_mfma_f32_16x16x32_bf16 v[36:39], v[152:155], v[204:207], v[36:39]
	v_mfma_f32_16x16x32_bf16 v[28:31], v[160:163], v[204:207], v[28:31]
	v_mfma_f32_16x16x32_bf16 v[20:23], v[152:155], v[212:215], v[20:23]
	v_mfma_f32_16x16x32_bf16 v[12:15], v[160:163], v[212:215], v[12:15]
	v_mfma_f32_16x16x32_bf16 v[60:63], v[156:159], v[192:195], v[60:63]
	v_mfma_f32_16x16x32_bf16 v[56:59], v[164:167], v[192:195], v[56:59]
	v_mfma_f32_16x16x32_bf16 v[52:55], v[156:159], v[200:203], v[52:55]
	v_mfma_f32_16x16x32_bf16 v[44:47], v[164:167], v[200:203], v[44:47]
	v_mfma_f32_16x16x32_bf16 v[36:39], v[156:159], v[208:211], v[36:39]
	v_mfma_f32_16x16x32_bf16 v[28:31], v[164:167], v[208:211], v[28:31]
	v_mfma_f32_16x16x32_bf16 v[20:23], v[156:159], v[216:219], v[20:23]
	v_mfma_f32_16x16x32_bf16 v[12:15], v[164:167], v[216:219], v[12:15]
	v_mfma_f32_16x16x32_bf16 v[48:51], v[168:171], v[184:187], v[48:51]
	v_mfma_f32_16x16x32_bf16 v[40:43], v[176:179], v[184:187], v[40:43]
	v_mfma_f32_16x16x32_bf16 v[32:35], v[168:171], v[196:199], v[32:35]
	v_mfma_f32_16x16x32_bf16 v[24:27], v[176:179], v[196:199], v[24:27]
	v_mfma_f32_16x16x32_bf16 v[16:19], v[168:171], v[204:207], v[16:19]
	v_mfma_f32_16x16x32_bf16 v[8:11], v[176:179], v[204:207], v[8:11]
	v_mfma_f32_16x16x32_bf16 v[4:7], v[168:171], v[212:215], v[4:7]
	v_mfma_f32_16x16x32_bf16 v[0:3], v[176:179], v[212:215], v[0:3]
	v_mfma_f32_16x16x32_bf16 v[48:51], v[172:175], v[192:195], v[48:51]
	v_mfma_f32_16x16x32_bf16 v[40:43], v[180:183], v[192:195], v[40:43]
	v_mfma_f32_16x16x32_bf16 v[32:35], v[172:175], v[200:203], v[32:35]
	v_mfma_f32_16x16x32_bf16 v[24:27], v[180:183], v[200:203], v[24:27]
	v_mfma_f32_16x16x32_bf16 v[16:19], v[172:175], v[208:211], v[16:19]
	v_mfma_f32_16x16x32_bf16 v[8:11], v[180:183], v[208:211], v[8:11]
	v_mfma_f32_16x16x32_bf16 v[4:7], v[172:175], v[216:219], v[4:7]
	v_mfma_f32_16x16x32_bf16 v[0:3], v[180:183], v[216:219], v[0:3]
	s_barrier
	s_add_i32 s76, 0, 0x18000
	s_add_i32 s77, 0, 0x1c000
	v_add_u32_e32 v164, s76, v147
	v_add_u32_e32 v180, s77, v147
	ds_read_b128 v[152:155], v164
	ds_read_b128 v[156:159], v164 offset:1024
	ds_read_b128 v[160:163], v164 offset:2048
	ds_read_b128 v[164:167], v164 offset:3072
	ds_read_b128 v[168:171], v180
	ds_read_b128 v[172:175], v180 offset:1024
	ds_read_b128 v[176:179], v180 offset:2048
	ds_read_b128 v[180:183], v180 offset:3072
	s_add_u32 s40, s40, 0x40000
	s_addc_u32 s41, s41, 0
	s_mov_b32 m0, s60
	ds_read_b128 v[184:187], v151 offset:32768
	ds_read_b128 v[192:195], v151 offset:33792
	ds_read_b128 v[196:199], v151 offset:34816
	ds_read_b128 v[200:203], v151 offset:35840
	ds_read_b128 v[204:207], v151 offset:36864
	ds_read_b128 v[208:211], v151 offset:37888
	ds_read_b128 v[212:215], v151 offset:38912
	ds_read_b128 v[216:219], v151 offset:39936
	global_load_lds_dwordx4 v128, s[40:41]
	s_mov_b32 m0, s61
	s_nop 0
	global_load_lds_dwordx4 v132, s[40:41]
	s_waitcnt vmcnt(8)
	s_waitcnt lgkmcnt(0)
	s_barrier
	v_mfma_f32_16x16x32_bf16 v[124:127], v[152:155], v[184:187], v[124:127]
	v_mfma_f32_16x16x32_bf16 v[120:123], v[160:163], v[184:187], v[120:123]
	v_mfma_f32_16x16x32_bf16 v[116:119], v[152:155], v[196:199], v[116:119]
	v_mfma_f32_16x16x32_bf16 v[108:111], v[160:163], v[196:199], v[108:111]
	v_mfma_f32_16x16x32_bf16 v[100:103], v[152:155], v[204:207], v[100:103]
	v_mfma_f32_16x16x32_bf16 v[92:95], v[160:163], v[204:207], v[92:95]
	v_mfma_f32_16x16x32_bf16 v[84:87], v[152:155], v[212:215], v[84:87]
	v_mfma_f32_16x16x32_bf16 v[76:79], v[160:163], v[212:215], v[76:79]
	v_mfma_f32_16x16x32_bf16 v[124:127], v[156:159], v[192:195], v[124:127]
	v_mfma_f32_16x16x32_bf16 v[120:123], v[164:167], v[192:195], v[120:123]
	v_mfma_f32_16x16x32_bf16 v[116:119], v[156:159], v[200:203], v[116:119]
	v_mfma_f32_16x16x32_bf16 v[108:111], v[164:167], v[200:203], v[108:111]
	v_mfma_f32_16x16x32_bf16 v[100:103], v[156:159], v[208:211], v[100:103]
	v_mfma_f32_16x16x32_bf16 v[92:95], v[164:167], v[208:211], v[92:95]
	v_mfma_f32_16x16x32_bf16 v[84:87], v[156:159], v[216:219], v[84:87]
	v_mfma_f32_16x16x32_bf16 v[76:79], v[164:167], v[216:219], v[76:79]
	v_mfma_f32_16x16x32_bf16 v[112:115], v[168:171], v[184:187], v[112:115]
	v_mfma_f32_16x16x32_bf16 v[104:107], v[176:179], v[184:187], v[104:107]
	v_mfma_f32_16x16x32_bf16 v[96:99], v[168:171], v[196:199], v[96:99]
	v_mfma_f32_16x16x32_bf16 v[88:91], v[176:179], v[196:199], v[88:91]
	v_mfma_f32_16x16x32_bf16 v[80:83], v[168:171], v[204:207], v[80:83]
	v_mfma_f32_16x16x32_bf16 v[72:75], v[176:179], v[204:207], v[72:75]
	v_mfma_f32_16x16x32_bf16 v[68:71], v[168:171], v[212:215], v[68:71]
	v_mfma_f32_16x16x32_bf16 v[64:67], v[176:179], v[212:215], v[64:67]
	v_mfma_f32_16x16x32_bf16 v[112:115], v[172:175], v[192:195], v[112:115]
	v_mfma_f32_16x16x32_bf16 v[104:107], v[180:183], v[192:195], v[104:107]
	v_mfma_f32_16x16x32_bf16 v[96:99], v[172:175], v[200:203], v[96:99]
	v_mfma_f32_16x16x32_bf16 v[88:91], v[180:183], v[200:203], v[88:91]
	v_mfma_f32_16x16x32_bf16 v[80:83], v[172:175], v[208:211], v[80:83]
	v_mfma_f32_16x16x32_bf16 v[72:75], v[180:183], v[208:211], v[72:75]
	v_mfma_f32_16x16x32_bf16 v[68:71], v[172:175], v[216:219], v[68:71]
	v_mfma_f32_16x16x32_bf16 v[64:67], v[180:183], v[216:219], v[64:67]
	s_barrier
	s_add_i32 s40, s76, s53
	v_lshl_add_u64 v[144:145], v[144:145], 0, s[12:13]
	s_mov_b32 m0, s40
	ds_read_b128 v[184:187], v151 offset:49152
	ds_read_b128 v[192:195], v151 offset:50176
	ds_read_b128 v[196:199], v151 offset:51200
	ds_read_b128 v[200:203], v151 offset:52224
	ds_read_b128 v[204:207], v151 offset:53248
	ds_read_b128 v[208:211], v151 offset:54272
	ds_read_b128 v[212:215], v151 offset:55296
	ds_read_b128 v[216:219], v151 offset:56320
	global_load_lds_dwordx4 v[144:145], off
	s_add_i32 m0, s40, 0x2000
	s_add_u32 s38, s38, 0x40080
	v_lshl_add_u64 v[144:145], v[188:189], 0, s[12:13]
	s_addc_u32 s39, s39, 0
	s_add_i32 s40, s77, s53
	global_load_lds_dwordx4 v[144:145], off
	s_mov_b32 m0, s40
	s_nop 0
	global_load_lds_dwordx4 v130, s[38:39]
	s_add_i32 m0, s40, 0x2000
	s_nop 0
	global_load_lds_dwordx4 v134, s[38:39]
	v_lshl_add_u64 v[144:145], v[220:221], 0, s[12:13]
	s_mov_b32 m0, s63
	s_nop 0
	global_load_lds_dwordx4 v[144:145], off
	v_lshl_add_u64 v[144:145], v[222:223], 0, s[12:13]
	s_mov_b32 m0, s64
	s_nop 0
	global_load_lds_dwordx4 v[144:145], off
	s_waitcnt vmcnt(8)
	s_waitcnt lgkmcnt(0)
	s_barrier
	v_mfma_f32_16x16x32_bf16 v[60:63], v[152:155], v[184:187], v[60:63]
	v_mfma_f32_16x16x32_bf16 v[56:59], v[160:163], v[184:187], v[56:59]
	v_mfma_f32_16x16x32_bf16 v[52:55], v[152:155], v[196:199], v[52:55]
	v_mfma_f32_16x16x32_bf16 v[44:47], v[160:163], v[196:199], v[44:47]
	v_mfma_f32_16x16x32_bf16 v[36:39], v[152:155], v[204:207], v[36:39]
	v_mfma_f32_16x16x32_bf16 v[28:31], v[160:163], v[204:207], v[28:31]
	v_mfma_f32_16x16x32_bf16 v[20:23], v[152:155], v[212:215], v[20:23]
	v_mfma_f32_16x16x32_bf16 v[12:15], v[160:163], v[212:215], v[12:15]
	v_mfma_f32_16x16x32_bf16 v[60:63], v[156:159], v[192:195], v[60:63]
	v_mfma_f32_16x16x32_bf16 v[56:59], v[164:167], v[192:195], v[56:59]
	v_mfma_f32_16x16x32_bf16 v[52:55], v[156:159], v[200:203], v[52:55]
	v_mfma_f32_16x16x32_bf16 v[44:47], v[164:167], v[200:203], v[44:47]
	v_mfma_f32_16x16x32_bf16 v[36:39], v[156:159], v[208:211], v[36:39]
	v_mfma_f32_16x16x32_bf16 v[28:31], v[164:167], v[208:211], v[28:31]
	v_mfma_f32_16x16x32_bf16 v[20:23], v[156:159], v[216:219], v[20:23]
	v_mfma_f32_16x16x32_bf16 v[12:15], v[164:167], v[216:219], v[12:15]
	v_mfma_f32_16x16x32_bf16 v[48:51], v[168:171], v[184:187], v[48:51]
	v_mfma_f32_16x16x32_bf16 v[40:43], v[176:179], v[184:187], v[40:43]
	v_mfma_f32_16x16x32_bf16 v[32:35], v[168:171], v[196:199], v[32:35]
	v_mfma_f32_16x16x32_bf16 v[24:27], v[176:179], v[196:199], v[24:27]
	v_mfma_f32_16x16x32_bf16 v[16:19], v[168:171], v[204:207], v[16:19]
	v_mfma_f32_16x16x32_bf16 v[8:11], v[176:179], v[204:207], v[8:11]
	v_mfma_f32_16x16x32_bf16 v[4:7], v[168:171], v[212:215], v[4:7]
	v_mfma_f32_16x16x32_bf16 v[0:3], v[176:179], v[212:215], v[0:3]
	v_mfma_f32_16x16x32_bf16 v[48:51], v[172:175], v[192:195], v[48:51]
	v_mfma_f32_16x16x32_bf16 v[40:43], v[180:183], v[192:195], v[40:43]
	v_mfma_f32_16x16x32_bf16 v[32:35], v[172:175], v[200:203], v[32:35]
	v_mfma_f32_16x16x32_bf16 v[24:27], v[180:183], v[200:203], v[24:27]
	v_mfma_f32_16x16x32_bf16 v[16:19], v[172:175], v[208:211], v[16:19]
	v_mfma_f32_16x16x32_bf16 v[8:11], v[180:183], v[208:211], v[8:11]
	v_mfma_f32_16x16x32_bf16 v[4:7], v[172:175], v[216:219], v[4:7]
	v_mfma_f32_16x16x32_bf16 v[0:3], v[180:183], v[216:219], v[0:3]
	s_barrier
	s_add_i32 s75, s75, 2
	s_add_u32 s34, s34, 0x100
	s_addc_u32 s35, s35, 0
	s_add_u32 s73, s73, 0x100
	s_addc_u32 s74, s74, 0
	s_cmp_gt_u32 s75, 13
	s_cbranch_scc0 .LBB0_700

.LBB0_836:
	s_ashr_i32 s25, s24, 31
	s_lshl_b64 s[26:27], s[24:25], 19
	s_add_u32 s26, s58, s26
	s_addc_u32 s27, s59, s27
	s_and_b64 s[28:29], s[4:5], exec
	s_cselect_b32 s25, s27, s35
	s_cselect_b32 s54, s26, s34
	s_ashr_i32 s23, s22, 31
	s_lshl_b64 s[28:29], s[22:23], 19
	s_add_u32 s28, s61, s28
	s_addc_u32 s29, s62, s29
	s_and_b64 s[42:43], s[4:5], exec
	s_cselect_b32 s23, s29, s41
	s_cselect_b32 s55, s28, s40
	s_add_u32 s34, s34, 0x40080
	s_addc_u32 s35, s35, 0
	s_add_u32 s75, s40, 0x100
	s_addc_u32 s76, s41, 0
	s_mov_b32 s77, -2
	ds_read_b128 v[152:155], v149
	ds_read_b128 v[156:159], v149 offset:1024
	ds_read_b128 v[160:163], v149 offset:2048
	ds_read_b128 v[164:167], v149 offset:3072
	ds_read_b128 v[168:171], v150
	ds_read_b128 v[172:175], v150 offset:1024
	ds_read_b128 v[176:179], v150 offset:2048
	ds_read_b128 v[180:183], v150 offset:3072
	s_add_u32 s40, s34, 0xfffc0080
	s_addc_u32 s41, s35, -1
	s_cmp_eq_u32 s77, 12
	s_cselect_b32 s43, s25, s41
	s_cselect_b32 s42, s54, s40
	s_cselect_b32 s41, s23, s76
	s_cselect_b32 s40, s55, s75
	s_add_i32 m0, s31, 0xc000
	ds_read_b128 v[184:187], v151
	ds_read_b128 v[192:195], v151 offset:1024
	ds_read_b128 v[196:199], v151 offset:2048
	ds_read_b128 v[200:203], v151 offset:3072
	ds_read_b128 v[204:207], v151 offset:4096
	ds_read_b128 v[208:211], v151 offset:5120
	ds_read_b128 v[212:215], v151 offset:6144
	ds_read_b128 v[216:219], v151 offset:7168
	global_load_lds_dwordx4 v136, s[34:35]
	s_add_i32 m0, s31, 0xe000
	s_nop 0
	global_load_lds_dwordx4 v138, s[34:35]
	s_waitcnt vmcnt(8)
	s_waitcnt lgkmcnt(0)
	s_barrier
	v_mfma_f32_16x16x32_bf16 v[124:127], v[152:155], v[184:187], 0
	v_mfma_f32_16x16x32_bf16 v[120:123], v[160:163], v[184:187], 0
	v_mfma_f32_16x16x32_bf16 v[108:111], v[152:155], v[196:199], 0
	v_mfma_f32_16x16x32_bf16 v[104:107], v[160:163], v[196:199], 0
	v_mfma_f32_16x16x32_bf16 v[92:95], v[152:155], v[204:207], 0
	v_mfma_f32_16x16x32_bf16 v[88:91], v[160:163], v[204:207], 0
	v_mfma_f32_16x16x32_bf16 v[76:79], v[152:155], v[212:215], 0
	v_mfma_f32_16x16x32_bf16 v[72:75], v[160:163], v[212:215], 0
	v_mfma_f32_16x16x32_bf16 v[124:127], v[156:159], v[192:195], v[124:127]
	v_mfma_f32_16x16x32_bf16 v[120:123], v[164:167], v[192:195], v[120:123]
	v_mfma_f32_16x16x32_bf16 v[108:111], v[156:159], v[200:203], v[108:111]
	v_mfma_f32_16x16x32_bf16 v[104:107], v[164:167], v[200:203], v[104:107]
	v_mfma_f32_16x16x32_bf16 v[92:95], v[156:159], v[208:211], v[92:95]
	v_mfma_f32_16x16x32_bf16 v[88:91], v[164:167], v[208:211], v[88:91]
	v_mfma_f32_16x16x32_bf16 v[76:79], v[156:159], v[216:219], v[76:79]
	v_mfma_f32_16x16x32_bf16 v[72:75], v[164:167], v[216:219], v[72:75]
	v_mfma_f32_16x16x32_bf16 v[116:119], v[168:171], v[184:187], 0
	v_mfma_f32_16x16x32_bf16 v[112:115], v[176:179], v[184:187], 0
	v_mfma_f32_16x16x32_bf16 v[100:103], v[168:171], v[196:199], 0
	v_mfma_f32_16x16x32_bf16 v[96:99], v[176:179], v[196:199], 0
	v_mfma_f32_16x16x32_bf16 v[84:87], v[168:171], v[204:207], 0
	v_mfma_f32_16x16x32_bf16 v[80:83], v[176:179], v[204:207], 0
	v_mfma_f32_16x16x32_bf16 v[68:71], v[168:171], v[212:215], 0
	v_mfma_f32_16x16x32_bf16 v[64:67], v[176:179], v[212:215], 0
	v_mfma_f32_16x16x32_bf16 v[116:119], v[172:175], v[192:195], v[116:119]
	v_mfma_f32_16x16x32_bf16 v[112:115], v[180:183], v[192:195], v[112:115]
	v_mfma_f32_16x16x32_bf16 v[100:103], v[172:175], v[200:203], v[100:103]
	v_mfma_f32_16x16x32_bf16 v[96:99], v[180:183], v[200:203], v[96:99]
	v_mfma_f32_16x16x32_bf16 v[84:87], v[172:175], v[208:211], v[84:87]
	v_mfma_f32_16x16x32_bf16 v[80:83], v[180:183], v[208:211], v[80:83]
	v_mfma_f32_16x16x32_bf16 v[68:71], v[172:175], v[216:219], v[68:71]
	v_mfma_f32_16x16x32_bf16 v[64:67], v[180:183], v[216:219], v[64:67]
	s_barrier
	s_add_i32 s79, s69, s63
	v_lshl_add_u64 v[144:145], s[40:41], 0, v[130:131]
	s_mov_b32 m0, s79
	ds_read_b128 v[184:187], v151 offset:16384
	ds_read_b128 v[192:195], v151 offset:17408
	ds_read_b128 v[196:199], v151 offset:18432
	ds_read_b128 v[200:203], v151 offset:19456
	ds_read_b128 v[204:207], v151 offset:20480
	ds_read_b128 v[208:211], v151 offset:21504
	ds_read_b128 v[212:215], v151 offset:22528
	ds_read_b128 v[216:219], v151 offset:23552
	global_load_lds_dwordx4 v[144:145], off
	s_add_i32 m0, s79, 0x2000
	s_add_u32 s80, s40, 0x40000
	v_lshl_add_u64 v[188:189], s[40:41], 0, v[134:135]
	s_addc_u32 s81, s41, 0
	s_add_i32 s79, s70, s63
	global_load_lds_dwordx4 v[188:189], off
	s_mov_b32 m0, s79
	v_lshl_add_u64 v[222:223], s[42:43], 0, v[132:133]
	global_load_lds_dwordx4 v130, s[80:81]
	s_add_i32 m0, s79, 0x2000
	s_nop 0
	global_load_lds_dwordx4 v134, s[80:81]
	v_lshl_add_u64 v[220:221], s[42:43], 0, v[128:129]
	s_mov_b32 m0, s31
	s_nop 0
	global_load_lds_dwordx4 v[220:221], off
	s_mov_b32 m0, s64
	s_nop 0
	global_load_lds_dwordx4 v[222:223], off
	s_waitcnt vmcnt(8)
	s_waitcnt lgkmcnt(0)
	s_barrier
	v_mfma_f32_16x16x32_bf16 v[60:63], v[152:155], v[184:187], 0
	v_mfma_f32_16x16x32_bf16 v[56:59], v[160:163], v[184:187], 0
	v_mfma_f32_16x16x32_bf16 v[44:47], v[152:155], v[196:199], 0
	v_mfma_f32_16x16x32_bf16 v[40:43], v[160:163], v[196:199], 0
	v_mfma_f32_16x16x32_bf16 v[28:31], v[152:155], v[204:207], 0
	v_mfma_f32_16x16x32_bf16 v[24:27], v[160:163], v[204:207], 0
	v_mfma_f32_16x16x32_bf16 v[12:15], v[152:155], v[212:215], 0
	v_mfma_f32_16x16x32_bf16 v[8:11], v[160:163], v[212:215], 0
	v_mfma_f32_16x16x32_bf16 v[60:63], v[156:159], v[192:195], v[60:63]
	v_mfma_f32_16x16x32_bf16 v[56:59], v[164:167], v[192:195], v[56:59]
	v_mfma_f32_16x16x32_bf16 v[44:47], v[156:159], v[200:203], v[44:47]
	v_mfma_f32_16x16x32_bf16 v[40:43], v[164:167], v[200:203], v[40:43]
	v_mfma_f32_16x16x32_bf16 v[28:31], v[156:159], v[208:211], v[28:31]
	v_mfma_f32_16x16x32_bf16 v[24:27], v[164:167], v[208:211], v[24:27]
	v_mfma_f32_16x16x32_bf16 v[12:15], v[156:159], v[216:219], v[12:15]
	v_mfma_f32_16x16x32_bf16 v[8:11], v[164:167], v[216:219], v[8:11]
	v_mfma_f32_16x16x32_bf16 v[52:55], v[168:171], v[184:187], 0
	v_mfma_f32_16x16x32_bf16 v[48:51], v[176:179], v[184:187], 0
	v_mfma_f32_16x16x32_bf16 v[36:39], v[168:171], v[196:199], 0
	v_mfma_f32_16x16x32_bf16 v[32:35], v[176:179], v[196:199], 0
	v_mfma_f32_16x16x32_bf16 v[20:23], v[168:171], v[204:207], 0
	v_mfma_f32_16x16x32_bf16 v[16:19], v[176:179], v[204:207], 0
	v_mfma_f32_16x16x32_bf16 v[4:7], v[168:171], v[212:215], 0
	v_mfma_f32_16x16x32_bf16 v[0:3], v[176:179], v[212:215], 0
	v_mfma_f32_16x16x32_bf16 v[52:55], v[172:175], v[192:195], v[52:55]
	v_mfma_f32_16x16x32_bf16 v[48:51], v[180:183], v[192:195], v[48:51]
	v_mfma_f32_16x16x32_bf16 v[36:39], v[172:175], v[200:203], v[36:39]
	v_mfma_f32_16x16x32_bf16 v[32:35], v[180:183], v[200:203], v[32:35]
	v_mfma_f32_16x16x32_bf16 v[20:23], v[172:175], v[208:211], v[20:23]
	v_mfma_f32_16x16x32_bf16 v[16:19], v[180:183], v[208:211], v[16:19]
	v_mfma_f32_16x16x32_bf16 v[4:7], v[172:175], v[216:219], v[4:7]
	v_mfma_f32_16x16x32_bf16 v[0:3], v[180:183], v[216:219], v[0:3]
	s_barrier
	s_add_i32 s79, 0, 0x18000
	s_add_i32 s80, 0, 0x1c000
	v_add_u32_e32 v164, s79, v147
	v_add_u32_e32 v180, s80, v147
	ds_read_b128 v[152:155], v164
	ds_read_b128 v[156:159], v164 offset:1024
	ds_read_b128 v[160:163], v164 offset:2048
	ds_read_b128 v[164:167], v164 offset:3072
	ds_read_b128 v[168:171], v180
	ds_read_b128 v[172:175], v180 offset:1024
	ds_read_b128 v[176:179], v180 offset:2048
	ds_read_b128 v[180:183], v180 offset:3072
	s_add_u32 s42, s42, 0x40000
	s_addc_u32 s43, s43, 0
	s_mov_b32 m0, s65
	ds_read_b128 v[184:187], v151 offset:32768
	ds_read_b128 v[192:195], v151 offset:33792
	ds_read_b128 v[196:199], v151 offset:34816
	ds_read_b128 v[200:203], v151 offset:35840
	ds_read_b128 v[204:207], v151 offset:36864
	ds_read_b128 v[208:211], v151 offset:37888
	ds_read_b128 v[212:215], v151 offset:38912
	ds_read_b128 v[216:219], v151 offset:39936
	global_load_lds_dwordx4 v128, s[42:43]
	s_mov_b32 m0, s66
	s_nop 0
	global_load_lds_dwordx4 v132, s[42:43]
	s_waitcnt vmcnt(8)
	s_waitcnt lgkmcnt(0)
	s_barrier
	v_mfma_f32_16x16x32_bf16 v[124:127], v[152:155], v[184:187], v[124:127]
	v_mfma_f32_16x16x32_bf16 v[120:123], v[160:163], v[184:187], v[120:123]
	v_mfma_f32_16x16x32_bf16 v[108:111], v[152:155], v[196:199], v[108:111]
	v_mfma_f32_16x16x32_bf16 v[104:107], v[160:163], v[196:199], v[104:107]
	v_mfma_f32_16x16x32_bf16 v[92:95], v[152:155], v[204:207], v[92:95]
	v_mfma_f32_16x16x32_bf16 v[88:91], v[160:163], v[204:207], v[88:91]
	v_mfma_f32_16x16x32_bf16 v[76:79], v[152:155], v[212:215], v[76:79]
	v_mfma_f32_16x16x32_bf16 v[72:75], v[160:163], v[212:215], v[72:75]
	v_mfma_f32_16x16x32_bf16 v[124:127], v[156:159], v[192:195], v[124:127]
	v_mfma_f32_16x16x32_bf16 v[120:123], v[164:167], v[192:195], v[120:123]
	v_mfma_f32_16x16x32_bf16 v[108:111], v[156:159], v[200:203], v[108:111]
	v_mfma_f32_16x16x32_bf16 v[104:107], v[164:167], v[200:203], v[104:107]
	v_mfma_f32_16x16x32_bf16 v[92:95], v[156:159], v[208:211], v[92:95]
	v_mfma_f32_16x16x32_bf16 v[88:91], v[164:167], v[208:211], v[88:91]
	v_mfma_f32_16x16x32_bf16 v[76:79], v[156:159], v[216:219], v[76:79]
	v_mfma_f32_16x16x32_bf16 v[72:75], v[164:167], v[216:219], v[72:75]
	v_mfma_f32_16x16x32_bf16 v[116:119], v[168:171], v[184:187], v[116:119]
	v_mfma_f32_16x16x32_bf16 v[112:115], v[176:179], v[184:187], v[112:115]
	v_mfma_f32_16x16x32_bf16 v[100:103], v[168:171], v[196:199], v[100:103]
	v_mfma_f32_16x16x32_bf16 v[96:99], v[176:179], v[196:199], v[96:99]
	v_mfma_f32_16x16x32_bf16 v[84:87], v[168:171], v[204:207], v[84:87]
	v_mfma_f32_16x16x32_bf16 v[80:83], v[176:179], v[204:207], v[80:83]
	v_mfma_f32_16x16x32_bf16 v[68:71], v[168:171], v[212:215], v[68:71]
	v_mfma_f32_16x16x32_bf16 v[64:67], v[176:179], v[212:215], v[64:67]
	v_mfma_f32_16x16x32_bf16 v[116:119], v[172:175], v[192:195], v[116:119]
	v_mfma_f32_16x16x32_bf16 v[112:115], v[180:183], v[192:195], v[112:115]
	v_mfma_f32_16x16x32_bf16 v[100:103], v[172:175], v[200:203], v[100:103]
	v_mfma_f32_16x16x32_bf16 v[96:99], v[180:183], v[200:203], v[96:99]
	v_mfma_f32_16x16x32_bf16 v[84:87], v[172:175], v[208:211], v[84:87]
	v_mfma_f32_16x16x32_bf16 v[80:83], v[180:183], v[208:211], v[80:83]
	v_mfma_f32_16x16x32_bf16 v[68:71], v[172:175], v[216:219], v[68:71]
	v_mfma_f32_16x16x32_bf16 v[64:67], v[180:183], v[216:219], v[64:67]
	s_barrier
	s_add_i32 s42, s79, s63
	v_lshl_add_u64 v[144:145], v[144:145], 0, s[10:11]
	s_mov_b32 m0, s42
	ds_read_b128 v[184:187], v151 offset:49152
	ds_read_b128 v[192:195], v151 offset:50176
	ds_read_b128 v[196:199], v151 offset:51200
	ds_read_b128 v[200:203], v151 offset:52224
	ds_read_b128 v[204:207], v151 offset:53248
	ds_read_b128 v[208:211], v151 offset:54272
	ds_read_b128 v[212:215], v151 offset:55296
	ds_read_b128 v[216:219], v151 offset:56320
	global_load_lds_dwordx4 v[144:145], off
	s_add_i32 m0, s42, 0x2000
	s_add_u32 s40, s40, 0x40080
	v_lshl_add_u64 v[144:145], v[188:189], 0, s[10:11]
	s_addc_u32 s41, s41, 0
	s_add_i32 s42, s80, s63
	global_load_lds_dwordx4 v[144:145], off
	s_mov_b32 m0, s42
	s_nop 0
	global_load_lds_dwordx4 v130, s[40:41]
	s_add_i32 m0, s42, 0x2000
	s_nop 0
	global_load_lds_dwordx4 v134, s[40:41]
	v_lshl_add_u64 v[144:145], v[220:221], 0, s[10:11]
	s_mov_b32 m0, s52
	s_nop 0
	global_load_lds_dwordx4 v[144:145], off
	v_lshl_add_u64 v[144:145], v[222:223], 0, s[10:11]
	s_mov_b32 m0, s53
	s_nop 0
	global_load_lds_dwordx4 v[144:145], off
	s_waitcnt vmcnt(8)
	s_waitcnt lgkmcnt(0)
	s_barrier
	v_mfma_f32_16x16x32_bf16 v[60:63], v[152:155], v[184:187], v[60:63]
	v_mfma_f32_16x16x32_bf16 v[56:59], v[160:163], v[184:187], v[56:59]
	v_mfma_f32_16x16x32_bf16 v[44:47], v[152:155], v[196:199], v[44:47]
	v_mfma_f32_16x16x32_bf16 v[40:43], v[160:163], v[196:199], v[40:43]
	v_mfma_f32_16x16x32_bf16 v[28:31], v[152:155], v[204:207], v[28:31]
	v_mfma_f32_16x16x32_bf16 v[24:27], v[160:163], v[204:207], v[24:27]
	v_mfma_f32_16x16x32_bf16 v[12:15], v[152:155], v[212:215], v[12:15]
	v_mfma_f32_16x16x32_bf16 v[8:11], v[160:163], v[212:215], v[8:11]
	v_mfma_f32_16x16x32_bf16 v[60:63], v[156:159], v[192:195], v[60:63]
	v_mfma_f32_16x16x32_bf16 v[56:59], v[164:167], v[192:195], v[56:59]
	v_mfma_f32_16x16x32_bf16 v[44:47], v[156:159], v[200:203], v[44:47]
	v_mfma_f32_16x16x32_bf16 v[40:43], v[164:167], v[200:203], v[40:43]
	v_mfma_f32_16x16x32_bf16 v[28:31], v[156:159], v[208:211], v[28:31]
	v_mfma_f32_16x16x32_bf16 v[24:27], v[164:167], v[208:211], v[24:27]
	v_mfma_f32_16x16x32_bf16 v[12:15], v[156:159], v[216:219], v[12:15]
	v_mfma_f32_16x16x32_bf16 v[8:11], v[164:167], v[216:219], v[8:11]
	v_mfma_f32_16x16x32_bf16 v[52:55], v[168:171], v[184:187], v[52:55]
	v_mfma_f32_16x16x32_bf16 v[48:51], v[176:179], v[184:187], v[48:51]
	v_mfma_f32_16x16x32_bf16 v[36:39], v[168:171], v[196:199], v[36:39]
	v_mfma_f32_16x16x32_bf16 v[32:35], v[176:179], v[196:199], v[32:35]
	v_mfma_f32_16x16x32_bf16 v[20:23], v[168:171], v[204:207], v[20:23]
	v_mfma_f32_16x16x32_bf16 v[16:19], v[176:179], v[204:207], v[16:19]
	v_mfma_f32_16x16x32_bf16 v[4:7], v[168:171], v[212:215], v[4:7]
	v_mfma_f32_16x16x32_bf16 v[0:3], v[176:179], v[212:215], v[0:3]
	v_mfma_f32_16x16x32_bf16 v[52:55], v[172:175], v[192:195], v[52:55]
	v_mfma_f32_16x16x32_bf16 v[48:51], v[180:183], v[192:195], v[48:51]
	v_mfma_f32_16x16x32_bf16 v[36:39], v[172:175], v[200:203], v[36:39]
	v_mfma_f32_16x16x32_bf16 v[32:35], v[180:183], v[200:203], v[32:35]
	v_mfma_f32_16x16x32_bf16 v[20:23], v[172:175], v[208:211], v[20:23]
	v_mfma_f32_16x16x32_bf16 v[16:19], v[180:183], v[208:211], v[16:19]
	v_mfma_f32_16x16x32_bf16 v[4:7], v[172:175], v[216:219], v[4:7]
	v_mfma_f32_16x16x32_bf16 v[0:3], v[180:183], v[216:219], v[0:3]
	s_barrier
	s_add_i32 s77, s77, 2
	s_add_u32 s34, s34, 0x100
	s_addc_u32 s35, s35, 0
	s_add_u32 s75, s75, 0x100
	s_addc_u32 s76, s76, 0
	s_cmp_gt_u32 s77, 13
	s_cbranch_scc0 .LBB0_837
	s_branch .Lpeel_exit3
.LBB0_837:
	ds_read_b128 v[152:155], v149
	ds_read_b128 v[156:159], v149 offset:1024
	ds_read_b128 v[160:163], v149 offset:2048
	ds_read_b128 v[164:167], v149 offset:3072
	ds_read_b128 v[168:171], v150
	ds_read_b128 v[172:175], v150 offset:1024
	ds_read_b128 v[176:179], v150 offset:2048
	ds_read_b128 v[180:183], v150 offset:3072
	s_add_u32 s40, s34, 0xfffc0080
	s_addc_u32 s41, s35, -1
	s_cmp_eq_u32 s77, 12
	s_cselect_b32 s43, s25, s41
	s_cselect_b32 s42, s54, s40
	s_cselect_b32 s41, s23, s76
	s_cselect_b32 s40, s55, s75
	s_add_i32 m0, s31, 0xc000
	ds_read_b128 v[184:187], v151
	ds_read_b128 v[192:195], v151 offset:1024
	ds_read_b128 v[196:199], v151 offset:2048
	ds_read_b128 v[200:203], v151 offset:3072
	ds_read_b128 v[204:207], v151 offset:4096
	ds_read_b128 v[208:211], v151 offset:5120
	ds_read_b128 v[212:215], v151 offset:6144
	ds_read_b128 v[216:219], v151 offset:7168
	global_load_lds_dwordx4 v136, s[34:35]
	s_add_i32 m0, s31, 0xe000
	s_nop 0
	global_load_lds_dwordx4 v138, s[34:35]
	s_waitcnt vmcnt(8)
	s_waitcnt lgkmcnt(0)
	s_barrier
	v_mfma_f32_16x16x32_bf16 v[124:127], v[152:155], v[184:187], v[124:127]
	v_mfma_f32_16x16x32_bf16 v[120:123], v[160:163], v[184:187], v[120:123]
	v_mfma_f32_16x16x32_bf16 v[108:111], v[152:155], v[196:199], v[108:111]
	v_mfma_f32_16x16x32_bf16 v[104:107], v[160:163], v[196:199], v[104:107]
	v_mfma_f32_16x16x32_bf16 v[92:95], v[152:155], v[204:207], v[92:95]
	v_mfma_f32_16x16x32_bf16 v[88:91], v[160:163], v[204:207], v[88:91]
	v_mfma_f32_16x16x32_bf16 v[76:79], v[152:155], v[212:215], v[76:79]
	v_mfma_f32_16x16x32_bf16 v[72:75], v[160:163], v[212:215], v[72:75]
	v_mfma_f32_16x16x32_bf16 v[124:127], v[156:159], v[192:195], v[124:127]
	v_mfma_f32_16x16x32_bf16 v[120:123], v[164:167], v[192:195], v[120:123]
	v_mfma_f32_16x16x32_bf16 v[108:111], v[156:159], v[200:203], v[108:111]
	v_mfma_f32_16x16x32_bf16 v[104:107], v[164:167], v[200:203], v[104:107]
	v_mfma_f32_16x16x32_bf16 v[92:95], v[156:159], v[208:211], v[92:95]
	v_mfma_f32_16x16x32_bf16 v[88:91], v[164:167], v[208:211], v[88:91]
	v_mfma_f32_16x16x32_bf16 v[76:79], v[156:159], v[216:219], v[76:79]
	v_mfma_f32_16x16x32_bf16 v[72:75], v[164:167], v[216:219], v[72:75]
	v_mfma_f32_16x16x32_bf16 v[116:119], v[168:171], v[184:187], v[116:119]
	v_mfma_f32_16x16x32_bf16 v[112:115], v[176:179], v[184:187], v[112:115]
	v_mfma_f32_16x16x32_bf16 v[100:103], v[168:171], v[196:199], v[100:103]
	v_mfma_f32_16x16x32_bf16 v[96:99], v[176:179], v[196:199], v[96:99]
	v_mfma_f32_16x16x32_bf16 v[84:87], v[168:171], v[204:207], v[84:87]
	v_mfma_f32_16x16x32_bf16 v[80:83], v[176:179], v[204:207], v[80:83]
	v_mfma_f32_16x16x32_bf16 v[68:71], v[168:171], v[212:215], v[68:71]
	v_mfma_f32_16x16x32_bf16 v[64:67], v[176:179], v[212:215], v[64:67]
	v_mfma_f32_16x16x32_bf16 v[116:119], v[172:175], v[192:195], v[116:119]
	v_mfma_f32_16x16x32_bf16 v[112:115], v[180:183], v[192:195], v[112:115]
	v_mfma_f32_16x16x32_bf16 v[100:103], v[172:175], v[200:203], v[100:103]
	v_mfma_f32_16x16x32_bf16 v[96:99], v[180:183], v[200:203], v[96:99]
	v_mfma_f32_16x16x32_bf16 v[84:87], v[172:175], v[208:211], v[84:87]
	v_mfma_f32_16x16x32_bf16 v[80:83], v[180:183], v[208:211], v[80:83]
	v_mfma_f32_16x16x32_bf16 v[68:71], v[172:175], v[216:219], v[68:71]
	v_mfma_f32_16x16x32_bf16 v[64:67], v[180:183], v[216:219], v[64:67]
	s_barrier
	s_add_i32 s79, s69, s63
	v_lshl_add_u64 v[144:145], s[40:41], 0, v[130:131]
	s_mov_b32 m0, s79
	ds_read_b128 v[184:187], v151 offset:16384
	ds_read_b128 v[192:195], v151 offset:17408
	ds_read_b128 v[196:199], v151 offset:18432
	ds_read_b128 v[200:203], v151 offset:19456
	ds_read_b128 v[204:207], v151 offset:20480
	ds_read_b128 v[208:211], v151 offset:21504
	ds_read_b128 v[212:215], v151 offset:22528
	ds_read_b128 v[216:219], v151 offset:23552
	global_load_lds_dwordx4 v[144:145], off
	s_add_i32 m0, s79, 0x2000
	s_add_u32 s80, s40, 0x40000
	v_lshl_add_u64 v[188:189], s[40:41], 0, v[134:135]
	s_addc_u32 s81, s41, 0
	s_add_i32 s79, s70, s63
	global_load_lds_dwordx4 v[188:189], off
	s_mov_b32 m0, s79
	v_lshl_add_u64 v[222:223], s[42:43], 0, v[132:133]
	global_load_lds_dwordx4 v130, s[80:81]
	s_add_i32 m0, s79, 0x2000
	s_nop 0
	global_load_lds_dwordx4 v134, s[80:81]
	v_lshl_add_u64 v[220:221], s[42:43], 0, v[128:129]
	s_mov_b32 m0, s31
	s_nop 0
	global_load_lds_dwordx4 v[220:221], off
	s_mov_b32 m0, s64
	s_nop 0
	global_load_lds_dwordx4 v[222:223], off
	s_waitcnt vmcnt(8)
	s_waitcnt lgkmcnt(0)
	s_barrier
	v_mfma_f32_16x16x32_bf16 v[60:63], v[152:155], v[184:187], v[60:63]
	v_mfma_f32_16x16x32_bf16 v[56:59], v[160:163], v[184:187], v[56:59]
	v_mfma_f32_16x16x32_bf16 v[44:47], v[152:155], v[196:199], v[44:47]
	v_mfma_f32_16x16x32_bf16 v[40:43], v[160:163], v[196:199], v[40:43]
	v_mfma_f32_16x16x32_bf16 v[28:31], v[152:155], v[204:207], v[28:31]
	v_mfma_f32_16x16x32_bf16 v[24:27], v[160:163], v[204:207], v[24:27]
	v_mfma_f32_16x16x32_bf16 v[12:15], v[152:155], v[212:215], v[12:15]
	v_mfma_f32_16x16x32_bf16 v[8:11], v[160:163], v[212:215], v[8:11]
	v_mfma_f32_16x16x32_bf16 v[60:63], v[156:159], v[192:195], v[60:63]
	v_mfma_f32_16x16x32_bf16 v[56:59], v[164:167], v[192:195], v[56:59]
	v_mfma_f32_16x16x32_bf16 v[44:47], v[156:159], v[200:203], v[44:47]
	v_mfma_f32_16x16x32_bf16 v[40:43], v[164:167], v[200:203], v[40:43]
	v_mfma_f32_16x16x32_bf16 v[28:31], v[156:159], v[208:211], v[28:31]
	v_mfma_f32_16x16x32_bf16 v[24:27], v[164:167], v[208:211], v[24:27]
	v_mfma_f32_16x16x32_bf16 v[12:15], v[156:159], v[216:219], v[12:15]
	v_mfma_f32_16x16x32_bf16 v[8:11], v[164:167], v[216:219], v[8:11]
	v_mfma_f32_16x16x32_bf16 v[52:55], v[168:171], v[184:187], v[52:55]
	v_mfma_f32_16x16x32_bf16 v[48:51], v[176:179], v[184:187], v[48:51]
	v_mfma_f32_16x16x32_bf16 v[36:39], v[168:171], v[196:199], v[36:39]
	v_mfma_f32_16x16x32_bf16 v[32:35], v[176:179], v[196:199], v[32:35]
	v_mfma_f32_16x16x32_bf16 v[20:23], v[168:171], v[204:207], v[20:23]
	v_mfma_f32_16x16x32_bf16 v[16:19], v[176:179], v[204:207], v[16:19]
	v_mfma_f32_16x16x32_bf16 v[4:7], v[168:171], v[212:215], v[4:7]
	v_mfma_f32_16x16x32_bf16 v[0:3], v[176:179], v[212:215], v[0:3]
	v_mfma_f32_16x16x32_bf16 v[52:55], v[172:175], v[192:195], v[52:55]
	v_mfma_f32_16x16x32_bf16 v[48:51], v[180:183], v[192:195], v[48:51]
	v_mfma_f32_16x16x32_bf16 v[36:39], v[172:175], v[200:203], v[36:39]
	v_mfma_f32_16x16x32_bf16 v[32:35], v[180:183], v[200:203], v[32:35]
	v_mfma_f32_16x16x32_bf16 v[20:23], v[172:175], v[208:211], v[20:23]
	v_mfma_f32_16x16x32_bf16 v[16:19], v[180:183], v[208:211], v[16:19]
	v_mfma_f32_16x16x32_bf16 v[4:7], v[172:175], v[216:219], v[4:7]
	v_mfma_f32_16x16x32_bf16 v[0:3], v[180:183], v[216:219], v[0:3]
	s_barrier
	s_add_i32 s79, 0, 0x18000
	s_add_i32 s80, 0, 0x1c000
	v_add_u32_e32 v164, s79, v147
	v_add_u32_e32 v180, s80, v147
	ds_read_b128 v[152:155], v164
	ds_read_b128 v[156:159], v164 offset:1024
	ds_read_b128 v[160:163], v164 offset:2048
	ds_read_b128 v[164:167], v164 offset:3072
	ds_read_b128 v[168:171], v180
	ds_read_b128 v[172:175], v180 offset:1024
	ds_read_b128 v[176:179], v180 offset:2048
	ds_read_b128 v[180:183], v180 offset:3072
	s_add_u32 s42, s42, 0x40000
	s_addc_u32 s43, s43, 0
	s_mov_b32 m0, s65
	ds_read_b128 v[184:187], v151 offset:32768
	ds_read_b128 v[192:195], v151 offset:33792
	ds_read_b128 v[196:199], v151 offset:34816
	ds_read_b128 v[200:203], v151 offset:35840
	ds_read_b128 v[204:207], v151 offset:36864
	ds_read_b128 v[208:211], v151 offset:37888
	ds_read_b128 v[212:215], v151 offset:38912
	ds_read_b128 v[216:219], v151 offset:39936
	global_load_lds_dwordx4 v128, s[42:43]
	s_mov_b32 m0, s66
	s_nop 0
	global_load_lds_dwordx4 v132, s[42:43]
	s_waitcnt vmcnt(8)
	s_waitcnt lgkmcnt(0)
	s_barrier
	v_mfma_f32_16x16x32_bf16 v[124:127], v[152:155], v[184:187], v[124:127]
	v_mfma_f32_16x16x32_bf16 v[120:123], v[160:163], v[184:187], v[120:123]
	v_mfma_f32_16x16x32_bf16 v[108:111], v[152:155], v[196:199], v[108:111]
	v_mfma_f32_16x16x32_bf16 v[104:107], v[160:163], v[196:199], v[104:107]
	v_mfma_f32_16x16x32_bf16 v[92:95], v[152:155], v[204:207], v[92:95]
	v_mfma_f32_16x16x32_bf16 v[88:91], v[160:163], v[204:207], v[88:91]
	v_mfma_f32_16x16x32_bf16 v[76:79], v[152:155], v[212:215], v[76:79]
	v_mfma_f32_16x16x32_bf16 v[72:75], v[160:163], v[212:215], v[72:75]
	v_mfma_f32_16x16x32_bf16 v[124:127], v[156:159], v[192:195], v[124:127]
	v_mfma_f32_16x16x32_bf16 v[120:123], v[164:167], v[192:195], v[120:123]
	v_mfma_f32_16x16x32_bf16 v[108:111], v[156:159], v[200:203], v[108:111]
	v_mfma_f32_16x16x32_bf16 v[104:107], v[164:167], v[200:203], v[104:107]
	v_mfma_f32_16x16x32_bf16 v[92:95], v[156:159], v[208:211], v[92:95]
	v_mfma_f32_16x16x32_bf16 v[88:91], v[164:167], v[208:211], v[88:91]
	v_mfma_f32_16x16x32_bf16 v[76:79], v[156:159], v[216:219], v[76:79]
	v_mfma_f32_16x16x32_bf16 v[72:75], v[164:167], v[216:219], v[72:75]
	v_mfma_f32_16x16x32_bf16 v[116:119], v[168:171], v[184:187], v[116:119]
	v_mfma_f32_16x16x32_bf16 v[112:115], v[176:179], v[184:187], v[112:115]
	v_mfma_f32_16x16x32_bf16 v[100:103], v[168:171], v[196:199], v[100:103]
	v_mfma_f32_16x16x32_bf16 v[96:99], v[176:179], v[196:199], v[96:99]
	v_mfma_f32_16x16x32_bf16 v[84:87], v[168:171], v[204:207], v[84:87]
	v_mfma_f32_16x16x32_bf16 v[80:83], v[176:179], v[204:207], v[80:83]
	v_mfma_f32_16x16x32_bf16 v[68:71], v[168:171], v[212:215], v[68:71]
	v_mfma_f32_16x16x32_bf16 v[64:67], v[176:179], v[212:215], v[64:67]
	v_mfma_f32_16x16x32_bf16 v[116:119], v[172:175], v[192:195], v[116:119]
	v_mfma_f32_16x16x32_bf16 v[112:115], v[180:183], v[192:195], v[112:115]
	v_mfma_f32_16x16x32_bf16 v[100:103], v[172:175], v[200:203], v[100:103]
	v_mfma_f32_16x16x32_bf16 v[96:99], v[180:183], v[200:203], v[96:99]
	v_mfma_f32_16x16x32_bf16 v[84:87], v[172:175], v[208:211], v[84:87]
	v_mfma_f32_16x16x32_bf16 v[80:83], v[180:183], v[208:211], v[80:83]
	v_mfma_f32_16x16x32_bf16 v[68:71], v[172:175], v[216:219], v[68:71]
	v_mfma_f32_16x16x32_bf16 v[64:67], v[180:183], v[216:219], v[64:67]
	s_barrier
	s_add_i32 s42, s79, s63
	v_lshl_add_u64 v[144:145], v[144:145], 0, s[10:11]
	s_mov_b32 m0, s42
	ds_read_b128 v[184:187], v151 offset:49152
	ds_read_b128 v[192:195], v151 offset:50176
	ds_read_b128 v[196:199], v151 offset:51200
	ds_read_b128 v[200:203], v151 offset:52224
	ds_read_b128 v[204:207], v151 offset:53248
	ds_read_b128 v[208:211], v151 offset:54272
	ds_read_b128 v[212:215], v151 offset:55296
	ds_read_b128 v[216:219], v151 offset:56320
	global_load_lds_dwordx4 v[144:145], off
	s_add_i32 m0, s42, 0x2000
	s_add_u32 s40, s40, 0x40080
	v_lshl_add_u64 v[144:145], v[188:189], 0, s[10:11]
	s_addc_u32 s41, s41, 0
	s_add_i32 s42, s80, s63
	global_load_lds_dwordx4 v[144:145], off
	s_mov_b32 m0, s42
	s_nop 0
	global_load_lds_dwordx4 v130, s[40:41]
	s_add_i32 m0, s42, 0x2000
	s_nop 0
	global_load_lds_dwordx4 v134, s[40:41]
	v_lshl_add_u64 v[144:145], v[220:221], 0, s[10:11]
	s_mov_b32 m0, s52
	s_nop 0
	global_load_lds_dwordx4 v[144:145], off
	v_lshl_add_u64 v[144:145], v[222:223], 0, s[10:11]
	s_mov_b32 m0, s53
	s_nop 0
	global_load_lds_dwordx4 v[144:145], off
	s_waitcnt vmcnt(8)
	s_waitcnt lgkmcnt(0)
	s_barrier
	v_mfma_f32_16x16x32_bf16 v[60:63], v[152:155], v[184:187], v[60:63]
	v_mfma_f32_16x16x32_bf16 v[56:59], v[160:163], v[184:187], v[56:59]
	v_mfma_f32_16x16x32_bf16 v[44:47], v[152:155], v[196:199], v[44:47]
	v_mfma_f32_16x16x32_bf16 v[40:43], v[160:163], v[196:199], v[40:43]
	v_mfma_f32_16x16x32_bf16 v[28:31], v[152:155], v[204:207], v[28:31]
	v_mfma_f32_16x16x32_bf16 v[24:27], v[160:163], v[204:207], v[24:27]
	v_mfma_f32_16x16x32_bf16 v[12:15], v[152:155], v[212:215], v[12:15]
	v_mfma_f32_16x16x32_bf16 v[8:11], v[160:163], v[212:215], v[8:11]
	v_mfma_f32_16x16x32_bf16 v[60:63], v[156:159], v[192:195], v[60:63]
	v_mfma_f32_16x16x32_bf16 v[56:59], v[164:167], v[192:195], v[56:59]
	v_mfma_f32_16x16x32_bf16 v[44:47], v[156:159], v[200:203], v[44:47]
	v_mfma_f32_16x16x32_bf16 v[40:43], v[164:167], v[200:203], v[40:43]
	v_mfma_f32_16x16x32_bf16 v[28:31], v[156:159], v[208:211], v[28:31]
	v_mfma_f32_16x16x32_bf16 v[24:27], v[164:167], v[208:211], v[24:27]
	v_mfma_f32_16x16x32_bf16 v[12:15], v[156:159], v[216:219], v[12:15]
	v_mfma_f32_16x16x32_bf16 v[8:11], v[164:167], v[216:219], v[8:11]
	v_mfma_f32_16x16x32_bf16 v[52:55], v[168:171], v[184:187], v[52:55]
	v_mfma_f32_16x16x32_bf16 v[48:51], v[176:179], v[184:187], v[48:51]
	v_mfma_f32_16x16x32_bf16 v[36:39], v[168:171], v[196:199], v[36:39]
	v_mfma_f32_16x16x32_bf16 v[32:35], v[176:179], v[196:199], v[32:35]
	v_mfma_f32_16x16x32_bf16 v[20:23], v[168:171], v[204:207], v[20:23]
	v_mfma_f32_16x16x32_bf16 v[16:19], v[176:179], v[204:207], v[16:19]
	v_mfma_f32_16x16x32_bf16 v[4:7], v[168:171], v[212:215], v[4:7]
	v_mfma_f32_16x16x32_bf16 v[0:3], v[176:179], v[212:215], v[0:3]
	v_mfma_f32_16x16x32_bf16 v[52:55], v[172:175], v[192:195], v[52:55]
	v_mfma_f32_16x16x32_bf16 v[48:51], v[180:183], v[192:195], v[48:51]
	v_mfma_f32_16x16x32_bf16 v[36:39], v[172:175], v[200:203], v[36:39]
	v_mfma_f32_16x16x32_bf16 v[32:35], v[180:183], v[200:203], v[32:35]
	v_mfma_f32_16x16x32_bf16 v[20:23], v[172:175], v[208:211], v[20:23]
	v_mfma_f32_16x16x32_bf16 v[16:19], v[180:183], v[208:211], v[16:19]
	v_mfma_f32_16x16x32_bf16 v[4:7], v[172:175], v[216:219], v[4:7]
	v_mfma_f32_16x16x32_bf16 v[0:3], v[180:183], v[216:219], v[0:3]
	s_barrier
	s_add_i32 s77, s77, 2
	s_add_u32 s34, s34, 0x100
	s_addc_u32 s35, s35, 0
	s_add_u32 s75, s75, 0x100
	s_addc_u32 s76, s76, 0
	s_cmp_gt_u32 s77, 13
	s_cbranch_scc0 .LBB0_837

.LBB0_915:
	s_ashr_i32 s25, s24, 31
	s_lshl_b64 s[26:27], s[24:25], 21
	s_add_u32 s26, s56, s26
	s_addc_u32 s27, s57, s27
	s_and_b64 s[28:29], s[4:5], exec
	s_cselect_b32 s25, s27, s35
	s_cselect_b32 s55, s26, s34
	s_ashr_i32 s23, s22, 31
	s_lshl_b64 s[28:29], s[22:23], 21
	s_add_u32 s28, s53, s28
	s_addc_u32 s29, s60, s29
	s_and_b64 s[42:43], s[4:5], exec
	s_cselect_b32 s23, s29, s41
	s_cselect_b32 s74, s28, s40
	s_add_u32 s34, s34, 0x100080
	s_addc_u32 s35, s35, 0
	s_add_u32 s75, s40, 0x100
	s_addc_u32 s76, s41, 0
	s_mov_b32 s77, -2
	ds_read_b128 v[152:155], v149
	ds_read_b128 v[156:159], v149 offset:1024
	ds_read_b128 v[160:163], v149 offset:2048
	ds_read_b128 v[164:167], v149 offset:3072
	ds_read_b128 v[168:171], v150
	ds_read_b128 v[172:175], v150 offset:1024
	ds_read_b128 v[176:179], v150 offset:2048
	ds_read_b128 v[180:183], v150 offset:3072
	s_add_u32 s40, s34, 0xfff00080
	s_addc_u32 s41, s35, -1
	s_cmp_eq_u32 s77, 60
	s_cselect_b32 s43, s25, s41
	s_cselect_b32 s42, s55, s40
	s_cselect_b32 s41, s23, s76
	s_cselect_b32 s40, s74, s75
	s_add_i32 m0, s31, 0xc000
	ds_read_b128 v[184:187], v151
	ds_read_b128 v[192:195], v151 offset:1024
	ds_read_b128 v[196:199], v151 offset:2048
	ds_read_b128 v[200:203], v151 offset:3072
	ds_read_b128 v[204:207], v151 offset:4096
	ds_read_b128 v[208:211], v151 offset:5120
	ds_read_b128 v[212:215], v151 offset:6144
	ds_read_b128 v[216:219], v151 offset:7168
	global_load_lds_dwordx4 v136, s[34:35]
	s_add_i32 m0, s31, 0xe000
	s_nop 0
	global_load_lds_dwordx4 v138, s[34:35]
	s_waitcnt vmcnt(8)
	s_waitcnt lgkmcnt(0)
	s_barrier
	v_mfma_f32_16x16x32_bf16 v[124:127], v[152:155], v[184:187], 0
	v_mfma_f32_16x16x32_bf16 v[120:123], v[160:163], v[184:187], 0
	v_mfma_f32_16x16x32_bf16 v[116:119], v[152:155], v[196:199], 0
	v_mfma_f32_16x16x32_bf16 v[108:111], v[160:163], v[196:199], 0
	v_mfma_f32_16x16x32_bf16 v[100:103], v[152:155], v[204:207], 0
	v_mfma_f32_16x16x32_bf16 v[92:95], v[160:163], v[204:207], 0
	v_mfma_f32_16x16x32_bf16 v[84:87], v[152:155], v[212:215], 0
	v_mfma_f32_16x16x32_bf16 v[76:79], v[160:163], v[212:215], 0
	v_mfma_f32_16x16x32_bf16 v[124:127], v[156:159], v[192:195], v[124:127]
	v_mfma_f32_16x16x32_bf16 v[120:123], v[164:167], v[192:195], v[120:123]
	v_mfma_f32_16x16x32_bf16 v[116:119], v[156:159], v[200:203], v[116:119]
	v_mfma_f32_16x16x32_bf16 v[108:111], v[164:167], v[200:203], v[108:111]
	v_mfma_f32_16x16x32_bf16 v[100:103], v[156:159], v[208:211], v[100:103]
	v_mfma_f32_16x16x32_bf16 v[92:95], v[164:167], v[208:211], v[92:95]
	v_mfma_f32_16x16x32_bf16 v[84:87], v[156:159], v[216:219], v[84:87]
	v_mfma_f32_16x16x32_bf16 v[76:79], v[164:167], v[216:219], v[76:79]
	v_mfma_f32_16x16x32_bf16 v[112:115], v[168:171], v[184:187], 0
	v_mfma_f32_16x16x32_bf16 v[104:107], v[176:179], v[184:187], 0
	v_mfma_f32_16x16x32_bf16 v[96:99], v[168:171], v[196:199], 0
	v_mfma_f32_16x16x32_bf16 v[88:91], v[176:179], v[196:199], 0
	v_mfma_f32_16x16x32_bf16 v[80:83], v[168:171], v[204:207], 0
	v_mfma_f32_16x16x32_bf16 v[72:75], v[176:179], v[204:207], 0
	v_mfma_f32_16x16x32_bf16 v[68:71], v[168:171], v[212:215], 0
	v_mfma_f32_16x16x32_bf16 v[64:67], v[176:179], v[212:215], 0
	v_mfma_f32_16x16x32_bf16 v[112:115], v[172:175], v[192:195], v[112:115]
	v_mfma_f32_16x16x32_bf16 v[104:107], v[180:183], v[192:195], v[104:107]
	v_mfma_f32_16x16x32_bf16 v[96:99], v[172:175], v[200:203], v[96:99]
	v_mfma_f32_16x16x32_bf16 v[88:91], v[180:183], v[200:203], v[88:91]
	v_mfma_f32_16x16x32_bf16 v[80:83], v[172:175], v[208:211], v[80:83]
	v_mfma_f32_16x16x32_bf16 v[72:75], v[180:183], v[208:211], v[72:75]
	v_mfma_f32_16x16x32_bf16 v[68:71], v[172:175], v[216:219], v[68:71]
	v_mfma_f32_16x16x32_bf16 v[64:67], v[180:183], v[216:219], v[64:67]
	s_barrier
	s_add_i32 s79, s68, s61
	v_lshl_add_u64 v[144:145], s[40:41], 0, v[130:131]
	s_mov_b32 m0, s79
	ds_read_b128 v[184:187], v151 offset:16384
	ds_read_b128 v[192:195], v151 offset:17408
	ds_read_b128 v[196:199], v151 offset:18432
	ds_read_b128 v[200:203], v151 offset:19456
	ds_read_b128 v[204:207], v151 offset:20480
	ds_read_b128 v[208:211], v151 offset:21504
	ds_read_b128 v[212:215], v151 offset:22528
	ds_read_b128 v[216:219], v151 offset:23552
	global_load_lds_dwordx4 v[144:145], off
	s_add_i32 m0, s79, 0x2000
	s_add_u32 s80, s40, 0x100000
	v_lshl_add_u64 v[188:189], s[40:41], 0, v[134:135]
	s_addc_u32 s81, s41, 0
	s_add_i32 s79, s69, s61
	global_load_lds_dwordx4 v[188:189], off
	s_mov_b32 m0, s79
	v_lshl_add_u64 v[222:223], s[42:43], 0, v[132:133]
	global_load_lds_dwordx4 v130, s[80:81]
	s_add_i32 m0, s79, 0x2000
	s_nop 0
	global_load_lds_dwordx4 v134, s[80:81]
	v_lshl_add_u64 v[220:221], s[42:43], 0, v[128:129]
	s_mov_b32 m0, s31
	s_nop 0
	global_load_lds_dwordx4 v[220:221], off
	s_mov_b32 m0, s33
	s_nop 0
	global_load_lds_dwordx4 v[222:223], off
	s_waitcnt vmcnt(8)
	s_waitcnt lgkmcnt(0)
	s_barrier
	v_mfma_f32_16x16x32_bf16 v[60:63], v[152:155], v[184:187], 0
	v_mfma_f32_16x16x32_bf16 v[56:59], v[160:163], v[184:187], 0
	v_mfma_f32_16x16x32_bf16 v[52:55], v[152:155], v[196:199], 0
	v_mfma_f32_16x16x32_bf16 v[44:47], v[160:163], v[196:199], 0
	v_mfma_f32_16x16x32_bf16 v[36:39], v[152:155], v[204:207], 0
	v_mfma_f32_16x16x32_bf16 v[28:31], v[160:163], v[204:207], 0
	v_mfma_f32_16x16x32_bf16 v[20:23], v[152:155], v[212:215], 0
	v_mfma_f32_16x16x32_bf16 v[12:15], v[160:163], v[212:215], 0
	v_mfma_f32_16x16x32_bf16 v[60:63], v[156:159], v[192:195], v[60:63]
	v_mfma_f32_16x16x32_bf16 v[56:59], v[164:167], v[192:195], v[56:59]
	v_mfma_f32_16x16x32_bf16 v[52:55], v[156:159], v[200:203], v[52:55]
	v_mfma_f32_16x16x32_bf16 v[44:47], v[164:167], v[200:203], v[44:47]
	v_mfma_f32_16x16x32_bf16 v[36:39], v[156:159], v[208:211], v[36:39]
	v_mfma_f32_16x16x32_bf16 v[28:31], v[164:167], v[208:211], v[28:31]
	v_mfma_f32_16x16x32_bf16 v[20:23], v[156:159], v[216:219], v[20:23]
	v_mfma_f32_16x16x32_bf16 v[12:15], v[164:167], v[216:219], v[12:15]
	v_mfma_f32_16x16x32_bf16 v[48:51], v[168:171], v[184:187], 0
	v_mfma_f32_16x16x32_bf16 v[40:43], v[176:179], v[184:187], 0
	v_mfma_f32_16x16x32_bf16 v[32:35], v[168:171], v[196:199], 0
	v_mfma_f32_16x16x32_bf16 v[24:27], v[176:179], v[196:199], 0
	v_mfma_f32_16x16x32_bf16 v[16:19], v[168:171], v[204:207], 0
	v_mfma_f32_16x16x32_bf16 v[8:11], v[176:179], v[204:207], 0
	v_mfma_f32_16x16x32_bf16 v[4:7], v[168:171], v[212:215], 0
	v_mfma_f32_16x16x32_bf16 v[0:3], v[176:179], v[212:215], 0
	v_mfma_f32_16x16x32_bf16 v[48:51], v[172:175], v[192:195], v[48:51]
	v_mfma_f32_16x16x32_bf16 v[40:43], v[180:183], v[192:195], v[40:43]
	v_mfma_f32_16x16x32_bf16 v[32:35], v[172:175], v[200:203], v[32:35]
	v_mfma_f32_16x16x32_bf16 v[24:27], v[180:183], v[200:203], v[24:27]
	v_mfma_f32_16x16x32_bf16 v[16:19], v[172:175], v[208:211], v[16:19]
	v_mfma_f32_16x16x32_bf16 v[8:11], v[180:183], v[208:211], v[8:11]
	v_mfma_f32_16x16x32_bf16 v[4:7], v[172:175], v[216:219], v[4:7]
	v_mfma_f32_16x16x32_bf16 v[0:3], v[180:183], v[216:219], v[0:3]
	s_barrier
	s_add_i32 s79, 0, 0x18000
	s_add_i32 s80, 0, 0x1c000
	v_add_u32_e32 v164, s79, v147
	v_add_u32_e32 v180, s80, v147
	ds_read_b128 v[152:155], v164
	ds_read_b128 v[156:159], v164 offset:1024
	ds_read_b128 v[160:163], v164 offset:2048
	ds_read_b128 v[164:167], v164 offset:3072
	ds_read_b128 v[168:171], v180
	ds_read_b128 v[172:175], v180 offset:1024
	ds_read_b128 v[176:179], v180 offset:2048
	ds_read_b128 v[180:183], v180 offset:3072
	s_add_u32 s42, s42, 0x100000
	s_addc_u32 s43, s43, 0
	s_mov_b32 m0, s62
	ds_read_b128 v[184:187], v151 offset:32768
	ds_read_b128 v[192:195], v151 offset:33792
	ds_read_b128 v[196:199], v151 offset:34816
	ds_read_b128 v[200:203], v151 offset:35840
	ds_read_b128 v[204:207], v151 offset:36864
	ds_read_b128 v[208:211], v151 offset:37888
	ds_read_b128 v[212:215], v151 offset:38912
	ds_read_b128 v[216:219], v151 offset:39936
	global_load_lds_dwordx4 v128, s[42:43]
	s_mov_b32 m0, s63
	s_nop 0
	global_load_lds_dwordx4 v132, s[42:43]
	s_waitcnt vmcnt(8)
	s_waitcnt lgkmcnt(0)
	s_barrier
	v_mfma_f32_16x16x32_bf16 v[124:127], v[152:155], v[184:187], v[124:127]
	v_mfma_f32_16x16x32_bf16 v[120:123], v[160:163], v[184:187], v[120:123]
	v_mfma_f32_16x16x32_bf16 v[116:119], v[152:155], v[196:199], v[116:119]
	v_mfma_f32_16x16x32_bf16 v[108:111], v[160:163], v[196:199], v[108:111]
	v_mfma_f32_16x16x32_bf16 v[100:103], v[152:155], v[204:207], v[100:103]
	v_mfma_f32_16x16x32_bf16 v[92:95], v[160:163], v[204:207], v[92:95]
	v_mfma_f32_16x16x32_bf16 v[84:87], v[152:155], v[212:215], v[84:87]
	v_mfma_f32_16x16x32_bf16 v[76:79], v[160:163], v[212:215], v[76:79]
	v_mfma_f32_16x16x32_bf16 v[124:127], v[156:159], v[192:195], v[124:127]
	v_mfma_f32_16x16x32_bf16 v[120:123], v[164:167], v[192:195], v[120:123]
	v_mfma_f32_16x16x32_bf16 v[116:119], v[156:159], v[200:203], v[116:119]
	v_mfma_f32_16x16x32_bf16 v[108:111], v[164:167], v[200:203], v[108:111]
	v_mfma_f32_16x16x32_bf16 v[100:103], v[156:159], v[208:211], v[100:103]
	v_mfma_f32_16x16x32_bf16 v[92:95], v[164:167], v[208:211], v[92:95]
	v_mfma_f32_16x16x32_bf16 v[84:87], v[156:159], v[216:219], v[84:87]
	v_mfma_f32_16x16x32_bf16 v[76:79], v[164:167], v[216:219], v[76:79]
	v_mfma_f32_16x16x32_bf16 v[112:115], v[168:171], v[184:187], v[112:115]
	v_mfma_f32_16x16x32_bf16 v[104:107], v[176:179], v[184:187], v[104:107]
	v_mfma_f32_16x16x32_bf16 v[96:99], v[168:171], v[196:199], v[96:99]
	v_mfma_f32_16x16x32_bf16 v[88:91], v[176:179], v[196:199], v[88:91]
	v_mfma_f32_16x16x32_bf16 v[80:83], v[168:171], v[204:207], v[80:83]
	v_mfma_f32_16x16x32_bf16 v[72:75], v[176:179], v[204:207], v[72:75]
	v_mfma_f32_16x16x32_bf16 v[68:71], v[168:171], v[212:215], v[68:71]
	v_mfma_f32_16x16x32_bf16 v[64:67], v[176:179], v[212:215], v[64:67]
	v_mfma_f32_16x16x32_bf16 v[112:115], v[172:175], v[192:195], v[112:115]
	v_mfma_f32_16x16x32_bf16 v[104:107], v[180:183], v[192:195], v[104:107]
	v_mfma_f32_16x16x32_bf16 v[96:99], v[172:175], v[200:203], v[96:99]
	v_mfma_f32_16x16x32_bf16 v[88:91], v[180:183], v[200:203], v[88:91]
	v_mfma_f32_16x16x32_bf16 v[80:83], v[172:175], v[208:211], v[80:83]
	v_mfma_f32_16x16x32_bf16 v[72:75], v[180:183], v[208:211], v[72:75]
	v_mfma_f32_16x16x32_bf16 v[68:71], v[172:175], v[216:219], v[68:71]
	v_mfma_f32_16x16x32_bf16 v[64:67], v[180:183], v[216:219], v[64:67]
	s_barrier
	s_add_i32 s42, s79, s61
	v_lshl_add_u64 v[144:145], v[144:145], 0, s[10:11]
	s_mov_b32 m0, s42
	ds_read_b128 v[184:187], v151 offset:49152
	ds_read_b128 v[192:195], v151 offset:50176
	ds_read_b128 v[196:199], v151 offset:51200
	ds_read_b128 v[200:203], v151 offset:52224
	ds_read_b128 v[204:207], v151 offset:53248
	ds_read_b128 v[208:211], v151 offset:54272
	ds_read_b128 v[212:215], v151 offset:55296
	ds_read_b128 v[216:219], v151 offset:56320
	global_load_lds_dwordx4 v[144:145], off
	s_add_i32 m0, s42, 0x2000
	s_add_u32 s40, s40, 0x100080
	v_lshl_add_u64 v[144:145], v[188:189], 0, s[10:11]
	s_addc_u32 s41, s41, 0
	s_add_i32 s42, s80, s61
	global_load_lds_dwordx4 v[144:145], off
	s_mov_b32 m0, s42
	s_nop 0
	global_load_lds_dwordx4 v130, s[40:41]
	s_add_i32 m0, s42, 0x2000
	s_nop 0
	global_load_lds_dwordx4 v134, s[40:41]
	v_lshl_add_u64 v[144:145], v[220:221], 0, s[10:11]
	s_mov_b32 m0, s65
	s_nop 0
	global_load_lds_dwordx4 v[144:145], off
	v_lshl_add_u64 v[144:145], v[222:223], 0, s[10:11]
	s_mov_b32 m0, s66
	s_nop 0
	global_load_lds_dwordx4 v[144:145], off
	s_waitcnt vmcnt(8)
	s_waitcnt lgkmcnt(0)
	s_barrier
	v_mfma_f32_16x16x32_bf16 v[60:63], v[152:155], v[184:187], v[60:63]
	v_mfma_f32_16x16x32_bf16 v[56:59], v[160:163], v[184:187], v[56:59]
	v_mfma_f32_16x16x32_bf16 v[52:55], v[152:155], v[196:199], v[52:55]
	v_mfma_f32_16x16x32_bf16 v[44:47], v[160:163], v[196:199], v[44:47]
	v_mfma_f32_16x16x32_bf16 v[36:39], v[152:155], v[204:207], v[36:39]
	v_mfma_f32_16x16x32_bf16 v[28:31], v[160:163], v[204:207], v[28:31]
	v_mfma_f32_16x16x32_bf16 v[20:23], v[152:155], v[212:215], v[20:23]
	v_mfma_f32_16x16x32_bf16 v[12:15], v[160:163], v[212:215], v[12:15]
	v_mfma_f32_16x16x32_bf16 v[60:63], v[156:159], v[192:195], v[60:63]
	v_mfma_f32_16x16x32_bf16 v[56:59], v[164:167], v[192:195], v[56:59]
	v_mfma_f32_16x16x32_bf16 v[52:55], v[156:159], v[200:203], v[52:55]
	v_mfma_f32_16x16x32_bf16 v[44:47], v[164:167], v[200:203], v[44:47]
	v_mfma_f32_16x16x32_bf16 v[36:39], v[156:159], v[208:211], v[36:39]
	v_mfma_f32_16x16x32_bf16 v[28:31], v[164:167], v[208:211], v[28:31]
	v_mfma_f32_16x16x32_bf16 v[20:23], v[156:159], v[216:219], v[20:23]
	v_mfma_f32_16x16x32_bf16 v[12:15], v[164:167], v[216:219], v[12:15]
	v_mfma_f32_16x16x32_bf16 v[48:51], v[168:171], v[184:187], v[48:51]
	v_mfma_f32_16x16x32_bf16 v[40:43], v[176:179], v[184:187], v[40:43]
	v_mfma_f32_16x16x32_bf16 v[32:35], v[168:171], v[196:199], v[32:35]
	v_mfma_f32_16x16x32_bf16 v[24:27], v[176:179], v[196:199], v[24:27]
	v_mfma_f32_16x16x32_bf16 v[16:19], v[168:171], v[204:207], v[16:19]
	v_mfma_f32_16x16x32_bf16 v[8:11], v[176:179], v[204:207], v[8:11]
	v_mfma_f32_16x16x32_bf16 v[4:7], v[168:171], v[212:215], v[4:7]
	v_mfma_f32_16x16x32_bf16 v[0:3], v[176:179], v[212:215], v[0:3]
	v_mfma_f32_16x16x32_bf16 v[48:51], v[172:175], v[192:195], v[48:51]
	v_mfma_f32_16x16x32_bf16 v[40:43], v[180:183], v[192:195], v[40:43]
	v_mfma_f32_16x16x32_bf16 v[32:35], v[172:175], v[200:203], v[32:35]
	v_mfma_f32_16x16x32_bf16 v[24:27], v[180:183], v[200:203], v[24:27]
	v_mfma_f32_16x16x32_bf16 v[16:19], v[172:175], v[208:211], v[16:19]
	v_mfma_f32_16x16x32_bf16 v[8:11], v[180:183], v[208:211], v[8:11]
	v_mfma_f32_16x16x32_bf16 v[4:7], v[172:175], v[216:219], v[4:7]
	v_mfma_f32_16x16x32_bf16 v[0:3], v[180:183], v[216:219], v[0:3]
	s_barrier
	s_add_i32 s77, s77, 2
	s_add_u32 s34, s34, 0x100
	s_addc_u32 s35, s35, 0
	s_add_u32 s75, s75, 0x100
	s_addc_u32 s76, s76, 0
	s_cmp_gt_u32 s77, 61
	s_cbranch_scc0 .LBB0_916
	s_branch .Lpeel_exit4
.LBB0_916:
	ds_read_b128 v[152:155], v149
	ds_read_b128 v[156:159], v149 offset:1024
	ds_read_b128 v[160:163], v149 offset:2048
	ds_read_b128 v[164:167], v149 offset:3072
	ds_read_b128 v[168:171], v150
	ds_read_b128 v[172:175], v150 offset:1024
	ds_read_b128 v[176:179], v150 offset:2048
	ds_read_b128 v[180:183], v150 offset:3072
	s_add_u32 s40, s34, 0xfff00080
	s_addc_u32 s41, s35, -1
	s_cmp_eq_u32 s77, 60
	s_cselect_b32 s43, s25, s41
	s_cselect_b32 s42, s55, s40
	s_cselect_b32 s41, s23, s76
	s_cselect_b32 s40, s74, s75
	s_add_i32 m0, s31, 0xc000
	ds_read_b128 v[184:187], v151
	ds_read_b128 v[192:195], v151 offset:1024
	ds_read_b128 v[196:199], v151 offset:2048
	ds_read_b128 v[200:203], v151 offset:3072
	ds_read_b128 v[204:207], v151 offset:4096
	ds_read_b128 v[208:211], v151 offset:5120
	ds_read_b128 v[212:215], v151 offset:6144
	ds_read_b128 v[216:219], v151 offset:7168
	global_load_lds_dwordx4 v136, s[34:35]
	s_add_i32 m0, s31, 0xe000
	s_nop 0
	global_load_lds_dwordx4 v138, s[34:35]
	s_waitcnt vmcnt(8)
	s_waitcnt lgkmcnt(0)
	s_barrier
	v_mfma_f32_16x16x32_bf16 v[124:127], v[152:155], v[184:187], v[124:127]
	v_mfma_f32_16x16x32_bf16 v[120:123], v[160:163], v[184:187], v[120:123]
	v_mfma_f32_16x16x32_bf16 v[116:119], v[152:155], v[196:199], v[116:119]
	v_mfma_f32_16x16x32_bf16 v[108:111], v[160:163], v[196:199], v[108:111]
	v_mfma_f32_16x16x32_bf16 v[100:103], v[152:155], v[204:207], v[100:103]
	v_mfma_f32_16x16x32_bf16 v[92:95], v[160:163], v[204:207], v[92:95]
	v_mfma_f32_16x16x32_bf16 v[84:87], v[152:155], v[212:215], v[84:87]
	v_mfma_f32_16x16x32_bf16 v[76:79], v[160:163], v[212:215], v[76:79]
	v_mfma_f32_16x16x32_bf16 v[124:127], v[156:159], v[192:195], v[124:127]
	v_mfma_f32_16x16x32_bf16 v[120:123], v[164:167], v[192:195], v[120:123]
	v_mfma_f32_16x16x32_bf16 v[116:119], v[156:159], v[200:203], v[116:119]
	v_mfma_f32_16x16x32_bf16 v[108:111], v[164:167], v[200:203], v[108:111]
	v_mfma_f32_16x16x32_bf16 v[100:103], v[156:159], v[208:211], v[100:103]
	v_mfma_f32_16x16x32_bf16 v[92:95], v[164:167], v[208:211], v[92:95]
	v_mfma_f32_16x16x32_bf16 v[84:87], v[156:159], v[216:219], v[84:87]
	v_mfma_f32_16x16x32_bf16 v[76:79], v[164:167], v[216:219], v[76:79]
	v_mfma_f32_16x16x32_bf16 v[112:115], v[168:171], v[184:187], v[112:115]
	v_mfma_f32_16x16x32_bf16 v[104:107], v[176:179], v[184:187], v[104:107]
	v_mfma_f32_16x16x32_bf16 v[96:99], v[168:171], v[196:199], v[96:99]
	v_mfma_f32_16x16x32_bf16 v[88:91], v[176:179], v[196:199], v[88:91]
	v_mfma_f32_16x16x32_bf16 v[80:83], v[168:171], v[204:207], v[80:83]
	v_mfma_f32_16x16x32_bf16 v[72:75], v[176:179], v[204:207], v[72:75]
	v_mfma_f32_16x16x32_bf16 v[68:71], v[168:171], v[212:215], v[68:71]
	v_mfma_f32_16x16x32_bf16 v[64:67], v[176:179], v[212:215], v[64:67]
	v_mfma_f32_16x16x32_bf16 v[112:115], v[172:175], v[192:195], v[112:115]
	v_mfma_f32_16x16x32_bf16 v[104:107], v[180:183], v[192:195], v[104:107]
	v_mfma_f32_16x16x32_bf16 v[96:99], v[172:175], v[200:203], v[96:99]
	v_mfma_f32_16x16x32_bf16 v[88:91], v[180:183], v[200:203], v[88:91]
	v_mfma_f32_16x16x32_bf16 v[80:83], v[172:175], v[208:211], v[80:83]
	v_mfma_f32_16x16x32_bf16 v[72:75], v[180:183], v[208:211], v[72:75]
	v_mfma_f32_16x16x32_bf16 v[68:71], v[172:175], v[216:219], v[68:71]
	v_mfma_f32_16x16x32_bf16 v[64:67], v[180:183], v[216:219], v[64:67]
	s_barrier
	s_add_i32 s79, s68, s61
	v_lshl_add_u64 v[144:145], s[40:41], 0, v[130:131]
	s_mov_b32 m0, s79
	ds_read_b128 v[184:187], v151 offset:16384
	ds_read_b128 v[192:195], v151 offset:17408
	ds_read_b128 v[196:199], v151 offset:18432
	ds_read_b128 v[200:203], v151 offset:19456
	ds_read_b128 v[204:207], v151 offset:20480
	ds_read_b128 v[208:211], v151 offset:21504
	ds_read_b128 v[212:215], v151 offset:22528
	ds_read_b128 v[216:219], v151 offset:23552
	global_load_lds_dwordx4 v[144:145], off
	s_add_i32 m0, s79, 0x2000
	s_add_u32 s80, s40, 0x100000
	v_lshl_add_u64 v[188:189], s[40:41], 0, v[134:135]
	s_addc_u32 s81, s41, 0
	s_add_i32 s79, s69, s61
	global_load_lds_dwordx4 v[188:189], off
	s_mov_b32 m0, s79
	v_lshl_add_u64 v[222:223], s[42:43], 0, v[132:133]
	global_load_lds_dwordx4 v130, s[80:81]
	s_add_i32 m0, s79, 0x2000
	s_nop 0
	global_load_lds_dwordx4 v134, s[80:81]
	v_lshl_add_u64 v[220:221], s[42:43], 0, v[128:129]
	s_mov_b32 m0, s31
	s_nop 0
	global_load_lds_dwordx4 v[220:221], off
	s_mov_b32 m0, s33
	s_nop 0
	global_load_lds_dwordx4 v[222:223], off
	s_waitcnt vmcnt(8)
	s_waitcnt lgkmcnt(0)
	s_barrier
	v_mfma_f32_16x16x32_bf16 v[60:63], v[152:155], v[184:187], v[60:63]
	v_mfma_f32_16x16x32_bf16 v[56:59], v[160:163], v[184:187], v[56:59]
	v_mfma_f32_16x16x32_bf16 v[52:55], v[152:155], v[196:199], v[52:55]
	v_mfma_f32_16x16x32_bf16 v[44:47], v[160:163], v[196:199], v[44:47]
	v_mfma_f32_16x16x32_bf16 v[36:39], v[152:155], v[204:207], v[36:39]
	v_mfma_f32_16x16x32_bf16 v[28:31], v[160:163], v[204:207], v[28:31]
	v_mfma_f32_16x16x32_bf16 v[20:23], v[152:155], v[212:215], v[20:23]
	v_mfma_f32_16x16x32_bf16 v[12:15], v[160:163], v[212:215], v[12:15]
	v_mfma_f32_16x16x32_bf16 v[60:63], v[156:159], v[192:195], v[60:63]
	v_mfma_f32_16x16x32_bf16 v[56:59], v[164:167], v[192:195], v[56:59]
	v_mfma_f32_16x16x32_bf16 v[52:55], v[156:159], v[200:203], v[52:55]
	v_mfma_f32_16x16x32_bf16 v[44:47], v[164:167], v[200:203], v[44:47]
	v_mfma_f32_16x16x32_bf16 v[36:39], v[156:159], v[208:211], v[36:39]
	v_mfma_f32_16x16x32_bf16 v[28:31], v[164:167], v[208:211], v[28:31]
	v_mfma_f32_16x16x32_bf16 v[20:23], v[156:159], v[216:219], v[20:23]
	v_mfma_f32_16x16x32_bf16 v[12:15], v[164:167], v[216:219], v[12:15]
	v_mfma_f32_16x16x32_bf16 v[48:51], v[168:171], v[184:187], v[48:51]
	v_mfma_f32_16x16x32_bf16 v[40:43], v[176:179], v[184:187], v[40:43]
	v_mfma_f32_16x16x32_bf16 v[32:35], v[168:171], v[196:199], v[32:35]
	v_mfma_f32_16x16x32_bf16 v[24:27], v[176:179], v[196:199], v[24:27]
	v_mfma_f32_16x16x32_bf16 v[16:19], v[168:171], v[204:207], v[16:19]
	v_mfma_f32_16x16x32_bf16 v[8:11], v[176:179], v[204:207], v[8:11]
	v_mfma_f32_16x16x32_bf16 v[4:7], v[168:171], v[212:215], v[4:7]
	v_mfma_f32_16x16x32_bf16 v[0:3], v[176:179], v[212:215], v[0:3]
	v_mfma_f32_16x16x32_bf16 v[48:51], v[172:175], v[192:195], v[48:51]
	v_mfma_f32_16x16x32_bf16 v[40:43], v[180:183], v[192:195], v[40:43]
	v_mfma_f32_16x16x32_bf16 v[32:35], v[172:175], v[200:203], v[32:35]
	v_mfma_f32_16x16x32_bf16 v[24:27], v[180:183], v[200:203], v[24:27]
	v_mfma_f32_16x16x32_bf16 v[16:19], v[172:175], v[208:211], v[16:19]
	v_mfma_f32_16x16x32_bf16 v[8:11], v[180:183], v[208:211], v[8:11]
	v_mfma_f32_16x16x32_bf16 v[4:7], v[172:175], v[216:219], v[4:7]
	v_mfma_f32_16x16x32_bf16 v[0:3], v[180:183], v[216:219], v[0:3]
	s_barrier
	s_add_i32 s79, 0, 0x18000
	s_add_i32 s80, 0, 0x1c000
	v_add_u32_e32 v164, s79, v147
	v_add_u32_e32 v180, s80, v147
	ds_read_b128 v[152:155], v164
	ds_read_b128 v[156:159], v164 offset:1024
	ds_read_b128 v[160:163], v164 offset:2048
	ds_read_b128 v[164:167], v164 offset:3072
	ds_read_b128 v[168:171], v180
	ds_read_b128 v[172:175], v180 offset:1024
	ds_read_b128 v[176:179], v180 offset:2048
	ds_read_b128 v[180:183], v180 offset:3072
	s_add_u32 s42, s42, 0x100000
	s_addc_u32 s43, s43, 0
	s_mov_b32 m0, s62
	ds_read_b128 v[184:187], v151 offset:32768
	ds_read_b128 v[192:195], v151 offset:33792
	ds_read_b128 v[196:199], v151 offset:34816
	ds_read_b128 v[200:203], v151 offset:35840
	ds_read_b128 v[204:207], v151 offset:36864
	ds_read_b128 v[208:211], v151 offset:37888
	ds_read_b128 v[212:215], v151 offset:38912
	ds_read_b128 v[216:219], v151 offset:39936
	global_load_lds_dwordx4 v128, s[42:43]
	s_mov_b32 m0, s63
	s_nop 0
	global_load_lds_dwordx4 v132, s[42:43]
	s_waitcnt vmcnt(8)
	s_waitcnt lgkmcnt(0)
	s_barrier
	v_mfma_f32_16x16x32_bf16 v[124:127], v[152:155], v[184:187], v[124:127]
	v_mfma_f32_16x16x32_bf16 v[120:123], v[160:163], v[184:187], v[120:123]
	v_mfma_f32_16x16x32_bf16 v[116:119], v[152:155], v[196:199], v[116:119]
	v_mfma_f32_16x16x32_bf16 v[108:111], v[160:163], v[196:199], v[108:111]
	v_mfma_f32_16x16x32_bf16 v[100:103], v[152:155], v[204:207], v[100:103]
	v_mfma_f32_16x16x32_bf16 v[92:95], v[160:163], v[204:207], v[92:95]
	v_mfma_f32_16x16x32_bf16 v[84:87], v[152:155], v[212:215], v[84:87]
	v_mfma_f32_16x16x32_bf16 v[76:79], v[160:163], v[212:215], v[76:79]
	v_mfma_f32_16x16x32_bf16 v[124:127], v[156:159], v[192:195], v[124:127]
	v_mfma_f32_16x16x32_bf16 v[120:123], v[164:167], v[192:195], v[120:123]
	v_mfma_f32_16x16x32_bf16 v[116:119], v[156:159], v[200:203], v[116:119]
	v_mfma_f32_16x16x32_bf16 v[108:111], v[164:167], v[200:203], v[108:111]
	v_mfma_f32_16x16x32_bf16 v[100:103], v[156:159], v[208:211], v[100:103]
	v_mfma_f32_16x16x32_bf16 v[92:95], v[164:167], v[208:211], v[92:95]
	v_mfma_f32_16x16x32_bf16 v[84:87], v[156:159], v[216:219], v[84:87]
	v_mfma_f32_16x16x32_bf16 v[76:79], v[164:167], v[216:219], v[76:79]
	v_mfma_f32_16x16x32_bf16 v[112:115], v[168:171], v[184:187], v[112:115]
	v_mfma_f32_16x16x32_bf16 v[104:107], v[176:179], v[184:187], v[104:107]
	v_mfma_f32_16x16x32_bf16 v[96:99], v[168:171], v[196:199], v[96:99]
	v_mfma_f32_16x16x32_bf16 v[88:91], v[176:179], v[196:199], v[88:91]
	v_mfma_f32_16x16x32_bf16 v[80:83], v[168:171], v[204:207], v[80:83]
	v_mfma_f32_16x16x32_bf16 v[72:75], v[176:179], v[204:207], v[72:75]
	v_mfma_f32_16x16x32_bf16 v[68:71], v[168:171], v[212:215], v[68:71]
	v_mfma_f32_16x16x32_bf16 v[64:67], v[176:179], v[212:215], v[64:67]
	v_mfma_f32_16x16x32_bf16 v[112:115], v[172:175], v[192:195], v[112:115]
	v_mfma_f32_16x16x32_bf16 v[104:107], v[180:183], v[192:195], v[104:107]
	v_mfma_f32_16x16x32_bf16 v[96:99], v[172:175], v[200:203], v[96:99]
	v_mfma_f32_16x16x32_bf16 v[88:91], v[180:183], v[200:203], v[88:91]
	v_mfma_f32_16x16x32_bf16 v[80:83], v[172:175], v[208:211], v[80:83]
	v_mfma_f32_16x16x32_bf16 v[72:75], v[180:183], v[208:211], v[72:75]
	v_mfma_f32_16x16x32_bf16 v[68:71], v[172:175], v[216:219], v[68:71]
	v_mfma_f32_16x16x32_bf16 v[64:67], v[180:183], v[216:219], v[64:67]
	s_barrier
	s_add_i32 s42, s79, s61
	v_lshl_add_u64 v[144:145], v[144:145], 0, s[10:11]
	s_mov_b32 m0, s42
	ds_read_b128 v[184:187], v151 offset:49152
	ds_read_b128 v[192:195], v151 offset:50176
	ds_read_b128 v[196:199], v151 offset:51200
	ds_read_b128 v[200:203], v151 offset:52224
	ds_read_b128 v[204:207], v151 offset:53248
	ds_read_b128 v[208:211], v151 offset:54272
	ds_read_b128 v[212:215], v151 offset:55296
	ds_read_b128 v[216:219], v151 offset:56320
	global_load_lds_dwordx4 v[144:145], off
	s_add_i32 m0, s42, 0x2000
	s_add_u32 s40, s40, 0x100080
	v_lshl_add_u64 v[144:145], v[188:189], 0, s[10:11]
	s_addc_u32 s41, s41, 0
	s_add_i32 s42, s80, s61
	global_load_lds_dwordx4 v[144:145], off
	s_mov_b32 m0, s42
	s_nop 0
	global_load_lds_dwordx4 v130, s[40:41]
	s_add_i32 m0, s42, 0x2000
	s_nop 0
	global_load_lds_dwordx4 v134, s[40:41]
	v_lshl_add_u64 v[144:145], v[220:221], 0, s[10:11]
	s_mov_b32 m0, s65
	s_nop 0
	global_load_lds_dwordx4 v[144:145], off
	v_lshl_add_u64 v[144:145], v[222:223], 0, s[10:11]
	s_mov_b32 m0, s66
	s_nop 0
	global_load_lds_dwordx4 v[144:145], off
	s_waitcnt vmcnt(8)
	s_waitcnt lgkmcnt(0)
	s_barrier
	v_mfma_f32_16x16x32_bf16 v[60:63], v[152:155], v[184:187], v[60:63]
	v_mfma_f32_16x16x32_bf16 v[56:59], v[160:163], v[184:187], v[56:59]
	v_mfma_f32_16x16x32_bf16 v[52:55], v[152:155], v[196:199], v[52:55]
	v_mfma_f32_16x16x32_bf16 v[44:47], v[160:163], v[196:199], v[44:47]
	v_mfma_f32_16x16x32_bf16 v[36:39], v[152:155], v[204:207], v[36:39]
	v_mfma_f32_16x16x32_bf16 v[28:31], v[160:163], v[204:207], v[28:31]
	v_mfma_f32_16x16x32_bf16 v[20:23], v[152:155], v[212:215], v[20:23]
	v_mfma_f32_16x16x32_bf16 v[12:15], v[160:163], v[212:215], v[12:15]
	v_mfma_f32_16x16x32_bf16 v[60:63], v[156:159], v[192:195], v[60:63]
	v_mfma_f32_16x16x32_bf16 v[56:59], v[164:167], v[192:195], v[56:59]
	v_mfma_f32_16x16x32_bf16 v[52:55], v[156:159], v[200:203], v[52:55]
	v_mfma_f32_16x16x32_bf16 v[44:47], v[164:167], v[200:203], v[44:47]
	v_mfma_f32_16x16x32_bf16 v[36:39], v[156:159], v[208:211], v[36:39]
	v_mfma_f32_16x16x32_bf16 v[28:31], v[164:167], v[208:211], v[28:31]
	v_mfma_f32_16x16x32_bf16 v[20:23], v[156:159], v[216:219], v[20:23]
	v_mfma_f32_16x16x32_bf16 v[12:15], v[164:167], v[216:219], v[12:15]
	v_mfma_f32_16x16x32_bf16 v[48:51], v[168:171], v[184:187], v[48:51]
	v_mfma_f32_16x16x32_bf16 v[40:43], v[176:179], v[184:187], v[40:43]
	v_mfma_f32_16x16x32_bf16 v[32:35], v[168:171], v[196:199], v[32:35]
	v_mfma_f32_16x16x32_bf16 v[24:27], v[176:179], v[196:199], v[24:27]
	v_mfma_f32_16x16x32_bf16 v[16:19], v[168:171], v[204:207], v[16:19]
	v_mfma_f32_16x16x32_bf16 v[8:11], v[176:179], v[204:207], v[8:11]
	v_mfma_f32_16x16x32_bf16 v[4:7], v[168:171], v[212:215], v[4:7]
	v_mfma_f32_16x16x32_bf16 v[0:3], v[176:179], v[212:215], v[0:3]
	v_mfma_f32_16x16x32_bf16 v[48:51], v[172:175], v[192:195], v[48:51]
	v_mfma_f32_16x16x32_bf16 v[40:43], v[180:183], v[192:195], v[40:43]
	v_mfma_f32_16x16x32_bf16 v[32:35], v[172:175], v[200:203], v[32:35]
	v_mfma_f32_16x16x32_bf16 v[24:27], v[180:183], v[200:203], v[24:27]
	v_mfma_f32_16x16x32_bf16 v[16:19], v[172:175], v[208:211], v[16:19]
	v_mfma_f32_16x16x32_bf16 v[8:11], v[180:183], v[208:211], v[8:11]
	v_mfma_f32_16x16x32_bf16 v[4:7], v[172:175], v[216:219], v[4:7]
	v_mfma_f32_16x16x32_bf16 v[0:3], v[180:183], v[216:219], v[0:3]
	s_barrier
	s_add_i32 s77, s77, 2
	s_add_u32 s34, s34, 0x100
	s_addc_u32 s35, s35, 0
	s_add_u32 s75, s75, 0x100
	s_addc_u32 s76, s76, 0
	s_cmp_gt_u32 s77, 61
	s_cbranch_scc0 .LBB0_916

.LBB0_1052:
	s_ashr_i32 s27, s26, 31
	s_lshl_b64 s[28:29], s[26:27], 19
	s_add_u32 s28, s58, s28
	s_addc_u32 s29, s59, s29
	s_and_b64 s[30:31], s[4:5], exec
	s_cselect_b32 s27, s29, s43
	s_cselect_b32 s55, s28, s42
	s_ashr_i32 s25, s24, 31
	s_lshl_b64 s[30:31], s[24:25], 19
	s_add_u32 s30, s53, s30
	s_addc_u32 s31, s64, s31
	s_and_b64 s[62:63], s[4:5], exec
	s_cselect_b32 s25, s31, s61
	s_cselect_b32 s79, s30, s60
	s_add_u32 s42, s42, 0x40080
	s_addc_u32 s43, s43, 0
	s_add_u32 s80, s60, 0x100
	s_addc_u32 s81, s61, 0
	s_mov_b32 s82, -2
	ds_read_b128 v[152:155], v149
	ds_read_b128 v[156:159], v149 offset:1024
	ds_read_b128 v[160:163], v149 offset:2048
	ds_read_b128 v[164:167], v149 offset:3072
	ds_read_b128 v[168:171], v150
	ds_read_b128 v[172:175], v150 offset:1024
	ds_read_b128 v[176:179], v150 offset:2048
	ds_read_b128 v[180:183], v150 offset:3072
	s_add_u32 s60, s42, 0xfffc0080
	s_addc_u32 s61, s43, -1
	s_cmp_eq_u32 s82, 12
	s_cselect_b32 s63, s27, s61
	s_cselect_b32 s62, s55, s60
	s_cselect_b32 s61, s25, s81
	s_cselect_b32 s60, s79, s80
	s_add_i32 m0, s35, 0xc000
	ds_read_b128 v[184:187], v151
	ds_read_b128 v[192:195], v151 offset:1024
	ds_read_b128 v[196:199], v151 offset:2048
	ds_read_b128 v[200:203], v151 offset:3072
	ds_read_b128 v[204:207], v151 offset:4096
	ds_read_b128 v[208:211], v151 offset:5120
	ds_read_b128 v[212:215], v151 offset:6144
	ds_read_b128 v[216:219], v151 offset:7168
	global_load_lds_dwordx4 v136, s[42:43]
	s_add_i32 m0, s35, 0xe000
	s_nop 0
	global_load_lds_dwordx4 v138, s[42:43]
	s_waitcnt vmcnt(8)
	s_waitcnt lgkmcnt(0)
	s_barrier
	v_mfma_f32_16x16x32_bf16 v[124:127], v[152:155], v[184:187], 0
	v_mfma_f32_16x16x32_bf16 v[120:123], v[160:163], v[184:187], 0
	v_mfma_f32_16x16x32_bf16 v[116:119], v[152:155], v[196:199], 0
	v_mfma_f32_16x16x32_bf16 v[108:111], v[160:163], v[196:199], 0
	v_mfma_f32_16x16x32_bf16 v[100:103], v[152:155], v[204:207], 0
	v_mfma_f32_16x16x32_bf16 v[92:95], v[160:163], v[204:207], 0
	v_mfma_f32_16x16x32_bf16 v[84:87], v[152:155], v[212:215], 0
	v_mfma_f32_16x16x32_bf16 v[76:79], v[160:163], v[212:215], 0
	v_mfma_f32_16x16x32_bf16 v[124:127], v[156:159], v[192:195], v[124:127]
	v_mfma_f32_16x16x32_bf16 v[120:123], v[164:167], v[192:195], v[120:123]
	v_mfma_f32_16x16x32_bf16 v[116:119], v[156:159], v[200:203], v[116:119]
	v_mfma_f32_16x16x32_bf16 v[108:111], v[164:167], v[200:203], v[108:111]
	v_mfma_f32_16x16x32_bf16 v[100:103], v[156:159], v[208:211], v[100:103]
	v_mfma_f32_16x16x32_bf16 v[92:95], v[164:167], v[208:211], v[92:95]
	v_mfma_f32_16x16x32_bf16 v[84:87], v[156:159], v[216:219], v[84:87]
	v_mfma_f32_16x16x32_bf16 v[76:79], v[164:167], v[216:219], v[76:79]
	v_mfma_f32_16x16x32_bf16 v[112:115], v[168:171], v[184:187], 0
	v_mfma_f32_16x16x32_bf16 v[104:107], v[176:179], v[184:187], 0
	v_mfma_f32_16x16x32_bf16 v[96:99], v[168:171], v[196:199], 0
	v_mfma_f32_16x16x32_bf16 v[88:91], v[176:179], v[196:199], 0
	v_mfma_f32_16x16x32_bf16 v[80:83], v[168:171], v[204:207], 0
	v_mfma_f32_16x16x32_bf16 v[72:75], v[176:179], v[204:207], 0
	v_mfma_f32_16x16x32_bf16 v[68:71], v[168:171], v[212:215], 0
	v_mfma_f32_16x16x32_bf16 v[64:67], v[176:179], v[212:215], 0
	v_mfma_f32_16x16x32_bf16 v[112:115], v[172:175], v[192:195], v[112:115]
	v_mfma_f32_16x16x32_bf16 v[104:107], v[180:183], v[192:195], v[104:107]
	v_mfma_f32_16x16x32_bf16 v[96:99], v[172:175], v[200:203], v[96:99]
	v_mfma_f32_16x16x32_bf16 v[88:91], v[180:183], v[200:203], v[88:91]
	v_mfma_f32_16x16x32_bf16 v[80:83], v[172:175], v[208:211], v[80:83]
	v_mfma_f32_16x16x32_bf16 v[72:75], v[180:183], v[208:211], v[72:75]
	v_mfma_f32_16x16x32_bf16 v[68:71], v[172:175], v[216:219], v[68:71]
	v_mfma_f32_16x16x32_bf16 v[64:67], v[180:183], v[216:219], v[64:67]
	s_barrier
	s_add_i32 s83, s72, s65
	v_lshl_add_u64 v[144:145], s[60:61], 0, v[130:131]
	s_mov_b32 m0, s83
	ds_read_b128 v[184:187], v151 offset:16384
	ds_read_b128 v[192:195], v151 offset:17408
	ds_read_b128 v[196:199], v151 offset:18432
	ds_read_b128 v[200:203], v151 offset:19456
	ds_read_b128 v[204:207], v151 offset:20480
	ds_read_b128 v[208:211], v151 offset:21504
	ds_read_b128 v[212:215], v151 offset:22528
	ds_read_b128 v[216:219], v151 offset:23552
	global_load_lds_dwordx4 v[144:145], off
	s_add_i32 m0, s83, 0x2000
	s_add_u32 s84, s60, 0x40000
	v_lshl_add_u64 v[188:189], s[60:61], 0, v[134:135]
	s_addc_u32 s85, s61, 0
	s_add_i32 s83, s73, s65
	global_load_lds_dwordx4 v[188:189], off
	s_mov_b32 m0, s83
	v_lshl_add_u64 v[222:223], s[62:63], 0, v[132:133]
	global_load_lds_dwordx4 v130, s[84:85]
	s_add_i32 m0, s83, 0x2000
	s_nop 0
	global_load_lds_dwordx4 v134, s[84:85]
	v_lshl_add_u64 v[220:221], s[62:63], 0, v[128:129]
	s_mov_b32 m0, s35
	s_nop 0
	global_load_lds_dwordx4 v[220:221], off
	s_mov_b32 m0, s33
	s_nop 0
	global_load_lds_dwordx4 v[222:223], off
	s_waitcnt vmcnt(8)
	s_waitcnt lgkmcnt(0)
	s_barrier
	v_mfma_f32_16x16x32_bf16 v[60:63], v[152:155], v[184:187], 0
	v_mfma_f32_16x16x32_bf16 v[56:59], v[160:163], v[184:187], 0
	v_mfma_f32_16x16x32_bf16 v[52:55], v[152:155], v[196:199], 0
	v_mfma_f32_16x16x32_bf16 v[44:47], v[160:163], v[196:199], 0
	v_mfma_f32_16x16x32_bf16 v[36:39], v[152:155], v[204:207], 0
	v_mfma_f32_16x16x32_bf16 v[28:31], v[160:163], v[204:207], 0
	v_mfma_f32_16x16x32_bf16 v[20:23], v[152:155], v[212:215], 0
	v_mfma_f32_16x16x32_bf16 v[12:15], v[160:163], v[212:215], 0
	v_mfma_f32_16x16x32_bf16 v[60:63], v[156:159], v[192:195], v[60:63]
	v_mfma_f32_16x16x32_bf16 v[56:59], v[164:167], v[192:195], v[56:59]
	v_mfma_f32_16x16x32_bf16 v[52:55], v[156:159], v[200:203], v[52:55]
	v_mfma_f32_16x16x32_bf16 v[44:47], v[164:167], v[200:203], v[44:47]
	v_mfma_f32_16x16x32_bf16 v[36:39], v[156:159], v[208:211], v[36:39]
	v_mfma_f32_16x16x32_bf16 v[28:31], v[164:167], v[208:211], v[28:31]
	v_mfma_f32_16x16x32_bf16 v[20:23], v[156:159], v[216:219], v[20:23]
	v_mfma_f32_16x16x32_bf16 v[12:15], v[164:167], v[216:219], v[12:15]
	v_mfma_f32_16x16x32_bf16 v[48:51], v[168:171], v[184:187], 0
	v_mfma_f32_16x16x32_bf16 v[40:43], v[176:179], v[184:187], 0
	v_mfma_f32_16x16x32_bf16 v[32:35], v[168:171], v[196:199], 0
	v_mfma_f32_16x16x32_bf16 v[24:27], v[176:179], v[196:199], 0
	v_mfma_f32_16x16x32_bf16 v[16:19], v[168:171], v[204:207], 0
	v_mfma_f32_16x16x32_bf16 v[8:11], v[176:179], v[204:207], 0
	v_mfma_f32_16x16x32_bf16 v[4:7], v[168:171], v[212:215], 0
	v_mfma_f32_16x16x32_bf16 v[0:3], v[176:179], v[212:215], 0
	v_mfma_f32_16x16x32_bf16 v[48:51], v[172:175], v[192:195], v[48:51]
	v_mfma_f32_16x16x32_bf16 v[40:43], v[180:183], v[192:195], v[40:43]
	v_mfma_f32_16x16x32_bf16 v[32:35], v[172:175], v[200:203], v[32:35]
	v_mfma_f32_16x16x32_bf16 v[24:27], v[180:183], v[200:203], v[24:27]
	v_mfma_f32_16x16x32_bf16 v[16:19], v[172:175], v[208:211], v[16:19]
	v_mfma_f32_16x16x32_bf16 v[8:11], v[180:183], v[208:211], v[8:11]
	v_mfma_f32_16x16x32_bf16 v[4:7], v[172:175], v[216:219], v[4:7]
	v_mfma_f32_16x16x32_bf16 v[0:3], v[180:183], v[216:219], v[0:3]
	s_barrier
	s_add_i32 s83, 0, 0x18000
	s_add_i32 s84, 0, 0x1c000
	v_add_u32_e32 v164, s83, v147
	v_add_u32_e32 v180, s84, v147
	ds_read_b128 v[152:155], v164
	ds_read_b128 v[156:159], v164 offset:1024
	ds_read_b128 v[160:163], v164 offset:2048
	ds_read_b128 v[164:167], v164 offset:3072
	ds_read_b128 v[168:171], v180
	ds_read_b128 v[172:175], v180 offset:1024
	ds_read_b128 v[176:179], v180 offset:2048
	ds_read_b128 v[180:183], v180 offset:3072
	s_add_u32 s62, s62, 0x40000
	s_addc_u32 s63, s63, 0
	s_mov_b32 m0, s66
	ds_read_b128 v[184:187], v151 offset:32768
	ds_read_b128 v[192:195], v151 offset:33792
	ds_read_b128 v[196:199], v151 offset:34816
	ds_read_b128 v[200:203], v151 offset:35840
	ds_read_b128 v[204:207], v151 offset:36864
	ds_read_b128 v[208:211], v151 offset:37888
	ds_read_b128 v[212:215], v151 offset:38912
	ds_read_b128 v[216:219], v151 offset:39936
	global_load_lds_dwordx4 v128, s[62:63]
	s_mov_b32 m0, s67
	s_nop 0
	global_load_lds_dwordx4 v132, s[62:63]
	s_waitcnt vmcnt(8)
	s_waitcnt lgkmcnt(0)
	s_barrier
	v_mfma_f32_16x16x32_bf16 v[124:127], v[152:155], v[184:187], v[124:127]
	v_mfma_f32_16x16x32_bf16 v[120:123], v[160:163], v[184:187], v[120:123]
	v_mfma_f32_16x16x32_bf16 v[116:119], v[152:155], v[196:199], v[116:119]
	v_mfma_f32_16x16x32_bf16 v[108:111], v[160:163], v[196:199], v[108:111]
	v_mfma_f32_16x16x32_bf16 v[100:103], v[152:155], v[204:207], v[100:103]
	v_mfma_f32_16x16x32_bf16 v[92:95], v[160:163], v[204:207], v[92:95]
	v_mfma_f32_16x16x32_bf16 v[84:87], v[152:155], v[212:215], v[84:87]
	v_mfma_f32_16x16x32_bf16 v[76:79], v[160:163], v[212:215], v[76:79]
	v_mfma_f32_16x16x32_bf16 v[124:127], v[156:159], v[192:195], v[124:127]
	v_mfma_f32_16x16x32_bf16 v[120:123], v[164:167], v[192:195], v[120:123]
	v_mfma_f32_16x16x32_bf16 v[116:119], v[156:159], v[200:203], v[116:119]
	v_mfma_f32_16x16x32_bf16 v[108:111], v[164:167], v[200:203], v[108:111]
	v_mfma_f32_16x16x32_bf16 v[100:103], v[156:159], v[208:211], v[100:103]
	v_mfma_f32_16x16x32_bf16 v[92:95], v[164:167], v[208:211], v[92:95]
	v_mfma_f32_16x16x32_bf16 v[84:87], v[156:159], v[216:219], v[84:87]
	v_mfma_f32_16x16x32_bf16 v[76:79], v[164:167], v[216:219], v[76:79]
	v_mfma_f32_16x16x32_bf16 v[112:115], v[168:171], v[184:187], v[112:115]
	v_mfma_f32_16x16x32_bf16 v[104:107], v[176:179], v[184:187], v[104:107]
	v_mfma_f32_16x16x32_bf16 v[96:99], v[168:171], v[196:199], v[96:99]
	v_mfma_f32_16x16x32_bf16 v[88:91], v[176:179], v[196:199], v[88:91]
	v_mfma_f32_16x16x32_bf16 v[80:83], v[168:171], v[204:207], v[80:83]
	v_mfma_f32_16x16x32_bf16 v[72:75], v[176:179], v[204:207], v[72:75]
	v_mfma_f32_16x16x32_bf16 v[68:71], v[168:171], v[212:215], v[68:71]
	v_mfma_f32_16x16x32_bf16 v[64:67], v[176:179], v[212:215], v[64:67]
	v_mfma_f32_16x16x32_bf16 v[112:115], v[172:175], v[192:195], v[112:115]
	v_mfma_f32_16x16x32_bf16 v[104:107], v[180:183], v[192:195], v[104:107]
	v_mfma_f32_16x16x32_bf16 v[96:99], v[172:175], v[200:203], v[96:99]
	v_mfma_f32_16x16x32_bf16 v[88:91], v[180:183], v[200:203], v[88:91]
	v_mfma_f32_16x16x32_bf16 v[80:83], v[172:175], v[208:211], v[80:83]
	v_mfma_f32_16x16x32_bf16 v[72:75], v[180:183], v[208:211], v[72:75]
	v_mfma_f32_16x16x32_bf16 v[68:71], v[172:175], v[216:219], v[68:71]
	v_mfma_f32_16x16x32_bf16 v[64:67], v[180:183], v[216:219], v[64:67]
	s_barrier
	s_add_i32 s62, s83, s65
	v_lshl_add_u64 v[144:145], v[144:145], 0, s[12:13]
	s_mov_b32 m0, s62
	ds_read_b128 v[184:187], v151 offset:49152
	ds_read_b128 v[192:195], v151 offset:50176
	ds_read_b128 v[196:199], v151 offset:51200
	ds_read_b128 v[200:203], v151 offset:52224
	ds_read_b128 v[204:207], v151 offset:53248
	ds_read_b128 v[208:211], v151 offset:54272
	ds_read_b128 v[212:215], v151 offset:55296
	ds_read_b128 v[216:219], v151 offset:56320
	global_load_lds_dwordx4 v[144:145], off
	s_add_i32 m0, s62, 0x2000
	s_add_u32 s60, s60, 0x40080
	v_lshl_add_u64 v[144:145], v[188:189], 0, s[12:13]
	s_addc_u32 s61, s61, 0
	s_add_i32 s62, s84, s65
	global_load_lds_dwordx4 v[144:145], off
	s_mov_b32 m0, s62
	s_nop 0
	global_load_lds_dwordx4 v130, s[60:61]
	s_add_i32 m0, s62, 0x2000
	s_nop 0
	global_load_lds_dwordx4 v134, s[60:61]
	v_lshl_add_u64 v[144:145], v[220:221], 0, s[12:13]
	s_mov_b32 m0, s69
	s_nop 0
	global_load_lds_dwordx4 v[144:145], off
	v_lshl_add_u64 v[144:145], v[222:223], 0, s[12:13]
	s_mov_b32 m0, s70
	s_nop 0
	global_load_lds_dwordx4 v[144:145], off
	s_waitcnt vmcnt(8)
	s_waitcnt lgkmcnt(0)
	s_barrier
	v_mfma_f32_16x16x32_bf16 v[60:63], v[152:155], v[184:187], v[60:63]
	v_mfma_f32_16x16x32_bf16 v[56:59], v[160:163], v[184:187], v[56:59]
	v_mfma_f32_16x16x32_bf16 v[52:55], v[152:155], v[196:199], v[52:55]
	v_mfma_f32_16x16x32_bf16 v[44:47], v[160:163], v[196:199], v[44:47]
	v_mfma_f32_16x16x32_bf16 v[36:39], v[152:155], v[204:207], v[36:39]
	v_mfma_f32_16x16x32_bf16 v[28:31], v[160:163], v[204:207], v[28:31]
	v_mfma_f32_16x16x32_bf16 v[20:23], v[152:155], v[212:215], v[20:23]
	v_mfma_f32_16x16x32_bf16 v[12:15], v[160:163], v[212:215], v[12:15]
	v_mfma_f32_16x16x32_bf16 v[60:63], v[156:159], v[192:195], v[60:63]
	v_mfma_f32_16x16x32_bf16 v[56:59], v[164:167], v[192:195], v[56:59]
	v_mfma_f32_16x16x32_bf16 v[52:55], v[156:159], v[200:203], v[52:55]
	v_mfma_f32_16x16x32_bf16 v[44:47], v[164:167], v[200:203], v[44:47]
	v_mfma_f32_16x16x32_bf16 v[36:39], v[156:159], v[208:211], v[36:39]
	v_mfma_f32_16x16x32_bf16 v[28:31], v[164:167], v[208:211], v[28:31]
	v_mfma_f32_16x16x32_bf16 v[20:23], v[156:159], v[216:219], v[20:23]
	v_mfma_f32_16x16x32_bf16 v[12:15], v[164:167], v[216:219], v[12:15]
	v_mfma_f32_16x16x32_bf16 v[48:51], v[168:171], v[184:187], v[48:51]
	v_mfma_f32_16x16x32_bf16 v[40:43], v[176:179], v[184:187], v[40:43]
	v_mfma_f32_16x16x32_bf16 v[32:35], v[168:171], v[196:199], v[32:35]
	v_mfma_f32_16x16x32_bf16 v[24:27], v[176:179], v[196:199], v[24:27]
	v_mfma_f32_16x16x32_bf16 v[16:19], v[168:171], v[204:207], v[16:19]
	v_mfma_f32_16x16x32_bf16 v[8:11], v[176:179], v[204:207], v[8:11]
	v_mfma_f32_16x16x32_bf16 v[4:7], v[168:171], v[212:215], v[4:7]
	v_mfma_f32_16x16x32_bf16 v[0:3], v[176:179], v[212:215], v[0:3]
	v_mfma_f32_16x16x32_bf16 v[48:51], v[172:175], v[192:195], v[48:51]
	v_mfma_f32_16x16x32_bf16 v[40:43], v[180:183], v[192:195], v[40:43]
	v_mfma_f32_16x16x32_bf16 v[32:35], v[172:175], v[200:203], v[32:35]
	v_mfma_f32_16x16x32_bf16 v[24:27], v[180:183], v[200:203], v[24:27]
	v_mfma_f32_16x16x32_bf16 v[16:19], v[172:175], v[208:211], v[16:19]
	v_mfma_f32_16x16x32_bf16 v[8:11], v[180:183], v[208:211], v[8:11]
	v_mfma_f32_16x16x32_bf16 v[4:7], v[172:175], v[216:219], v[4:7]
	v_mfma_f32_16x16x32_bf16 v[0:3], v[180:183], v[216:219], v[0:3]
	s_barrier
	s_add_i32 s82, s82, 2
	s_add_u32 s42, s42, 0x100
	s_addc_u32 s43, s43, 0
	s_add_u32 s80, s80, 0x100
	s_addc_u32 s81, s81, 0
	s_cmp_gt_u32 s82, 13
	s_cbranch_scc0 .LBB0_1053
	s_branch .Lpeel_exit5
.LBB0_1053:
	ds_read_b128 v[152:155], v149
	ds_read_b128 v[156:159], v149 offset:1024
	ds_read_b128 v[160:163], v149 offset:2048
	ds_read_b128 v[164:167], v149 offset:3072
	ds_read_b128 v[168:171], v150
	ds_read_b128 v[172:175], v150 offset:1024
	ds_read_b128 v[176:179], v150 offset:2048
	ds_read_b128 v[180:183], v150 offset:3072
	s_add_u32 s60, s42, 0xfffc0080
	s_addc_u32 s61, s43, -1
	s_cmp_eq_u32 s82, 12
	s_cselect_b32 s63, s27, s61
	s_cselect_b32 s62, s55, s60
	s_cselect_b32 s61, s25, s81
	s_cselect_b32 s60, s79, s80
	s_add_i32 m0, s35, 0xc000
	ds_read_b128 v[184:187], v151
	ds_read_b128 v[192:195], v151 offset:1024
	ds_read_b128 v[196:199], v151 offset:2048
	ds_read_b128 v[200:203], v151 offset:3072
	ds_read_b128 v[204:207], v151 offset:4096
	ds_read_b128 v[208:211], v151 offset:5120
	ds_read_b128 v[212:215], v151 offset:6144
	ds_read_b128 v[216:219], v151 offset:7168
	global_load_lds_dwordx4 v136, s[42:43]
	s_add_i32 m0, s35, 0xe000
	s_nop 0
	global_load_lds_dwordx4 v138, s[42:43]
	s_waitcnt vmcnt(8)
	s_waitcnt lgkmcnt(0)
	s_barrier
	v_mfma_f32_16x16x32_bf16 v[124:127], v[152:155], v[184:187], v[124:127]
	v_mfma_f32_16x16x32_bf16 v[120:123], v[160:163], v[184:187], v[120:123]
	v_mfma_f32_16x16x32_bf16 v[116:119], v[152:155], v[196:199], v[116:119]
	v_mfma_f32_16x16x32_bf16 v[108:111], v[160:163], v[196:199], v[108:111]
	v_mfma_f32_16x16x32_bf16 v[100:103], v[152:155], v[204:207], v[100:103]
	v_mfma_f32_16x16x32_bf16 v[92:95], v[160:163], v[204:207], v[92:95]
	v_mfma_f32_16x16x32_bf16 v[84:87], v[152:155], v[212:215], v[84:87]
	v_mfma_f32_16x16x32_bf16 v[76:79], v[160:163], v[212:215], v[76:79]
	v_mfma_f32_16x16x32_bf16 v[124:127], v[156:159], v[192:195], v[124:127]
	v_mfma_f32_16x16x32_bf16 v[120:123], v[164:167], v[192:195], v[120:123]
	v_mfma_f32_16x16x32_bf16 v[116:119], v[156:159], v[200:203], v[116:119]
	v_mfma_f32_16x16x32_bf16 v[108:111], v[164:167], v[200:203], v[108:111]
	v_mfma_f32_16x16x32_bf16 v[100:103], v[156:159], v[208:211], v[100:103]
	v_mfma_f32_16x16x32_bf16 v[92:95], v[164:167], v[208:211], v[92:95]
	v_mfma_f32_16x16x32_bf16 v[84:87], v[156:159], v[216:219], v[84:87]
	v_mfma_f32_16x16x32_bf16 v[76:79], v[164:167], v[216:219], v[76:79]
	v_mfma_f32_16x16x32_bf16 v[112:115], v[168:171], v[184:187], v[112:115]
	v_mfma_f32_16x16x32_bf16 v[104:107], v[176:179], v[184:187], v[104:107]
	v_mfma_f32_16x16x32_bf16 v[96:99], v[168:171], v[196:199], v[96:99]
	v_mfma_f32_16x16x32_bf16 v[88:91], v[176:179], v[196:199], v[88:91]
	v_mfma_f32_16x16x32_bf16 v[80:83], v[168:171], v[204:207], v[80:83]
	v_mfma_f32_16x16x32_bf16 v[72:75], v[176:179], v[204:207], v[72:75]
	v_mfma_f32_16x16x32_bf16 v[68:71], v[168:171], v[212:215], v[68:71]
	v_mfma_f32_16x16x32_bf16 v[64:67], v[176:179], v[212:215], v[64:67]
	v_mfma_f32_16x16x32_bf16 v[112:115], v[172:175], v[192:195], v[112:115]
	v_mfma_f32_16x16x32_bf16 v[104:107], v[180:183], v[192:195], v[104:107]
	v_mfma_f32_16x16x32_bf16 v[96:99], v[172:175], v[200:203], v[96:99]
	v_mfma_f32_16x16x32_bf16 v[88:91], v[180:183], v[200:203], v[88:91]
	v_mfma_f32_16x16x32_bf16 v[80:83], v[172:175], v[208:211], v[80:83]
	v_mfma_f32_16x16x32_bf16 v[72:75], v[180:183], v[208:211], v[72:75]
	v_mfma_f32_16x16x32_bf16 v[68:71], v[172:175], v[216:219], v[68:71]
	v_mfma_f32_16x16x32_bf16 v[64:67], v[180:183], v[216:219], v[64:67]
	s_barrier
	s_add_i32 s83, s72, s65
	v_lshl_add_u64 v[144:145], s[60:61], 0, v[130:131]
	s_mov_b32 m0, s83
	ds_read_b128 v[184:187], v151 offset:16384
	ds_read_b128 v[192:195], v151 offset:17408
	ds_read_b128 v[196:199], v151 offset:18432
	ds_read_b128 v[200:203], v151 offset:19456
	ds_read_b128 v[204:207], v151 offset:20480
	ds_read_b128 v[208:211], v151 offset:21504
	ds_read_b128 v[212:215], v151 offset:22528
	ds_read_b128 v[216:219], v151 offset:23552
	global_load_lds_dwordx4 v[144:145], off
	s_add_i32 m0, s83, 0x2000
	s_add_u32 s84, s60, 0x40000
	v_lshl_add_u64 v[188:189], s[60:61], 0, v[134:135]
	s_addc_u32 s85, s61, 0
	s_add_i32 s83, s73, s65
	global_load_lds_dwordx4 v[188:189], off
	s_mov_b32 m0, s83
	v_lshl_add_u64 v[222:223], s[62:63], 0, v[132:133]
	global_load_lds_dwordx4 v130, s[84:85]
	s_add_i32 m0, s83, 0x2000
	s_nop 0
	global_load_lds_dwordx4 v134, s[84:85]
	v_lshl_add_u64 v[220:221], s[62:63], 0, v[128:129]
	s_mov_b32 m0, s35
	s_nop 0
	global_load_lds_dwordx4 v[220:221], off
	s_mov_b32 m0, s33
	s_nop 0
	global_load_lds_dwordx4 v[222:223], off
	s_waitcnt vmcnt(8)
	s_waitcnt lgkmcnt(0)
	s_barrier
	v_mfma_f32_16x16x32_bf16 v[60:63], v[152:155], v[184:187], v[60:63]
	v_mfma_f32_16x16x32_bf16 v[56:59], v[160:163], v[184:187], v[56:59]
	v_mfma_f32_16x16x32_bf16 v[52:55], v[152:155], v[196:199], v[52:55]
	v_mfma_f32_16x16x32_bf16 v[44:47], v[160:163], v[196:199], v[44:47]
	v_mfma_f32_16x16x32_bf16 v[36:39], v[152:155], v[204:207], v[36:39]
	v_mfma_f32_16x16x32_bf16 v[28:31], v[160:163], v[204:207], v[28:31]
	v_mfma_f32_16x16x32_bf16 v[20:23], v[152:155], v[212:215], v[20:23]
	v_mfma_f32_16x16x32_bf16 v[12:15], v[160:163], v[212:215], v[12:15]
	v_mfma_f32_16x16x32_bf16 v[60:63], v[156:159], v[192:195], v[60:63]
	v_mfma_f32_16x16x32_bf16 v[56:59], v[164:167], v[192:195], v[56:59]
	v_mfma_f32_16x16x32_bf16 v[52:55], v[156:159], v[200:203], v[52:55]
	v_mfma_f32_16x16x32_bf16 v[44:47], v[164:167], v[200:203], v[44:47]
	v_mfma_f32_16x16x32_bf16 v[36:39], v[156:159], v[208:211], v[36:39]
	v_mfma_f32_16x16x32_bf16 v[28:31], v[164:167], v[208:211], v[28:31]
	v_mfma_f32_16x16x32_bf16 v[20:23], v[156:159], v[216:219], v[20:23]
	v_mfma_f32_16x16x32_bf16 v[12:15], v[164:167], v[216:219], v[12:15]
	v_mfma_f32_16x16x32_bf16 v[48:51], v[168:171], v[184:187], v[48:51]
	v_mfma_f32_16x16x32_bf16 v[40:43], v[176:179], v[184:187], v[40:43]
	v_mfma_f32_16x16x32_bf16 v[32:35], v[168:171], v[196:199], v[32:35]
	v_mfma_f32_16x16x32_bf16 v[24:27], v[176:179], v[196:199], v[24:27]
	v_mfma_f32_16x16x32_bf16 v[16:19], v[168:171], v[204:207], v[16:19]
	v_mfma_f32_16x16x32_bf16 v[8:11], v[176:179], v[204:207], v[8:11]
	v_mfma_f32_16x16x32_bf16 v[4:7], v[168:171], v[212:215], v[4:7]
	v_mfma_f32_16x16x32_bf16 v[0:3], v[176:179], v[212:215], v[0:3]
	v_mfma_f32_16x16x32_bf16 v[48:51], v[172:175], v[192:195], v[48:51]
	v_mfma_f32_16x16x32_bf16 v[40:43], v[180:183], v[192:195], v[40:43]
	v_mfma_f32_16x16x32_bf16 v[32:35], v[172:175], v[200:203], v[32:35]
	v_mfma_f32_16x16x32_bf16 v[24:27], v[180:183], v[200:203], v[24:27]
	v_mfma_f32_16x16x32_bf16 v[16:19], v[172:175], v[208:211], v[16:19]
	v_mfma_f32_16x16x32_bf16 v[8:11], v[180:183], v[208:211], v[8:11]
	v_mfma_f32_16x16x32_bf16 v[4:7], v[172:175], v[216:219], v[4:7]
	v_mfma_f32_16x16x32_bf16 v[0:3], v[180:183], v[216:219], v[0:3]
	s_barrier
	s_add_i32 s83, 0, 0x18000
	s_add_i32 s84, 0, 0x1c000
	v_add_u32_e32 v164, s83, v147
	v_add_u32_e32 v180, s84, v147
	ds_read_b128 v[152:155], v164
	ds_read_b128 v[156:159], v164 offset:1024
	ds_read_b128 v[160:163], v164 offset:2048
	ds_read_b128 v[164:167], v164 offset:3072
	ds_read_b128 v[168:171], v180
	ds_read_b128 v[172:175], v180 offset:1024
	ds_read_b128 v[176:179], v180 offset:2048
	ds_read_b128 v[180:183], v180 offset:3072
	s_add_u32 s62, s62, 0x40000
	s_addc_u32 s63, s63, 0
	s_mov_b32 m0, s66
	ds_read_b128 v[184:187], v151 offset:32768
	ds_read_b128 v[192:195], v151 offset:33792
	ds_read_b128 v[196:199], v151 offset:34816
	ds_read_b128 v[200:203], v151 offset:35840
	ds_read_b128 v[204:207], v151 offset:36864
	ds_read_b128 v[208:211], v151 offset:37888
	ds_read_b128 v[212:215], v151 offset:38912
	ds_read_b128 v[216:219], v151 offset:39936
	global_load_lds_dwordx4 v128, s[62:63]
	s_mov_b32 m0, s67
	s_nop 0
	global_load_lds_dwordx4 v132, s[62:63]
	s_waitcnt vmcnt(8)
	s_waitcnt lgkmcnt(0)
	s_barrier
	v_mfma_f32_16x16x32_bf16 v[124:127], v[152:155], v[184:187], v[124:127]
	v_mfma_f32_16x16x32_bf16 v[120:123], v[160:163], v[184:187], v[120:123]
	v_mfma_f32_16x16x32_bf16 v[116:119], v[152:155], v[196:199], v[116:119]
	v_mfma_f32_16x16x32_bf16 v[108:111], v[160:163], v[196:199], v[108:111]
	v_mfma_f32_16x16x32_bf16 v[100:103], v[152:155], v[204:207], v[100:103]
	v_mfma_f32_16x16x32_bf16 v[92:95], v[160:163], v[204:207], v[92:95]
	v_mfma_f32_16x16x32_bf16 v[84:87], v[152:155], v[212:215], v[84:87]
	v_mfma_f32_16x16x32_bf16 v[76:79], v[160:163], v[212:215], v[76:79]
	v_mfma_f32_16x16x32_bf16 v[124:127], v[156:159], v[192:195], v[124:127]
	v_mfma_f32_16x16x32_bf16 v[120:123], v[164:167], v[192:195], v[120:123]
	v_mfma_f32_16x16x32_bf16 v[116:119], v[156:159], v[200:203], v[116:119]
	v_mfma_f32_16x16x32_bf16 v[108:111], v[164:167], v[200:203], v[108:111]
	v_mfma_f32_16x16x32_bf16 v[100:103], v[156:159], v[208:211], v[100:103]
	v_mfma_f32_16x16x32_bf16 v[92:95], v[164:167], v[208:211], v[92:95]
	v_mfma_f32_16x16x32_bf16 v[84:87], v[156:159], v[216:219], v[84:87]
	v_mfma_f32_16x16x32_bf16 v[76:79], v[164:167], v[216:219], v[76:79]
	v_mfma_f32_16x16x32_bf16 v[112:115], v[168:171], v[184:187], v[112:115]
	v_mfma_f32_16x16x32_bf16 v[104:107], v[176:179], v[184:187], v[104:107]
	v_mfma_f32_16x16x32_bf16 v[96:99], v[168:171], v[196:199], v[96:99]
	v_mfma_f32_16x16x32_bf16 v[88:91], v[176:179], v[196:199], v[88:91]
	v_mfma_f32_16x16x32_bf16 v[80:83], v[168:171], v[204:207], v[80:83]
	v_mfma_f32_16x16x32_bf16 v[72:75], v[176:179], v[204:207], v[72:75]
	v_mfma_f32_16x16x32_bf16 v[68:71], v[168:171], v[212:215], v[68:71]
	v_mfma_f32_16x16x32_bf16 v[64:67], v[176:179], v[212:215], v[64:67]
	v_mfma_f32_16x16x32_bf16 v[112:115], v[172:175], v[192:195], v[112:115]
	v_mfma_f32_16x16x32_bf16 v[104:107], v[180:183], v[192:195], v[104:107]
	v_mfma_f32_16x16x32_bf16 v[96:99], v[172:175], v[200:203], v[96:99]
	v_mfma_f32_16x16x32_bf16 v[88:91], v[180:183], v[200:203], v[88:91]
	v_mfma_f32_16x16x32_bf16 v[80:83], v[172:175], v[208:211], v[80:83]
	v_mfma_f32_16x16x32_bf16 v[72:75], v[180:183], v[208:211], v[72:75]
	v_mfma_f32_16x16x32_bf16 v[68:71], v[172:175], v[216:219], v[68:71]
	v_mfma_f32_16x16x32_bf16 v[64:67], v[180:183], v[216:219], v[64:67]
	s_barrier
	s_add_i32 s62, s83, s65
	v_lshl_add_u64 v[144:145], v[144:145], 0, s[12:13]
	s_mov_b32 m0, s62
	ds_read_b128 v[184:187], v151 offset:49152
	ds_read_b128 v[192:195], v151 offset:50176
	ds_read_b128 v[196:199], v151 offset:51200
	ds_read_b128 v[200:203], v151 offset:52224
	ds_read_b128 v[204:207], v151 offset:53248
	ds_read_b128 v[208:211], v151 offset:54272
	ds_read_b128 v[212:215], v151 offset:55296
	ds_read_b128 v[216:219], v151 offset:56320
	global_load_lds_dwordx4 v[144:145], off
	s_add_i32 m0, s62, 0x2000
	s_add_u32 s60, s60, 0x40080
	v_lshl_add_u64 v[144:145], v[188:189], 0, s[12:13]
	s_addc_u32 s61, s61, 0
	s_add_i32 s62, s84, s65
	global_load_lds_dwordx4 v[144:145], off
	s_mov_b32 m0, s62
	s_nop 0
	global_load_lds_dwordx4 v130, s[60:61]
	s_add_i32 m0, s62, 0x2000
	s_nop 0
	global_load_lds_dwordx4 v134, s[60:61]
	v_lshl_add_u64 v[144:145], v[220:221], 0, s[12:13]
	s_mov_b32 m0, s69
	s_nop 0
	global_load_lds_dwordx4 v[144:145], off
	v_lshl_add_u64 v[144:145], v[222:223], 0, s[12:13]
	s_mov_b32 m0, s70
	s_nop 0
	global_load_lds_dwordx4 v[144:145], off
	s_waitcnt vmcnt(8)
	s_waitcnt lgkmcnt(0)
	s_barrier
	v_mfma_f32_16x16x32_bf16 v[60:63], v[152:155], v[184:187], v[60:63]
	v_mfma_f32_16x16x32_bf16 v[56:59], v[160:163], v[184:187], v[56:59]
	v_mfma_f32_16x16x32_bf16 v[52:55], v[152:155], v[196:199], v[52:55]
	v_mfma_f32_16x16x32_bf16 v[44:47], v[160:163], v[196:199], v[44:47]
	v_mfma_f32_16x16x32_bf16 v[36:39], v[152:155], v[204:207], v[36:39]
	v_mfma_f32_16x16x32_bf16 v[28:31], v[160:163], v[204:207], v[28:31]
	v_mfma_f32_16x16x32_bf16 v[20:23], v[152:155], v[212:215], v[20:23]
	v_mfma_f32_16x16x32_bf16 v[12:15], v[160:163], v[212:215], v[12:15]
	v_mfma_f32_16x16x32_bf16 v[60:63], v[156:159], v[192:195], v[60:63]
	v_mfma_f32_16x16x32_bf16 v[56:59], v[164:167], v[192:195], v[56:59]
	v_mfma_f32_16x16x32_bf16 v[52:55], v[156:159], v[200:203], v[52:55]
	v_mfma_f32_16x16x32_bf16 v[44:47], v[164:167], v[200:203], v[44:47]
	v_mfma_f32_16x16x32_bf16 v[36:39], v[156:159], v[208:211], v[36:39]
	v_mfma_f32_16x16x32_bf16 v[28:31], v[164:167], v[208:211], v[28:31]
	v_mfma_f32_16x16x32_bf16 v[20:23], v[156:159], v[216:219], v[20:23]
	v_mfma_f32_16x16x32_bf16 v[12:15], v[164:167], v[216:219], v[12:15]
	v_mfma_f32_16x16x32_bf16 v[48:51], v[168:171], v[184:187], v[48:51]
	v_mfma_f32_16x16x32_bf16 v[40:43], v[176:179], v[184:187], v[40:43]
	v_mfma_f32_16x16x32_bf16 v[32:35], v[168:171], v[196:199], v[32:35]
	v_mfma_f32_16x16x32_bf16 v[24:27], v[176:179], v[196:199], v[24:27]
	v_mfma_f32_16x16x32_bf16 v[16:19], v[168:171], v[204:207], v[16:19]
	v_mfma_f32_16x16x32_bf16 v[8:11], v[176:179], v[204:207], v[8:11]
	v_mfma_f32_16x16x32_bf16 v[4:7], v[168:171], v[212:215], v[4:7]
	v_mfma_f32_16x16x32_bf16 v[0:3], v[176:179], v[212:215], v[0:3]
	v_mfma_f32_16x16x32_bf16 v[48:51], v[172:175], v[192:195], v[48:51]
	v_mfma_f32_16x16x32_bf16 v[40:43], v[180:183], v[192:195], v[40:43]
	v_mfma_f32_16x16x32_bf16 v[32:35], v[172:175], v[200:203], v[32:35]
	v_mfma_f32_16x16x32_bf16 v[24:27], v[180:183], v[200:203], v[24:27]
	v_mfma_f32_16x16x32_bf16 v[16:19], v[172:175], v[208:211], v[16:19]
	v_mfma_f32_16x16x32_bf16 v[8:11], v[180:183], v[208:211], v[8:11]
	v_mfma_f32_16x16x32_bf16 v[4:7], v[172:175], v[216:219], v[4:7]
	v_mfma_f32_16x16x32_bf16 v[0:3], v[180:183], v[216:219], v[0:3]
	s_barrier
	s_add_i32 s82, s82, 2
	s_add_u32 s42, s42, 0x100
	s_addc_u32 s43, s43, 0
	s_add_u32 s80, s80, 0x100
	s_addc_u32 s81, s81, 0
	s_cmp_gt_u32 s82, 13
	s_cbranch_scc0 .LBB0_1053

.LBB0_1076:
	s_ashr_i32 s27, s26, 31
	s_lshl_b64 s[28:29], s[26:27], 19
	s_add_u32 s28, s40, s28
	s_addc_u32 s29, s41, s29
	s_and_b64 s[30:31], s[4:5], exec
	s_cselect_b32 s27, s29, s43
	s_cselect_b32 s55, s28, s42
	s_ashr_i32 s25, s24, 31
	s_lshl_b64 s[30:31], s[24:25], 19
	s_add_u32 s30, s53, s30
	s_addc_u32 s31, s64, s31
	s_and_b64 s[62:63], s[4:5], exec
	s_cselect_b32 s25, s31, s61
	s_cselect_b32 s79, s30, s60
	s_add_u32 s42, s42, 0x40080
	s_addc_u32 s43, s43, 0
	s_add_u32 s80, s60, 0x100
	s_addc_u32 s81, s61, 0
	s_mov_b32 s82, -2
	ds_read_b128 v[152:155], v149
	ds_read_b128 v[156:159], v149 offset:1024
	ds_read_b128 v[160:163], v149 offset:2048
	ds_read_b128 v[164:167], v149 offset:3072
	ds_read_b128 v[168:171], v150
	ds_read_b128 v[172:175], v150 offset:1024
	ds_read_b128 v[176:179], v150 offset:2048
	ds_read_b128 v[180:183], v150 offset:3072
	s_add_u32 s60, s42, 0xfffc0080
	s_addc_u32 s61, s43, -1
	s_cmp_eq_u32 s82, 12
	s_cselect_b32 s63, s27, s61
	s_cselect_b32 s62, s55, s60
	s_cselect_b32 s61, s25, s81
	s_cselect_b32 s60, s79, s80
	s_add_i32 m0, s35, 0xc000
	ds_read_b128 v[184:187], v151
	ds_read_b128 v[192:195], v151 offset:1024
	ds_read_b128 v[196:199], v151 offset:2048
	ds_read_b128 v[200:203], v151 offset:3072
	ds_read_b128 v[204:207], v151 offset:4096
	ds_read_b128 v[208:211], v151 offset:5120
	ds_read_b128 v[212:215], v151 offset:6144
	ds_read_b128 v[216:219], v151 offset:7168
	global_load_lds_dwordx4 v136, s[42:43]
	s_add_i32 m0, s35, 0xe000
	s_nop 0
	global_load_lds_dwordx4 v138, s[42:43]
	s_waitcnt vmcnt(8)
	s_waitcnt lgkmcnt(0)
	s_barrier
	v_mfma_f32_16x16x32_bf16 v[124:127], v[152:155], v[184:187], 0
	v_mfma_f32_16x16x32_bf16 v[120:123], v[160:163], v[184:187], 0
	v_mfma_f32_16x16x32_bf16 v[116:119], v[152:155], v[196:199], 0
	v_mfma_f32_16x16x32_bf16 v[108:111], v[160:163], v[196:199], 0
	v_mfma_f32_16x16x32_bf16 v[100:103], v[152:155], v[204:207], 0
	v_mfma_f32_16x16x32_bf16 v[92:95], v[160:163], v[204:207], 0
	v_mfma_f32_16x16x32_bf16 v[84:87], v[152:155], v[212:215], 0
	v_mfma_f32_16x16x32_bf16 v[76:79], v[160:163], v[212:215], 0
	v_mfma_f32_16x16x32_bf16 v[124:127], v[156:159], v[192:195], v[124:127]
	v_mfma_f32_16x16x32_bf16 v[120:123], v[164:167], v[192:195], v[120:123]
	v_mfma_f32_16x16x32_bf16 v[116:119], v[156:159], v[200:203], v[116:119]
	v_mfma_f32_16x16x32_bf16 v[108:111], v[164:167], v[200:203], v[108:111]
	v_mfma_f32_16x16x32_bf16 v[100:103], v[156:159], v[208:211], v[100:103]
	v_mfma_f32_16x16x32_bf16 v[92:95], v[164:167], v[208:211], v[92:95]
	v_mfma_f32_16x16x32_bf16 v[84:87], v[156:159], v[216:219], v[84:87]
	v_mfma_f32_16x16x32_bf16 v[76:79], v[164:167], v[216:219], v[76:79]
	v_mfma_f32_16x16x32_bf16 v[112:115], v[168:171], v[184:187], 0
	v_mfma_f32_16x16x32_bf16 v[104:107], v[176:179], v[184:187], 0
	v_mfma_f32_16x16x32_bf16 v[96:99], v[168:171], v[196:199], 0
	v_mfma_f32_16x16x32_bf16 v[88:91], v[176:179], v[196:199], 0
	v_mfma_f32_16x16x32_bf16 v[80:83], v[168:171], v[204:207], 0
	v_mfma_f32_16x16x32_bf16 v[72:75], v[176:179], v[204:207], 0
	v_mfma_f32_16x16x32_bf16 v[68:71], v[168:171], v[212:215], 0
	v_mfma_f32_16x16x32_bf16 v[64:67], v[176:179], v[212:215], 0
	v_mfma_f32_16x16x32_bf16 v[112:115], v[172:175], v[192:195], v[112:115]
	v_mfma_f32_16x16x32_bf16 v[104:107], v[180:183], v[192:195], v[104:107]
	v_mfma_f32_16x16x32_bf16 v[96:99], v[172:175], v[200:203], v[96:99]
	v_mfma_f32_16x16x32_bf16 v[88:91], v[180:183], v[200:203], v[88:91]
	v_mfma_f32_16x16x32_bf16 v[80:83], v[172:175], v[208:211], v[80:83]
	v_mfma_f32_16x16x32_bf16 v[72:75], v[180:183], v[208:211], v[72:75]
	v_mfma_f32_16x16x32_bf16 v[68:71], v[172:175], v[216:219], v[68:71]
	v_mfma_f32_16x16x32_bf16 v[64:67], v[180:183], v[216:219], v[64:67]
	s_barrier
	s_add_i32 s83, s72, s65
	v_lshl_add_u64 v[144:145], s[60:61], 0, v[130:131]
	s_mov_b32 m0, s83
	ds_read_b128 v[184:187], v151 offset:16384
	ds_read_b128 v[192:195], v151 offset:17408
	ds_read_b128 v[196:199], v151 offset:18432
	ds_read_b128 v[200:203], v151 offset:19456
	ds_read_b128 v[204:207], v151 offset:20480
	ds_read_b128 v[208:211], v151 offset:21504
	ds_read_b128 v[212:215], v151 offset:22528
	ds_read_b128 v[216:219], v151 offset:23552
	global_load_lds_dwordx4 v[144:145], off
	s_add_i32 m0, s83, 0x2000
	s_add_u32 s84, s60, 0x40000
	v_lshl_add_u64 v[188:189], s[60:61], 0, v[134:135]
	s_addc_u32 s85, s61, 0
	s_add_i32 s83, s73, s65
	global_load_lds_dwordx4 v[188:189], off
	s_mov_b32 m0, s83
	v_lshl_add_u64 v[222:223], s[62:63], 0, v[132:133]
	global_load_lds_dwordx4 v130, s[84:85]
	s_add_i32 m0, s83, 0x2000
	s_nop 0
	global_load_lds_dwordx4 v134, s[84:85]
	v_lshl_add_u64 v[220:221], s[62:63], 0, v[128:129]
	s_mov_b32 m0, s35
	s_nop 0
	global_load_lds_dwordx4 v[220:221], off
	s_mov_b32 m0, s33
	s_nop 0
	global_load_lds_dwordx4 v[222:223], off
	s_waitcnt vmcnt(8)
	s_waitcnt lgkmcnt(0)
	s_barrier
	v_mfma_f32_16x16x32_bf16 v[60:63], v[152:155], v[184:187], 0
	v_mfma_f32_16x16x32_bf16 v[56:59], v[160:163], v[184:187], 0
	v_mfma_f32_16x16x32_bf16 v[52:55], v[152:155], v[196:199], 0
	v_mfma_f32_16x16x32_bf16 v[44:47], v[160:163], v[196:199], 0
	v_mfma_f32_16x16x32_bf16 v[36:39], v[152:155], v[204:207], 0
	v_mfma_f32_16x16x32_bf16 v[28:31], v[160:163], v[204:207], 0
	v_mfma_f32_16x16x32_bf16 v[20:23], v[152:155], v[212:215], 0
	v_mfma_f32_16x16x32_bf16 v[12:15], v[160:163], v[212:215], 0
	v_mfma_f32_16x16x32_bf16 v[60:63], v[156:159], v[192:195], v[60:63]
	v_mfma_f32_16x16x32_bf16 v[56:59], v[164:167], v[192:195], v[56:59]
	v_mfma_f32_16x16x32_bf16 v[52:55], v[156:159], v[200:203], v[52:55]
	v_mfma_f32_16x16x32_bf16 v[44:47], v[164:167], v[200:203], v[44:47]
	v_mfma_f32_16x16x32_bf16 v[36:39], v[156:159], v[208:211], v[36:39]
	v_mfma_f32_16x16x32_bf16 v[28:31], v[164:167], v[208:211], v[28:31]
	v_mfma_f32_16x16x32_bf16 v[20:23], v[156:159], v[216:219], v[20:23]
	v_mfma_f32_16x16x32_bf16 v[12:15], v[164:167], v[216:219], v[12:15]
	v_mfma_f32_16x16x32_bf16 v[48:51], v[168:171], v[184:187], 0
	v_mfma_f32_16x16x32_bf16 v[40:43], v[176:179], v[184:187], 0
	v_mfma_f32_16x16x32_bf16 v[32:35], v[168:171], v[196:199], 0
	v_mfma_f32_16x16x32_bf16 v[24:27], v[176:179], v[196:199], 0
	v_mfma_f32_16x16x32_bf16 v[16:19], v[168:171], v[204:207], 0
	v_mfma_f32_16x16x32_bf16 v[8:11], v[176:179], v[204:207], 0
	v_mfma_f32_16x16x32_bf16 v[4:7], v[168:171], v[212:215], 0
	v_mfma_f32_16x16x32_bf16 v[0:3], v[176:179], v[212:215], 0
	v_mfma_f32_16x16x32_bf16 v[48:51], v[172:175], v[192:195], v[48:51]
	v_mfma_f32_16x16x32_bf16 v[40:43], v[180:183], v[192:195], v[40:43]
	v_mfma_f32_16x16x32_bf16 v[32:35], v[172:175], v[200:203], v[32:35]
	v_mfma_f32_16x16x32_bf16 v[24:27], v[180:183], v[200:203], v[24:27]
	v_mfma_f32_16x16x32_bf16 v[16:19], v[172:175], v[208:211], v[16:19]
	v_mfma_f32_16x16x32_bf16 v[8:11], v[180:183], v[208:211], v[8:11]
	v_mfma_f32_16x16x32_bf16 v[4:7], v[172:175], v[216:219], v[4:7]
	v_mfma_f32_16x16x32_bf16 v[0:3], v[180:183], v[216:219], v[0:3]
	s_barrier
	s_add_i32 s83, 0, 0x18000
	s_add_i32 s84, 0, 0x1c000
	v_add_u32_e32 v164, s83, v147
	v_add_u32_e32 v180, s84, v147
	ds_read_b128 v[152:155], v164
	ds_read_b128 v[156:159], v164 offset:1024
	ds_read_b128 v[160:163], v164 offset:2048
	ds_read_b128 v[164:167], v164 offset:3072
	ds_read_b128 v[168:171], v180
	ds_read_b128 v[172:175], v180 offset:1024
	ds_read_b128 v[176:179], v180 offset:2048
	ds_read_b128 v[180:183], v180 offset:3072
	s_add_u32 s62, s62, 0x40000
	s_addc_u32 s63, s63, 0
	s_mov_b32 m0, s66
	ds_read_b128 v[184:187], v151 offset:32768
	ds_read_b128 v[192:195], v151 offset:33792
	ds_read_b128 v[196:199], v151 offset:34816
	ds_read_b128 v[200:203], v151 offset:35840
	ds_read_b128 v[204:207], v151 offset:36864
	ds_read_b128 v[208:211], v151 offset:37888
	ds_read_b128 v[212:215], v151 offset:38912
	ds_read_b128 v[216:219], v151 offset:39936
	global_load_lds_dwordx4 v128, s[62:63]
	s_mov_b32 m0, s67
	s_nop 0
	global_load_lds_dwordx4 v132, s[62:63]
	s_waitcnt vmcnt(8)
	s_waitcnt lgkmcnt(0)
	s_barrier
	v_mfma_f32_16x16x32_bf16 v[124:127], v[152:155], v[184:187], v[124:127]
	v_mfma_f32_16x16x32_bf16 v[120:123], v[160:163], v[184:187], v[120:123]
	v_mfma_f32_16x16x32_bf16 v[116:119], v[152:155], v[196:199], v[116:119]
	v_mfma_f32_16x16x32_bf16 v[108:111], v[160:163], v[196:199], v[108:111]
	v_mfma_f32_16x16x32_bf16 v[100:103], v[152:155], v[204:207], v[100:103]
	v_mfma_f32_16x16x32_bf16 v[92:95], v[160:163], v[204:207], v[92:95]
	v_mfma_f32_16x16x32_bf16 v[84:87], v[152:155], v[212:215], v[84:87]
	v_mfma_f32_16x16x32_bf16 v[76:79], v[160:163], v[212:215], v[76:79]
	v_mfma_f32_16x16x32_bf16 v[124:127], v[156:159], v[192:195], v[124:127]
	v_mfma_f32_16x16x32_bf16 v[120:123], v[164:167], v[192:195], v[120:123]
	v_mfma_f32_16x16x32_bf16 v[116:119], v[156:159], v[200:203], v[116:119]
	v_mfma_f32_16x16x32_bf16 v[108:111], v[164:167], v[200:203], v[108:111]
	v_mfma_f32_16x16x32_bf16 v[100:103], v[156:159], v[208:211], v[100:103]
	v_mfma_f32_16x16x32_bf16 v[92:95], v[164:167], v[208:211], v[92:95]
	v_mfma_f32_16x16x32_bf16 v[84:87], v[156:159], v[216:219], v[84:87]
	v_mfma_f32_16x16x32_bf16 v[76:79], v[164:167], v[216:219], v[76:79]
	v_mfma_f32_16x16x32_bf16 v[112:115], v[168:171], v[184:187], v[112:115]
	v_mfma_f32_16x16x32_bf16 v[104:107], v[176:179], v[184:187], v[104:107]
	v_mfma_f32_16x16x32_bf16 v[96:99], v[168:171], v[196:199], v[96:99]
	v_mfma_f32_16x16x32_bf16 v[88:91], v[176:179], v[196:199], v[88:91]
	v_mfma_f32_16x16x32_bf16 v[80:83], v[168:171], v[204:207], v[80:83]
	v_mfma_f32_16x16x32_bf16 v[72:75], v[176:179], v[204:207], v[72:75]
	v_mfma_f32_16x16x32_bf16 v[68:71], v[168:171], v[212:215], v[68:71]
	v_mfma_f32_16x16x32_bf16 v[64:67], v[176:179], v[212:215], v[64:67]
	v_mfma_f32_16x16x32_bf16 v[112:115], v[172:175], v[192:195], v[112:115]
	v_mfma_f32_16x16x32_bf16 v[104:107], v[180:183], v[192:195], v[104:107]
	v_mfma_f32_16x16x32_bf16 v[96:99], v[172:175], v[200:203], v[96:99]
	v_mfma_f32_16x16x32_bf16 v[88:91], v[180:183], v[200:203], v[88:91]
	v_mfma_f32_16x16x32_bf16 v[80:83], v[172:175], v[208:211], v[80:83]
	v_mfma_f32_16x16x32_bf16 v[72:75], v[180:183], v[208:211], v[72:75]
	v_mfma_f32_16x16x32_bf16 v[68:71], v[172:175], v[216:219], v[68:71]
	v_mfma_f32_16x16x32_bf16 v[64:67], v[180:183], v[216:219], v[64:67]
	s_barrier
	s_add_i32 s62, s83, s65
	v_lshl_add_u64 v[144:145], v[144:145], 0, s[12:13]
	s_mov_b32 m0, s62
	ds_read_b128 v[184:187], v151 offset:49152
	ds_read_b128 v[192:195], v151 offset:50176
	ds_read_b128 v[196:199], v151 offset:51200
	ds_read_b128 v[200:203], v151 offset:52224
	ds_read_b128 v[204:207], v151 offset:53248
	ds_read_b128 v[208:211], v151 offset:54272
	ds_read_b128 v[212:215], v151 offset:55296
	ds_read_b128 v[216:219], v151 offset:56320
	global_load_lds_dwordx4 v[144:145], off
	s_add_i32 m0, s62, 0x2000
	s_add_u32 s60, s60, 0x40080
	v_lshl_add_u64 v[144:145], v[188:189], 0, s[12:13]
	s_addc_u32 s61, s61, 0
	s_add_i32 s62, s84, s65
	global_load_lds_dwordx4 v[144:145], off
	s_mov_b32 m0, s62
	s_nop 0
	global_load_lds_dwordx4 v130, s[60:61]
	s_add_i32 m0, s62, 0x2000
	s_nop 0
	global_load_lds_dwordx4 v134, s[60:61]
	v_lshl_add_u64 v[144:145], v[220:221], 0, s[12:13]
	s_mov_b32 m0, s69
	s_nop 0
	global_load_lds_dwordx4 v[144:145], off
	v_lshl_add_u64 v[144:145], v[222:223], 0, s[12:13]
	s_mov_b32 m0, s70
	s_nop 0
	global_load_lds_dwordx4 v[144:145], off
	s_waitcnt vmcnt(8)
	s_waitcnt lgkmcnt(0)
	s_barrier
	v_mfma_f32_16x16x32_bf16 v[60:63], v[152:155], v[184:187], v[60:63]
	v_mfma_f32_16x16x32_bf16 v[56:59], v[160:163], v[184:187], v[56:59]
	v_mfma_f32_16x16x32_bf16 v[52:55], v[152:155], v[196:199], v[52:55]
	v_mfma_f32_16x16x32_bf16 v[44:47], v[160:163], v[196:199], v[44:47]
	v_mfma_f32_16x16x32_bf16 v[36:39], v[152:155], v[204:207], v[36:39]
	v_mfma_f32_16x16x32_bf16 v[28:31], v[160:163], v[204:207], v[28:31]
	v_mfma_f32_16x16x32_bf16 v[20:23], v[152:155], v[212:215], v[20:23]
	v_mfma_f32_16x16x32_bf16 v[12:15], v[160:163], v[212:215], v[12:15]
	v_mfma_f32_16x16x32_bf16 v[60:63], v[156:159], v[192:195], v[60:63]
	v_mfma_f32_16x16x32_bf16 v[56:59], v[164:167], v[192:195], v[56:59]
	v_mfma_f32_16x16x32_bf16 v[52:55], v[156:159], v[200:203], v[52:55]
	v_mfma_f32_16x16x32_bf16 v[44:47], v[164:167], v[200:203], v[44:47]
	v_mfma_f32_16x16x32_bf16 v[36:39], v[156:159], v[208:211], v[36:39]
	v_mfma_f32_16x16x32_bf16 v[28:31], v[164:167], v[208:211], v[28:31]
	v_mfma_f32_16x16x32_bf16 v[20:23], v[156:159], v[216:219], v[20:23]
	v_mfma_f32_16x16x32_bf16 v[12:15], v[164:167], v[216:219], v[12:15]
	v_mfma_f32_16x16x32_bf16 v[48:51], v[168:171], v[184:187], v[48:51]
	v_mfma_f32_16x16x32_bf16 v[40:43], v[176:179], v[184:187], v[40:43]
	v_mfma_f32_16x16x32_bf16 v[32:35], v[168:171], v[196:199], v[32:35]
	v_mfma_f32_16x16x32_bf16 v[24:27], v[176:179], v[196:199], v[24:27]
	v_mfma_f32_16x16x32_bf16 v[16:19], v[168:171], v[204:207], v[16:19]
	v_mfma_f32_16x16x32_bf16 v[8:11], v[176:179], v[204:207], v[8:11]
	v_mfma_f32_16x16x32_bf16 v[4:7], v[168:171], v[212:215], v[4:7]
	v_mfma_f32_16x16x32_bf16 v[0:3], v[176:179], v[212:215], v[0:3]
	v_mfma_f32_16x16x32_bf16 v[48:51], v[172:175], v[192:195], v[48:51]
	v_mfma_f32_16x16x32_bf16 v[40:43], v[180:183], v[192:195], v[40:43]
	v_mfma_f32_16x16x32_bf16 v[32:35], v[172:175], v[200:203], v[32:35]
	v_mfma_f32_16x16x32_bf16 v[24:27], v[180:183], v[200:203], v[24:27]
	v_mfma_f32_16x16x32_bf16 v[16:19], v[172:175], v[208:211], v[16:19]
	v_mfma_f32_16x16x32_bf16 v[8:11], v[180:183], v[208:211], v[8:11]
	v_mfma_f32_16x16x32_bf16 v[4:7], v[172:175], v[216:219], v[4:7]
	v_mfma_f32_16x16x32_bf16 v[0:3], v[180:183], v[216:219], v[0:3]
	s_barrier
	s_add_i32 s82, s82, 2
	s_add_u32 s42, s42, 0x100
	s_addc_u32 s43, s43, 0
	s_add_u32 s80, s80, 0x100
	s_addc_u32 s81, s81, 0
	s_cmp_gt_u32 s82, 13
	s_cbranch_scc0 .LBB0_1077
	s_branch .Lpeel_exit6

.LBB0_1221:
	s_ashr_i32 s21, s20, 31
	s_lshl_b64 s[22:23], s[20:21], 17
	s_add_u32 s22, s70, s22
	s_addc_u32 s23, s71, s23
	s_and_b64 s[24:25], s[0:1], exec
	s_cselect_b32 s21, s23, s31
	s_cselect_b32 s55, s22, s30
	s_ashr_i32 s19, s18, 31
	s_lshl_b64 s[24:25], s[18:19], 17
	s_add_u32 s24, s53, s24
	s_addc_u32 s25, s72, s25
	s_and_b64 s[34:35], s[0:1], exec
	s_cselect_b32 s19, s25, s29
	s_cselect_b32 s85, s24, s28
	s_mov_b32 s60, 0
	s_mov_b64 s[34:35], -1
	s_mov_b64 s[42:43], 0
	s_add_u32 s61, s30, s60
	s_addc_u32 s66, s31, 0
	s_add_u32 s64, s61, 0x100
	s_addc_u32 s65, s66, 0
	s_and_b64 s[62:63], s[42:43], exec
	s_cselect_b32 s63, s21, s65
	s_cselect_b32 s62, s55, s64
	s_add_u32 s60, s28, s60
	s_addc_u32 s64, s29, 0
	s_add_u32 s60, s60, 0x100
	s_addc_u32 s64, s64, 0
	s_and_b64 s[42:43], s[42:43], exec
	s_cselect_b32 s65, s19, s64
	s_cselect_b32 s64, s85, s60
	s_add_u32 s68, s61, 0x10080
	ds_read_b128 v[148:151], v145
	ds_read_b128 v[152:155], v145 offset:1024
	ds_read_b128 v[156:159], v145 offset:2048
	ds_read_b128 v[160:163], v145 offset:3072
	ds_read_b128 v[164:167], v146
	ds_read_b128 v[168:171], v146 offset:1024
	ds_read_b128 v[172:175], v146 offset:2048
	ds_read_b128 v[176:179], v146 offset:3072
	s_addc_u32 s69, s66, 0
	s_add_i32 s95, s81, s73
	s_add_i32 m0, s27, 0xc000
	s_add_i32 s96, s27, 0xe000
	s_add_i32 s92, s95, 0x2000
	s_add_u32 s66, s64, 0x10000
	s_addc_u32 s67, s65, 0
	s_add_i32 s94, s82, s73
	s_add_i32 s93, s94, 0x2000
	s_add_i32 s91, 0, 0x18000
	s_add_i32 s90, 0, 0x1c000
	s_add_u32 s60, s62, 0x10000
	s_addc_u32 s61, s63, 0
	s_add_i32 s89, s91, s73
	s_add_i32 s87, s89, 0x2000
	s_add_u32 s42, s64, 0x10080
	s_addc_u32 s43, s65, 0
	s_add_i32 s88, s90, s73
	s_add_i32 s86, s88, 0x2000
	ds_read_b128 v[180:183], v147
	ds_read_b128 v[184:187], v147 offset:1024
	ds_read_b128 v[192:195], v147 offset:2048
	ds_read_b128 v[196:199], v147 offset:3072
	ds_read_b128 v[200:203], v147 offset:4096
	ds_read_b128 v[204:207], v147 offset:5120
	ds_read_b128 v[208:211], v147 offset:6144
	ds_read_b128 v[212:215], v147 offset:7168
	global_load_lds_dwordx4 v128, s[68:69]
	s_mov_b32 m0, s96
	s_nop 0
	global_load_lds_dwordx4 v132, s[68:69]
	s_waitcnt vmcnt(8)
	s_waitcnt lgkmcnt(0)
	s_barrier
	v_mfma_f32_16x16x32_bf16 v[124:127], v[148:151], v[180:183], 0
	v_mfma_f32_16x16x32_bf16 v[120:123], v[156:159], v[180:183], 0
	v_mfma_f32_16x16x32_bf16 v[116:119], v[148:151], v[192:195], 0
	v_mfma_f32_16x16x32_bf16 v[108:111], v[156:159], v[192:195], 0
	v_mfma_f32_16x16x32_bf16 v[100:103], v[148:151], v[200:203], 0
	v_mfma_f32_16x16x32_bf16 v[92:95], v[156:159], v[200:203], 0
	v_mfma_f32_16x16x32_bf16 v[84:87], v[148:151], v[208:211], 0
	v_mfma_f32_16x16x32_bf16 v[76:79], v[156:159], v[208:211], 0
	v_mfma_f32_16x16x32_bf16 v[124:127], v[152:155], v[184:187], v[124:127]
	v_mfma_f32_16x16x32_bf16 v[120:123], v[160:163], v[184:187], v[120:123]
	v_mfma_f32_16x16x32_bf16 v[116:119], v[152:155], v[196:199], v[116:119]
	v_mfma_f32_16x16x32_bf16 v[108:111], v[160:163], v[196:199], v[108:111]
	v_mfma_f32_16x16x32_bf16 v[100:103], v[152:155], v[204:207], v[100:103]
	v_mfma_f32_16x16x32_bf16 v[92:95], v[160:163], v[204:207], v[92:95]
	v_mfma_f32_16x16x32_bf16 v[84:87], v[152:155], v[212:215], v[84:87]
	v_mfma_f32_16x16x32_bf16 v[76:79], v[160:163], v[212:215], v[76:79]
	v_mfma_f32_16x16x32_bf16 v[112:115], v[164:167], v[180:183], 0
	v_mfma_f32_16x16x32_bf16 v[104:107], v[172:175], v[180:183], 0
	v_mfma_f32_16x16x32_bf16 v[96:99], v[164:167], v[192:195], 0
	v_mfma_f32_16x16x32_bf16 v[88:91], v[172:175], v[192:195], 0
	v_mfma_f32_16x16x32_bf16 v[80:83], v[164:167], v[200:203], 0
	v_mfma_f32_16x16x32_bf16 v[72:75], v[172:175], v[200:203], 0
	v_mfma_f32_16x16x32_bf16 v[68:71], v[164:167], v[208:211], 0
	v_mfma_f32_16x16x32_bf16 v[64:67], v[172:175], v[208:211], 0
	v_mfma_f32_16x16x32_bf16 v[112:115], v[168:171], v[184:187], v[112:115]
	v_mfma_f32_16x16x32_bf16 v[104:107], v[176:179], v[184:187], v[104:107]
	v_mfma_f32_16x16x32_bf16 v[96:99], v[168:171], v[196:199], v[96:99]
	v_mfma_f32_16x16x32_bf16 v[88:91], v[176:179], v[196:199], v[88:91]
	v_mfma_f32_16x16x32_bf16 v[80:83], v[168:171], v[204:207], v[80:83]
	v_mfma_f32_16x16x32_bf16 v[72:75], v[176:179], v[204:207], v[72:75]
	v_mfma_f32_16x16x32_bf16 v[68:71], v[168:171], v[212:215], v[68:71]
	v_mfma_f32_16x16x32_bf16 v[64:67], v[176:179], v[212:215], v[64:67]
	s_barrier
	s_mov_b32 m0, s95
	v_lshl_add_u64 v[140:141], s[64:65], 0, v[130:131]
	ds_read_b128 v[180:183], v147 offset:16384
	ds_read_b128 v[184:187], v147 offset:17408
	ds_read_b128 v[192:195], v147 offset:18432
	ds_read_b128 v[196:199], v147 offset:19456
	ds_read_b128 v[200:203], v147 offset:20480
	ds_read_b128 v[204:207], v147 offset:21504
	ds_read_b128 v[208:211], v147 offset:22528
	ds_read_b128 v[212:215], v147 offset:23552
	global_load_lds_dwordx4 v[140:141], off
	v_lshl_add_u64 v[188:189], s[64:65], 0, v[134:135]
	s_mov_b32 m0, s92
	s_nop 0
	global_load_lds_dwordx4 v[188:189], off
	s_mov_b32 m0, s94
	v_lshl_add_u64 v[218:219], s[62:63], 0, v[132:133]
	global_load_lds_dwordx4 v130, s[66:67]
	s_mov_b32 m0, s93
	s_nop 0
	global_load_lds_dwordx4 v134, s[66:67]
	v_lshl_add_u64 v[216:217], s[62:63], 0, v[128:129]
	s_mov_b32 m0, s27
	s_nop 0
	global_load_lds_dwordx4 v[216:217], off
	s_mov_b32 m0, s33
	s_nop 0
	global_load_lds_dwordx4 v[218:219], off
	s_waitcnt vmcnt(8)
	s_waitcnt lgkmcnt(0)
	s_barrier
	v_mfma_f32_16x16x32_bf16 v[60:63], v[148:151], v[180:183], 0
	v_mfma_f32_16x16x32_bf16 v[56:59], v[156:159], v[180:183], 0
	v_mfma_f32_16x16x32_bf16 v[52:55], v[148:151], v[192:195], 0
	v_mfma_f32_16x16x32_bf16 v[44:47], v[156:159], v[192:195], 0
	v_mfma_f32_16x16x32_bf16 v[36:39], v[148:151], v[200:203], 0
	v_mfma_f32_16x16x32_bf16 v[28:31], v[156:159], v[200:203], 0
	v_mfma_f32_16x16x32_bf16 v[20:23], v[148:151], v[208:211], 0
	v_mfma_f32_16x16x32_bf16 v[12:15], v[156:159], v[208:211], 0
	v_mfma_f32_16x16x32_bf16 v[60:63], v[152:155], v[184:187], v[60:63]
	v_mfma_f32_16x16x32_bf16 v[56:59], v[160:163], v[184:187], v[56:59]
	v_mfma_f32_16x16x32_bf16 v[52:55], v[152:155], v[196:199], v[52:55]
	v_mfma_f32_16x16x32_bf16 v[44:47], v[160:163], v[196:199], v[44:47]
	v_mfma_f32_16x16x32_bf16 v[36:39], v[152:155], v[204:207], v[36:39]
	v_mfma_f32_16x16x32_bf16 v[28:31], v[160:163], v[204:207], v[28:31]
	v_mfma_f32_16x16x32_bf16 v[20:23], v[152:155], v[212:215], v[20:23]
	v_mfma_f32_16x16x32_bf16 v[12:15], v[160:163], v[212:215], v[12:15]
	v_mfma_f32_16x16x32_bf16 v[48:51], v[164:167], v[180:183], 0
	v_mfma_f32_16x16x32_bf16 v[40:43], v[172:175], v[180:183], 0
	v_mfma_f32_16x16x32_bf16 v[32:35], v[164:167], v[192:195], 0
	v_mfma_f32_16x16x32_bf16 v[24:27], v[172:175], v[192:195], 0
	v_mfma_f32_16x16x32_bf16 v[16:19], v[164:167], v[200:203], 0
	v_mfma_f32_16x16x32_bf16 v[8:11], v[172:175], v[200:203], 0
	v_mfma_f32_16x16x32_bf16 v[4:7], v[164:167], v[208:211], 0
	v_mfma_f32_16x16x32_bf16 v[0:3], v[172:175], v[208:211], 0
	v_mfma_f32_16x16x32_bf16 v[48:51], v[168:171], v[184:187], v[48:51]
	v_mfma_f32_16x16x32_bf16 v[40:43], v[176:179], v[184:187], v[40:43]
	v_mfma_f32_16x16x32_bf16 v[32:35], v[168:171], v[196:199], v[32:35]
	v_mfma_f32_16x16x32_bf16 v[24:27], v[176:179], v[196:199], v[24:27]
	v_mfma_f32_16x16x32_bf16 v[16:19], v[168:171], v[204:207], v[16:19]
	v_mfma_f32_16x16x32_bf16 v[8:11], v[176:179], v[204:207], v[8:11]
	v_mfma_f32_16x16x32_bf16 v[4:7], v[168:171], v[212:215], v[4:7]
	v_mfma_f32_16x16x32_bf16 v[0:3], v[176:179], v[212:215], v[0:3]
	s_barrier
	v_add_u32_e32 v160, s91, v143
	v_add_u32_e32 v176, s90, v143
	ds_read_b128 v[148:151], v160
	ds_read_b128 v[152:155], v160 offset:1024
	ds_read_b128 v[156:159], v160 offset:2048
	ds_read_b128 v[160:163], v160 offset:3072
	ds_read_b128 v[164:167], v176
	ds_read_b128 v[168:171], v176 offset:1024
	ds_read_b128 v[172:175], v176 offset:2048
	ds_read_b128 v[176:179], v176 offset:3072
	s_mov_b32 m0, s74
	ds_read_b128 v[180:183], v147 offset:32768
	ds_read_b128 v[184:187], v147 offset:33792
	ds_read_b128 v[192:195], v147 offset:34816
	ds_read_b128 v[196:199], v147 offset:35840
	ds_read_b128 v[200:203], v147 offset:36864
	ds_read_b128 v[204:207], v147 offset:37888
	ds_read_b128 v[208:211], v147 offset:38912
	ds_read_b128 v[212:215], v147 offset:39936
	global_load_lds_dwordx4 v128, s[60:61]
	s_mov_b32 m0, s75
	s_nop 0
	global_load_lds_dwordx4 v132, s[60:61]
	s_waitcnt vmcnt(8)
	s_waitcnt lgkmcnt(0)
	s_barrier
	v_mfma_f32_16x16x32_bf16 v[124:127], v[148:151], v[180:183], v[124:127]
	v_mfma_f32_16x16x32_bf16 v[120:123], v[156:159], v[180:183], v[120:123]
	v_mfma_f32_16x16x32_bf16 v[116:119], v[148:151], v[192:195], v[116:119]
	v_mfma_f32_16x16x32_bf16 v[108:111], v[156:159], v[192:195], v[108:111]
	v_mfma_f32_16x16x32_bf16 v[100:103], v[148:151], v[200:203], v[100:103]
	v_mfma_f32_16x16x32_bf16 v[92:95], v[156:159], v[200:203], v[92:95]
	v_mfma_f32_16x16x32_bf16 v[84:87], v[148:151], v[208:211], v[84:87]
	v_mfma_f32_16x16x32_bf16 v[76:79], v[156:159], v[208:211], v[76:79]
	v_mfma_f32_16x16x32_bf16 v[124:127], v[152:155], v[184:187], v[124:127]
	v_mfma_f32_16x16x32_bf16 v[120:123], v[160:163], v[184:187], v[120:123]
	v_mfma_f32_16x16x32_bf16 v[116:119], v[152:155], v[196:199], v[116:119]
	v_mfma_f32_16x16x32_bf16 v[108:111], v[160:163], v[196:199], v[108:111]
	v_mfma_f32_16x16x32_bf16 v[100:103], v[152:155], v[204:207], v[100:103]
	v_mfma_f32_16x16x32_bf16 v[92:95], v[160:163], v[204:207], v[92:95]
	v_mfma_f32_16x16x32_bf16 v[84:87], v[152:155], v[212:215], v[84:87]
	v_mfma_f32_16x16x32_bf16 v[76:79], v[160:163], v[212:215], v[76:79]
	v_mfma_f32_16x16x32_bf16 v[112:115], v[164:167], v[180:183], v[112:115]
	v_mfma_f32_16x16x32_bf16 v[104:107], v[172:175], v[180:183], v[104:107]
	v_mfma_f32_16x16x32_bf16 v[96:99], v[164:167], v[192:195], v[96:99]
	v_mfma_f32_16x16x32_bf16 v[88:91], v[172:175], v[192:195], v[88:91]
	v_mfma_f32_16x16x32_bf16 v[80:83], v[164:167], v[200:203], v[80:83]
	v_mfma_f32_16x16x32_bf16 v[72:75], v[172:175], v[200:203], v[72:75]
	v_mfma_f32_16x16x32_bf16 v[68:71], v[164:167], v[208:211], v[68:71]
	v_mfma_f32_16x16x32_bf16 v[64:67], v[172:175], v[208:211], v[64:67]
	v_mfma_f32_16x16x32_bf16 v[112:115], v[168:171], v[184:187], v[112:115]
	v_mfma_f32_16x16x32_bf16 v[104:107], v[176:179], v[184:187], v[104:107]
	v_mfma_f32_16x16x32_bf16 v[96:99], v[168:171], v[196:199], v[96:99]
	v_mfma_f32_16x16x32_bf16 v[88:91], v[176:179], v[196:199], v[88:91]
	v_mfma_f32_16x16x32_bf16 v[80:83], v[168:171], v[204:207], v[80:83]
	v_mfma_f32_16x16x32_bf16 v[72:75], v[176:179], v[204:207], v[72:75]
	v_mfma_f32_16x16x32_bf16 v[68:71], v[168:171], v[212:215], v[68:71]
	v_mfma_f32_16x16x32_bf16 v[64:67], v[176:179], v[212:215], v[64:67]
	s_barrier
	s_mov_b32 m0, s89
	v_lshl_add_u64 v[140:141], v[140:141], 0, s[12:13]
	ds_read_b128 v[180:183], v147 offset:49152
	ds_read_b128 v[184:187], v147 offset:50176
	ds_read_b128 v[192:195], v147 offset:51200
	ds_read_b128 v[196:199], v147 offset:52224
	ds_read_b128 v[200:203], v147 offset:53248
	ds_read_b128 v[204:207], v147 offset:54272
	ds_read_b128 v[208:211], v147 offset:55296
	ds_read_b128 v[212:215], v147 offset:56320
	global_load_lds_dwordx4 v[140:141], off
	v_lshl_add_u64 v[140:141], v[188:189], 0, s[12:13]
	s_mov_b32 m0, s87
	s_nop 0
	global_load_lds_dwordx4 v[140:141], off
	s_mov_b32 m0, s88
	s_nop 0
	global_load_lds_dwordx4 v130, s[42:43]
	s_mov_b32 m0, s86
	s_nop 0
	global_load_lds_dwordx4 v134, s[42:43]
	v_lshl_add_u64 v[140:141], v[216:217], 0, s[12:13]
	s_mov_b32 m0, s77
	s_nop 0
	global_load_lds_dwordx4 v[140:141], off
	v_lshl_add_u64 v[140:141], v[218:219], 0, s[12:13]
	s_mov_b32 m0, s79
	s_nop 0
	global_load_lds_dwordx4 v[140:141], off
	s_waitcnt vmcnt(8)
	s_waitcnt lgkmcnt(0)
	s_barrier
	v_mfma_f32_16x16x32_bf16 v[60:63], v[148:151], v[180:183], v[60:63]
	v_mfma_f32_16x16x32_bf16 v[56:59], v[156:159], v[180:183], v[56:59]
	v_mfma_f32_16x16x32_bf16 v[52:55], v[148:151], v[192:195], v[52:55]
	v_mfma_f32_16x16x32_bf16 v[44:47], v[156:159], v[192:195], v[44:47]
	v_mfma_f32_16x16x32_bf16 v[36:39], v[148:151], v[200:203], v[36:39]
	v_mfma_f32_16x16x32_bf16 v[28:31], v[156:159], v[200:203], v[28:31]
	v_mfma_f32_16x16x32_bf16 v[20:23], v[148:151], v[208:211], v[20:23]
	v_mfma_f32_16x16x32_bf16 v[12:15], v[156:159], v[208:211], v[12:15]
	v_mfma_f32_16x16x32_bf16 v[60:63], v[152:155], v[184:187], v[60:63]
	v_mfma_f32_16x16x32_bf16 v[56:59], v[160:163], v[184:187], v[56:59]
	v_mfma_f32_16x16x32_bf16 v[52:55], v[152:155], v[196:199], v[52:55]
	v_mfma_f32_16x16x32_bf16 v[44:47], v[160:163], v[196:199], v[44:47]
	v_mfma_f32_16x16x32_bf16 v[36:39], v[152:155], v[204:207], v[36:39]
	v_mfma_f32_16x16x32_bf16 v[28:31], v[160:163], v[204:207], v[28:31]
	v_mfma_f32_16x16x32_bf16 v[20:23], v[152:155], v[212:215], v[20:23]
	v_mfma_f32_16x16x32_bf16 v[12:15], v[160:163], v[212:215], v[12:15]
	v_mfma_f32_16x16x32_bf16 v[48:51], v[164:167], v[180:183], v[48:51]
	v_mfma_f32_16x16x32_bf16 v[40:43], v[172:175], v[180:183], v[40:43]
	v_mfma_f32_16x16x32_bf16 v[32:35], v[164:167], v[192:195], v[32:35]
	v_mfma_f32_16x16x32_bf16 v[24:27], v[172:175], v[192:195], v[24:27]
	v_mfma_f32_16x16x32_bf16 v[16:19], v[164:167], v[200:203], v[16:19]
	v_mfma_f32_16x16x32_bf16 v[8:11], v[172:175], v[200:203], v[8:11]
	v_mfma_f32_16x16x32_bf16 v[4:7], v[164:167], v[208:211], v[4:7]
	v_mfma_f32_16x16x32_bf16 v[0:3], v[172:175], v[208:211], v[0:3]
	v_mfma_f32_16x16x32_bf16 v[48:51], v[168:171], v[184:187], v[48:51]
	v_mfma_f32_16x16x32_bf16 v[40:43], v[176:179], v[184:187], v[40:43]
	v_mfma_f32_16x16x32_bf16 v[32:35], v[168:171], v[196:199], v[32:35]
	v_mfma_f32_16x16x32_bf16 v[24:27], v[176:179], v[196:199], v[24:27]
	v_mfma_f32_16x16x32_bf16 v[16:19], v[168:171], v[204:207], v[16:19]
	v_mfma_f32_16x16x32_bf16 v[8:11], v[176:179], v[204:207], v[8:11]
	v_mfma_f32_16x16x32_bf16 v[4:7], v[168:171], v[212:215], v[4:7]
	v_mfma_f32_16x16x32_bf16 v[0:3], v[176:179], v[212:215], v[0:3]
	s_barrier
	s_movk_i32 s60, 0x100
	s_andn2_b64 vcc, exec, s[34:35]
	s_mov_b64 s[42:43], -1
	s_mov_b64 s[34:35], 0
	s_cbranch_vccz .LBB0_1222
	s_branch .Lpeel_exit7
.LBB0_1222:
	s_add_u32 s61, s30, s60
	s_addc_u32 s66, s31, 0
	s_add_u32 s64, s61, 0x100
	s_addc_u32 s65, s66, 0
	s_and_b64 s[62:63], s[42:43], exec
	s_cselect_b32 s63, s21, s65
	s_cselect_b32 s62, s55, s64
	s_add_u32 s60, s28, s60
	s_addc_u32 s64, s29, 0
	s_add_u32 s60, s60, 0x100
	s_addc_u32 s64, s64, 0
	s_and_b64 s[42:43], s[42:43], exec
	s_cselect_b32 s65, s19, s64
	s_cselect_b32 s64, s85, s60
	s_add_u32 s68, s61, 0x10080
	ds_read_b128 v[148:151], v145
	ds_read_b128 v[152:155], v145 offset:1024
	ds_read_b128 v[156:159], v145 offset:2048
	ds_read_b128 v[160:163], v145 offset:3072
	ds_read_b128 v[164:167], v146
	ds_read_b128 v[168:171], v146 offset:1024
	ds_read_b128 v[172:175], v146 offset:2048
	ds_read_b128 v[176:179], v146 offset:3072
	s_addc_u32 s69, s66, 0
	s_add_i32 s95, s81, s73
	s_add_i32 m0, s27, 0xc000
	s_add_i32 s96, s27, 0xe000
	s_add_i32 s92, s95, 0x2000
	s_add_u32 s66, s64, 0x10000
	s_addc_u32 s67, s65, 0
	s_add_i32 s94, s82, s73
	s_add_i32 s93, s94, 0x2000
	s_add_i32 s91, 0, 0x18000
	s_add_i32 s90, 0, 0x1c000
	s_add_u32 s60, s62, 0x10000
	s_addc_u32 s61, s63, 0
	s_add_i32 s89, s91, s73
	s_add_i32 s87, s89, 0x2000
	s_add_u32 s42, s64, 0x10080
	s_addc_u32 s43, s65, 0
	s_add_i32 s88, s90, s73
	s_add_i32 s86, s88, 0x2000
	ds_read_b128 v[180:183], v147
	ds_read_b128 v[184:187], v147 offset:1024
	ds_read_b128 v[192:195], v147 offset:2048
	ds_read_b128 v[196:199], v147 offset:3072
	ds_read_b128 v[200:203], v147 offset:4096
	ds_read_b128 v[204:207], v147 offset:5120
	ds_read_b128 v[208:211], v147 offset:6144
	ds_read_b128 v[212:215], v147 offset:7168
	global_load_lds_dwordx4 v128, s[68:69]
	s_mov_b32 m0, s96
	s_nop 0
	global_load_lds_dwordx4 v132, s[68:69]
	s_waitcnt vmcnt(8)
	s_waitcnt lgkmcnt(0)
	s_barrier
	v_mfma_f32_16x16x32_bf16 v[124:127], v[148:151], v[180:183], v[124:127]
	v_mfma_f32_16x16x32_bf16 v[120:123], v[156:159], v[180:183], v[120:123]
	v_mfma_f32_16x16x32_bf16 v[116:119], v[148:151], v[192:195], v[116:119]
	v_mfma_f32_16x16x32_bf16 v[108:111], v[156:159], v[192:195], v[108:111]
	v_mfma_f32_16x16x32_bf16 v[100:103], v[148:151], v[200:203], v[100:103]
	v_mfma_f32_16x16x32_bf16 v[92:95], v[156:159], v[200:203], v[92:95]
	v_mfma_f32_16x16x32_bf16 v[84:87], v[148:151], v[208:211], v[84:87]
	v_mfma_f32_16x16x32_bf16 v[76:79], v[156:159], v[208:211], v[76:79]
	v_mfma_f32_16x16x32_bf16 v[124:127], v[152:155], v[184:187], v[124:127]
	v_mfma_f32_16x16x32_bf16 v[120:123], v[160:163], v[184:187], v[120:123]
	v_mfma_f32_16x16x32_bf16 v[116:119], v[152:155], v[196:199], v[116:119]
	v_mfma_f32_16x16x32_bf16 v[108:111], v[160:163], v[196:199], v[108:111]
	v_mfma_f32_16x16x32_bf16 v[100:103], v[152:155], v[204:207], v[100:103]
	v_mfma_f32_16x16x32_bf16 v[92:95], v[160:163], v[204:207], v[92:95]
	v_mfma_f32_16x16x32_bf16 v[84:87], v[152:155], v[212:215], v[84:87]
	v_mfma_f32_16x16x32_bf16 v[76:79], v[160:163], v[212:215], v[76:79]
	v_mfma_f32_16x16x32_bf16 v[112:115], v[164:167], v[180:183], v[112:115]
	v_mfma_f32_16x16x32_bf16 v[104:107], v[172:175], v[180:183], v[104:107]
	v_mfma_f32_16x16x32_bf16 v[96:99], v[164:167], v[192:195], v[96:99]
	v_mfma_f32_16x16x32_bf16 v[88:91], v[172:175], v[192:195], v[88:91]
	v_mfma_f32_16x16x32_bf16 v[80:83], v[164:167], v[200:203], v[80:83]
	v_mfma_f32_16x16x32_bf16 v[72:75], v[172:175], v[200:203], v[72:75]
	v_mfma_f32_16x16x32_bf16 v[68:71], v[164:167], v[208:211], v[68:71]
	v_mfma_f32_16x16x32_bf16 v[64:67], v[172:175], v[208:211], v[64:67]
	v_mfma_f32_16x16x32_bf16 v[112:115], v[168:171], v[184:187], v[112:115]
	v_mfma_f32_16x16x32_bf16 v[104:107], v[176:179], v[184:187], v[104:107]
	v_mfma_f32_16x16x32_bf16 v[96:99], v[168:171], v[196:199], v[96:99]
	v_mfma_f32_16x16x32_bf16 v[88:91], v[176:179], v[196:199], v[88:91]
	v_mfma_f32_16x16x32_bf16 v[80:83], v[168:171], v[204:207], v[80:83]
	v_mfma_f32_16x16x32_bf16 v[72:75], v[176:179], v[204:207], v[72:75]
	v_mfma_f32_16x16x32_bf16 v[68:71], v[168:171], v[212:215], v[68:71]
	v_mfma_f32_16x16x32_bf16 v[64:67], v[176:179], v[212:215], v[64:67]
	s_barrier
	s_mov_b32 m0, s95
	v_lshl_add_u64 v[140:141], s[64:65], 0, v[130:131]
	ds_read_b128 v[180:183], v147 offset:16384
	ds_read_b128 v[184:187], v147 offset:17408
	ds_read_b128 v[192:195], v147 offset:18432
	ds_read_b128 v[196:199], v147 offset:19456
	ds_read_b128 v[200:203], v147 offset:20480
	ds_read_b128 v[204:207], v147 offset:21504
	ds_read_b128 v[208:211], v147 offset:22528
	ds_read_b128 v[212:215], v147 offset:23552
	global_load_lds_dwordx4 v[140:141], off
	v_lshl_add_u64 v[188:189], s[64:65], 0, v[134:135]
	s_mov_b32 m0, s92
	s_nop 0
	global_load_lds_dwordx4 v[188:189], off
	s_mov_b32 m0, s94
	v_lshl_add_u64 v[218:219], s[62:63], 0, v[132:133]
	global_load_lds_dwordx4 v130, s[66:67]
	s_mov_b32 m0, s93
	s_nop 0
	global_load_lds_dwordx4 v134, s[66:67]
	v_lshl_add_u64 v[216:217], s[62:63], 0, v[128:129]
	s_mov_b32 m0, s27
	s_nop 0
	global_load_lds_dwordx4 v[216:217], off
	s_mov_b32 m0, s33
	s_nop 0
	global_load_lds_dwordx4 v[218:219], off
	s_waitcnt vmcnt(8)
	s_waitcnt lgkmcnt(0)
	s_barrier
	v_mfma_f32_16x16x32_bf16 v[60:63], v[148:151], v[180:183], v[60:63]
	v_mfma_f32_16x16x32_bf16 v[56:59], v[156:159], v[180:183], v[56:59]
	v_mfma_f32_16x16x32_bf16 v[52:55], v[148:151], v[192:195], v[52:55]
	v_mfma_f32_16x16x32_bf16 v[44:47], v[156:159], v[192:195], v[44:47]
	v_mfma_f32_16x16x32_bf16 v[36:39], v[148:151], v[200:203], v[36:39]
	v_mfma_f32_16x16x32_bf16 v[28:31], v[156:159], v[200:203], v[28:31]
	v_mfma_f32_16x16x32_bf16 v[20:23], v[148:151], v[208:211], v[20:23]
	v_mfma_f32_16x16x32_bf16 v[12:15], v[156:159], v[208:211], v[12:15]
	v_mfma_f32_16x16x32_bf16 v[60:63], v[152:155], v[184:187], v[60:63]
	v_mfma_f32_16x16x32_bf16 v[56:59], v[160:163], v[184:187], v[56:59]
	v_mfma_f32_16x16x32_bf16 v[52:55], v[152:155], v[196:199], v[52:55]
	v_mfma_f32_16x16x32_bf16 v[44:47], v[160:163], v[196:199], v[44:47]
	v_mfma_f32_16x16x32_bf16 v[36:39], v[152:155], v[204:207], v[36:39]
	v_mfma_f32_16x16x32_bf16 v[28:31], v[160:163], v[204:207], v[28:31]
	v_mfma_f32_16x16x32_bf16 v[20:23], v[152:155], v[212:215], v[20:23]
	v_mfma_f32_16x16x32_bf16 v[12:15], v[160:163], v[212:215], v[12:15]
	v_mfma_f32_16x16x32_bf16 v[48:51], v[164:167], v[180:183], v[48:51]
	v_mfma_f32_16x16x32_bf16 v[40:43], v[172:175], v[180:183], v[40:43]
	v_mfma_f32_16x16x32_bf16 v[32:35], v[164:167], v[192:195], v[32:35]
	v_mfma_f32_16x16x32_bf16 v[24:27], v[172:175], v[192:195], v[24:27]
	v_mfma_f32_16x16x32_bf16 v[16:19], v[164:167], v[200:203], v[16:19]
	v_mfma_f32_16x16x32_bf16 v[8:11], v[172:175], v[200:203], v[8:11]
	v_mfma_f32_16x16x32_bf16 v[4:7], v[164:167], v[208:211], v[4:7]
	v_mfma_f32_16x16x32_bf16 v[0:3], v[172:175], v[208:211], v[0:3]
	v_mfma_f32_16x16x32_bf16 v[48:51], v[168:171], v[184:187], v[48:51]
	v_mfma_f32_16x16x32_bf16 v[40:43], v[176:179], v[184:187], v[40:43]
	v_mfma_f32_16x16x32_bf16 v[32:35], v[168:171], v[196:199], v[32:35]
	v_mfma_f32_16x16x32_bf16 v[24:27], v[176:179], v[196:199], v[24:27]
	v_mfma_f32_16x16x32_bf16 v[16:19], v[168:171], v[204:207], v[16:19]
	v_mfma_f32_16x16x32_bf16 v[8:11], v[176:179], v[204:207], v[8:11]
	v_mfma_f32_16x16x32_bf16 v[4:7], v[168:171], v[212:215], v[4:7]
	v_mfma_f32_16x16x32_bf16 v[0:3], v[176:179], v[212:215], v[0:3]
	s_barrier
	v_add_u32_e32 v160, s91, v143
	v_add_u32_e32 v176, s90, v143
	ds_read_b128 v[148:151], v160
	ds_read_b128 v[152:155], v160 offset:1024
	ds_read_b128 v[156:159], v160 offset:2048
	ds_read_b128 v[160:163], v160 offset:3072
	ds_read_b128 v[164:167], v176
	ds_read_b128 v[168:171], v176 offset:1024
	ds_read_b128 v[172:175], v176 offset:2048
	ds_read_b128 v[176:179], v176 offset:3072
	s_mov_b32 m0, s74
	ds_read_b128 v[180:183], v147 offset:32768
	ds_read_b128 v[184:187], v147 offset:33792
	ds_read_b128 v[192:195], v147 offset:34816
	ds_read_b128 v[196:199], v147 offset:35840
	ds_read_b128 v[200:203], v147 offset:36864
	ds_read_b128 v[204:207], v147 offset:37888
	ds_read_b128 v[208:211], v147 offset:38912
	ds_read_b128 v[212:215], v147 offset:39936
	global_load_lds_dwordx4 v128, s[60:61]
	s_mov_b32 m0, s75
	s_nop 0
	global_load_lds_dwordx4 v132, s[60:61]
	s_waitcnt vmcnt(8)
	s_waitcnt lgkmcnt(0)
	s_barrier
	v_mfma_f32_16x16x32_bf16 v[124:127], v[148:151], v[180:183], v[124:127]
	v_mfma_f32_16x16x32_bf16 v[120:123], v[156:159], v[180:183], v[120:123]
	v_mfma_f32_16x16x32_bf16 v[116:119], v[148:151], v[192:195], v[116:119]
	v_mfma_f32_16x16x32_bf16 v[108:111], v[156:159], v[192:195], v[108:111]
	v_mfma_f32_16x16x32_bf16 v[100:103], v[148:151], v[200:203], v[100:103]
	v_mfma_f32_16x16x32_bf16 v[92:95], v[156:159], v[200:203], v[92:95]
	v_mfma_f32_16x16x32_bf16 v[84:87], v[148:151], v[208:211], v[84:87]
	v_mfma_f32_16x16x32_bf16 v[76:79], v[156:159], v[208:211], v[76:79]
	v_mfma_f32_16x16x32_bf16 v[124:127], v[152:155], v[184:187], v[124:127]
	v_mfma_f32_16x16x32_bf16 v[120:123], v[160:163], v[184:187], v[120:123]
	v_mfma_f32_16x16x32_bf16 v[116:119], v[152:155], v[196:199], v[116:119]
	v_mfma_f32_16x16x32_bf16 v[108:111], v[160:163], v[196:199], v[108:111]
	v_mfma_f32_16x16x32_bf16 v[100:103], v[152:155], v[204:207], v[100:103]
	v_mfma_f32_16x16x32_bf16 v[92:95], v[160:163], v[204:207], v[92:95]
	v_mfma_f32_16x16x32_bf16 v[84:87], v[152:155], v[212:215], v[84:87]
	v_mfma_f32_16x16x32_bf16 v[76:79], v[160:163], v[212:215], v[76:79]
	v_mfma_f32_16x16x32_bf16 v[112:115], v[164:167], v[180:183], v[112:115]
	v_mfma_f32_16x16x32_bf16 v[104:107], v[172:175], v[180:183], v[104:107]
	v_mfma_f32_16x16x32_bf16 v[96:99], v[164:167], v[192:195], v[96:99]
	v_mfma_f32_16x16x32_bf16 v[88:91], v[172:175], v[192:195], v[88:91]
	v_mfma_f32_16x16x32_bf16 v[80:83], v[164:167], v[200:203], v[80:83]
	v_mfma_f32_16x16x32_bf16 v[72:75], v[172:175], v[200:203], v[72:75]
	v_mfma_f32_16x16x32_bf16 v[68:71], v[164:167], v[208:211], v[68:71]
	v_mfma_f32_16x16x32_bf16 v[64:67], v[172:175], v[208:211], v[64:67]
	v_mfma_f32_16x16x32_bf16 v[112:115], v[168:171], v[184:187], v[112:115]
	v_mfma_f32_16x16x32_bf16 v[104:107], v[176:179], v[184:187], v[104:107]
	v_mfma_f32_16x16x32_bf16 v[96:99], v[168:171], v[196:199], v[96:99]
	v_mfma_f32_16x16x32_bf16 v[88:91], v[176:179], v[196:199], v[88:91]
	v_mfma_f32_16x16x32_bf16 v[80:83], v[168:171], v[204:207], v[80:83]
	v_mfma_f32_16x16x32_bf16 v[72:75], v[176:179], v[204:207], v[72:75]
	v_mfma_f32_16x16x32_bf16 v[68:71], v[168:171], v[212:215], v[68:71]
	v_mfma_f32_16x16x32_bf16 v[64:67], v[176:179], v[212:215], v[64:67]
	s_barrier
	s_mov_b32 m0, s89
	v_lshl_add_u64 v[140:141], v[140:141], 0, s[12:13]
	ds_read_b128 v[180:183], v147 offset:49152
	ds_read_b128 v[184:187], v147 offset:50176
	ds_read_b128 v[192:195], v147 offset:51200
	ds_read_b128 v[196:199], v147 offset:52224
	ds_read_b128 v[200:203], v147 offset:53248
	ds_read_b128 v[204:207], v147 offset:54272
	ds_read_b128 v[208:211], v147 offset:55296
	ds_read_b128 v[212:215], v147 offset:56320
	global_load_lds_dwordx4 v[140:141], off
	v_lshl_add_u64 v[140:141], v[188:189], 0, s[12:13]
	s_mov_b32 m0, s87
	s_nop 0
	global_load_lds_dwordx4 v[140:141], off
	s_mov_b32 m0, s88
	s_nop 0
	global_load_lds_dwordx4 v130, s[42:43]
	s_mov_b32 m0, s86
	s_nop 0
	global_load_lds_dwordx4 v134, s[42:43]
	v_lshl_add_u64 v[140:141], v[216:217], 0, s[12:13]
	s_mov_b32 m0, s77
	s_nop 0
	global_load_lds_dwordx4 v[140:141], off
	v_lshl_add_u64 v[140:141], v[218:219], 0, s[12:13]
	s_mov_b32 m0, s79
	s_nop 0
	global_load_lds_dwordx4 v[140:141], off
	s_waitcnt vmcnt(8)
	s_waitcnt lgkmcnt(0)
	s_barrier
	v_mfma_f32_16x16x32_bf16 v[60:63], v[148:151], v[180:183], v[60:63]
	v_mfma_f32_16x16x32_bf16 v[56:59], v[156:159], v[180:183], v[56:59]
	v_mfma_f32_16x16x32_bf16 v[52:55], v[148:151], v[192:195], v[52:55]
	v_mfma_f32_16x16x32_bf16 v[44:47], v[156:159], v[192:195], v[44:47]
	v_mfma_f32_16x16x32_bf16 v[36:39], v[148:151], v[200:203], v[36:39]
	v_mfma_f32_16x16x32_bf16 v[28:31], v[156:159], v[200:203], v[28:31]
	v_mfma_f32_16x16x32_bf16 v[20:23], v[148:151], v[208:211], v[20:23]
	v_mfma_f32_16x16x32_bf16 v[12:15], v[156:159], v[208:211], v[12:15]
	v_mfma_f32_16x16x32_bf16 v[60:63], v[152:155], v[184:187], v[60:63]
	v_mfma_f32_16x16x32_bf16 v[56:59], v[160:163], v[184:187], v[56:59]
	v_mfma_f32_16x16x32_bf16 v[52:55], v[152:155], v[196:199], v[52:55]
	v_mfma_f32_16x16x32_bf16 v[44:47], v[160:163], v[196:199], v[44:47]
	v_mfma_f32_16x16x32_bf16 v[36:39], v[152:155], v[204:207], v[36:39]
	v_mfma_f32_16x16x32_bf16 v[28:31], v[160:163], v[204:207], v[28:31]
	v_mfma_f32_16x16x32_bf16 v[20:23], v[152:155], v[212:215], v[20:23]
	v_mfma_f32_16x16x32_bf16 v[12:15], v[160:163], v[212:215], v[12:15]
	v_mfma_f32_16x16x32_bf16 v[48:51], v[164:167], v[180:183], v[48:51]
	v_mfma_f32_16x16x32_bf16 v[40:43], v[172:175], v[180:183], v[40:43]
	v_mfma_f32_16x16x32_bf16 v[32:35], v[164:167], v[192:195], v[32:35]
	v_mfma_f32_16x16x32_bf16 v[24:27], v[172:175], v[192:195], v[24:27]
	v_mfma_f32_16x16x32_bf16 v[16:19], v[164:167], v[200:203], v[16:19]
	v_mfma_f32_16x16x32_bf16 v[8:11], v[172:175], v[200:203], v[8:11]
	v_mfma_f32_16x16x32_bf16 v[4:7], v[164:167], v[208:211], v[4:7]
	v_mfma_f32_16x16x32_bf16 v[0:3], v[172:175], v[208:211], v[0:3]
	v_mfma_f32_16x16x32_bf16 v[48:51], v[168:171], v[184:187], v[48:51]
	v_mfma_f32_16x16x32_bf16 v[40:43], v[176:179], v[184:187], v[40:43]
	v_mfma_f32_16x16x32_bf16 v[32:35], v[168:171], v[196:199], v[32:35]
	v_mfma_f32_16x16x32_bf16 v[24:27], v[176:179], v[196:199], v[24:27]
	v_mfma_f32_16x16x32_bf16 v[16:19], v[168:171], v[204:207], v[16:19]
	v_mfma_f32_16x16x32_bf16 v[8:11], v[176:179], v[204:207], v[8:11]
	v_mfma_f32_16x16x32_bf16 v[4:7], v[168:171], v[212:215], v[4:7]
	v_mfma_f32_16x16x32_bf16 v[0:3], v[176:179], v[212:215], v[0:3]
	s_barrier
	s_movk_i32 s60, 0x100
	s_andn2_b64 vcc, exec, s[34:35]
	s_mov_b64 s[42:43], -1
	s_mov_b64 s[34:35], 0
	s_cbranch_vccz .LBB0_1222

.LBB0_1245:
	s_ashr_i32 s21, s20, 31
	s_lshl_b64 s[22:23], s[20:21], 17
	s_add_u32 s22, s52, s22
	s_addc_u32 s23, s53, s23
	s_and_b64 s[24:25], s[0:1], exec
	s_cselect_b32 s21, s23, s31
	s_cselect_b32 s55, s22, s30
	s_ashr_i32 s19, s18, 31
	s_lshl_b64 s[24:25], s[18:19], 17
	s_add_u32 s24, s70, s24
	s_addc_u32 s25, s71, s25
	s_and_b64 s[34:35], s[0:1], exec
	s_cselect_b32 s19, s25, s29
	s_cselect_b32 s86, s24, s28
	s_mov_b32 s60, 0
	s_mov_b64 s[34:35], -1
	s_mov_b64 s[42:43], 0
	s_add_u32 s61, s30, s60
	s_addc_u32 s66, s31, 0
	s_add_u32 s64, s61, 0x100
	s_addc_u32 s65, s66, 0
	s_and_b64 s[62:63], s[42:43], exec
	s_cselect_b32 s63, s21, s65
	s_cselect_b32 s62, s55, s64
	s_add_u32 s60, s28, s60
	s_addc_u32 s64, s29, 0
	s_add_u32 s60, s60, 0x100
	s_addc_u32 s64, s64, 0
	s_and_b64 s[42:43], s[42:43], exec
	s_cselect_b32 s65, s19, s64
	s_cselect_b32 s64, s86, s60
	s_add_u32 s68, s61, 0x10080
	ds_read_b128 v[148:151], v145
	ds_read_b128 v[152:155], v145 offset:1024
	ds_read_b128 v[156:159], v145 offset:2048
	ds_read_b128 v[160:163], v145 offset:3072
	ds_read_b128 v[164:167], v146
	ds_read_b128 v[168:171], v146 offset:1024
	ds_read_b128 v[172:175], v146 offset:2048
	ds_read_b128 v[176:179], v146 offset:3072
	s_addc_u32 s69, s66, 0
	s_add_i32 s96, s81, s73
	s_add_i32 m0, s27, 0xc000
	s_add_i32 s97, s27, 0xe000
	s_add_i32 s93, s96, 0x2000
	s_add_u32 s66, s64, 0x10000
	s_addc_u32 s67, s65, 0
	s_add_i32 s95, s82, s73
	s_add_i32 s94, s95, 0x2000
	s_add_i32 s92, 0, 0x18000
	s_add_i32 s91, 0, 0x1c000
	s_add_u32 s60, s62, 0x10000
	s_addc_u32 s61, s63, 0
	s_add_i32 s90, s92, s73
	s_add_i32 s88, s90, 0x2000
	s_add_u32 s42, s64, 0x10080
	s_addc_u32 s43, s65, 0
	s_add_i32 s89, s91, s73
	s_add_i32 s87, s89, 0x2000
	ds_read_b128 v[180:183], v147
	ds_read_b128 v[184:187], v147 offset:1024
	ds_read_b128 v[192:195], v147 offset:2048
	ds_read_b128 v[196:199], v147 offset:3072
	ds_read_b128 v[200:203], v147 offset:4096
	ds_read_b128 v[204:207], v147 offset:5120
	ds_read_b128 v[208:211], v147 offset:6144
	ds_read_b128 v[212:215], v147 offset:7168
	global_load_lds_dwordx4 v128, s[68:69]
	s_mov_b32 m0, s97
	s_nop 0
	global_load_lds_dwordx4 v132, s[68:69]
	s_waitcnt vmcnt(8)
	s_waitcnt lgkmcnt(0)
	s_barrier
	v_mfma_f32_16x16x32_bf16 v[124:127], v[148:151], v[180:183], 0
	v_mfma_f32_16x16x32_bf16 v[120:123], v[156:159], v[180:183], 0
	v_mfma_f32_16x16x32_bf16 v[116:119], v[148:151], v[192:195], 0
	v_mfma_f32_16x16x32_bf16 v[108:111], v[156:159], v[192:195], 0
	v_mfma_f32_16x16x32_bf16 v[100:103], v[148:151], v[200:203], 0
	v_mfma_f32_16x16x32_bf16 v[92:95], v[156:159], v[200:203], 0
	v_mfma_f32_16x16x32_bf16 v[84:87], v[148:151], v[208:211], 0
	v_mfma_f32_16x16x32_bf16 v[76:79], v[156:159], v[208:211], 0
	v_mfma_f32_16x16x32_bf16 v[124:127], v[152:155], v[184:187], v[124:127]
	v_mfma_f32_16x16x32_bf16 v[120:123], v[160:163], v[184:187], v[120:123]
	v_mfma_f32_16x16x32_bf16 v[116:119], v[152:155], v[196:199], v[116:119]
	v_mfma_f32_16x16x32_bf16 v[108:111], v[160:163], v[196:199], v[108:111]
	v_mfma_f32_16x16x32_bf16 v[100:103], v[152:155], v[204:207], v[100:103]
	v_mfma_f32_16x16x32_bf16 v[92:95], v[160:163], v[204:207], v[92:95]
	v_mfma_f32_16x16x32_bf16 v[84:87], v[152:155], v[212:215], v[84:87]
	v_mfma_f32_16x16x32_bf16 v[76:79], v[160:163], v[212:215], v[76:79]
	v_mfma_f32_16x16x32_bf16 v[112:115], v[164:167], v[180:183], 0
	v_mfma_f32_16x16x32_bf16 v[104:107], v[172:175], v[180:183], 0
	v_mfma_f32_16x16x32_bf16 v[96:99], v[164:167], v[192:195], 0
	v_mfma_f32_16x16x32_bf16 v[88:91], v[172:175], v[192:195], 0
	v_mfma_f32_16x16x32_bf16 v[80:83], v[164:167], v[200:203], 0
	v_mfma_f32_16x16x32_bf16 v[72:75], v[172:175], v[200:203], 0
	v_mfma_f32_16x16x32_bf16 v[68:71], v[164:167], v[208:211], 0
	v_mfma_f32_16x16x32_bf16 v[64:67], v[172:175], v[208:211], 0
	v_mfma_f32_16x16x32_bf16 v[112:115], v[168:171], v[184:187], v[112:115]
	v_mfma_f32_16x16x32_bf16 v[104:107], v[176:179], v[184:187], v[104:107]
	v_mfma_f32_16x16x32_bf16 v[96:99], v[168:171], v[196:199], v[96:99]
	v_mfma_f32_16x16x32_bf16 v[88:91], v[176:179], v[196:199], v[88:91]
	v_mfma_f32_16x16x32_bf16 v[80:83], v[168:171], v[204:207], v[80:83]
	v_mfma_f32_16x16x32_bf16 v[72:75], v[176:179], v[204:207], v[72:75]
	v_mfma_f32_16x16x32_bf16 v[68:71], v[168:171], v[212:215], v[68:71]
	v_mfma_f32_16x16x32_bf16 v[64:67], v[176:179], v[212:215], v[64:67]
	s_barrier
	s_mov_b32 m0, s96
	v_lshl_add_u64 v[140:141], s[64:65], 0, v[130:131]
	ds_read_b128 v[180:183], v147 offset:16384
	ds_read_b128 v[184:187], v147 offset:17408
	ds_read_b128 v[192:195], v147 offset:18432
	ds_read_b128 v[196:199], v147 offset:19456
	ds_read_b128 v[200:203], v147 offset:20480
	ds_read_b128 v[204:207], v147 offset:21504
	ds_read_b128 v[208:211], v147 offset:22528
	ds_read_b128 v[212:215], v147 offset:23552
	global_load_lds_dwordx4 v[140:141], off
	v_lshl_add_u64 v[188:189], s[64:65], 0, v[134:135]
	s_mov_b32 m0, s93
	s_nop 0
	global_load_lds_dwordx4 v[188:189], off
	s_mov_b32 m0, s95
	v_lshl_add_u64 v[218:219], s[62:63], 0, v[132:133]
	global_load_lds_dwordx4 v130, s[66:67]
	s_mov_b32 m0, s94
	s_nop 0
	global_load_lds_dwordx4 v134, s[66:67]
	v_lshl_add_u64 v[216:217], s[62:63], 0, v[128:129]
	s_mov_b32 m0, s27
	s_nop 0
	global_load_lds_dwordx4 v[216:217], off
	s_mov_b32 m0, s33
	s_nop 0
	global_load_lds_dwordx4 v[218:219], off
	s_waitcnt vmcnt(8)
	s_waitcnt lgkmcnt(0)
	s_barrier
	v_mfma_f32_16x16x32_bf16 v[60:63], v[148:151], v[180:183], 0
	v_mfma_f32_16x16x32_bf16 v[56:59], v[156:159], v[180:183], 0
	v_mfma_f32_16x16x32_bf16 v[52:55], v[148:151], v[192:195], 0
	v_mfma_f32_16x16x32_bf16 v[44:47], v[156:159], v[192:195], 0
	v_mfma_f32_16x16x32_bf16 v[36:39], v[148:151], v[200:203], 0
	v_mfma_f32_16x16x32_bf16 v[28:31], v[156:159], v[200:203], 0
	v_mfma_f32_16x16x32_bf16 v[20:23], v[148:151], v[208:211], 0
	v_mfma_f32_16x16x32_bf16 v[12:15], v[156:159], v[208:211], 0
	v_mfma_f32_16x16x32_bf16 v[60:63], v[152:155], v[184:187], v[60:63]
	v_mfma_f32_16x16x32_bf16 v[56:59], v[160:163], v[184:187], v[56:59]
	v_mfma_f32_16x16x32_bf16 v[52:55], v[152:155], v[196:199], v[52:55]
	v_mfma_f32_16x16x32_bf16 v[44:47], v[160:163], v[196:199], v[44:47]
	v_mfma_f32_16x16x32_bf16 v[36:39], v[152:155], v[204:207], v[36:39]
	v_mfma_f32_16x16x32_bf16 v[28:31], v[160:163], v[204:207], v[28:31]
	v_mfma_f32_16x16x32_bf16 v[20:23], v[152:155], v[212:215], v[20:23]
	v_mfma_f32_16x16x32_bf16 v[12:15], v[160:163], v[212:215], v[12:15]
	v_mfma_f32_16x16x32_bf16 v[48:51], v[164:167], v[180:183], 0
	v_mfma_f32_16x16x32_bf16 v[40:43], v[172:175], v[180:183], 0
	v_mfma_f32_16x16x32_bf16 v[32:35], v[164:167], v[192:195], 0
	v_mfma_f32_16x16x32_bf16 v[24:27], v[172:175], v[192:195], 0
	v_mfma_f32_16x16x32_bf16 v[16:19], v[164:167], v[200:203], 0
	v_mfma_f32_16x16x32_bf16 v[8:11], v[172:175], v[200:203], 0
	v_mfma_f32_16x16x32_bf16 v[4:7], v[164:167], v[208:211], 0
	v_mfma_f32_16x16x32_bf16 v[0:3], v[172:175], v[208:211], 0
	v_mfma_f32_16x16x32_bf16 v[48:51], v[168:171], v[184:187], v[48:51]
	v_mfma_f32_16x16x32_bf16 v[40:43], v[176:179], v[184:187], v[40:43]
	v_mfma_f32_16x16x32_bf16 v[32:35], v[168:171], v[196:199], v[32:35]
	v_mfma_f32_16x16x32_bf16 v[24:27], v[176:179], v[196:199], v[24:27]
	v_mfma_f32_16x16x32_bf16 v[16:19], v[168:171], v[204:207], v[16:19]
	v_mfma_f32_16x16x32_bf16 v[8:11], v[176:179], v[204:207], v[8:11]
	v_mfma_f32_16x16x32_bf16 v[4:7], v[168:171], v[212:215], v[4:7]
	v_mfma_f32_16x16x32_bf16 v[0:3], v[176:179], v[212:215], v[0:3]
	s_barrier
	v_add_u32_e32 v160, s92, v143
	v_add_u32_e32 v176, s91, v143
	ds_read_b128 v[148:151], v160
	ds_read_b128 v[152:155], v160 offset:1024
	ds_read_b128 v[156:159], v160 offset:2048
	ds_read_b128 v[160:163], v160 offset:3072
	ds_read_b128 v[164:167], v176
	ds_read_b128 v[168:171], v176 offset:1024
	ds_read_b128 v[172:175], v176 offset:2048
	ds_read_b128 v[176:179], v176 offset:3072
	s_mov_b32 m0, s74
	ds_read_b128 v[180:183], v147 offset:32768
	ds_read_b128 v[184:187], v147 offset:33792
	ds_read_b128 v[192:195], v147 offset:34816
	ds_read_b128 v[196:199], v147 offset:35840
	ds_read_b128 v[200:203], v147 offset:36864
	ds_read_b128 v[204:207], v147 offset:37888
	ds_read_b128 v[208:211], v147 offset:38912
	ds_read_b128 v[212:215], v147 offset:39936
	global_load_lds_dwordx4 v128, s[60:61]
	s_mov_b32 m0, s75
	s_nop 0
	global_load_lds_dwordx4 v132, s[60:61]
	s_waitcnt vmcnt(8)
	s_waitcnt lgkmcnt(0)
	s_barrier
	v_mfma_f32_16x16x32_bf16 v[124:127], v[148:151], v[180:183], v[124:127]
	v_mfma_f32_16x16x32_bf16 v[120:123], v[156:159], v[180:183], v[120:123]
	v_mfma_f32_16x16x32_bf16 v[116:119], v[148:151], v[192:195], v[116:119]
	v_mfma_f32_16x16x32_bf16 v[108:111], v[156:159], v[192:195], v[108:111]
	v_mfma_f32_16x16x32_bf16 v[100:103], v[148:151], v[200:203], v[100:103]
	v_mfma_f32_16x16x32_bf16 v[92:95], v[156:159], v[200:203], v[92:95]
	v_mfma_f32_16x16x32_bf16 v[84:87], v[148:151], v[208:211], v[84:87]
	v_mfma_f32_16x16x32_bf16 v[76:79], v[156:159], v[208:211], v[76:79]
	v_mfma_f32_16x16x32_bf16 v[124:127], v[152:155], v[184:187], v[124:127]
	v_mfma_f32_16x16x32_bf16 v[120:123], v[160:163], v[184:187], v[120:123]
	v_mfma_f32_16x16x32_bf16 v[116:119], v[152:155], v[196:199], v[116:119]
	v_mfma_f32_16x16x32_bf16 v[108:111], v[160:163], v[196:199], v[108:111]
	v_mfma_f32_16x16x32_bf16 v[100:103], v[152:155], v[204:207], v[100:103]
	v_mfma_f32_16x16x32_bf16 v[92:95], v[160:163], v[204:207], v[92:95]
	v_mfma_f32_16x16x32_bf16 v[84:87], v[152:155], v[212:215], v[84:87]
	v_mfma_f32_16x16x32_bf16 v[76:79], v[160:163], v[212:215], v[76:79]
	v_mfma_f32_16x16x32_bf16 v[112:115], v[164:167], v[180:183], v[112:115]
	v_mfma_f32_16x16x32_bf16 v[104:107], v[172:175], v[180:183], v[104:107]
	v_mfma_f32_16x16x32_bf16 v[96:99], v[164:167], v[192:195], v[96:99]
	v_mfma_f32_16x16x32_bf16 v[88:91], v[172:175], v[192:195], v[88:91]
	v_mfma_f32_16x16x32_bf16 v[80:83], v[164:167], v[200:203], v[80:83]
	v_mfma_f32_16x16x32_bf16 v[72:75], v[172:175], v[200:203], v[72:75]
	v_mfma_f32_16x16x32_bf16 v[68:71], v[164:167], v[208:211], v[68:71]
	v_mfma_f32_16x16x32_bf16 v[64:67], v[172:175], v[208:211], v[64:67]
	v_mfma_f32_16x16x32_bf16 v[112:115], v[168:171], v[184:187], v[112:115]
	v_mfma_f32_16x16x32_bf16 v[104:107], v[176:179], v[184:187], v[104:107]
	v_mfma_f32_16x16x32_bf16 v[96:99], v[168:171], v[196:199], v[96:99]
	v_mfma_f32_16x16x32_bf16 v[88:91], v[176:179], v[196:199], v[88:91]
	v_mfma_f32_16x16x32_bf16 v[80:83], v[168:171], v[204:207], v[80:83]
	v_mfma_f32_16x16x32_bf16 v[72:75], v[176:179], v[204:207], v[72:75]
	v_mfma_f32_16x16x32_bf16 v[68:71], v[168:171], v[212:215], v[68:71]
	v_mfma_f32_16x16x32_bf16 v[64:67], v[176:179], v[212:215], v[64:67]
	s_barrier
	s_mov_b32 m0, s90
	v_lshl_add_u64 v[140:141], v[140:141], 0, s[10:11]
	ds_read_b128 v[180:183], v147 offset:49152
	ds_read_b128 v[184:187], v147 offset:50176
	ds_read_b128 v[192:195], v147 offset:51200
	ds_read_b128 v[196:199], v147 offset:52224
	ds_read_b128 v[200:203], v147 offset:53248
	ds_read_b128 v[204:207], v147 offset:54272
	ds_read_b128 v[208:211], v147 offset:55296
	ds_read_b128 v[212:215], v147 offset:56320
	global_load_lds_dwordx4 v[140:141], off
	v_lshl_add_u64 v[140:141], v[188:189], 0, s[10:11]
	s_mov_b32 m0, s88
	s_nop 0
	global_load_lds_dwordx4 v[140:141], off
	s_mov_b32 m0, s89
	s_nop 0
	global_load_lds_dwordx4 v130, s[42:43]
	s_mov_b32 m0, s87
	s_nop 0
	global_load_lds_dwordx4 v134, s[42:43]
	v_lshl_add_u64 v[140:141], v[216:217], 0, s[10:11]
	s_mov_b32 m0, s77
	s_nop 0
	global_load_lds_dwordx4 v[140:141], off
	v_lshl_add_u64 v[140:141], v[218:219], 0, s[10:11]
	s_mov_b32 m0, s79
	s_nop 0
	global_load_lds_dwordx4 v[140:141], off
	s_waitcnt vmcnt(8)
	s_waitcnt lgkmcnt(0)
	s_barrier
	v_mfma_f32_16x16x32_bf16 v[60:63], v[148:151], v[180:183], v[60:63]
	v_mfma_f32_16x16x32_bf16 v[56:59], v[156:159], v[180:183], v[56:59]
	v_mfma_f32_16x16x32_bf16 v[52:55], v[148:151], v[192:195], v[52:55]
	v_mfma_f32_16x16x32_bf16 v[44:47], v[156:159], v[192:195], v[44:47]
	v_mfma_f32_16x16x32_bf16 v[36:39], v[148:151], v[200:203], v[36:39]
	v_mfma_f32_16x16x32_bf16 v[28:31], v[156:159], v[200:203], v[28:31]
	v_mfma_f32_16x16x32_bf16 v[20:23], v[148:151], v[208:211], v[20:23]
	v_mfma_f32_16x16x32_bf16 v[12:15], v[156:159], v[208:211], v[12:15]
	v_mfma_f32_16x16x32_bf16 v[60:63], v[152:155], v[184:187], v[60:63]
	v_mfma_f32_16x16x32_bf16 v[56:59], v[160:163], v[184:187], v[56:59]
	v_mfma_f32_16x16x32_bf16 v[52:55], v[152:155], v[196:199], v[52:55]
	v_mfma_f32_16x16x32_bf16 v[44:47], v[160:163], v[196:199], v[44:47]
	v_mfma_f32_16x16x32_bf16 v[36:39], v[152:155], v[204:207], v[36:39]
	v_mfma_f32_16x16x32_bf16 v[28:31], v[160:163], v[204:207], v[28:31]
	v_mfma_f32_16x16x32_bf16 v[20:23], v[152:155], v[212:215], v[20:23]
	v_mfma_f32_16x16x32_bf16 v[12:15], v[160:163], v[212:215], v[12:15]
	v_mfma_f32_16x16x32_bf16 v[48:51], v[164:167], v[180:183], v[48:51]
	v_mfma_f32_16x16x32_bf16 v[40:43], v[172:175], v[180:183], v[40:43]
	v_mfma_f32_16x16x32_bf16 v[32:35], v[164:167], v[192:195], v[32:35]
	v_mfma_f32_16x16x32_bf16 v[24:27], v[172:175], v[192:195], v[24:27]
	v_mfma_f32_16x16x32_bf16 v[16:19], v[164:167], v[200:203], v[16:19]
	v_mfma_f32_16x16x32_bf16 v[8:11], v[172:175], v[200:203], v[8:11]
	v_mfma_f32_16x16x32_bf16 v[4:7], v[164:167], v[208:211], v[4:7]
	v_mfma_f32_16x16x32_bf16 v[0:3], v[172:175], v[208:211], v[0:3]
	v_mfma_f32_16x16x32_bf16 v[48:51], v[168:171], v[184:187], v[48:51]
	v_mfma_f32_16x16x32_bf16 v[40:43], v[176:179], v[184:187], v[40:43]
	v_mfma_f32_16x16x32_bf16 v[32:35], v[168:171], v[196:199], v[32:35]
	v_mfma_f32_16x16x32_bf16 v[24:27], v[176:179], v[196:199], v[24:27]
	v_mfma_f32_16x16x32_bf16 v[16:19], v[168:171], v[204:207], v[16:19]
	v_mfma_f32_16x16x32_bf16 v[8:11], v[176:179], v[204:207], v[8:11]
	v_mfma_f32_16x16x32_bf16 v[4:7], v[168:171], v[212:215], v[4:7]
	v_mfma_f32_16x16x32_bf16 v[0:3], v[176:179], v[212:215], v[0:3]
	s_barrier
	s_movk_i32 s60, 0x100
	s_andn2_b64 vcc, exec, s[34:35]
	s_mov_b64 s[42:43], -1
	s_mov_b64 s[34:35], 0
	s_cbranch_vccz .LBB0_1246
	s_branch .Lpeel_exit8
.LBB0_1246:
	s_add_u32 s61, s30, s60
	s_addc_u32 s66, s31, 0
	s_add_u32 s64, s61, 0x100
	s_addc_u32 s65, s66, 0
	s_and_b64 s[62:63], s[42:43], exec
	s_cselect_b32 s63, s21, s65
	s_cselect_b32 s62, s55, s64
	s_add_u32 s60, s28, s60
	s_addc_u32 s64, s29, 0
	s_add_u32 s60, s60, 0x100
	s_addc_u32 s64, s64, 0
	s_and_b64 s[42:43], s[42:43], exec
	s_cselect_b32 s65, s19, s64
	s_cselect_b32 s64, s86, s60
	s_add_u32 s68, s61, 0x10080
	ds_read_b128 v[148:151], v145
	ds_read_b128 v[152:155], v145 offset:1024
	ds_read_b128 v[156:159], v145 offset:2048
	ds_read_b128 v[160:163], v145 offset:3072
	ds_read_b128 v[164:167], v146
	ds_read_b128 v[168:171], v146 offset:1024
	ds_read_b128 v[172:175], v146 offset:2048
	ds_read_b128 v[176:179], v146 offset:3072
	s_addc_u32 s69, s66, 0
	s_add_i32 s96, s81, s73
	s_add_i32 m0, s27, 0xc000
	s_add_i32 s97, s27, 0xe000
	s_add_i32 s93, s96, 0x2000
	s_add_u32 s66, s64, 0x10000
	s_addc_u32 s67, s65, 0
	s_add_i32 s95, s82, s73
	s_add_i32 s94, s95, 0x2000
	s_add_i32 s92, 0, 0x18000
	s_add_i32 s91, 0, 0x1c000
	s_add_u32 s60, s62, 0x10000
	s_addc_u32 s61, s63, 0
	s_add_i32 s90, s92, s73
	s_add_i32 s88, s90, 0x2000
	s_add_u32 s42, s64, 0x10080
	s_addc_u32 s43, s65, 0
	s_add_i32 s89, s91, s73
	s_add_i32 s87, s89, 0x2000
	ds_read_b128 v[180:183], v147
	ds_read_b128 v[184:187], v147 offset:1024
	ds_read_b128 v[192:195], v147 offset:2048
	ds_read_b128 v[196:199], v147 offset:3072
	ds_read_b128 v[200:203], v147 offset:4096
	ds_read_b128 v[204:207], v147 offset:5120
	ds_read_b128 v[208:211], v147 offset:6144
	ds_read_b128 v[212:215], v147 offset:7168
	global_load_lds_dwordx4 v128, s[68:69]
	s_mov_b32 m0, s97
	s_nop 0
	global_load_lds_dwordx4 v132, s[68:69]
	s_waitcnt vmcnt(8)
	s_waitcnt lgkmcnt(0)
	s_barrier
	v_mfma_f32_16x16x32_bf16 v[124:127], v[148:151], v[180:183], v[124:127]
	v_mfma_f32_16x16x32_bf16 v[120:123], v[156:159], v[180:183], v[120:123]
	v_mfma_f32_16x16x32_bf16 v[116:119], v[148:151], v[192:195], v[116:119]
	v_mfma_f32_16x16x32_bf16 v[108:111], v[156:159], v[192:195], v[108:111]
	v_mfma_f32_16x16x32_bf16 v[100:103], v[148:151], v[200:203], v[100:103]
	v_mfma_f32_16x16x32_bf16 v[92:95], v[156:159], v[200:203], v[92:95]
	v_mfma_f32_16x16x32_bf16 v[84:87], v[148:151], v[208:211], v[84:87]
	v_mfma_f32_16x16x32_bf16 v[76:79], v[156:159], v[208:211], v[76:79]
	v_mfma_f32_16x16x32_bf16 v[124:127], v[152:155], v[184:187], v[124:127]
	v_mfma_f32_16x16x32_bf16 v[120:123], v[160:163], v[184:187], v[120:123]
	v_mfma_f32_16x16x32_bf16 v[116:119], v[152:155], v[196:199], v[116:119]
	v_mfma_f32_16x16x32_bf16 v[108:111], v[160:163], v[196:199], v[108:111]
	v_mfma_f32_16x16x32_bf16 v[100:103], v[152:155], v[204:207], v[100:103]
	v_mfma_f32_16x16x32_bf16 v[92:95], v[160:163], v[204:207], v[92:95]
	v_mfma_f32_16x16x32_bf16 v[84:87], v[152:155], v[212:215], v[84:87]
	v_mfma_f32_16x16x32_bf16 v[76:79], v[160:163], v[212:215], v[76:79]
	v_mfma_f32_16x16x32_bf16 v[112:115], v[164:167], v[180:183], v[112:115]
	v_mfma_f32_16x16x32_bf16 v[104:107], v[172:175], v[180:183], v[104:107]
	v_mfma_f32_16x16x32_bf16 v[96:99], v[164:167], v[192:195], v[96:99]
	v_mfma_f32_16x16x32_bf16 v[88:91], v[172:175], v[192:195], v[88:91]
	v_mfma_f32_16x16x32_bf16 v[80:83], v[164:167], v[200:203], v[80:83]
	v_mfma_f32_16x16x32_bf16 v[72:75], v[172:175], v[200:203], v[72:75]
	v_mfma_f32_16x16x32_bf16 v[68:71], v[164:167], v[208:211], v[68:71]
	v_mfma_f32_16x16x32_bf16 v[64:67], v[172:175], v[208:211], v[64:67]
	v_mfma_f32_16x16x32_bf16 v[112:115], v[168:171], v[184:187], v[112:115]
	v_mfma_f32_16x16x32_bf16 v[104:107], v[176:179], v[184:187], v[104:107]
	v_mfma_f32_16x16x32_bf16 v[96:99], v[168:171], v[196:199], v[96:99]
	v_mfma_f32_16x16x32_bf16 v[88:91], v[176:179], v[196:199], v[88:91]
	v_mfma_f32_16x16x32_bf16 v[80:83], v[168:171], v[204:207], v[80:83]
	v_mfma_f32_16x16x32_bf16 v[72:75], v[176:179], v[204:207], v[72:75]
	v_mfma_f32_16x16x32_bf16 v[68:71], v[168:171], v[212:215], v[68:71]
	v_mfma_f32_16x16x32_bf16 v[64:67], v[176:179], v[212:215], v[64:67]
	s_barrier
	s_mov_b32 m0, s96
	v_lshl_add_u64 v[140:141], s[64:65], 0, v[130:131]
	ds_read_b128 v[180:183], v147 offset:16384
	ds_read_b128 v[184:187], v147 offset:17408
	ds_read_b128 v[192:195], v147 offset:18432
	ds_read_b128 v[196:199], v147 offset:19456
	ds_read_b128 v[200:203], v147 offset:20480
	ds_read_b128 v[204:207], v147 offset:21504
	ds_read_b128 v[208:211], v147 offset:22528
	ds_read_b128 v[212:215], v147 offset:23552
	global_load_lds_dwordx4 v[140:141], off
	v_lshl_add_u64 v[188:189], s[64:65], 0, v[134:135]
	s_mov_b32 m0, s93
	s_nop 0
	global_load_lds_dwordx4 v[188:189], off
	s_mov_b32 m0, s95
	v_lshl_add_u64 v[218:219], s[62:63], 0, v[132:133]
	global_load_lds_dwordx4 v130, s[66:67]
	s_mov_b32 m0, s94
	s_nop 0
	global_load_lds_dwordx4 v134, s[66:67]
	v_lshl_add_u64 v[216:217], s[62:63], 0, v[128:129]
	s_mov_b32 m0, s27
	s_nop 0
	global_load_lds_dwordx4 v[216:217], off
	s_mov_b32 m0, s33
	s_nop 0
	global_load_lds_dwordx4 v[218:219], off
	s_waitcnt vmcnt(8)
	s_waitcnt lgkmcnt(0)
	s_barrier
	v_mfma_f32_16x16x32_bf16 v[60:63], v[148:151], v[180:183], v[60:63]
	v_mfma_f32_16x16x32_bf16 v[56:59], v[156:159], v[180:183], v[56:59]
	v_mfma_f32_16x16x32_bf16 v[52:55], v[148:151], v[192:195], v[52:55]
	v_mfma_f32_16x16x32_bf16 v[44:47], v[156:159], v[192:195], v[44:47]
	v_mfma_f32_16x16x32_bf16 v[36:39], v[148:151], v[200:203], v[36:39]
	v_mfma_f32_16x16x32_bf16 v[28:31], v[156:159], v[200:203], v[28:31]
	v_mfma_f32_16x16x32_bf16 v[20:23], v[148:151], v[208:211], v[20:23]
	v_mfma_f32_16x16x32_bf16 v[12:15], v[156:159], v[208:211], v[12:15]
	v_mfma_f32_16x16x32_bf16 v[60:63], v[152:155], v[184:187], v[60:63]
	v_mfma_f32_16x16x32_bf16 v[56:59], v[160:163], v[184:187], v[56:59]
	v_mfma_f32_16x16x32_bf16 v[52:55], v[152:155], v[196:199], v[52:55]
	v_mfma_f32_16x16x32_bf16 v[44:47], v[160:163], v[196:199], v[44:47]
	v_mfma_f32_16x16x32_bf16 v[36:39], v[152:155], v[204:207], v[36:39]
	v_mfma_f32_16x16x32_bf16 v[28:31], v[160:163], v[204:207], v[28:31]
	v_mfma_f32_16x16x32_bf16 v[20:23], v[152:155], v[212:215], v[20:23]
	v_mfma_f32_16x16x32_bf16 v[12:15], v[160:163], v[212:215], v[12:15]
	v_mfma_f32_16x16x32_bf16 v[48:51], v[164:167], v[180:183], v[48:51]
	v_mfma_f32_16x16x32_bf16 v[40:43], v[172:175], v[180:183], v[40:43]
	v_mfma_f32_16x16x32_bf16 v[32:35], v[164:167], v[192:195], v[32:35]
	v_mfma_f32_16x16x32_bf16 v[24:27], v[172:175], v[192:195], v[24:27]
	v_mfma_f32_16x16x32_bf16 v[16:19], v[164:167], v[200:203], v[16:19]
	v_mfma_f32_16x16x32_bf16 v[8:11], v[172:175], v[200:203], v[8:11]
	v_mfma_f32_16x16x32_bf16 v[4:7], v[164:167], v[208:211], v[4:7]
	v_mfma_f32_16x16x32_bf16 v[0:3], v[172:175], v[208:211], v[0:3]
	v_mfma_f32_16x16x32_bf16 v[48:51], v[168:171], v[184:187], v[48:51]
	v_mfma_f32_16x16x32_bf16 v[40:43], v[176:179], v[184:187], v[40:43]
	v_mfma_f32_16x16x32_bf16 v[32:35], v[168:171], v[196:199], v[32:35]
	v_mfma_f32_16x16x32_bf16 v[24:27], v[176:179], v[196:199], v[24:27]
	v_mfma_f32_16x16x32_bf16 v[16:19], v[168:171], v[204:207], v[16:19]
	v_mfma_f32_16x16x32_bf16 v[8:11], v[176:179], v[204:207], v[8:11]
	v_mfma_f32_16x16x32_bf16 v[4:7], v[168:171], v[212:215], v[4:7]
	v_mfma_f32_16x16x32_bf16 v[0:3], v[176:179], v[212:215], v[0:3]
	s_barrier
	v_add_u32_e32 v160, s92, v143
	v_add_u32_e32 v176, s91, v143
	ds_read_b128 v[148:151], v160
	ds_read_b128 v[152:155], v160 offset:1024
	ds_read_b128 v[156:159], v160 offset:2048
	ds_read_b128 v[160:163], v160 offset:3072
	ds_read_b128 v[164:167], v176
	ds_read_b128 v[168:171], v176 offset:1024
	ds_read_b128 v[172:175], v176 offset:2048
	ds_read_b128 v[176:179], v176 offset:3072
	s_mov_b32 m0, s74
	ds_read_b128 v[180:183], v147 offset:32768
	ds_read_b128 v[184:187], v147 offset:33792
	ds_read_b128 v[192:195], v147 offset:34816
	ds_read_b128 v[196:199], v147 offset:35840
	ds_read_b128 v[200:203], v147 offset:36864
	ds_read_b128 v[204:207], v147 offset:37888
	ds_read_b128 v[208:211], v147 offset:38912
	ds_read_b128 v[212:215], v147 offset:39936
	global_load_lds_dwordx4 v128, s[60:61]
	s_mov_b32 m0, s75
	s_nop 0
	global_load_lds_dwordx4 v132, s[60:61]
	s_waitcnt vmcnt(8)
	s_waitcnt lgkmcnt(0)
	s_barrier
	v_mfma_f32_16x16x32_bf16 v[124:127], v[148:151], v[180:183], v[124:127]
	v_mfma_f32_16x16x32_bf16 v[120:123], v[156:159], v[180:183], v[120:123]
	v_mfma_f32_16x16x32_bf16 v[116:119], v[148:151], v[192:195], v[116:119]
	v_mfma_f32_16x16x32_bf16 v[108:111], v[156:159], v[192:195], v[108:111]
	v_mfma_f32_16x16x32_bf16 v[100:103], v[148:151], v[200:203], v[100:103]
	v_mfma_f32_16x16x32_bf16 v[92:95], v[156:159], v[200:203], v[92:95]
	v_mfma_f32_16x16x32_bf16 v[84:87], v[148:151], v[208:211], v[84:87]
	v_mfma_f32_16x16x32_bf16 v[76:79], v[156:159], v[208:211], v[76:79]
	v_mfma_f32_16x16x32_bf16 v[124:127], v[152:155], v[184:187], v[124:127]
	v_mfma_f32_16x16x32_bf16 v[120:123], v[160:163], v[184:187], v[120:123]
	v_mfma_f32_16x16x32_bf16 v[116:119], v[152:155], v[196:199], v[116:119]
	v_mfma_f32_16x16x32_bf16 v[108:111], v[160:163], v[196:199], v[108:111]
	v_mfma_f32_16x16x32_bf16 v[100:103], v[152:155], v[204:207], v[100:103]
	v_mfma_f32_16x16x32_bf16 v[92:95], v[160:163], v[204:207], v[92:95]
	v_mfma_f32_16x16x32_bf16 v[84:87], v[152:155], v[212:215], v[84:87]
	v_mfma_f32_16x16x32_bf16 v[76:79], v[160:163], v[212:215], v[76:79]
	v_mfma_f32_16x16x32_bf16 v[112:115], v[164:167], v[180:183], v[112:115]
	v_mfma_f32_16x16x32_bf16 v[104:107], v[172:175], v[180:183], v[104:107]
	v_mfma_f32_16x16x32_bf16 v[96:99], v[164:167], v[192:195], v[96:99]
	v_mfma_f32_16x16x32_bf16 v[88:91], v[172:175], v[192:195], v[88:91]
	v_mfma_f32_16x16x32_bf16 v[80:83], v[164:167], v[200:203], v[80:83]
	v_mfma_f32_16x16x32_bf16 v[72:75], v[172:175], v[200:203], v[72:75]
	v_mfma_f32_16x16x32_bf16 v[68:71], v[164:167], v[208:211], v[68:71]
	v_mfma_f32_16x16x32_bf16 v[64:67], v[172:175], v[208:211], v[64:67]
	v_mfma_f32_16x16x32_bf16 v[112:115], v[168:171], v[184:187], v[112:115]
	v_mfma_f32_16x16x32_bf16 v[104:107], v[176:179], v[184:187], v[104:107]
	v_mfma_f32_16x16x32_bf16 v[96:99], v[168:171], v[196:199], v[96:99]
	v_mfma_f32_16x16x32_bf16 v[88:91], v[176:179], v[196:199], v[88:91]
	v_mfma_f32_16x16x32_bf16 v[80:83], v[168:171], v[204:207], v[80:83]
	v_mfma_f32_16x16x32_bf16 v[72:75], v[176:179], v[204:207], v[72:75]
	v_mfma_f32_16x16x32_bf16 v[68:71], v[168:171], v[212:215], v[68:71]
	v_mfma_f32_16x16x32_bf16 v[64:67], v[176:179], v[212:215], v[64:67]
	s_barrier
	s_mov_b32 m0, s90
	v_lshl_add_u64 v[140:141], v[140:141], 0, s[10:11]
	ds_read_b128 v[180:183], v147 offset:49152
	ds_read_b128 v[184:187], v147 offset:50176
	ds_read_b128 v[192:195], v147 offset:51200
	ds_read_b128 v[196:199], v147 offset:52224
	ds_read_b128 v[200:203], v147 offset:53248
	ds_read_b128 v[204:207], v147 offset:54272
	ds_read_b128 v[208:211], v147 offset:55296
	ds_read_b128 v[212:215], v147 offset:56320
	global_load_lds_dwordx4 v[140:141], off
	v_lshl_add_u64 v[140:141], v[188:189], 0, s[10:11]
	s_mov_b32 m0, s88
	s_nop 0
	global_load_lds_dwordx4 v[140:141], off
	s_mov_b32 m0, s89
	s_nop 0
	global_load_lds_dwordx4 v130, s[42:43]
	s_mov_b32 m0, s87
	s_nop 0
	global_load_lds_dwordx4 v134, s[42:43]
	v_lshl_add_u64 v[140:141], v[216:217], 0, s[10:11]
	s_mov_b32 m0, s77
	s_nop 0
	global_load_lds_dwordx4 v[140:141], off
	v_lshl_add_u64 v[140:141], v[218:219], 0, s[10:11]
	s_mov_b32 m0, s79
	s_nop 0
	global_load_lds_dwordx4 v[140:141], off
	s_waitcnt vmcnt(8)
	s_waitcnt lgkmcnt(0)
	s_barrier
	v_mfma_f32_16x16x32_bf16 v[60:63], v[148:151], v[180:183], v[60:63]
	v_mfma_f32_16x16x32_bf16 v[56:59], v[156:159], v[180:183], v[56:59]
	v_mfma_f32_16x16x32_bf16 v[52:55], v[148:151], v[192:195], v[52:55]
	v_mfma_f32_16x16x32_bf16 v[44:47], v[156:159], v[192:195], v[44:47]
	v_mfma_f32_16x16x32_bf16 v[36:39], v[148:151], v[200:203], v[36:39]
	v_mfma_f32_16x16x32_bf16 v[28:31], v[156:159], v[200:203], v[28:31]
	v_mfma_f32_16x16x32_bf16 v[20:23], v[148:151], v[208:211], v[20:23]
	v_mfma_f32_16x16x32_bf16 v[12:15], v[156:159], v[208:211], v[12:15]
	v_mfma_f32_16x16x32_bf16 v[60:63], v[152:155], v[184:187], v[60:63]
	v_mfma_f32_16x16x32_bf16 v[56:59], v[160:163], v[184:187], v[56:59]
	v_mfma_f32_16x16x32_bf16 v[52:55], v[152:155], v[196:199], v[52:55]
	v_mfma_f32_16x16x32_bf16 v[44:47], v[160:163], v[196:199], v[44:47]
	v_mfma_f32_16x16x32_bf16 v[36:39], v[152:155], v[204:207], v[36:39]
	v_mfma_f32_16x16x32_bf16 v[28:31], v[160:163], v[204:207], v[28:31]
	v_mfma_f32_16x16x32_bf16 v[20:23], v[152:155], v[212:215], v[20:23]
	v_mfma_f32_16x16x32_bf16 v[12:15], v[160:163], v[212:215], v[12:15]
	v_mfma_f32_16x16x32_bf16 v[48:51], v[164:167], v[180:183], v[48:51]
	v_mfma_f32_16x16x32_bf16 v[40:43], v[172:175], v[180:183], v[40:43]
	v_mfma_f32_16x16x32_bf16 v[32:35], v[164:167], v[192:195], v[32:35]
	v_mfma_f32_16x16x32_bf16 v[24:27], v[172:175], v[192:195], v[24:27]
	v_mfma_f32_16x16x32_bf16 v[16:19], v[164:167], v[200:203], v[16:19]
	v_mfma_f32_16x16x32_bf16 v[8:11], v[172:175], v[200:203], v[8:11]
	v_mfma_f32_16x16x32_bf16 v[4:7], v[164:167], v[208:211], v[4:7]
	v_mfma_f32_16x16x32_bf16 v[0:3], v[172:175], v[208:211], v[0:3]
	v_mfma_f32_16x16x32_bf16 v[48:51], v[168:171], v[184:187], v[48:51]
	v_mfma_f32_16x16x32_bf16 v[40:43], v[176:179], v[184:187], v[40:43]
	v_mfma_f32_16x16x32_bf16 v[32:35], v[168:171], v[196:199], v[32:35]
	v_mfma_f32_16x16x32_bf16 v[24:27], v[176:179], v[196:199], v[24:27]
	v_mfma_f32_16x16x32_bf16 v[16:19], v[168:171], v[204:207], v[16:19]
	v_mfma_f32_16x16x32_bf16 v[8:11], v[176:179], v[204:207], v[8:11]
	v_mfma_f32_16x16x32_bf16 v[4:7], v[168:171], v[212:215], v[4:7]
	v_mfma_f32_16x16x32_bf16 v[0:3], v[176:179], v[212:215], v[0:3]
	s_barrier
	s_movk_i32 s60, 0x100
	s_andn2_b64 vcc, exec, s[34:35]
	s_mov_b64 s[42:43], -1
	s_mov_b64 s[34:35], 0
	s_cbranch_vccz .LBB0_1246

.LBB0_1265:
	s_add_u32 s65, s18, 0x100
	s_addc_u32 s66, s19, 0
	s_mov_b32 s67, -2
	ds_read_b128 v[144:147], v151
	ds_read_b128 v[154:157], v151 offset:1024
	ds_read_b128 v[158:161], v151 offset:2048
	ds_read_b128 v[162:165], v151 offset:3072
	ds_read_b128 v[166:169], v152
	ds_read_b128 v[170:173], v152 offset:1024
	ds_read_b128 v[174:177], v152 offset:2048
	ds_read_b128 v[178:181], v152 offset:3072
	s_add_u32 s18, s16, 0x100
	s_addc_u32 s19, s17, 0
	s_cmp_eq_u32 s67, 2
	s_cselect_b32 s23, s5, s19
	s_cselect_b32 s22, s4, s18
	s_cselect_b32 s21, s15, s66
	s_cselect_b32 s20, s14, s65
	v_lshl_add_u64 v[216:217], s[16:17], 0, v[136:137]
	s_add_i32 m0, s31, 0xc000
	ds_read_b128 v[182:185], v153
	ds_read_b128 v[186:189], v153 offset:1024
	ds_read_b128 v[192:195], v153 offset:2048
	ds_read_b128 v[196:199], v153 offset:3072
	ds_read_b128 v[200:203], v153 offset:4096
	ds_read_b128 v[204:207], v153 offset:5120
	ds_read_b128 v[208:211], v153 offset:6144
	ds_read_b128 v[212:215], v153 offset:7168
	global_load_lds_dwordx4 v[216:217], off
	v_lshl_add_u64 v[216:217], s[16:17], 0, v[138:139]
	s_add_i32 m0, s31, 0xe000
	s_nop 0
	global_load_lds_dwordx4 v[216:217], off
	s_waitcnt vmcnt(8)
	s_waitcnt lgkmcnt(0)
	s_barrier
	v_mfma_f32_16x16x32_bf16 v[124:127], v[144:147], v[182:185], 0
	v_mfma_f32_16x16x32_bf16 v[120:123], v[158:161], v[182:185], 0
	v_mfma_f32_16x16x32_bf16 v[116:119], v[144:147], v[192:195], 0
	v_mfma_f32_16x16x32_bf16 v[108:111], v[158:161], v[192:195], 0
	v_mfma_f32_16x16x32_bf16 v[100:103], v[144:147], v[200:203], 0
	v_mfma_f32_16x16x32_bf16 v[92:95], v[158:161], v[200:203], 0
	v_mfma_f32_16x16x32_bf16 v[84:87], v[144:147], v[208:211], 0
	v_mfma_f32_16x16x32_bf16 v[76:79], v[158:161], v[208:211], 0
	v_mfma_f32_16x16x32_bf16 v[124:127], v[154:157], v[186:189], v[124:127]
	v_mfma_f32_16x16x32_bf16 v[120:123], v[162:165], v[186:189], v[120:123]
	v_mfma_f32_16x16x32_bf16 v[116:119], v[154:157], v[196:199], v[116:119]
	v_mfma_f32_16x16x32_bf16 v[108:111], v[162:165], v[196:199], v[108:111]
	v_mfma_f32_16x16x32_bf16 v[100:103], v[154:157], v[204:207], v[100:103]
	v_mfma_f32_16x16x32_bf16 v[92:95], v[162:165], v[204:207], v[92:95]
	v_mfma_f32_16x16x32_bf16 v[84:87], v[154:157], v[212:215], v[84:87]
	v_mfma_f32_16x16x32_bf16 v[76:79], v[162:165], v[212:215], v[76:79]
	v_mfma_f32_16x16x32_bf16 v[112:115], v[166:169], v[182:185], 0
	v_mfma_f32_16x16x32_bf16 v[104:107], v[174:177], v[182:185], 0
	v_mfma_f32_16x16x32_bf16 v[96:99], v[166:169], v[192:195], 0
	v_mfma_f32_16x16x32_bf16 v[88:91], v[174:177], v[192:195], 0
	v_mfma_f32_16x16x32_bf16 v[80:83], v[166:169], v[200:203], 0
	v_mfma_f32_16x16x32_bf16 v[72:75], v[174:177], v[200:203], 0
	v_mfma_f32_16x16x32_bf16 v[68:71], v[166:169], v[208:211], 0
	v_mfma_f32_16x16x32_bf16 v[64:67], v[174:177], v[208:211], 0
	v_mfma_f32_16x16x32_bf16 v[112:115], v[170:173], v[186:189], v[112:115]
	v_mfma_f32_16x16x32_bf16 v[104:107], v[178:181], v[186:189], v[104:107]
	v_mfma_f32_16x16x32_bf16 v[96:99], v[170:173], v[196:199], v[96:99]
	v_mfma_f32_16x16x32_bf16 v[88:91], v[178:181], v[196:199], v[88:91]
	v_mfma_f32_16x16x32_bf16 v[80:83], v[170:173], v[204:207], v[80:83]
	v_mfma_f32_16x16x32_bf16 v[72:75], v[178:181], v[204:207], v[72:75]
	v_mfma_f32_16x16x32_bf16 v[68:71], v[170:173], v[212:215], v[68:71]
	v_mfma_f32_16x16x32_bf16 v[64:67], v[178:181], v[212:215], v[64:67]
	s_barrier
	s_add_i32 s16, s60, s28
	v_lshl_add_u64 v[216:217], s[20:21], 0, v[132:133]
	s_mov_b32 m0, s16
	ds_read_b128 v[182:185], v153 offset:16384
	ds_read_b128 v[186:189], v153 offset:17408
	ds_read_b128 v[192:195], v153 offset:18432
	ds_read_b128 v[196:199], v153 offset:19456
	ds_read_b128 v[200:203], v153 offset:20480
	ds_read_b128 v[204:207], v153 offset:21504
	ds_read_b128 v[208:211], v153 offset:22528
	ds_read_b128 v[212:215], v153 offset:23552
	global_load_lds_dwordx4 v[216:217], off
	s_add_i32 m0, s16, 0x2000
	s_add_u32 s16, s20, 0x18000
	v_lshl_add_u64 v[218:219], s[20:21], 0, v[128:129]
	s_addc_u32 s17, s21, 0
	s_add_i32 s68, s61, s28
	global_load_lds_dwordx4 v[218:219], off
	s_mov_b32 m0, s68
	v_lshl_add_u64 v[222:223], s[22:23], 0, v[130:131]
	global_load_lds_dwordx4 v132, s[16:17]
	s_add_i32 m0, s68, 0x2000
	s_nop 0
	global_load_lds_dwordx4 v128, s[16:17]
	v_lshl_add_u64 v[220:221], s[22:23], 0, v[134:135]
	s_mov_b32 m0, s31
	s_nop 0
	global_load_lds_dwordx4 v[220:221], off
	s_mov_b32 m0, s33
	s_nop 0
	global_load_lds_dwordx4 v[222:223], off
	s_waitcnt vmcnt(8)
	s_waitcnt lgkmcnt(0)
	s_barrier
	v_mfma_f32_16x16x32_bf16 v[60:63], v[144:147], v[182:185], 0
	v_mfma_f32_16x16x32_bf16 v[56:59], v[158:161], v[182:185], 0
	v_mfma_f32_16x16x32_bf16 v[52:55], v[144:147], v[192:195], 0
	v_mfma_f32_16x16x32_bf16 v[44:47], v[158:161], v[192:195], 0
	v_mfma_f32_16x16x32_bf16 v[36:39], v[144:147], v[200:203], 0
	v_mfma_f32_16x16x32_bf16 v[28:31], v[158:161], v[200:203], 0
	v_mfma_f32_16x16x32_bf16 v[20:23], v[144:147], v[208:211], 0
	v_mfma_f32_16x16x32_bf16 v[12:15], v[158:161], v[208:211], 0
	v_mfma_f32_16x16x32_bf16 v[60:63], v[154:157], v[186:189], v[60:63]
	v_mfma_f32_16x16x32_bf16 v[56:59], v[162:165], v[186:189], v[56:59]
	v_mfma_f32_16x16x32_bf16 v[52:55], v[154:157], v[196:199], v[52:55]
	v_mfma_f32_16x16x32_bf16 v[44:47], v[162:165], v[196:199], v[44:47]
	v_mfma_f32_16x16x32_bf16 v[36:39], v[154:157], v[204:207], v[36:39]
	v_mfma_f32_16x16x32_bf16 v[28:31], v[162:165], v[204:207], v[28:31]
	v_mfma_f32_16x16x32_bf16 v[20:23], v[154:157], v[212:215], v[20:23]
	v_mfma_f32_16x16x32_bf16 v[12:15], v[162:165], v[212:215], v[12:15]
	v_mfma_f32_16x16x32_bf16 v[48:51], v[166:169], v[182:185], 0
	v_mfma_f32_16x16x32_bf16 v[40:43], v[174:177], v[182:185], 0
	v_mfma_f32_16x16x32_bf16 v[32:35], v[166:169], v[192:195], 0
	v_mfma_f32_16x16x32_bf16 v[24:27], v[174:177], v[192:195], 0
	v_mfma_f32_16x16x32_bf16 v[16:19], v[166:169], v[200:203], 0
	v_mfma_f32_16x16x32_bf16 v[8:11], v[174:177], v[200:203], 0
	v_mfma_f32_16x16x32_bf16 v[4:7], v[166:169], v[208:211], 0
	v_mfma_f32_16x16x32_bf16 v[0:3], v[174:177], v[208:211], 0
	v_mfma_f32_16x16x32_bf16 v[48:51], v[170:173], v[186:189], v[48:51]
	v_mfma_f32_16x16x32_bf16 v[40:43], v[178:181], v[186:189], v[40:43]
	v_mfma_f32_16x16x32_bf16 v[32:35], v[170:173], v[196:199], v[32:35]
	v_mfma_f32_16x16x32_bf16 v[24:27], v[178:181], v[196:199], v[24:27]
	v_mfma_f32_16x16x32_bf16 v[16:19], v[170:173], v[204:207], v[16:19]
	v_mfma_f32_16x16x32_bf16 v[8:11], v[178:181], v[204:207], v[8:11]
	v_mfma_f32_16x16x32_bf16 v[4:7], v[170:173], v[212:215], v[4:7]
	v_mfma_f32_16x16x32_bf16 v[0:3], v[178:181], v[212:215], v[0:3]
	s_barrier
	s_add_i32 s68, 0, 0x18000
	s_add_i32 s69, 0, 0x1c000
	v_add_u32_e32 v162, s68, v149
	v_add_u32_e32 v178, s69, v149
	ds_read_b128 v[144:147], v162
	ds_read_b128 v[154:157], v162 offset:1024
	ds_read_b128 v[158:161], v162 offset:2048
	ds_read_b128 v[162:165], v162 offset:3072
	ds_read_b128 v[166:169], v178
	ds_read_b128 v[170:173], v178 offset:1024
	ds_read_b128 v[174:177], v178 offset:2048
	ds_read_b128 v[178:181], v178 offset:3072
	s_add_u32 s16, s22, 0x18000
	s_addc_u32 s17, s23, 0
	s_mov_b32 m0, s34
	ds_read_b128 v[182:185], v153 offset:32768
	ds_read_b128 v[186:189], v153 offset:33792
	ds_read_b128 v[192:195], v153 offset:34816
	ds_read_b128 v[196:199], v153 offset:35840
	ds_read_b128 v[200:203], v153 offset:36864
	ds_read_b128 v[204:207], v153 offset:37888
	ds_read_b128 v[208:211], v153 offset:38912
	ds_read_b128 v[212:215], v153 offset:39936
	global_load_lds_dwordx4 v134, s[16:17]
	s_mov_b32 m0, s35
	s_nop 0
	global_load_lds_dwordx4 v130, s[16:17]
	s_waitcnt vmcnt(8)
	s_waitcnt lgkmcnt(0)
	s_barrier
	v_mfma_f32_16x16x32_bf16 v[124:127], v[144:147], v[182:185], v[124:127]
	v_mfma_f32_16x16x32_bf16 v[120:123], v[158:161], v[182:185], v[120:123]
	v_mfma_f32_16x16x32_bf16 v[116:119], v[144:147], v[192:195], v[116:119]
	v_mfma_f32_16x16x32_bf16 v[108:111], v[158:161], v[192:195], v[108:111]
	v_mfma_f32_16x16x32_bf16 v[100:103], v[144:147], v[200:203], v[100:103]
	v_mfma_f32_16x16x32_bf16 v[92:95], v[158:161], v[200:203], v[92:95]
	v_mfma_f32_16x16x32_bf16 v[84:87], v[144:147], v[208:211], v[84:87]
	v_mfma_f32_16x16x32_bf16 v[76:79], v[158:161], v[208:211], v[76:79]
	v_mfma_f32_16x16x32_bf16 v[124:127], v[154:157], v[186:189], v[124:127]
	v_mfma_f32_16x16x32_bf16 v[120:123], v[162:165], v[186:189], v[120:123]
	v_mfma_f32_16x16x32_bf16 v[116:119], v[154:157], v[196:199], v[116:119]
	v_mfma_f32_16x16x32_bf16 v[108:111], v[162:165], v[196:199], v[108:111]
	v_mfma_f32_16x16x32_bf16 v[100:103], v[154:157], v[204:207], v[100:103]
	v_mfma_f32_16x16x32_bf16 v[92:95], v[162:165], v[204:207], v[92:95]
	v_mfma_f32_16x16x32_bf16 v[84:87], v[154:157], v[212:215], v[84:87]
	v_mfma_f32_16x16x32_bf16 v[76:79], v[162:165], v[212:215], v[76:79]
	v_mfma_f32_16x16x32_bf16 v[112:115], v[166:169], v[182:185], v[112:115]
	v_mfma_f32_16x16x32_bf16 v[104:107], v[174:177], v[182:185], v[104:107]
	v_mfma_f32_16x16x32_bf16 v[96:99], v[166:169], v[192:195], v[96:99]
	v_mfma_f32_16x16x32_bf16 v[88:91], v[174:177], v[192:195], v[88:91]
	v_mfma_f32_16x16x32_bf16 v[80:83], v[166:169], v[200:203], v[80:83]
	v_mfma_f32_16x16x32_bf16 v[72:75], v[174:177], v[200:203], v[72:75]
	v_mfma_f32_16x16x32_bf16 v[68:71], v[166:169], v[208:211], v[68:71]
	v_mfma_f32_16x16x32_bf16 v[64:67], v[174:177], v[208:211], v[64:67]
	v_mfma_f32_16x16x32_bf16 v[112:115], v[170:173], v[186:189], v[112:115]
	v_mfma_f32_16x16x32_bf16 v[104:107], v[178:181], v[186:189], v[104:107]
	v_mfma_f32_16x16x32_bf16 v[96:99], v[170:173], v[196:199], v[96:99]
	v_mfma_f32_16x16x32_bf16 v[88:91], v[178:181], v[196:199], v[88:91]
	v_mfma_f32_16x16x32_bf16 v[80:83], v[170:173], v[204:207], v[80:83]
	v_mfma_f32_16x16x32_bf16 v[72:75], v[178:181], v[204:207], v[72:75]
	v_mfma_f32_16x16x32_bf16 v[68:71], v[170:173], v[212:215], v[68:71]
	v_mfma_f32_16x16x32_bf16 v[64:67], v[178:181], v[212:215], v[64:67]
	s_barrier
	s_add_i32 s16, s68, s28
	v_lshl_add_u64 v[216:217], v[216:217], 0, s[10:11]
	s_mov_b32 m0, s16
	ds_read_b128 v[182:185], v153 offset:49152
	ds_read_b128 v[186:189], v153 offset:50176
	ds_read_b128 v[192:195], v153 offset:51200
	ds_read_b128 v[196:199], v153 offset:52224
	ds_read_b128 v[200:203], v153 offset:53248
	ds_read_b128 v[204:207], v153 offset:54272
	ds_read_b128 v[208:211], v153 offset:55296
	ds_read_b128 v[212:215], v153 offset:56320
	global_load_lds_dwordx4 v[216:217], off
	s_add_i32 m0, s16, 0x2000
	s_add_u32 s16, s20, 0x18080
	v_lshl_add_u64 v[216:217], v[218:219], 0, s[10:11]
	s_addc_u32 s17, s21, 0
	s_add_i32 s20, s69, s28
	global_load_lds_dwordx4 v[216:217], off
	s_mov_b32 m0, s20
	s_nop 0
	global_load_lds_dwordx4 v132, s[16:17]
	s_add_i32 m0, s20, 0x2000
	s_nop 0
	global_load_lds_dwordx4 v128, s[16:17]
	v_lshl_add_u64 v[216:217], v[220:221], 0, s[10:11]
	s_mov_b32 m0, s43
	s_nop 0
	global_load_lds_dwordx4 v[216:217], off
	v_lshl_add_u64 v[216:217], v[222:223], 0, s[10:11]
	s_mov_b32 m0, s52
	s_nop 0
	global_load_lds_dwordx4 v[216:217], off
	s_waitcnt vmcnt(8)
	s_waitcnt lgkmcnt(0)
	s_barrier
	v_mfma_f32_16x16x32_bf16 v[60:63], v[144:147], v[182:185], v[60:63]
	v_mfma_f32_16x16x32_bf16 v[56:59], v[158:161], v[182:185], v[56:59]
	v_mfma_f32_16x16x32_bf16 v[52:55], v[144:147], v[192:195], v[52:55]
	v_mfma_f32_16x16x32_bf16 v[44:47], v[158:161], v[192:195], v[44:47]
	v_mfma_f32_16x16x32_bf16 v[36:39], v[144:147], v[200:203], v[36:39]
	v_mfma_f32_16x16x32_bf16 v[28:31], v[158:161], v[200:203], v[28:31]
	v_mfma_f32_16x16x32_bf16 v[20:23], v[144:147], v[208:211], v[20:23]
	v_mfma_f32_16x16x32_bf16 v[12:15], v[158:161], v[208:211], v[12:15]
	v_mfma_f32_16x16x32_bf16 v[60:63], v[154:157], v[186:189], v[60:63]
	v_mfma_f32_16x16x32_bf16 v[56:59], v[162:165], v[186:189], v[56:59]
	v_mfma_f32_16x16x32_bf16 v[52:55], v[154:157], v[196:199], v[52:55]
	v_mfma_f32_16x16x32_bf16 v[44:47], v[162:165], v[196:199], v[44:47]
	v_mfma_f32_16x16x32_bf16 v[36:39], v[154:157], v[204:207], v[36:39]
	v_mfma_f32_16x16x32_bf16 v[28:31], v[162:165], v[204:207], v[28:31]
	v_mfma_f32_16x16x32_bf16 v[20:23], v[154:157], v[212:215], v[20:23]
	v_mfma_f32_16x16x32_bf16 v[12:15], v[162:165], v[212:215], v[12:15]
	v_mfma_f32_16x16x32_bf16 v[48:51], v[166:169], v[182:185], v[48:51]
	v_mfma_f32_16x16x32_bf16 v[40:43], v[174:177], v[182:185], v[40:43]
	v_mfma_f32_16x16x32_bf16 v[32:35], v[166:169], v[192:195], v[32:35]
	v_mfma_f32_16x16x32_bf16 v[24:27], v[174:177], v[192:195], v[24:27]
	v_mfma_f32_16x16x32_bf16 v[16:19], v[166:169], v[200:203], v[16:19]
	v_mfma_f32_16x16x32_bf16 v[8:11], v[174:177], v[200:203], v[8:11]
	v_mfma_f32_16x16x32_bf16 v[4:7], v[166:169], v[208:211], v[4:7]
	v_mfma_f32_16x16x32_bf16 v[0:3], v[174:177], v[208:211], v[0:3]
	v_mfma_f32_16x16x32_bf16 v[48:51], v[170:173], v[186:189], v[48:51]
	v_mfma_f32_16x16x32_bf16 v[40:43], v[178:181], v[186:189], v[40:43]
	v_mfma_f32_16x16x32_bf16 v[32:35], v[170:173], v[196:199], v[32:35]
	v_mfma_f32_16x16x32_bf16 v[24:27], v[178:181], v[196:199], v[24:27]
	v_mfma_f32_16x16x32_bf16 v[16:19], v[170:173], v[204:207], v[16:19]
	v_mfma_f32_16x16x32_bf16 v[8:11], v[178:181], v[204:207], v[8:11]
	v_mfma_f32_16x16x32_bf16 v[4:7], v[170:173], v[212:215], v[4:7]
	v_mfma_f32_16x16x32_bf16 v[0:3], v[178:181], v[212:215], v[0:3]
	s_barrier
	s_add_i32 s67, s67, 2
	s_add_u32 s65, s65, 0x100
	s_addc_u32 s66, s66, 0
	s_cmp_gt_u32 s67, 3
	s_mov_b64 s[16:17], s[18:19]
	s_cbranch_scc0 .LBB0_1266
	s_branch .Lpeel_exit9
.LBB0_1266:
	ds_read_b128 v[144:147], v151
	ds_read_b128 v[154:157], v151 offset:1024
	ds_read_b128 v[158:161], v151 offset:2048
	ds_read_b128 v[162:165], v151 offset:3072
	ds_read_b128 v[166:169], v152
	ds_read_b128 v[170:173], v152 offset:1024
	ds_read_b128 v[174:177], v152 offset:2048
	ds_read_b128 v[178:181], v152 offset:3072
	s_add_u32 s18, s16, 0x100
	s_addc_u32 s19, s17, 0
	s_cmp_eq_u32 s67, 2
	s_cselect_b32 s23, s5, s19
	s_cselect_b32 s22, s4, s18
	s_cselect_b32 s21, s15, s66
	s_cselect_b32 s20, s14, s65
	v_lshl_add_u64 v[216:217], s[16:17], 0, v[136:137]
	s_add_i32 m0, s31, 0xc000
	ds_read_b128 v[182:185], v153
	ds_read_b128 v[186:189], v153 offset:1024
	ds_read_b128 v[192:195], v153 offset:2048
	ds_read_b128 v[196:199], v153 offset:3072
	ds_read_b128 v[200:203], v153 offset:4096
	ds_read_b128 v[204:207], v153 offset:5120
	ds_read_b128 v[208:211], v153 offset:6144
	ds_read_b128 v[212:215], v153 offset:7168
	global_load_lds_dwordx4 v[216:217], off
	v_lshl_add_u64 v[216:217], s[16:17], 0, v[138:139]
	s_add_i32 m0, s31, 0xe000
	s_nop 0
	global_load_lds_dwordx4 v[216:217], off
	s_waitcnt vmcnt(8)
	s_waitcnt lgkmcnt(0)
	s_barrier
	v_mfma_f32_16x16x32_bf16 v[124:127], v[144:147], v[182:185], v[124:127]
	v_mfma_f32_16x16x32_bf16 v[120:123], v[158:161], v[182:185], v[120:123]
	v_mfma_f32_16x16x32_bf16 v[116:119], v[144:147], v[192:195], v[116:119]
	v_mfma_f32_16x16x32_bf16 v[108:111], v[158:161], v[192:195], v[108:111]
	v_mfma_f32_16x16x32_bf16 v[100:103], v[144:147], v[200:203], v[100:103]
	v_mfma_f32_16x16x32_bf16 v[92:95], v[158:161], v[200:203], v[92:95]
	v_mfma_f32_16x16x32_bf16 v[84:87], v[144:147], v[208:211], v[84:87]
	v_mfma_f32_16x16x32_bf16 v[76:79], v[158:161], v[208:211], v[76:79]
	v_mfma_f32_16x16x32_bf16 v[124:127], v[154:157], v[186:189], v[124:127]
	v_mfma_f32_16x16x32_bf16 v[120:123], v[162:165], v[186:189], v[120:123]
	v_mfma_f32_16x16x32_bf16 v[116:119], v[154:157], v[196:199], v[116:119]
	v_mfma_f32_16x16x32_bf16 v[108:111], v[162:165], v[196:199], v[108:111]
	v_mfma_f32_16x16x32_bf16 v[100:103], v[154:157], v[204:207], v[100:103]
	v_mfma_f32_16x16x32_bf16 v[92:95], v[162:165], v[204:207], v[92:95]
	v_mfma_f32_16x16x32_bf16 v[84:87], v[154:157], v[212:215], v[84:87]
	v_mfma_f32_16x16x32_bf16 v[76:79], v[162:165], v[212:215], v[76:79]
	v_mfma_f32_16x16x32_bf16 v[112:115], v[166:169], v[182:185], v[112:115]
	v_mfma_f32_16x16x32_bf16 v[104:107], v[174:177], v[182:185], v[104:107]
	v_mfma_f32_16x16x32_bf16 v[96:99], v[166:169], v[192:195], v[96:99]
	v_mfma_f32_16x16x32_bf16 v[88:91], v[174:177], v[192:195], v[88:91]
	v_mfma_f32_16x16x32_bf16 v[80:83], v[166:169], v[200:203], v[80:83]
	v_mfma_f32_16x16x32_bf16 v[72:75], v[174:177], v[200:203], v[72:75]
	v_mfma_f32_16x16x32_bf16 v[68:71], v[166:169], v[208:211], v[68:71]
	v_mfma_f32_16x16x32_bf16 v[64:67], v[174:177], v[208:211], v[64:67]
	v_mfma_f32_16x16x32_bf16 v[112:115], v[170:173], v[186:189], v[112:115]
	v_mfma_f32_16x16x32_bf16 v[104:107], v[178:181], v[186:189], v[104:107]
	v_mfma_f32_16x16x32_bf16 v[96:99], v[170:173], v[196:199], v[96:99]
	v_mfma_f32_16x16x32_bf16 v[88:91], v[178:181], v[196:199], v[88:91]
	v_mfma_f32_16x16x32_bf16 v[80:83], v[170:173], v[204:207], v[80:83]
	v_mfma_f32_16x16x32_bf16 v[72:75], v[178:181], v[204:207], v[72:75]
	v_mfma_f32_16x16x32_bf16 v[68:71], v[170:173], v[212:215], v[68:71]
	v_mfma_f32_16x16x32_bf16 v[64:67], v[178:181], v[212:215], v[64:67]
	s_barrier
	s_add_i32 s16, s60, s28
	v_lshl_add_u64 v[216:217], s[20:21], 0, v[132:133]
	s_mov_b32 m0, s16
	ds_read_b128 v[182:185], v153 offset:16384
	ds_read_b128 v[186:189], v153 offset:17408
	ds_read_b128 v[192:195], v153 offset:18432
	ds_read_b128 v[196:199], v153 offset:19456
	ds_read_b128 v[200:203], v153 offset:20480
	ds_read_b128 v[204:207], v153 offset:21504
	ds_read_b128 v[208:211], v153 offset:22528
	ds_read_b128 v[212:215], v153 offset:23552
	global_load_lds_dwordx4 v[216:217], off
	s_add_i32 m0, s16, 0x2000
	s_add_u32 s16, s20, 0x18000
	v_lshl_add_u64 v[218:219], s[20:21], 0, v[128:129]
	s_addc_u32 s17, s21, 0
	s_add_i32 s68, s61, s28
	global_load_lds_dwordx4 v[218:219], off
	s_mov_b32 m0, s68
	v_lshl_add_u64 v[222:223], s[22:23], 0, v[130:131]
	global_load_lds_dwordx4 v132, s[16:17]
	s_add_i32 m0, s68, 0x2000
	s_nop 0
	global_load_lds_dwordx4 v128, s[16:17]
	v_lshl_add_u64 v[220:221], s[22:23], 0, v[134:135]
	s_mov_b32 m0, s31
	s_nop 0
	global_load_lds_dwordx4 v[220:221], off
	s_mov_b32 m0, s33
	s_nop 0
	global_load_lds_dwordx4 v[222:223], off
	s_waitcnt vmcnt(8)
	s_waitcnt lgkmcnt(0)
	s_barrier
	v_mfma_f32_16x16x32_bf16 v[60:63], v[144:147], v[182:185], v[60:63]
	v_mfma_f32_16x16x32_bf16 v[56:59], v[158:161], v[182:185], v[56:59]
	v_mfma_f32_16x16x32_bf16 v[52:55], v[144:147], v[192:195], v[52:55]
	v_mfma_f32_16x16x32_bf16 v[44:47], v[158:161], v[192:195], v[44:47]
	v_mfma_f32_16x16x32_bf16 v[36:39], v[144:147], v[200:203], v[36:39]
	v_mfma_f32_16x16x32_bf16 v[28:31], v[158:161], v[200:203], v[28:31]
	v_mfma_f32_16x16x32_bf16 v[20:23], v[144:147], v[208:211], v[20:23]
	v_mfma_f32_16x16x32_bf16 v[12:15], v[158:161], v[208:211], v[12:15]
	v_mfma_f32_16x16x32_bf16 v[60:63], v[154:157], v[186:189], v[60:63]
	v_mfma_f32_16x16x32_bf16 v[56:59], v[162:165], v[186:189], v[56:59]
	v_mfma_f32_16x16x32_bf16 v[52:55], v[154:157], v[196:199], v[52:55]
	v_mfma_f32_16x16x32_bf16 v[44:47], v[162:165], v[196:199], v[44:47]
	v_mfma_f32_16x16x32_bf16 v[36:39], v[154:157], v[204:207], v[36:39]
	v_mfma_f32_16x16x32_bf16 v[28:31], v[162:165], v[204:207], v[28:31]
	v_mfma_f32_16x16x32_bf16 v[20:23], v[154:157], v[212:215], v[20:23]
	v_mfma_f32_16x16x32_bf16 v[12:15], v[162:165], v[212:215], v[12:15]
	v_mfma_f32_16x16x32_bf16 v[48:51], v[166:169], v[182:185], v[48:51]
	v_mfma_f32_16x16x32_bf16 v[40:43], v[174:177], v[182:185], v[40:43]
	v_mfma_f32_16x16x32_bf16 v[32:35], v[166:169], v[192:195], v[32:35]
	v_mfma_f32_16x16x32_bf16 v[24:27], v[174:177], v[192:195], v[24:27]
	v_mfma_f32_16x16x32_bf16 v[16:19], v[166:169], v[200:203], v[16:19]
	v_mfma_f32_16x16x32_bf16 v[8:11], v[174:177], v[200:203], v[8:11]
	v_mfma_f32_16x16x32_bf16 v[4:7], v[166:169], v[208:211], v[4:7]
	v_mfma_f32_16x16x32_bf16 v[0:3], v[174:177], v[208:211], v[0:3]
	v_mfma_f32_16x16x32_bf16 v[48:51], v[170:173], v[186:189], v[48:51]
	v_mfma_f32_16x16x32_bf16 v[40:43], v[178:181], v[186:189], v[40:43]
	v_mfma_f32_16x16x32_bf16 v[32:35], v[170:173], v[196:199], v[32:35]
	v_mfma_f32_16x16x32_bf16 v[24:27], v[178:181], v[196:199], v[24:27]
	v_mfma_f32_16x16x32_bf16 v[16:19], v[170:173], v[204:207], v[16:19]
	v_mfma_f32_16x16x32_bf16 v[8:11], v[178:181], v[204:207], v[8:11]
	v_mfma_f32_16x16x32_bf16 v[4:7], v[170:173], v[212:215], v[4:7]
	v_mfma_f32_16x16x32_bf16 v[0:3], v[178:181], v[212:215], v[0:3]
	s_barrier
	s_add_i32 s68, 0, 0x18000
	s_add_i32 s69, 0, 0x1c000
	v_add_u32_e32 v162, s68, v149
	v_add_u32_e32 v178, s69, v149
	ds_read_b128 v[144:147], v162
	ds_read_b128 v[154:157], v162 offset:1024
	ds_read_b128 v[158:161], v162 offset:2048
	ds_read_b128 v[162:165], v162 offset:3072
	ds_read_b128 v[166:169], v178
	ds_read_b128 v[170:173], v178 offset:1024
	ds_read_b128 v[174:177], v178 offset:2048
	ds_read_b128 v[178:181], v178 offset:3072
	s_add_u32 s16, s22, 0x18000
	s_addc_u32 s17, s23, 0
	s_mov_b32 m0, s34
	ds_read_b128 v[182:185], v153 offset:32768
	ds_read_b128 v[186:189], v153 offset:33792
	ds_read_b128 v[192:195], v153 offset:34816
	ds_read_b128 v[196:199], v153 offset:35840
	ds_read_b128 v[200:203], v153 offset:36864
	ds_read_b128 v[204:207], v153 offset:37888
	ds_read_b128 v[208:211], v153 offset:38912
	ds_read_b128 v[212:215], v153 offset:39936
	global_load_lds_dwordx4 v134, s[16:17]
	s_mov_b32 m0, s35
	s_nop 0
	global_load_lds_dwordx4 v130, s[16:17]
	s_waitcnt vmcnt(8)
	s_waitcnt lgkmcnt(0)
	s_barrier
	v_mfma_f32_16x16x32_bf16 v[124:127], v[144:147], v[182:185], v[124:127]
	v_mfma_f32_16x16x32_bf16 v[120:123], v[158:161], v[182:185], v[120:123]
	v_mfma_f32_16x16x32_bf16 v[116:119], v[144:147], v[192:195], v[116:119]
	v_mfma_f32_16x16x32_bf16 v[108:111], v[158:161], v[192:195], v[108:111]
	v_mfma_f32_16x16x32_bf16 v[100:103], v[144:147], v[200:203], v[100:103]
	v_mfma_f32_16x16x32_bf16 v[92:95], v[158:161], v[200:203], v[92:95]
	v_mfma_f32_16x16x32_bf16 v[84:87], v[144:147], v[208:211], v[84:87]
	v_mfma_f32_16x16x32_bf16 v[76:79], v[158:161], v[208:211], v[76:79]
	v_mfma_f32_16x16x32_bf16 v[124:127], v[154:157], v[186:189], v[124:127]
	v_mfma_f32_16x16x32_bf16 v[120:123], v[162:165], v[186:189], v[120:123]
	v_mfma_f32_16x16x32_bf16 v[116:119], v[154:157], v[196:199], v[116:119]
	v_mfma_f32_16x16x32_bf16 v[108:111], v[162:165], v[196:199], v[108:111]
	v_mfma_f32_16x16x32_bf16 v[100:103], v[154:157], v[204:207], v[100:103]
	v_mfma_f32_16x16x32_bf16 v[92:95], v[162:165], v[204:207], v[92:95]
	v_mfma_f32_16x16x32_bf16 v[84:87], v[154:157], v[212:215], v[84:87]
	v_mfma_f32_16x16x32_bf16 v[76:79], v[162:165], v[212:215], v[76:79]
	v_mfma_f32_16x16x32_bf16 v[112:115], v[166:169], v[182:185], v[112:115]
	v_mfma_f32_16x16x32_bf16 v[104:107], v[174:177], v[182:185], v[104:107]
	v_mfma_f32_16x16x32_bf16 v[96:99], v[166:169], v[192:195], v[96:99]
	v_mfma_f32_16x16x32_bf16 v[88:91], v[174:177], v[192:195], v[88:91]
	v_mfma_f32_16x16x32_bf16 v[80:83], v[166:169], v[200:203], v[80:83]
	v_mfma_f32_16x16x32_bf16 v[72:75], v[174:177], v[200:203], v[72:75]
	v_mfma_f32_16x16x32_bf16 v[68:71], v[166:169], v[208:211], v[68:71]
	v_mfma_f32_16x16x32_bf16 v[64:67], v[174:177], v[208:211], v[64:67]
	v_mfma_f32_16x16x32_bf16 v[112:115], v[170:173], v[186:189], v[112:115]
	v_mfma_f32_16x16x32_bf16 v[104:107], v[178:181], v[186:189], v[104:107]
	v_mfma_f32_16x16x32_bf16 v[96:99], v[170:173], v[196:199], v[96:99]
	v_mfma_f32_16x16x32_bf16 v[88:91], v[178:181], v[196:199], v[88:91]
	v_mfma_f32_16x16x32_bf16 v[80:83], v[170:173], v[204:207], v[80:83]
	v_mfma_f32_16x16x32_bf16 v[72:75], v[178:181], v[204:207], v[72:75]
	v_mfma_f32_16x16x32_bf16 v[68:71], v[170:173], v[212:215], v[68:71]
	v_mfma_f32_16x16x32_bf16 v[64:67], v[178:181], v[212:215], v[64:67]
	s_barrier
	s_add_i32 s16, s68, s28
	v_lshl_add_u64 v[216:217], v[216:217], 0, s[10:11]
	s_mov_b32 m0, s16
	ds_read_b128 v[182:185], v153 offset:49152
	ds_read_b128 v[186:189], v153 offset:50176
	ds_read_b128 v[192:195], v153 offset:51200
	ds_read_b128 v[196:199], v153 offset:52224
	ds_read_b128 v[200:203], v153 offset:53248
	ds_read_b128 v[204:207], v153 offset:54272
	ds_read_b128 v[208:211], v153 offset:55296
	ds_read_b128 v[212:215], v153 offset:56320
	global_load_lds_dwordx4 v[216:217], off
	s_add_i32 m0, s16, 0x2000
	s_add_u32 s16, s20, 0x18080
	v_lshl_add_u64 v[216:217], v[218:219], 0, s[10:11]
	s_addc_u32 s17, s21, 0
	s_add_i32 s20, s69, s28
	global_load_lds_dwordx4 v[216:217], off
	s_mov_b32 m0, s20
	s_nop 0
	global_load_lds_dwordx4 v132, s[16:17]
	s_add_i32 m0, s20, 0x2000
	s_nop 0
	global_load_lds_dwordx4 v128, s[16:17]
	v_lshl_add_u64 v[216:217], v[220:221], 0, s[10:11]
	s_mov_b32 m0, s43
	s_nop 0
	global_load_lds_dwordx4 v[216:217], off
	v_lshl_add_u64 v[216:217], v[222:223], 0, s[10:11]
	s_mov_b32 m0, s52
	s_nop 0
	global_load_lds_dwordx4 v[216:217], off
	s_waitcnt vmcnt(8)
	s_waitcnt lgkmcnt(0)
	s_barrier
	v_mfma_f32_16x16x32_bf16 v[60:63], v[144:147], v[182:185], v[60:63]
	v_mfma_f32_16x16x32_bf16 v[56:59], v[158:161], v[182:185], v[56:59]
	v_mfma_f32_16x16x32_bf16 v[52:55], v[144:147], v[192:195], v[52:55]
	v_mfma_f32_16x16x32_bf16 v[44:47], v[158:161], v[192:195], v[44:47]
	v_mfma_f32_16x16x32_bf16 v[36:39], v[144:147], v[200:203], v[36:39]
	v_mfma_f32_16x16x32_bf16 v[28:31], v[158:161], v[200:203], v[28:31]
	v_mfma_f32_16x16x32_bf16 v[20:23], v[144:147], v[208:211], v[20:23]
	v_mfma_f32_16x16x32_bf16 v[12:15], v[158:161], v[208:211], v[12:15]
	v_mfma_f32_16x16x32_bf16 v[60:63], v[154:157], v[186:189], v[60:63]
	v_mfma_f32_16x16x32_bf16 v[56:59], v[162:165], v[186:189], v[56:59]
	v_mfma_f32_16x16x32_bf16 v[52:55], v[154:157], v[196:199], v[52:55]
	v_mfma_f32_16x16x32_bf16 v[44:47], v[162:165], v[196:199], v[44:47]
	v_mfma_f32_16x16x32_bf16 v[36:39], v[154:157], v[204:207], v[36:39]
	v_mfma_f32_16x16x32_bf16 v[28:31], v[162:165], v[204:207], v[28:31]
	v_mfma_f32_16x16x32_bf16 v[20:23], v[154:157], v[212:215], v[20:23]
	v_mfma_f32_16x16x32_bf16 v[12:15], v[162:165], v[212:215], v[12:15]
	v_mfma_f32_16x16x32_bf16 v[48:51], v[166:169], v[182:185], v[48:51]
	v_mfma_f32_16x16x32_bf16 v[40:43], v[174:177], v[182:185], v[40:43]
	v_mfma_f32_16x16x32_bf16 v[32:35], v[166:169], v[192:195], v[32:35]
	v_mfma_f32_16x16x32_bf16 v[24:27], v[174:177], v[192:195], v[24:27]
	v_mfma_f32_16x16x32_bf16 v[16:19], v[166:169], v[200:203], v[16:19]
	v_mfma_f32_16x16x32_bf16 v[8:11], v[174:177], v[200:203], v[8:11]
	v_mfma_f32_16x16x32_bf16 v[4:7], v[166:169], v[208:211], v[4:7]
	v_mfma_f32_16x16x32_bf16 v[0:3], v[174:177], v[208:211], v[0:3]
	v_mfma_f32_16x16x32_bf16 v[48:51], v[170:173], v[186:189], v[48:51]
	v_mfma_f32_16x16x32_bf16 v[40:43], v[178:181], v[186:189], v[40:43]
	v_mfma_f32_16x16x32_bf16 v[32:35], v[170:173], v[196:199], v[32:35]
	v_mfma_f32_16x16x32_bf16 v[24:27], v[178:181], v[196:199], v[24:27]
	v_mfma_f32_16x16x32_bf16 v[16:19], v[170:173], v[204:207], v[16:19]
	v_mfma_f32_16x16x32_bf16 v[8:11], v[178:181], v[204:207], v[8:11]
	v_mfma_f32_16x16x32_bf16 v[4:7], v[170:173], v[212:215], v[4:7]
	v_mfma_f32_16x16x32_bf16 v[0:3], v[178:181], v[212:215], v[0:3]
	s_barrier
	s_add_i32 s67, s67, 2
	s_add_u32 s65, s65, 0x100
	s_addc_u32 s66, s66, 0
	s_cmp_gt_u32 s67, 3
	s_mov_b64 s[16:17], s[18:19]
	s_cbranch_scc0 .LBB0_1266

.LBB0_1433:
	s_ashr_i32 s23, s22, 31
	s_lshl_b64 s[24:25], s[22:23], 19
	s_add_u32 s24, s56, s24
	s_addc_u32 s25, s57, s25
	s_and_b64 s[26:27], s[0:1], exec
	s_cselect_b32 s23, s25, s31
	s_cselect_b32 s55, s24, s30
	s_ashr_i32 s21, s20, 31
	s_lshl_b64 s[26:27], s[20:21], 19
	s_add_u32 s26, s53, s26
	s_addc_u32 s27, s60, s27
	s_and_b64 s[42:43], s[0:1], exec
	s_cselect_b32 s21, s27, s35
	s_cselect_b32 s74, s26, s34
	s_add_u32 s30, s30, 0x40080
	s_addc_u32 s31, s31, 0
	s_add_u32 s75, s34, 0x100
	s_addc_u32 s76, s35, 0
	s_mov_b32 s77, -2
	ds_read_b128 v[152:155], v149
	ds_read_b128 v[156:159], v149 offset:1024
	ds_read_b128 v[160:163], v149 offset:2048
	ds_read_b128 v[164:167], v149 offset:3072
	ds_read_b128 v[168:171], v150
	ds_read_b128 v[172:175], v150 offset:1024
	ds_read_b128 v[176:179], v150 offset:2048
	ds_read_b128 v[180:183], v150 offset:3072
	s_add_u32 s34, s30, 0xfffc0080
	s_addc_u32 s35, s31, -1
	s_cmp_eq_u32 s77, 12
	s_cselect_b32 s43, s23, s35
	s_cselect_b32 s42, s55, s34
	s_cselect_b32 s35, s21, s76
	s_cselect_b32 s34, s74, s75
	s_add_i32 m0, s29, 0xc000
	ds_read_b128 v[184:187], v151
	ds_read_b128 v[192:195], v151 offset:1024
	ds_read_b128 v[196:199], v151 offset:2048
	ds_read_b128 v[200:203], v151 offset:3072
	ds_read_b128 v[204:207], v151 offset:4096
	ds_read_b128 v[208:211], v151 offset:5120
	ds_read_b128 v[212:215], v151 offset:6144
	ds_read_b128 v[216:219], v151 offset:7168
	global_load_lds_dwordx4 v136, s[30:31]
	s_add_i32 m0, s29, 0xe000
	s_nop 0
	global_load_lds_dwordx4 v138, s[30:31]
	s_waitcnt vmcnt(8)
	s_waitcnt lgkmcnt(0)
	s_barrier
	v_mfma_f32_16x16x32_bf16 v[124:127], v[152:155], v[184:187], 0
	v_mfma_f32_16x16x32_bf16 v[120:123], v[160:163], v[184:187], 0
	v_mfma_f32_16x16x32_bf16 v[116:119], v[152:155], v[196:199], 0
	v_mfma_f32_16x16x32_bf16 v[108:111], v[160:163], v[196:199], 0
	v_mfma_f32_16x16x32_bf16 v[100:103], v[152:155], v[204:207], 0
	v_mfma_f32_16x16x32_bf16 v[92:95], v[160:163], v[204:207], 0
	v_mfma_f32_16x16x32_bf16 v[84:87], v[152:155], v[212:215], 0
	v_mfma_f32_16x16x32_bf16 v[76:79], v[160:163], v[212:215], 0
	v_mfma_f32_16x16x32_bf16 v[124:127], v[156:159], v[192:195], v[124:127]
	v_mfma_f32_16x16x32_bf16 v[120:123], v[164:167], v[192:195], v[120:123]
	v_mfma_f32_16x16x32_bf16 v[116:119], v[156:159], v[200:203], v[116:119]
	v_mfma_f32_16x16x32_bf16 v[108:111], v[164:167], v[200:203], v[108:111]
	v_mfma_f32_16x16x32_bf16 v[100:103], v[156:159], v[208:211], v[100:103]
	v_mfma_f32_16x16x32_bf16 v[92:95], v[164:167], v[208:211], v[92:95]
	v_mfma_f32_16x16x32_bf16 v[84:87], v[156:159], v[216:219], v[84:87]
	v_mfma_f32_16x16x32_bf16 v[76:79], v[164:167], v[216:219], v[76:79]
	v_mfma_f32_16x16x32_bf16 v[112:115], v[168:171], v[184:187], 0
	v_mfma_f32_16x16x32_bf16 v[104:107], v[176:179], v[184:187], 0
	v_mfma_f32_16x16x32_bf16 v[96:99], v[168:171], v[196:199], 0
	v_mfma_f32_16x16x32_bf16 v[88:91], v[176:179], v[196:199], 0
	v_mfma_f32_16x16x32_bf16 v[80:83], v[168:171], v[204:207], 0
	v_mfma_f32_16x16x32_bf16 v[72:75], v[176:179], v[204:207], 0
	v_mfma_f32_16x16x32_bf16 v[68:71], v[168:171], v[212:215], 0
	v_mfma_f32_16x16x32_bf16 v[64:67], v[176:179], v[212:215], 0
	v_mfma_f32_16x16x32_bf16 v[112:115], v[172:175], v[192:195], v[112:115]
	v_mfma_f32_16x16x32_bf16 v[104:107], v[180:183], v[192:195], v[104:107]
	v_mfma_f32_16x16x32_bf16 v[96:99], v[172:175], v[200:203], v[96:99]
	v_mfma_f32_16x16x32_bf16 v[88:91], v[180:183], v[200:203], v[88:91]
	v_mfma_f32_16x16x32_bf16 v[80:83], v[172:175], v[208:211], v[80:83]
	v_mfma_f32_16x16x32_bf16 v[72:75], v[180:183], v[208:211], v[72:75]
	v_mfma_f32_16x16x32_bf16 v[68:71], v[172:175], v[216:219], v[68:71]
	v_mfma_f32_16x16x32_bf16 v[64:67], v[180:183], v[216:219], v[64:67]
	s_barrier
	s_add_i32 s79, s68, s61
	v_lshl_add_u64 v[144:145], s[34:35], 0, v[130:131]
	s_mov_b32 m0, s79
	ds_read_b128 v[184:187], v151 offset:16384
	ds_read_b128 v[192:195], v151 offset:17408
	ds_read_b128 v[196:199], v151 offset:18432
	ds_read_b128 v[200:203], v151 offset:19456
	ds_read_b128 v[204:207], v151 offset:20480
	ds_read_b128 v[208:211], v151 offset:21504
	ds_read_b128 v[212:215], v151 offset:22528
	ds_read_b128 v[216:219], v151 offset:23552
	global_load_lds_dwordx4 v[144:145], off
	s_add_i32 m0, s79, 0x2000
	s_add_u32 s80, s34, 0x40000
	v_lshl_add_u64 v[188:189], s[34:35], 0, v[134:135]
	s_addc_u32 s81, s35, 0
	s_add_i32 s79, s69, s61
	global_load_lds_dwordx4 v[188:189], off
	s_mov_b32 m0, s79
	v_lshl_add_u64 v[222:223], s[42:43], 0, v[132:133]
	global_load_lds_dwordx4 v130, s[80:81]
	s_add_i32 m0, s79, 0x2000
	s_nop 0
	global_load_lds_dwordx4 v134, s[80:81]
	v_lshl_add_u64 v[220:221], s[42:43], 0, v[128:129]
	s_mov_b32 m0, s29
	s_nop 0
	global_load_lds_dwordx4 v[220:221], off
	s_mov_b32 m0, s33
	s_nop 0
	global_load_lds_dwordx4 v[222:223], off
	s_waitcnt vmcnt(8)
	s_waitcnt lgkmcnt(0)
	s_barrier
	v_mfma_f32_16x16x32_bf16 v[60:63], v[152:155], v[184:187], 0
	v_mfma_f32_16x16x32_bf16 v[56:59], v[160:163], v[184:187], 0
	v_mfma_f32_16x16x32_bf16 v[52:55], v[152:155], v[196:199], 0
	v_mfma_f32_16x16x32_bf16 v[44:47], v[160:163], v[196:199], 0
	v_mfma_f32_16x16x32_bf16 v[36:39], v[152:155], v[204:207], 0
	v_mfma_f32_16x16x32_bf16 v[28:31], v[160:163], v[204:207], 0
	v_mfma_f32_16x16x32_bf16 v[20:23], v[152:155], v[212:215], 0
	v_mfma_f32_16x16x32_bf16 v[12:15], v[160:163], v[212:215], 0
	v_mfma_f32_16x16x32_bf16 v[60:63], v[156:159], v[192:195], v[60:63]
	v_mfma_f32_16x16x32_bf16 v[56:59], v[164:167], v[192:195], v[56:59]
	v_mfma_f32_16x16x32_bf16 v[52:55], v[156:159], v[200:203], v[52:55]
	v_mfma_f32_16x16x32_bf16 v[44:47], v[164:167], v[200:203], v[44:47]
	v_mfma_f32_16x16x32_bf16 v[36:39], v[156:159], v[208:211], v[36:39]
	v_mfma_f32_16x16x32_bf16 v[28:31], v[164:167], v[208:211], v[28:31]
	v_mfma_f32_16x16x32_bf16 v[20:23], v[156:159], v[216:219], v[20:23]
	v_mfma_f32_16x16x32_bf16 v[12:15], v[164:167], v[216:219], v[12:15]
	v_mfma_f32_16x16x32_bf16 v[48:51], v[168:171], v[184:187], 0
	v_mfma_f32_16x16x32_bf16 v[40:43], v[176:179], v[184:187], 0
	v_mfma_f32_16x16x32_bf16 v[32:35], v[168:171], v[196:199], 0
	v_mfma_f32_16x16x32_bf16 v[24:27], v[176:179], v[196:199], 0
	v_mfma_f32_16x16x32_bf16 v[16:19], v[168:171], v[204:207], 0
	v_mfma_f32_16x16x32_bf16 v[8:11], v[176:179], v[204:207], 0
	v_mfma_f32_16x16x32_bf16 v[4:7], v[168:171], v[212:215], 0
	v_mfma_f32_16x16x32_bf16 v[0:3], v[176:179], v[212:215], 0
	v_mfma_f32_16x16x32_bf16 v[48:51], v[172:175], v[192:195], v[48:51]
	v_mfma_f32_16x16x32_bf16 v[40:43], v[180:183], v[192:195], v[40:43]
	v_mfma_f32_16x16x32_bf16 v[32:35], v[172:175], v[200:203], v[32:35]
	v_mfma_f32_16x16x32_bf16 v[24:27], v[180:183], v[200:203], v[24:27]
	v_mfma_f32_16x16x32_bf16 v[16:19], v[172:175], v[208:211], v[16:19]
	v_mfma_f32_16x16x32_bf16 v[8:11], v[180:183], v[208:211], v[8:11]
	v_mfma_f32_16x16x32_bf16 v[4:7], v[172:175], v[216:219], v[4:7]
	v_mfma_f32_16x16x32_bf16 v[0:3], v[180:183], v[216:219], v[0:3]
	s_barrier
	s_add_i32 s79, 0, 0x18000
	s_add_i32 s80, 0, 0x1c000
	v_add_u32_e32 v164, s79, v147
	v_add_u32_e32 v180, s80, v147
	ds_read_b128 v[152:155], v164
	ds_read_b128 v[156:159], v164 offset:1024
	ds_read_b128 v[160:163], v164 offset:2048
	ds_read_b128 v[164:167], v164 offset:3072
	ds_read_b128 v[168:171], v180
	ds_read_b128 v[172:175], v180 offset:1024
	ds_read_b128 v[176:179], v180 offset:2048
	ds_read_b128 v[180:183], v180 offset:3072
	s_add_u32 s42, s42, 0x40000
	s_addc_u32 s43, s43, 0
	s_mov_b32 m0, s62
	ds_read_b128 v[184:187], v151 offset:32768
	ds_read_b128 v[192:195], v151 offset:33792
	ds_read_b128 v[196:199], v151 offset:34816
	ds_read_b128 v[200:203], v151 offset:35840
	ds_read_b128 v[204:207], v151 offset:36864
	ds_read_b128 v[208:211], v151 offset:37888
	ds_read_b128 v[212:215], v151 offset:38912
	ds_read_b128 v[216:219], v151 offset:39936
	global_load_lds_dwordx4 v128, s[42:43]
	s_mov_b32 m0, s63
	s_nop 0
	global_load_lds_dwordx4 v132, s[42:43]
	s_waitcnt vmcnt(8)
	s_waitcnt lgkmcnt(0)
	s_barrier
	v_mfma_f32_16x16x32_bf16 v[124:127], v[152:155], v[184:187], v[124:127]
	v_mfma_f32_16x16x32_bf16 v[120:123], v[160:163], v[184:187], v[120:123]
	v_mfma_f32_16x16x32_bf16 v[116:119], v[152:155], v[196:199], v[116:119]
	v_mfma_f32_16x16x32_bf16 v[108:111], v[160:163], v[196:199], v[108:111]
	v_mfma_f32_16x16x32_bf16 v[100:103], v[152:155], v[204:207], v[100:103]
	v_mfma_f32_16x16x32_bf16 v[92:95], v[160:163], v[204:207], v[92:95]
	v_mfma_f32_16x16x32_bf16 v[84:87], v[152:155], v[212:215], v[84:87]
	v_mfma_f32_16x16x32_bf16 v[76:79], v[160:163], v[212:215], v[76:79]
	v_mfma_f32_16x16x32_bf16 v[124:127], v[156:159], v[192:195], v[124:127]
	v_mfma_f32_16x16x32_bf16 v[120:123], v[164:167], v[192:195], v[120:123]
	v_mfma_f32_16x16x32_bf16 v[116:119], v[156:159], v[200:203], v[116:119]
	v_mfma_f32_16x16x32_bf16 v[108:111], v[164:167], v[200:203], v[108:111]
	v_mfma_f32_16x16x32_bf16 v[100:103], v[156:159], v[208:211], v[100:103]
	v_mfma_f32_16x16x32_bf16 v[92:95], v[164:167], v[208:211], v[92:95]
	v_mfma_f32_16x16x32_bf16 v[84:87], v[156:159], v[216:219], v[84:87]
	v_mfma_f32_16x16x32_bf16 v[76:79], v[164:167], v[216:219], v[76:79]
	v_mfma_f32_16x16x32_bf16 v[112:115], v[168:171], v[184:187], v[112:115]
	v_mfma_f32_16x16x32_bf16 v[104:107], v[176:179], v[184:187], v[104:107]
	v_mfma_f32_16x16x32_bf16 v[96:99], v[168:171], v[196:199], v[96:99]
	v_mfma_f32_16x16x32_bf16 v[88:91], v[176:179], v[196:199], v[88:91]
	v_mfma_f32_16x16x32_bf16 v[80:83], v[168:171], v[204:207], v[80:83]
	v_mfma_f32_16x16x32_bf16 v[72:75], v[176:179], v[204:207], v[72:75]
	v_mfma_f32_16x16x32_bf16 v[68:71], v[168:171], v[212:215], v[68:71]
	v_mfma_f32_16x16x32_bf16 v[64:67], v[176:179], v[212:215], v[64:67]
	v_mfma_f32_16x16x32_bf16 v[112:115], v[172:175], v[192:195], v[112:115]
	v_mfma_f32_16x16x32_bf16 v[104:107], v[180:183], v[192:195], v[104:107]
	v_mfma_f32_16x16x32_bf16 v[96:99], v[172:175], v[200:203], v[96:99]
	v_mfma_f32_16x16x32_bf16 v[88:91], v[180:183], v[200:203], v[88:91]
	v_mfma_f32_16x16x32_bf16 v[80:83], v[172:175], v[208:211], v[80:83]
	v_mfma_f32_16x16x32_bf16 v[72:75], v[180:183], v[208:211], v[72:75]
	v_mfma_f32_16x16x32_bf16 v[68:71], v[172:175], v[216:219], v[68:71]
	v_mfma_f32_16x16x32_bf16 v[64:67], v[180:183], v[216:219], v[64:67]
	s_barrier
	s_add_i32 s42, s79, s61
	v_lshl_add_u64 v[144:145], v[144:145], 0, s[10:11]
	s_mov_b32 m0, s42
	ds_read_b128 v[184:187], v151 offset:49152
	ds_read_b128 v[192:195], v151 offset:50176
	ds_read_b128 v[196:199], v151 offset:51200
	ds_read_b128 v[200:203], v151 offset:52224
	ds_read_b128 v[204:207], v151 offset:53248
	ds_read_b128 v[208:211], v151 offset:54272
	ds_read_b128 v[212:215], v151 offset:55296
	ds_read_b128 v[216:219], v151 offset:56320
	global_load_lds_dwordx4 v[144:145], off
	s_add_i32 m0, s42, 0x2000
	s_add_u32 s34, s34, 0x40080
	v_lshl_add_u64 v[144:145], v[188:189], 0, s[10:11]
	s_addc_u32 s35, s35, 0
	s_add_i32 s42, s80, s61
	global_load_lds_dwordx4 v[144:145], off
	s_mov_b32 m0, s42
	s_nop 0
	global_load_lds_dwordx4 v130, s[34:35]
	s_add_i32 m0, s42, 0x2000
	s_nop 0
	global_load_lds_dwordx4 v134, s[34:35]
	v_lshl_add_u64 v[144:145], v[220:221], 0, s[10:11]
	s_mov_b32 m0, s65
	s_nop 0
	global_load_lds_dwordx4 v[144:145], off
	v_lshl_add_u64 v[144:145], v[222:223], 0, s[10:11]
	s_mov_b32 m0, s66
	s_nop 0
	global_load_lds_dwordx4 v[144:145], off
	s_waitcnt vmcnt(8)
	s_waitcnt lgkmcnt(0)
	s_barrier
	v_mfma_f32_16x16x32_bf16 v[60:63], v[152:155], v[184:187], v[60:63]
	v_mfma_f32_16x16x32_bf16 v[56:59], v[160:163], v[184:187], v[56:59]
	v_mfma_f32_16x16x32_bf16 v[52:55], v[152:155], v[196:199], v[52:55]
	v_mfma_f32_16x16x32_bf16 v[44:47], v[160:163], v[196:199], v[44:47]
	v_mfma_f32_16x16x32_bf16 v[36:39], v[152:155], v[204:207], v[36:39]
	v_mfma_f32_16x16x32_bf16 v[28:31], v[160:163], v[204:207], v[28:31]
	v_mfma_f32_16x16x32_bf16 v[20:23], v[152:155], v[212:215], v[20:23]
	v_mfma_f32_16x16x32_bf16 v[12:15], v[160:163], v[212:215], v[12:15]
	v_mfma_f32_16x16x32_bf16 v[60:63], v[156:159], v[192:195], v[60:63]
	v_mfma_f32_16x16x32_bf16 v[56:59], v[164:167], v[192:195], v[56:59]
	v_mfma_f32_16x16x32_bf16 v[52:55], v[156:159], v[200:203], v[52:55]
	v_mfma_f32_16x16x32_bf16 v[44:47], v[164:167], v[200:203], v[44:47]
	v_mfma_f32_16x16x32_bf16 v[36:39], v[156:159], v[208:211], v[36:39]
	v_mfma_f32_16x16x32_bf16 v[28:31], v[164:167], v[208:211], v[28:31]
	v_mfma_f32_16x16x32_bf16 v[20:23], v[156:159], v[216:219], v[20:23]
	v_mfma_f32_16x16x32_bf16 v[12:15], v[164:167], v[216:219], v[12:15]
	v_mfma_f32_16x16x32_bf16 v[48:51], v[168:171], v[184:187], v[48:51]
	v_mfma_f32_16x16x32_bf16 v[40:43], v[176:179], v[184:187], v[40:43]
	v_mfma_f32_16x16x32_bf16 v[32:35], v[168:171], v[196:199], v[32:35]
	v_mfma_f32_16x16x32_bf16 v[24:27], v[176:179], v[196:199], v[24:27]
	v_mfma_f32_16x16x32_bf16 v[16:19], v[168:171], v[204:207], v[16:19]
	v_mfma_f32_16x16x32_bf16 v[8:11], v[176:179], v[204:207], v[8:11]
	v_mfma_f32_16x16x32_bf16 v[4:7], v[168:171], v[212:215], v[4:7]
	v_mfma_f32_16x16x32_bf16 v[0:3], v[176:179], v[212:215], v[0:3]
	v_mfma_f32_16x16x32_bf16 v[48:51], v[172:175], v[192:195], v[48:51]
	v_mfma_f32_16x16x32_bf16 v[40:43], v[180:183], v[192:195], v[40:43]
	v_mfma_f32_16x16x32_bf16 v[32:35], v[172:175], v[200:203], v[32:35]
	v_mfma_f32_16x16x32_bf16 v[24:27], v[180:183], v[200:203], v[24:27]
	v_mfma_f32_16x16x32_bf16 v[16:19], v[172:175], v[208:211], v[16:19]
	v_mfma_f32_16x16x32_bf16 v[8:11], v[180:183], v[208:211], v[8:11]
	v_mfma_f32_16x16x32_bf16 v[4:7], v[172:175], v[216:219], v[4:7]
	v_mfma_f32_16x16x32_bf16 v[0:3], v[180:183], v[216:219], v[0:3]
	s_barrier
	s_add_i32 s77, s77, 2
	s_add_u32 s30, s30, 0x100
	s_addc_u32 s31, s31, 0
	s_add_u32 s75, s75, 0x100
	s_addc_u32 s76, s76, 0
	s_cmp_gt_u32 s77, 13
	s_cbranch_scc0 .LBB0_1434
	s_branch .Lpeel_exit10
.LBB0_1434:
	ds_read_b128 v[152:155], v149
	ds_read_b128 v[156:159], v149 offset:1024
	ds_read_b128 v[160:163], v149 offset:2048
	ds_read_b128 v[164:167], v149 offset:3072
	ds_read_b128 v[168:171], v150
	ds_read_b128 v[172:175], v150 offset:1024
	ds_read_b128 v[176:179], v150 offset:2048
	ds_read_b128 v[180:183], v150 offset:3072
	s_add_u32 s34, s30, 0xfffc0080
	s_addc_u32 s35, s31, -1
	s_cmp_eq_u32 s77, 12
	s_cselect_b32 s43, s23, s35
	s_cselect_b32 s42, s55, s34
	s_cselect_b32 s35, s21, s76
	s_cselect_b32 s34, s74, s75
	s_add_i32 m0, s29, 0xc000
	ds_read_b128 v[184:187], v151
	ds_read_b128 v[192:195], v151 offset:1024
	ds_read_b128 v[196:199], v151 offset:2048
	ds_read_b128 v[200:203], v151 offset:3072
	ds_read_b128 v[204:207], v151 offset:4096
	ds_read_b128 v[208:211], v151 offset:5120
	ds_read_b128 v[212:215], v151 offset:6144
	ds_read_b128 v[216:219], v151 offset:7168
	global_load_lds_dwordx4 v136, s[30:31]
	s_add_i32 m0, s29, 0xe000
	s_nop 0
	global_load_lds_dwordx4 v138, s[30:31]
	s_waitcnt vmcnt(8)
	s_waitcnt lgkmcnt(0)
	s_barrier
	v_mfma_f32_16x16x32_bf16 v[124:127], v[152:155], v[184:187], v[124:127]
	v_mfma_f32_16x16x32_bf16 v[120:123], v[160:163], v[184:187], v[120:123]
	v_mfma_f32_16x16x32_bf16 v[116:119], v[152:155], v[196:199], v[116:119]
	v_mfma_f32_16x16x32_bf16 v[108:111], v[160:163], v[196:199], v[108:111]
	v_mfma_f32_16x16x32_bf16 v[100:103], v[152:155], v[204:207], v[100:103]
	v_mfma_f32_16x16x32_bf16 v[92:95], v[160:163], v[204:207], v[92:95]
	v_mfma_f32_16x16x32_bf16 v[84:87], v[152:155], v[212:215], v[84:87]
	v_mfma_f32_16x16x32_bf16 v[76:79], v[160:163], v[212:215], v[76:79]
	v_mfma_f32_16x16x32_bf16 v[124:127], v[156:159], v[192:195], v[124:127]
	v_mfma_f32_16x16x32_bf16 v[120:123], v[164:167], v[192:195], v[120:123]
	v_mfma_f32_16x16x32_bf16 v[116:119], v[156:159], v[200:203], v[116:119]
	v_mfma_f32_16x16x32_bf16 v[108:111], v[164:167], v[200:203], v[108:111]
	v_mfma_f32_16x16x32_bf16 v[100:103], v[156:159], v[208:211], v[100:103]
	v_mfma_f32_16x16x32_bf16 v[92:95], v[164:167], v[208:211], v[92:95]
	v_mfma_f32_16x16x32_bf16 v[84:87], v[156:159], v[216:219], v[84:87]
	v_mfma_f32_16x16x32_bf16 v[76:79], v[164:167], v[216:219], v[76:79]
	v_mfma_f32_16x16x32_bf16 v[112:115], v[168:171], v[184:187], v[112:115]
	v_mfma_f32_16x16x32_bf16 v[104:107], v[176:179], v[184:187], v[104:107]
	v_mfma_f32_16x16x32_bf16 v[96:99], v[168:171], v[196:199], v[96:99]
	v_mfma_f32_16x16x32_bf16 v[88:91], v[176:179], v[196:199], v[88:91]
	v_mfma_f32_16x16x32_bf16 v[80:83], v[168:171], v[204:207], v[80:83]
	v_mfma_f32_16x16x32_bf16 v[72:75], v[176:179], v[204:207], v[72:75]
	v_mfma_f32_16x16x32_bf16 v[68:71], v[168:171], v[212:215], v[68:71]
	v_mfma_f32_16x16x32_bf16 v[64:67], v[176:179], v[212:215], v[64:67]
	v_mfma_f32_16x16x32_bf16 v[112:115], v[172:175], v[192:195], v[112:115]
	v_mfma_f32_16x16x32_bf16 v[104:107], v[180:183], v[192:195], v[104:107]
	v_mfma_f32_16x16x32_bf16 v[96:99], v[172:175], v[200:203], v[96:99]
	v_mfma_f32_16x16x32_bf16 v[88:91], v[180:183], v[200:203], v[88:91]
	v_mfma_f32_16x16x32_bf16 v[80:83], v[172:175], v[208:211], v[80:83]
	v_mfma_f32_16x16x32_bf16 v[72:75], v[180:183], v[208:211], v[72:75]
	v_mfma_f32_16x16x32_bf16 v[68:71], v[172:175], v[216:219], v[68:71]
	v_mfma_f32_16x16x32_bf16 v[64:67], v[180:183], v[216:219], v[64:67]
	s_barrier
	s_add_i32 s79, s68, s61
	v_lshl_add_u64 v[144:145], s[34:35], 0, v[130:131]
	s_mov_b32 m0, s79
	ds_read_b128 v[184:187], v151 offset:16384
	ds_read_b128 v[192:195], v151 offset:17408
	ds_read_b128 v[196:199], v151 offset:18432
	ds_read_b128 v[200:203], v151 offset:19456
	ds_read_b128 v[204:207], v151 offset:20480
	ds_read_b128 v[208:211], v151 offset:21504
	ds_read_b128 v[212:215], v151 offset:22528
	ds_read_b128 v[216:219], v151 offset:23552
	global_load_lds_dwordx4 v[144:145], off
	s_add_i32 m0, s79, 0x2000
	s_add_u32 s80, s34, 0x40000
	v_lshl_add_u64 v[188:189], s[34:35], 0, v[134:135]
	s_addc_u32 s81, s35, 0
	s_add_i32 s79, s69, s61
	global_load_lds_dwordx4 v[188:189], off
	s_mov_b32 m0, s79
	v_lshl_add_u64 v[222:223], s[42:43], 0, v[132:133]
	global_load_lds_dwordx4 v130, s[80:81]
	s_add_i32 m0, s79, 0x2000
	s_nop 0
	global_load_lds_dwordx4 v134, s[80:81]
	v_lshl_add_u64 v[220:221], s[42:43], 0, v[128:129]
	s_mov_b32 m0, s29
	s_nop 0
	global_load_lds_dwordx4 v[220:221], off
	s_mov_b32 m0, s33
	s_nop 0
	global_load_lds_dwordx4 v[222:223], off
	s_waitcnt vmcnt(8)
	s_waitcnt lgkmcnt(0)
	s_barrier
	v_mfma_f32_16x16x32_bf16 v[60:63], v[152:155], v[184:187], v[60:63]
	v_mfma_f32_16x16x32_bf16 v[56:59], v[160:163], v[184:187], v[56:59]
	v_mfma_f32_16x16x32_bf16 v[52:55], v[152:155], v[196:199], v[52:55]
	v_mfma_f32_16x16x32_bf16 v[44:47], v[160:163], v[196:199], v[44:47]
	v_mfma_f32_16x16x32_bf16 v[36:39], v[152:155], v[204:207], v[36:39]
	v_mfma_f32_16x16x32_bf16 v[28:31], v[160:163], v[204:207], v[28:31]
	v_mfma_f32_16x16x32_bf16 v[20:23], v[152:155], v[212:215], v[20:23]
	v_mfma_f32_16x16x32_bf16 v[12:15], v[160:163], v[212:215], v[12:15]
	v_mfma_f32_16x16x32_bf16 v[60:63], v[156:159], v[192:195], v[60:63]
	v_mfma_f32_16x16x32_bf16 v[56:59], v[164:167], v[192:195], v[56:59]
	v_mfma_f32_16x16x32_bf16 v[52:55], v[156:159], v[200:203], v[52:55]
	v_mfma_f32_16x16x32_bf16 v[44:47], v[164:167], v[200:203], v[44:47]
	v_mfma_f32_16x16x32_bf16 v[36:39], v[156:159], v[208:211], v[36:39]
	v_mfma_f32_16x16x32_bf16 v[28:31], v[164:167], v[208:211], v[28:31]
	v_mfma_f32_16x16x32_bf16 v[20:23], v[156:159], v[216:219], v[20:23]
	v_mfma_f32_16x16x32_bf16 v[12:15], v[164:167], v[216:219], v[12:15]
	v_mfma_f32_16x16x32_bf16 v[48:51], v[168:171], v[184:187], v[48:51]
	v_mfma_f32_16x16x32_bf16 v[40:43], v[176:179], v[184:187], v[40:43]
	v_mfma_f32_16x16x32_bf16 v[32:35], v[168:171], v[196:199], v[32:35]
	v_mfma_f32_16x16x32_bf16 v[24:27], v[176:179], v[196:199], v[24:27]
	v_mfma_f32_16x16x32_bf16 v[16:19], v[168:171], v[204:207], v[16:19]
	v_mfma_f32_16x16x32_bf16 v[8:11], v[176:179], v[204:207], v[8:11]
	v_mfma_f32_16x16x32_bf16 v[4:7], v[168:171], v[212:215], v[4:7]
	v_mfma_f32_16x16x32_bf16 v[0:3], v[176:179], v[212:215], v[0:3]
	v_mfma_f32_16x16x32_bf16 v[48:51], v[172:175], v[192:195], v[48:51]
	v_mfma_f32_16x16x32_bf16 v[40:43], v[180:183], v[192:195], v[40:43]
	v_mfma_f32_16x16x32_bf16 v[32:35], v[172:175], v[200:203], v[32:35]
	v_mfma_f32_16x16x32_bf16 v[24:27], v[180:183], v[200:203], v[24:27]
	v_mfma_f32_16x16x32_bf16 v[16:19], v[172:175], v[208:211], v[16:19]
	v_mfma_f32_16x16x32_bf16 v[8:11], v[180:183], v[208:211], v[8:11]
	v_mfma_f32_16x16x32_bf16 v[4:7], v[172:175], v[216:219], v[4:7]
	v_mfma_f32_16x16x32_bf16 v[0:3], v[180:183], v[216:219], v[0:3]
	s_barrier
	s_add_i32 s79, 0, 0x18000
	s_add_i32 s80, 0, 0x1c000
	v_add_u32_e32 v164, s79, v147
	v_add_u32_e32 v180, s80, v147
	ds_read_b128 v[152:155], v164
	ds_read_b128 v[156:159], v164 offset:1024
	ds_read_b128 v[160:163], v164 offset:2048
	ds_read_b128 v[164:167], v164 offset:3072
	ds_read_b128 v[168:171], v180
	ds_read_b128 v[172:175], v180 offset:1024
	ds_read_b128 v[176:179], v180 offset:2048
	ds_read_b128 v[180:183], v180 offset:3072
	s_add_u32 s42, s42, 0x40000
	s_addc_u32 s43, s43, 0
	s_mov_b32 m0, s62
	ds_read_b128 v[184:187], v151 offset:32768
	ds_read_b128 v[192:195], v151 offset:33792
	ds_read_b128 v[196:199], v151 offset:34816
	ds_read_b128 v[200:203], v151 offset:35840
	ds_read_b128 v[204:207], v151 offset:36864
	ds_read_b128 v[208:211], v151 offset:37888
	ds_read_b128 v[212:215], v151 offset:38912
	ds_read_b128 v[216:219], v151 offset:39936
	global_load_lds_dwordx4 v128, s[42:43]
	s_mov_b32 m0, s63
	s_nop 0
	global_load_lds_dwordx4 v132, s[42:43]
	s_waitcnt vmcnt(8)
	s_waitcnt lgkmcnt(0)
	s_barrier
	v_mfma_f32_16x16x32_bf16 v[124:127], v[152:155], v[184:187], v[124:127]
	v_mfma_f32_16x16x32_bf16 v[120:123], v[160:163], v[184:187], v[120:123]
	v_mfma_f32_16x16x32_bf16 v[116:119], v[152:155], v[196:199], v[116:119]
	v_mfma_f32_16x16x32_bf16 v[108:111], v[160:163], v[196:199], v[108:111]
	v_mfma_f32_16x16x32_bf16 v[100:103], v[152:155], v[204:207], v[100:103]
	v_mfma_f32_16x16x32_bf16 v[92:95], v[160:163], v[204:207], v[92:95]
	v_mfma_f32_16x16x32_bf16 v[84:87], v[152:155], v[212:215], v[84:87]
	v_mfma_f32_16x16x32_bf16 v[76:79], v[160:163], v[212:215], v[76:79]
	v_mfma_f32_16x16x32_bf16 v[124:127], v[156:159], v[192:195], v[124:127]
	v_mfma_f32_16x16x32_bf16 v[120:123], v[164:167], v[192:195], v[120:123]
	v_mfma_f32_16x16x32_bf16 v[116:119], v[156:159], v[200:203], v[116:119]
	v_mfma_f32_16x16x32_bf16 v[108:111], v[164:167], v[200:203], v[108:111]
	v_mfma_f32_16x16x32_bf16 v[100:103], v[156:159], v[208:211], v[100:103]
	v_mfma_f32_16x16x32_bf16 v[92:95], v[164:167], v[208:211], v[92:95]
	v_mfma_f32_16x16x32_bf16 v[84:87], v[156:159], v[216:219], v[84:87]
	v_mfma_f32_16x16x32_bf16 v[76:79], v[164:167], v[216:219], v[76:79]
	v_mfma_f32_16x16x32_bf16 v[112:115], v[168:171], v[184:187], v[112:115]
	v_mfma_f32_16x16x32_bf16 v[104:107], v[176:179], v[184:187], v[104:107]
	v_mfma_f32_16x16x32_bf16 v[96:99], v[168:171], v[196:199], v[96:99]
	v_mfma_f32_16x16x32_bf16 v[88:91], v[176:179], v[196:199], v[88:91]
	v_mfma_f32_16x16x32_bf16 v[80:83], v[168:171], v[204:207], v[80:83]
	v_mfma_f32_16x16x32_bf16 v[72:75], v[176:179], v[204:207], v[72:75]
	v_mfma_f32_16x16x32_bf16 v[68:71], v[168:171], v[212:215], v[68:71]
	v_mfma_f32_16x16x32_bf16 v[64:67], v[176:179], v[212:215], v[64:67]
	v_mfma_f32_16x16x32_bf16 v[112:115], v[172:175], v[192:195], v[112:115]
	v_mfma_f32_16x16x32_bf16 v[104:107], v[180:183], v[192:195], v[104:107]
	v_mfma_f32_16x16x32_bf16 v[96:99], v[172:175], v[200:203], v[96:99]
	v_mfma_f32_16x16x32_bf16 v[88:91], v[180:183], v[200:203], v[88:91]
	v_mfma_f32_16x16x32_bf16 v[80:83], v[172:175], v[208:211], v[80:83]
	v_mfma_f32_16x16x32_bf16 v[72:75], v[180:183], v[208:211], v[72:75]
	v_mfma_f32_16x16x32_bf16 v[68:71], v[172:175], v[216:219], v[68:71]
	v_mfma_f32_16x16x32_bf16 v[64:67], v[180:183], v[216:219], v[64:67]
	s_barrier
	s_add_i32 s42, s79, s61
	v_lshl_add_u64 v[144:145], v[144:145], 0, s[10:11]
	s_mov_b32 m0, s42
	ds_read_b128 v[184:187], v151 offset:49152
	ds_read_b128 v[192:195], v151 offset:50176
	ds_read_b128 v[196:199], v151 offset:51200
	ds_read_b128 v[200:203], v151 offset:52224
	ds_read_b128 v[204:207], v151 offset:53248
	ds_read_b128 v[208:211], v151 offset:54272
	ds_read_b128 v[212:215], v151 offset:55296
	ds_read_b128 v[216:219], v151 offset:56320
	global_load_lds_dwordx4 v[144:145], off
	s_add_i32 m0, s42, 0x2000
	s_add_u32 s34, s34, 0x40080
	v_lshl_add_u64 v[144:145], v[188:189], 0, s[10:11]
	s_addc_u32 s35, s35, 0
	s_add_i32 s42, s80, s61
	global_load_lds_dwordx4 v[144:145], off
	s_mov_b32 m0, s42
	s_nop 0
	global_load_lds_dwordx4 v130, s[34:35]
	s_add_i32 m0, s42, 0x2000
	s_nop 0
	global_load_lds_dwordx4 v134, s[34:35]
	v_lshl_add_u64 v[144:145], v[220:221], 0, s[10:11]
	s_mov_b32 m0, s65
	s_nop 0
	global_load_lds_dwordx4 v[144:145], off
	v_lshl_add_u64 v[144:145], v[222:223], 0, s[10:11]
	s_mov_b32 m0, s66
	s_nop 0
	global_load_lds_dwordx4 v[144:145], off
	s_waitcnt vmcnt(8)
	s_waitcnt lgkmcnt(0)
	s_barrier
	v_mfma_f32_16x16x32_bf16 v[60:63], v[152:155], v[184:187], v[60:63]
	v_mfma_f32_16x16x32_bf16 v[56:59], v[160:163], v[184:187], v[56:59]
	v_mfma_f32_16x16x32_bf16 v[52:55], v[152:155], v[196:199], v[52:55]
	v_mfma_f32_16x16x32_bf16 v[44:47], v[160:163], v[196:199], v[44:47]
	v_mfma_f32_16x16x32_bf16 v[36:39], v[152:155], v[204:207], v[36:39]
	v_mfma_f32_16x16x32_bf16 v[28:31], v[160:163], v[204:207], v[28:31]
	v_mfma_f32_16x16x32_bf16 v[20:23], v[152:155], v[212:215], v[20:23]
	v_mfma_f32_16x16x32_bf16 v[12:15], v[160:163], v[212:215], v[12:15]
	v_mfma_f32_16x16x32_bf16 v[60:63], v[156:159], v[192:195], v[60:63]
	v_mfma_f32_16x16x32_bf16 v[56:59], v[164:167], v[192:195], v[56:59]
	v_mfma_f32_16x16x32_bf16 v[52:55], v[156:159], v[200:203], v[52:55]
	v_mfma_f32_16x16x32_bf16 v[44:47], v[164:167], v[200:203], v[44:47]
	v_mfma_f32_16x16x32_bf16 v[36:39], v[156:159], v[208:211], v[36:39]
	v_mfma_f32_16x16x32_bf16 v[28:31], v[164:167], v[208:211], v[28:31]
	v_mfma_f32_16x16x32_bf16 v[20:23], v[156:159], v[216:219], v[20:23]
	v_mfma_f32_16x16x32_bf16 v[12:15], v[164:167], v[216:219], v[12:15]
	v_mfma_f32_16x16x32_bf16 v[48:51], v[168:171], v[184:187], v[48:51]
	v_mfma_f32_16x16x32_bf16 v[40:43], v[176:179], v[184:187], v[40:43]
	v_mfma_f32_16x16x32_bf16 v[32:35], v[168:171], v[196:199], v[32:35]
	v_mfma_f32_16x16x32_bf16 v[24:27], v[176:179], v[196:199], v[24:27]
	v_mfma_f32_16x16x32_bf16 v[16:19], v[168:171], v[204:207], v[16:19]
	v_mfma_f32_16x16x32_bf16 v[8:11], v[176:179], v[204:207], v[8:11]
	v_mfma_f32_16x16x32_bf16 v[4:7], v[168:171], v[212:215], v[4:7]
	v_mfma_f32_16x16x32_bf16 v[0:3], v[176:179], v[212:215], v[0:3]
	v_mfma_f32_16x16x32_bf16 v[48:51], v[172:175], v[192:195], v[48:51]
	v_mfma_f32_16x16x32_bf16 v[40:43], v[180:183], v[192:195], v[40:43]
	v_mfma_f32_16x16x32_bf16 v[32:35], v[172:175], v[200:203], v[32:35]
	v_mfma_f32_16x16x32_bf16 v[24:27], v[180:183], v[200:203], v[24:27]
	v_mfma_f32_16x16x32_bf16 v[16:19], v[172:175], v[208:211], v[16:19]
	v_mfma_f32_16x16x32_bf16 v[8:11], v[180:183], v[208:211], v[8:11]
	v_mfma_f32_16x16x32_bf16 v[4:7], v[172:175], v[216:219], v[4:7]
	v_mfma_f32_16x16x32_bf16 v[0:3], v[180:183], v[216:219], v[0:3]
	s_barrier
	s_add_i32 s77, s77, 2
	s_add_u32 s30, s30, 0x100
	s_addc_u32 s31, s31, 0
	s_add_u32 s75, s75, 0x100
	s_addc_u32 s76, s76, 0
	s_cmp_gt_u32 s77, 13
	s_cbranch_scc0 .LBB0_1434

.LBB0_1570:
	s_ashr_i32 s23, s22, 31
	s_lshl_b64 s[24:25], s[22:23], 19
	s_add_u32 s24, s58, s24
	s_addc_u32 s25, s59, s25
	s_and_b64 s[26:27], s[0:1], exec
	s_cselect_b32 s23, s25, s31
	s_cselect_b32 s54, s24, s30
	s_ashr_i32 s21, s20, 31
	s_lshl_b64 s[26:27], s[20:21], 19
	s_add_u32 s26, s61, s26
	s_addc_u32 s27, s62, s27
	s_and_b64 s[42:43], s[0:1], exec
	s_cselect_b32 s21, s27, s35
	s_cselect_b32 s55, s26, s34
	s_add_u32 s30, s30, 0x40080
	s_addc_u32 s31, s31, 0
	s_add_u32 s75, s34, 0x100
	s_addc_u32 s76, s35, 0
	s_mov_b32 s77, -2
	ds_read_b128 v[152:155], v149
	ds_read_b128 v[156:159], v149 offset:1024
	ds_read_b128 v[160:163], v149 offset:2048
	ds_read_b128 v[164:167], v149 offset:3072
	ds_read_b128 v[168:171], v150
	ds_read_b128 v[172:175], v150 offset:1024
	ds_read_b128 v[176:179], v150 offset:2048
	ds_read_b128 v[180:183], v150 offset:3072
	s_add_u32 s34, s30, 0xfffc0080
	s_addc_u32 s35, s31, -1
	s_cmp_eq_u32 s77, 12
	s_cselect_b32 s43, s23, s35
	s_cselect_b32 s42, s54, s34
	s_cselect_b32 s35, s21, s76
	s_cselect_b32 s34, s55, s75
	s_add_i32 m0, s29, 0xc000
	ds_read_b128 v[184:187], v151
	ds_read_b128 v[192:195], v151 offset:1024
	ds_read_b128 v[196:199], v151 offset:2048
	ds_read_b128 v[200:203], v151 offset:3072
	ds_read_b128 v[204:207], v151 offset:4096
	ds_read_b128 v[208:211], v151 offset:5120
	ds_read_b128 v[212:215], v151 offset:6144
	ds_read_b128 v[216:219], v151 offset:7168
	global_load_lds_dwordx4 v136, s[30:31]
	s_add_i32 m0, s29, 0xe000
	s_nop 0
	global_load_lds_dwordx4 v138, s[30:31]
	s_waitcnt vmcnt(8)
	s_waitcnt lgkmcnt(0)
	s_barrier
	v_mfma_f32_16x16x32_bf16 v[124:127], v[152:155], v[184:187], 0
	v_mfma_f32_16x16x32_bf16 v[120:123], v[160:163], v[184:187], 0
	v_mfma_f32_16x16x32_bf16 v[108:111], v[152:155], v[196:199], 0
	v_mfma_f32_16x16x32_bf16 v[104:107], v[160:163], v[196:199], 0
	v_mfma_f32_16x16x32_bf16 v[92:95], v[152:155], v[204:207], 0
	v_mfma_f32_16x16x32_bf16 v[88:91], v[160:163], v[204:207], 0
	v_mfma_f32_16x16x32_bf16 v[76:79], v[152:155], v[212:215], 0
	v_mfma_f32_16x16x32_bf16 v[72:75], v[160:163], v[212:215], 0
	v_mfma_f32_16x16x32_bf16 v[124:127], v[156:159], v[192:195], v[124:127]
	v_mfma_f32_16x16x32_bf16 v[120:123], v[164:167], v[192:195], v[120:123]
	v_mfma_f32_16x16x32_bf16 v[108:111], v[156:159], v[200:203], v[108:111]
	v_mfma_f32_16x16x32_bf16 v[104:107], v[164:167], v[200:203], v[104:107]
	v_mfma_f32_16x16x32_bf16 v[92:95], v[156:159], v[208:211], v[92:95]
	v_mfma_f32_16x16x32_bf16 v[88:91], v[164:167], v[208:211], v[88:91]
	v_mfma_f32_16x16x32_bf16 v[76:79], v[156:159], v[216:219], v[76:79]
	v_mfma_f32_16x16x32_bf16 v[72:75], v[164:167], v[216:219], v[72:75]
	v_mfma_f32_16x16x32_bf16 v[116:119], v[168:171], v[184:187], 0
	v_mfma_f32_16x16x32_bf16 v[112:115], v[176:179], v[184:187], 0
	v_mfma_f32_16x16x32_bf16 v[100:103], v[168:171], v[196:199], 0
	v_mfma_f32_16x16x32_bf16 v[96:99], v[176:179], v[196:199], 0
	v_mfma_f32_16x16x32_bf16 v[84:87], v[168:171], v[204:207], 0
	v_mfma_f32_16x16x32_bf16 v[80:83], v[176:179], v[204:207], 0
	v_mfma_f32_16x16x32_bf16 v[68:71], v[168:171], v[212:215], 0
	v_mfma_f32_16x16x32_bf16 v[64:67], v[176:179], v[212:215], 0
	v_mfma_f32_16x16x32_bf16 v[116:119], v[172:175], v[192:195], v[116:119]
	v_mfma_f32_16x16x32_bf16 v[112:115], v[180:183], v[192:195], v[112:115]
	v_mfma_f32_16x16x32_bf16 v[100:103], v[172:175], v[200:203], v[100:103]
	v_mfma_f32_16x16x32_bf16 v[96:99], v[180:183], v[200:203], v[96:99]
	v_mfma_f32_16x16x32_bf16 v[84:87], v[172:175], v[208:211], v[84:87]
	v_mfma_f32_16x16x32_bf16 v[80:83], v[180:183], v[208:211], v[80:83]
	v_mfma_f32_16x16x32_bf16 v[68:71], v[172:175], v[216:219], v[68:71]
	v_mfma_f32_16x16x32_bf16 v[64:67], v[180:183], v[216:219], v[64:67]
	s_barrier
	s_add_i32 s79, s69, s63
	v_lshl_add_u64 v[144:145], s[34:35], 0, v[130:131]
	s_mov_b32 m0, s79
	ds_read_b128 v[184:187], v151 offset:16384
	ds_read_b128 v[192:195], v151 offset:17408
	ds_read_b128 v[196:199], v151 offset:18432
	ds_read_b128 v[200:203], v151 offset:19456
	ds_read_b128 v[204:207], v151 offset:20480
	ds_read_b128 v[208:211], v151 offset:21504
	ds_read_b128 v[212:215], v151 offset:22528
	ds_read_b128 v[216:219], v151 offset:23552
	global_load_lds_dwordx4 v[144:145], off
	s_add_i32 m0, s79, 0x2000
	s_add_u32 s80, s34, 0x40000
	v_lshl_add_u64 v[188:189], s[34:35], 0, v[134:135]
	s_addc_u32 s81, s35, 0
	s_add_i32 s79, s70, s63
	global_load_lds_dwordx4 v[188:189], off
	s_mov_b32 m0, s79
	v_lshl_add_u64 v[222:223], s[42:43], 0, v[132:133]
	global_load_lds_dwordx4 v130, s[80:81]
	s_add_i32 m0, s79, 0x2000
	s_nop 0
	global_load_lds_dwordx4 v134, s[80:81]
	v_lshl_add_u64 v[220:221], s[42:43], 0, v[128:129]
	s_mov_b32 m0, s29
	s_nop 0
	global_load_lds_dwordx4 v[220:221], off
	s_mov_b32 m0, s64
	s_nop 0
	global_load_lds_dwordx4 v[222:223], off
	s_waitcnt vmcnt(8)
	s_waitcnt lgkmcnt(0)
	s_barrier
	v_mfma_f32_16x16x32_bf16 v[60:63], v[152:155], v[184:187], 0
	v_mfma_f32_16x16x32_bf16 v[56:59], v[160:163], v[184:187], 0
	v_mfma_f32_16x16x32_bf16 v[44:47], v[152:155], v[196:199], 0
	v_mfma_f32_16x16x32_bf16 v[40:43], v[160:163], v[196:199], 0
	v_mfma_f32_16x16x32_bf16 v[28:31], v[152:155], v[204:207], 0
	v_mfma_f32_16x16x32_bf16 v[24:27], v[160:163], v[204:207], 0
	v_mfma_f32_16x16x32_bf16 v[12:15], v[152:155], v[212:215], 0
	v_mfma_f32_16x16x32_bf16 v[8:11], v[160:163], v[212:215], 0
	v_mfma_f32_16x16x32_bf16 v[60:63], v[156:159], v[192:195], v[60:63]
	v_mfma_f32_16x16x32_bf16 v[56:59], v[164:167], v[192:195], v[56:59]
	v_mfma_f32_16x16x32_bf16 v[44:47], v[156:159], v[200:203], v[44:47]
	v_mfma_f32_16x16x32_bf16 v[40:43], v[164:167], v[200:203], v[40:43]
	v_mfma_f32_16x16x32_bf16 v[28:31], v[156:159], v[208:211], v[28:31]
	v_mfma_f32_16x16x32_bf16 v[24:27], v[164:167], v[208:211], v[24:27]
	v_mfma_f32_16x16x32_bf16 v[12:15], v[156:159], v[216:219], v[12:15]
	v_mfma_f32_16x16x32_bf16 v[8:11], v[164:167], v[216:219], v[8:11]
	v_mfma_f32_16x16x32_bf16 v[52:55], v[168:171], v[184:187], 0
	v_mfma_f32_16x16x32_bf16 v[48:51], v[176:179], v[184:187], 0
	v_mfma_f32_16x16x32_bf16 v[36:39], v[168:171], v[196:199], 0
	v_mfma_f32_16x16x32_bf16 v[32:35], v[176:179], v[196:199], 0
	v_mfma_f32_16x16x32_bf16 v[20:23], v[168:171], v[204:207], 0
	v_mfma_f32_16x16x32_bf16 v[16:19], v[176:179], v[204:207], 0
	v_mfma_f32_16x16x32_bf16 v[4:7], v[168:171], v[212:215], 0
	v_mfma_f32_16x16x32_bf16 v[0:3], v[176:179], v[212:215], 0
	v_mfma_f32_16x16x32_bf16 v[52:55], v[172:175], v[192:195], v[52:55]
	v_mfma_f32_16x16x32_bf16 v[48:51], v[180:183], v[192:195], v[48:51]
	v_mfma_f32_16x16x32_bf16 v[36:39], v[172:175], v[200:203], v[36:39]
	v_mfma_f32_16x16x32_bf16 v[32:35], v[180:183], v[200:203], v[32:35]
	v_mfma_f32_16x16x32_bf16 v[20:23], v[172:175], v[208:211], v[20:23]
	v_mfma_f32_16x16x32_bf16 v[16:19], v[180:183], v[208:211], v[16:19]
	v_mfma_f32_16x16x32_bf16 v[4:7], v[172:175], v[216:219], v[4:7]
	v_mfma_f32_16x16x32_bf16 v[0:3], v[180:183], v[216:219], v[0:3]
	s_barrier
	s_add_i32 s79, 0, 0x18000
	s_add_i32 s80, 0, 0x1c000
	v_add_u32_e32 v164, s79, v147
	v_add_u32_e32 v180, s80, v147
	ds_read_b128 v[152:155], v164
	ds_read_b128 v[156:159], v164 offset:1024
	ds_read_b128 v[160:163], v164 offset:2048
	ds_read_b128 v[164:167], v164 offset:3072
	ds_read_b128 v[168:171], v180
	ds_read_b128 v[172:175], v180 offset:1024
	ds_read_b128 v[176:179], v180 offset:2048
	ds_read_b128 v[180:183], v180 offset:3072
	s_add_u32 s42, s42, 0x40000
	s_addc_u32 s43, s43, 0
	s_mov_b32 m0, s65
	ds_read_b128 v[184:187], v151 offset:32768
	ds_read_b128 v[192:195], v151 offset:33792
	ds_read_b128 v[196:199], v151 offset:34816
	ds_read_b128 v[200:203], v151 offset:35840
	ds_read_b128 v[204:207], v151 offset:36864
	ds_read_b128 v[208:211], v151 offset:37888
	ds_read_b128 v[212:215], v151 offset:38912
	ds_read_b128 v[216:219], v151 offset:39936
	global_load_lds_dwordx4 v128, s[42:43]
	s_mov_b32 m0, s66
	s_nop 0
	global_load_lds_dwordx4 v132, s[42:43]
	s_waitcnt vmcnt(8)
	s_waitcnt lgkmcnt(0)
	s_barrier
	v_mfma_f32_16x16x32_bf16 v[124:127], v[152:155], v[184:187], v[124:127]
	v_mfma_f32_16x16x32_bf16 v[120:123], v[160:163], v[184:187], v[120:123]
	v_mfma_f32_16x16x32_bf16 v[108:111], v[152:155], v[196:199], v[108:111]
	v_mfma_f32_16x16x32_bf16 v[104:107], v[160:163], v[196:199], v[104:107]
	v_mfma_f32_16x16x32_bf16 v[92:95], v[152:155], v[204:207], v[92:95]
	v_mfma_f32_16x16x32_bf16 v[88:91], v[160:163], v[204:207], v[88:91]
	v_mfma_f32_16x16x32_bf16 v[76:79], v[152:155], v[212:215], v[76:79]
	v_mfma_f32_16x16x32_bf16 v[72:75], v[160:163], v[212:215], v[72:75]
	v_mfma_f32_16x16x32_bf16 v[124:127], v[156:159], v[192:195], v[124:127]
	v_mfma_f32_16x16x32_bf16 v[120:123], v[164:167], v[192:195], v[120:123]
	v_mfma_f32_16x16x32_bf16 v[108:111], v[156:159], v[200:203], v[108:111]
	v_mfma_f32_16x16x32_bf16 v[104:107], v[164:167], v[200:203], v[104:107]
	v_mfma_f32_16x16x32_bf16 v[92:95], v[156:159], v[208:211], v[92:95]
	v_mfma_f32_16x16x32_bf16 v[88:91], v[164:167], v[208:211], v[88:91]
	v_mfma_f32_16x16x32_bf16 v[76:79], v[156:159], v[216:219], v[76:79]
	v_mfma_f32_16x16x32_bf16 v[72:75], v[164:167], v[216:219], v[72:75]
	v_mfma_f32_16x16x32_bf16 v[116:119], v[168:171], v[184:187], v[116:119]
	v_mfma_f32_16x16x32_bf16 v[112:115], v[176:179], v[184:187], v[112:115]
	v_mfma_f32_16x16x32_bf16 v[100:103], v[168:171], v[196:199], v[100:103]
	v_mfma_f32_16x16x32_bf16 v[96:99], v[176:179], v[196:199], v[96:99]
	v_mfma_f32_16x16x32_bf16 v[84:87], v[168:171], v[204:207], v[84:87]
	v_mfma_f32_16x16x32_bf16 v[80:83], v[176:179], v[204:207], v[80:83]
	v_mfma_f32_16x16x32_bf16 v[68:71], v[168:171], v[212:215], v[68:71]
	v_mfma_f32_16x16x32_bf16 v[64:67], v[176:179], v[212:215], v[64:67]
	v_mfma_f32_16x16x32_bf16 v[116:119], v[172:175], v[192:195], v[116:119]
	v_mfma_f32_16x16x32_bf16 v[112:115], v[180:183], v[192:195], v[112:115]
	v_mfma_f32_16x16x32_bf16 v[100:103], v[172:175], v[200:203], v[100:103]
	v_mfma_f32_16x16x32_bf16 v[96:99], v[180:183], v[200:203], v[96:99]
	v_mfma_f32_16x16x32_bf16 v[84:87], v[172:175], v[208:211], v[84:87]
	v_mfma_f32_16x16x32_bf16 v[80:83], v[180:183], v[208:211], v[80:83]
	v_mfma_f32_16x16x32_bf16 v[68:71], v[172:175], v[216:219], v[68:71]
	v_mfma_f32_16x16x32_bf16 v[64:67], v[180:183], v[216:219], v[64:67]
	s_barrier
	s_add_i32 s42, s79, s63
	v_lshl_add_u64 v[144:145], v[144:145], 0, s[8:9]
	s_mov_b32 m0, s42
	ds_read_b128 v[184:187], v151 offset:49152
	ds_read_b128 v[192:195], v151 offset:50176
	ds_read_b128 v[196:199], v151 offset:51200
	ds_read_b128 v[200:203], v151 offset:52224
	ds_read_b128 v[204:207], v151 offset:53248
	ds_read_b128 v[208:211], v151 offset:54272
	ds_read_b128 v[212:215], v151 offset:55296
	ds_read_b128 v[216:219], v151 offset:56320
	global_load_lds_dwordx4 v[144:145], off
	s_add_i32 m0, s42, 0x2000
	s_add_u32 s34, s34, 0x40080
	v_lshl_add_u64 v[144:145], v[188:189], 0, s[8:9]
	s_addc_u32 s35, s35, 0
	s_add_i32 s42, s80, s63
	global_load_lds_dwordx4 v[144:145], off
	s_mov_b32 m0, s42
	s_nop 0
	global_load_lds_dwordx4 v130, s[34:35]
	s_add_i32 m0, s42, 0x2000
	s_nop 0
	global_load_lds_dwordx4 v134, s[34:35]
	v_lshl_add_u64 v[144:145], v[220:221], 0, s[8:9]
	s_mov_b32 m0, s52
	s_nop 0
	global_load_lds_dwordx4 v[144:145], off
	v_lshl_add_u64 v[144:145], v[222:223], 0, s[8:9]
	s_mov_b32 m0, s53
	s_nop 0
	global_load_lds_dwordx4 v[144:145], off
	s_waitcnt vmcnt(8)
	s_waitcnt lgkmcnt(0)
	s_barrier
	v_mfma_f32_16x16x32_bf16 v[60:63], v[152:155], v[184:187], v[60:63]
	v_mfma_f32_16x16x32_bf16 v[56:59], v[160:163], v[184:187], v[56:59]
	v_mfma_f32_16x16x32_bf16 v[44:47], v[152:155], v[196:199], v[44:47]
	v_mfma_f32_16x16x32_bf16 v[40:43], v[160:163], v[196:199], v[40:43]
	v_mfma_f32_16x16x32_bf16 v[28:31], v[152:155], v[204:207], v[28:31]
	v_mfma_f32_16x16x32_bf16 v[24:27], v[160:163], v[204:207], v[24:27]
	v_mfma_f32_16x16x32_bf16 v[12:15], v[152:155], v[212:215], v[12:15]
	v_mfma_f32_16x16x32_bf16 v[8:11], v[160:163], v[212:215], v[8:11]
	v_mfma_f32_16x16x32_bf16 v[60:63], v[156:159], v[192:195], v[60:63]
	v_mfma_f32_16x16x32_bf16 v[56:59], v[164:167], v[192:195], v[56:59]
	v_mfma_f32_16x16x32_bf16 v[44:47], v[156:159], v[200:203], v[44:47]
	v_mfma_f32_16x16x32_bf16 v[40:43], v[164:167], v[200:203], v[40:43]
	v_mfma_f32_16x16x32_bf16 v[28:31], v[156:159], v[208:211], v[28:31]
	v_mfma_f32_16x16x32_bf16 v[24:27], v[164:167], v[208:211], v[24:27]
	v_mfma_f32_16x16x32_bf16 v[12:15], v[156:159], v[216:219], v[12:15]
	v_mfma_f32_16x16x32_bf16 v[8:11], v[164:167], v[216:219], v[8:11]
	v_mfma_f32_16x16x32_bf16 v[52:55], v[168:171], v[184:187], v[52:55]
	v_mfma_f32_16x16x32_bf16 v[48:51], v[176:179], v[184:187], v[48:51]
	v_mfma_f32_16x16x32_bf16 v[36:39], v[168:171], v[196:199], v[36:39]
	v_mfma_f32_16x16x32_bf16 v[32:35], v[176:179], v[196:199], v[32:35]
	v_mfma_f32_16x16x32_bf16 v[20:23], v[168:171], v[204:207], v[20:23]
	v_mfma_f32_16x16x32_bf16 v[16:19], v[176:179], v[204:207], v[16:19]
	v_mfma_f32_16x16x32_bf16 v[4:7], v[168:171], v[212:215], v[4:7]
	v_mfma_f32_16x16x32_bf16 v[0:3], v[176:179], v[212:215], v[0:3]
	v_mfma_f32_16x16x32_bf16 v[52:55], v[172:175], v[192:195], v[52:55]
	v_mfma_f32_16x16x32_bf16 v[48:51], v[180:183], v[192:195], v[48:51]
	v_mfma_f32_16x16x32_bf16 v[36:39], v[172:175], v[200:203], v[36:39]
	v_mfma_f32_16x16x32_bf16 v[32:35], v[180:183], v[200:203], v[32:35]
	v_mfma_f32_16x16x32_bf16 v[20:23], v[172:175], v[208:211], v[20:23]
	v_mfma_f32_16x16x32_bf16 v[16:19], v[180:183], v[208:211], v[16:19]
	v_mfma_f32_16x16x32_bf16 v[4:7], v[172:175], v[216:219], v[4:7]
	v_mfma_f32_16x16x32_bf16 v[0:3], v[180:183], v[216:219], v[0:3]
	s_barrier
	s_add_i32 s77, s77, 2
	s_add_u32 s30, s30, 0x100
	s_addc_u32 s31, s31, 0
	s_add_u32 s75, s75, 0x100
	s_addc_u32 s76, s76, 0
	s_cmp_gt_u32 s77, 13
	s_cbranch_scc0 .LBB0_1571
	s_branch .Lpeel_exit11
.LBB0_1571:
	ds_read_b128 v[152:155], v149
	ds_read_b128 v[156:159], v149 offset:1024
	ds_read_b128 v[160:163], v149 offset:2048
	ds_read_b128 v[164:167], v149 offset:3072
	ds_read_b128 v[168:171], v150
	ds_read_b128 v[172:175], v150 offset:1024
	ds_read_b128 v[176:179], v150 offset:2048
	ds_read_b128 v[180:183], v150 offset:3072
	s_add_u32 s34, s30, 0xfffc0080
	s_addc_u32 s35, s31, -1
	s_cmp_eq_u32 s77, 12
	s_cselect_b32 s43, s23, s35
	s_cselect_b32 s42, s54, s34
	s_cselect_b32 s35, s21, s76
	s_cselect_b32 s34, s55, s75
	s_add_i32 m0, s29, 0xc000
	ds_read_b128 v[184:187], v151
	ds_read_b128 v[192:195], v151 offset:1024
	ds_read_b128 v[196:199], v151 offset:2048
	ds_read_b128 v[200:203], v151 offset:3072
	ds_read_b128 v[204:207], v151 offset:4096
	ds_read_b128 v[208:211], v151 offset:5120
	ds_read_b128 v[212:215], v151 offset:6144
	ds_read_b128 v[216:219], v151 offset:7168
	global_load_lds_dwordx4 v136, s[30:31]
	s_add_i32 m0, s29, 0xe000
	s_nop 0
	global_load_lds_dwordx4 v138, s[30:31]
	s_waitcnt vmcnt(8)
	s_waitcnt lgkmcnt(0)
	s_barrier
	v_mfma_f32_16x16x32_bf16 v[124:127], v[152:155], v[184:187], v[124:127]
	v_mfma_f32_16x16x32_bf16 v[120:123], v[160:163], v[184:187], v[120:123]
	v_mfma_f32_16x16x32_bf16 v[108:111], v[152:155], v[196:199], v[108:111]
	v_mfma_f32_16x16x32_bf16 v[104:107], v[160:163], v[196:199], v[104:107]
	v_mfma_f32_16x16x32_bf16 v[92:95], v[152:155], v[204:207], v[92:95]
	v_mfma_f32_16x16x32_bf16 v[88:91], v[160:163], v[204:207], v[88:91]
	v_mfma_f32_16x16x32_bf16 v[76:79], v[152:155], v[212:215], v[76:79]
	v_mfma_f32_16x16x32_bf16 v[72:75], v[160:163], v[212:215], v[72:75]
	v_mfma_f32_16x16x32_bf16 v[124:127], v[156:159], v[192:195], v[124:127]
	v_mfma_f32_16x16x32_bf16 v[120:123], v[164:167], v[192:195], v[120:123]
	v_mfma_f32_16x16x32_bf16 v[108:111], v[156:159], v[200:203], v[108:111]
	v_mfma_f32_16x16x32_bf16 v[104:107], v[164:167], v[200:203], v[104:107]
	v_mfma_f32_16x16x32_bf16 v[92:95], v[156:159], v[208:211], v[92:95]
	v_mfma_f32_16x16x32_bf16 v[88:91], v[164:167], v[208:211], v[88:91]
	v_mfma_f32_16x16x32_bf16 v[76:79], v[156:159], v[216:219], v[76:79]
	v_mfma_f32_16x16x32_bf16 v[72:75], v[164:167], v[216:219], v[72:75]
	v_mfma_f32_16x16x32_bf16 v[116:119], v[168:171], v[184:187], v[116:119]
	v_mfma_f32_16x16x32_bf16 v[112:115], v[176:179], v[184:187], v[112:115]
	v_mfma_f32_16x16x32_bf16 v[100:103], v[168:171], v[196:199], v[100:103]
	v_mfma_f32_16x16x32_bf16 v[96:99], v[176:179], v[196:199], v[96:99]
	v_mfma_f32_16x16x32_bf16 v[84:87], v[168:171], v[204:207], v[84:87]
	v_mfma_f32_16x16x32_bf16 v[80:83], v[176:179], v[204:207], v[80:83]
	v_mfma_f32_16x16x32_bf16 v[68:71], v[168:171], v[212:215], v[68:71]
	v_mfma_f32_16x16x32_bf16 v[64:67], v[176:179], v[212:215], v[64:67]
	v_mfma_f32_16x16x32_bf16 v[116:119], v[172:175], v[192:195], v[116:119]
	v_mfma_f32_16x16x32_bf16 v[112:115], v[180:183], v[192:195], v[112:115]
	v_mfma_f32_16x16x32_bf16 v[100:103], v[172:175], v[200:203], v[100:103]
	v_mfma_f32_16x16x32_bf16 v[96:99], v[180:183], v[200:203], v[96:99]
	v_mfma_f32_16x16x32_bf16 v[84:87], v[172:175], v[208:211], v[84:87]
	v_mfma_f32_16x16x32_bf16 v[80:83], v[180:183], v[208:211], v[80:83]
	v_mfma_f32_16x16x32_bf16 v[68:71], v[172:175], v[216:219], v[68:71]
	v_mfma_f32_16x16x32_bf16 v[64:67], v[180:183], v[216:219], v[64:67]
	s_barrier
	s_add_i32 s79, s69, s63
	v_lshl_add_u64 v[144:145], s[34:35], 0, v[130:131]
	s_mov_b32 m0, s79
	ds_read_b128 v[184:187], v151 offset:16384
	ds_read_b128 v[192:195], v151 offset:17408
	ds_read_b128 v[196:199], v151 offset:18432
	ds_read_b128 v[200:203], v151 offset:19456
	ds_read_b128 v[204:207], v151 offset:20480
	ds_read_b128 v[208:211], v151 offset:21504
	ds_read_b128 v[212:215], v151 offset:22528
	ds_read_b128 v[216:219], v151 offset:23552
	global_load_lds_dwordx4 v[144:145], off
	s_add_i32 m0, s79, 0x2000
	s_add_u32 s80, s34, 0x40000
	v_lshl_add_u64 v[188:189], s[34:35], 0, v[134:135]
	s_addc_u32 s81, s35, 0
	s_add_i32 s79, s70, s63
	global_load_lds_dwordx4 v[188:189], off
	s_mov_b32 m0, s79
	v_lshl_add_u64 v[222:223], s[42:43], 0, v[132:133]
	global_load_lds_dwordx4 v130, s[80:81]
	s_add_i32 m0, s79, 0x2000
	s_nop 0
	global_load_lds_dwordx4 v134, s[80:81]
	v_lshl_add_u64 v[220:221], s[42:43], 0, v[128:129]
	s_mov_b32 m0, s29
	s_nop 0
	global_load_lds_dwordx4 v[220:221], off
	s_mov_b32 m0, s64
	s_nop 0
	global_load_lds_dwordx4 v[222:223], off
	s_waitcnt vmcnt(8)
	s_waitcnt lgkmcnt(0)
	s_barrier
	v_mfma_f32_16x16x32_bf16 v[60:63], v[152:155], v[184:187], v[60:63]
	v_mfma_f32_16x16x32_bf16 v[56:59], v[160:163], v[184:187], v[56:59]
	v_mfma_f32_16x16x32_bf16 v[44:47], v[152:155], v[196:199], v[44:47]
	v_mfma_f32_16x16x32_bf16 v[40:43], v[160:163], v[196:199], v[40:43]
	v_mfma_f32_16x16x32_bf16 v[28:31], v[152:155], v[204:207], v[28:31]
	v_mfma_f32_16x16x32_bf16 v[24:27], v[160:163], v[204:207], v[24:27]
	v_mfma_f32_16x16x32_bf16 v[12:15], v[152:155], v[212:215], v[12:15]
	v_mfma_f32_16x16x32_bf16 v[8:11], v[160:163], v[212:215], v[8:11]
	v_mfma_f32_16x16x32_bf16 v[60:63], v[156:159], v[192:195], v[60:63]
	v_mfma_f32_16x16x32_bf16 v[56:59], v[164:167], v[192:195], v[56:59]
	v_mfma_f32_16x16x32_bf16 v[44:47], v[156:159], v[200:203], v[44:47]
	v_mfma_f32_16x16x32_bf16 v[40:43], v[164:167], v[200:203], v[40:43]
	v_mfma_f32_16x16x32_bf16 v[28:31], v[156:159], v[208:211], v[28:31]
	v_mfma_f32_16x16x32_bf16 v[24:27], v[164:167], v[208:211], v[24:27]
	v_mfma_f32_16x16x32_bf16 v[12:15], v[156:159], v[216:219], v[12:15]
	v_mfma_f32_16x16x32_bf16 v[8:11], v[164:167], v[216:219], v[8:11]
	v_mfma_f32_16x16x32_bf16 v[52:55], v[168:171], v[184:187], v[52:55]
	v_mfma_f32_16x16x32_bf16 v[48:51], v[176:179], v[184:187], v[48:51]
	v_mfma_f32_16x16x32_bf16 v[36:39], v[168:171], v[196:199], v[36:39]
	v_mfma_f32_16x16x32_bf16 v[32:35], v[176:179], v[196:199], v[32:35]
	v_mfma_f32_16x16x32_bf16 v[20:23], v[168:171], v[204:207], v[20:23]
	v_mfma_f32_16x16x32_bf16 v[16:19], v[176:179], v[204:207], v[16:19]
	v_mfma_f32_16x16x32_bf16 v[4:7], v[168:171], v[212:215], v[4:7]
	v_mfma_f32_16x16x32_bf16 v[0:3], v[176:179], v[212:215], v[0:3]
	v_mfma_f32_16x16x32_bf16 v[52:55], v[172:175], v[192:195], v[52:55]
	v_mfma_f32_16x16x32_bf16 v[48:51], v[180:183], v[192:195], v[48:51]
	v_mfma_f32_16x16x32_bf16 v[36:39], v[172:175], v[200:203], v[36:39]
	v_mfma_f32_16x16x32_bf16 v[32:35], v[180:183], v[200:203], v[32:35]
	v_mfma_f32_16x16x32_bf16 v[20:23], v[172:175], v[208:211], v[20:23]
	v_mfma_f32_16x16x32_bf16 v[16:19], v[180:183], v[208:211], v[16:19]
	v_mfma_f32_16x16x32_bf16 v[4:7], v[172:175], v[216:219], v[4:7]
	v_mfma_f32_16x16x32_bf16 v[0:3], v[180:183], v[216:219], v[0:3]
	s_barrier
	s_add_i32 s79, 0, 0x18000
	s_add_i32 s80, 0, 0x1c000
	v_add_u32_e32 v164, s79, v147
	v_add_u32_e32 v180, s80, v147
	ds_read_b128 v[152:155], v164
	ds_read_b128 v[156:159], v164 offset:1024
	ds_read_b128 v[160:163], v164 offset:2048
	ds_read_b128 v[164:167], v164 offset:3072
	ds_read_b128 v[168:171], v180
	ds_read_b128 v[172:175], v180 offset:1024
	ds_read_b128 v[176:179], v180 offset:2048
	ds_read_b128 v[180:183], v180 offset:3072
	s_add_u32 s42, s42, 0x40000
	s_addc_u32 s43, s43, 0
	s_mov_b32 m0, s65
	ds_read_b128 v[184:187], v151 offset:32768
	ds_read_b128 v[192:195], v151 offset:33792
	ds_read_b128 v[196:199], v151 offset:34816
	ds_read_b128 v[200:203], v151 offset:35840
	ds_read_b128 v[204:207], v151 offset:36864
	ds_read_b128 v[208:211], v151 offset:37888
	ds_read_b128 v[212:215], v151 offset:38912
	ds_read_b128 v[216:219], v151 offset:39936
	global_load_lds_dwordx4 v128, s[42:43]
	s_mov_b32 m0, s66
	s_nop 0
	global_load_lds_dwordx4 v132, s[42:43]
	s_waitcnt vmcnt(8)
	s_waitcnt lgkmcnt(0)
	s_barrier
	v_mfma_f32_16x16x32_bf16 v[124:127], v[152:155], v[184:187], v[124:127]
	v_mfma_f32_16x16x32_bf16 v[120:123], v[160:163], v[184:187], v[120:123]
	v_mfma_f32_16x16x32_bf16 v[108:111], v[152:155], v[196:199], v[108:111]
	v_mfma_f32_16x16x32_bf16 v[104:107], v[160:163], v[196:199], v[104:107]
	v_mfma_f32_16x16x32_bf16 v[92:95], v[152:155], v[204:207], v[92:95]
	v_mfma_f32_16x16x32_bf16 v[88:91], v[160:163], v[204:207], v[88:91]
	v_mfma_f32_16x16x32_bf16 v[76:79], v[152:155], v[212:215], v[76:79]
	v_mfma_f32_16x16x32_bf16 v[72:75], v[160:163], v[212:215], v[72:75]
	v_mfma_f32_16x16x32_bf16 v[124:127], v[156:159], v[192:195], v[124:127]
	v_mfma_f32_16x16x32_bf16 v[120:123], v[164:167], v[192:195], v[120:123]
	v_mfma_f32_16x16x32_bf16 v[108:111], v[156:159], v[200:203], v[108:111]
	v_mfma_f32_16x16x32_bf16 v[104:107], v[164:167], v[200:203], v[104:107]
	v_mfma_f32_16x16x32_bf16 v[92:95], v[156:159], v[208:211], v[92:95]
	v_mfma_f32_16x16x32_bf16 v[88:91], v[164:167], v[208:211], v[88:91]
	v_mfma_f32_16x16x32_bf16 v[76:79], v[156:159], v[216:219], v[76:79]
	v_mfma_f32_16x16x32_bf16 v[72:75], v[164:167], v[216:219], v[72:75]
	v_mfma_f32_16x16x32_bf16 v[116:119], v[168:171], v[184:187], v[116:119]
	v_mfma_f32_16x16x32_bf16 v[112:115], v[176:179], v[184:187], v[112:115]
	v_mfma_f32_16x16x32_bf16 v[100:103], v[168:171], v[196:199], v[100:103]
	v_mfma_f32_16x16x32_bf16 v[96:99], v[176:179], v[196:199], v[96:99]
	v_mfma_f32_16x16x32_bf16 v[84:87], v[168:171], v[204:207], v[84:87]
	v_mfma_f32_16x16x32_bf16 v[80:83], v[176:179], v[204:207], v[80:83]
	v_mfma_f32_16x16x32_bf16 v[68:71], v[168:171], v[212:215], v[68:71]
	v_mfma_f32_16x16x32_bf16 v[64:67], v[176:179], v[212:215], v[64:67]
	v_mfma_f32_16x16x32_bf16 v[116:119], v[172:175], v[192:195], v[116:119]
	v_mfma_f32_16x16x32_bf16 v[112:115], v[180:183], v[192:195], v[112:115]
	v_mfma_f32_16x16x32_bf16 v[100:103], v[172:175], v[200:203], v[100:103]
	v_mfma_f32_16x16x32_bf16 v[96:99], v[180:183], v[200:203], v[96:99]
	v_mfma_f32_16x16x32_bf16 v[84:87], v[172:175], v[208:211], v[84:87]
	v_mfma_f32_16x16x32_bf16 v[80:83], v[180:183], v[208:211], v[80:83]
	v_mfma_f32_16x16x32_bf16 v[68:71], v[172:175], v[216:219], v[68:71]
	v_mfma_f32_16x16x32_bf16 v[64:67], v[180:183], v[216:219], v[64:67]
	s_barrier
	s_add_i32 s42, s79, s63
	v_lshl_add_u64 v[144:145], v[144:145], 0, s[8:9]
	s_mov_b32 m0, s42
	ds_read_b128 v[184:187], v151 offset:49152
	ds_read_b128 v[192:195], v151 offset:50176
	ds_read_b128 v[196:199], v151 offset:51200
	ds_read_b128 v[200:203], v151 offset:52224
	ds_read_b128 v[204:207], v151 offset:53248
	ds_read_b128 v[208:211], v151 offset:54272
	ds_read_b128 v[212:215], v151 offset:55296
	ds_read_b128 v[216:219], v151 offset:56320
	global_load_lds_dwordx4 v[144:145], off
	s_add_i32 m0, s42, 0x2000
	s_add_u32 s34, s34, 0x40080
	v_lshl_add_u64 v[144:145], v[188:189], 0, s[8:9]
	s_addc_u32 s35, s35, 0
	s_add_i32 s42, s80, s63
	global_load_lds_dwordx4 v[144:145], off
	s_mov_b32 m0, s42
	s_nop 0
	global_load_lds_dwordx4 v130, s[34:35]
	s_add_i32 m0, s42, 0x2000
	s_nop 0
	global_load_lds_dwordx4 v134, s[34:35]
	v_lshl_add_u64 v[144:145], v[220:221], 0, s[8:9]
	s_mov_b32 m0, s52
	s_nop 0
	global_load_lds_dwordx4 v[144:145], off
	v_lshl_add_u64 v[144:145], v[222:223], 0, s[8:9]
	s_mov_b32 m0, s53
	s_nop 0
	global_load_lds_dwordx4 v[144:145], off
	s_waitcnt vmcnt(8)
	s_waitcnt lgkmcnt(0)
	s_barrier
	v_mfma_f32_16x16x32_bf16 v[60:63], v[152:155], v[184:187], v[60:63]
	v_mfma_f32_16x16x32_bf16 v[56:59], v[160:163], v[184:187], v[56:59]
	v_mfma_f32_16x16x32_bf16 v[44:47], v[152:155], v[196:199], v[44:47]
	v_mfma_f32_16x16x32_bf16 v[40:43], v[160:163], v[196:199], v[40:43]
	v_mfma_f32_16x16x32_bf16 v[28:31], v[152:155], v[204:207], v[28:31]
	v_mfma_f32_16x16x32_bf16 v[24:27], v[160:163], v[204:207], v[24:27]
	v_mfma_f32_16x16x32_bf16 v[12:15], v[152:155], v[212:215], v[12:15]
	v_mfma_f32_16x16x32_bf16 v[8:11], v[160:163], v[212:215], v[8:11]
	v_mfma_f32_16x16x32_bf16 v[60:63], v[156:159], v[192:195], v[60:63]
	v_mfma_f32_16x16x32_bf16 v[56:59], v[164:167], v[192:195], v[56:59]
	v_mfma_f32_16x16x32_bf16 v[44:47], v[156:159], v[200:203], v[44:47]
	v_mfma_f32_16x16x32_bf16 v[40:43], v[164:167], v[200:203], v[40:43]
	v_mfma_f32_16x16x32_bf16 v[28:31], v[156:159], v[208:211], v[28:31]
	v_mfma_f32_16x16x32_bf16 v[24:27], v[164:167], v[208:211], v[24:27]
	v_mfma_f32_16x16x32_bf16 v[12:15], v[156:159], v[216:219], v[12:15]
	v_mfma_f32_16x16x32_bf16 v[8:11], v[164:167], v[216:219], v[8:11]
	v_mfma_f32_16x16x32_bf16 v[52:55], v[168:171], v[184:187], v[52:55]
	v_mfma_f32_16x16x32_bf16 v[48:51], v[176:179], v[184:187], v[48:51]
	v_mfma_f32_16x16x32_bf16 v[36:39], v[168:171], v[196:199], v[36:39]
	v_mfma_f32_16x16x32_bf16 v[32:35], v[176:179], v[196:199], v[32:35]
	v_mfma_f32_16x16x32_bf16 v[20:23], v[168:171], v[204:207], v[20:23]
	v_mfma_f32_16x16x32_bf16 v[16:19], v[176:179], v[204:207], v[16:19]
	v_mfma_f32_16x16x32_bf16 v[4:7], v[168:171], v[212:215], v[4:7]
	v_mfma_f32_16x16x32_bf16 v[0:3], v[176:179], v[212:215], v[0:3]
	v_mfma_f32_16x16x32_bf16 v[52:55], v[172:175], v[192:195], v[52:55]
	v_mfma_f32_16x16x32_bf16 v[48:51], v[180:183], v[192:195], v[48:51]
	v_mfma_f32_16x16x32_bf16 v[36:39], v[172:175], v[200:203], v[36:39]
	v_mfma_f32_16x16x32_bf16 v[32:35], v[180:183], v[200:203], v[32:35]
	v_mfma_f32_16x16x32_bf16 v[20:23], v[172:175], v[208:211], v[20:23]
	v_mfma_f32_16x16x32_bf16 v[16:19], v[180:183], v[208:211], v[16:19]
	v_mfma_f32_16x16x32_bf16 v[4:7], v[172:175], v[216:219], v[4:7]
	v_mfma_f32_16x16x32_bf16 v[0:3], v[180:183], v[216:219], v[0:3]
	s_barrier
	s_add_i32 s77, s77, 2
	s_add_u32 s30, s30, 0x100
	s_addc_u32 s31, s31, 0
	s_add_u32 s75, s75, 0x100
	s_addc_u32 s76, s76, 0
	s_cmp_gt_u32 s77, 13
	s_cbranch_scc0 .LBB0_1571

.LBB0_1649:
	s_ashr_i32 s23, s22, 31
	s_lshl_b64 s[24:25], s[22:23], 21
	s_add_u32 s24, s56, s24
	s_addc_u32 s25, s57, s25
	s_and_b64 s[26:27], s[0:1], exec
	s_cselect_b32 s23, s25, s31
	s_cselect_b32 s55, s24, s30
	s_ashr_i32 s21, s20, 31
	s_lshl_b64 s[26:27], s[20:21], 21
	s_add_u32 s26, s53, s26
	s_addc_u32 s27, s58, s27
	s_and_b64 s[42:43], s[0:1], exec
	s_cselect_b32 s21, s27, s35
	s_cselect_b32 s72, s26, s34
	s_add_u32 s30, s30, 0x100080
	s_addc_u32 s31, s31, 0
	s_add_u32 s73, s34, 0x100
	s_addc_u32 s74, s35, 0
	s_mov_b32 s75, -2
	ds_read_b128 v[152:155], v149
	ds_read_b128 v[156:159], v149 offset:1024
	ds_read_b128 v[160:163], v149 offset:2048
	ds_read_b128 v[164:167], v149 offset:3072
	ds_read_b128 v[168:171], v150
	ds_read_b128 v[172:175], v150 offset:1024
	ds_read_b128 v[176:179], v150 offset:2048
	ds_read_b128 v[180:183], v150 offset:3072
	s_add_u32 s34, s30, 0xfff00080
	s_addc_u32 s35, s31, -1
	s_cmp_eq_u32 s75, 60
	s_cselect_b32 s43, s23, s35
	s_cselect_b32 s42, s55, s34
	s_cselect_b32 s35, s21, s74
	s_cselect_b32 s34, s72, s73
	s_add_i32 m0, s29, 0xc000
	ds_read_b128 v[184:187], v151
	ds_read_b128 v[192:195], v151 offset:1024
	ds_read_b128 v[196:199], v151 offset:2048
	ds_read_b128 v[200:203], v151 offset:3072
	ds_read_b128 v[204:207], v151 offset:4096
	ds_read_b128 v[208:211], v151 offset:5120
	ds_read_b128 v[212:215], v151 offset:6144
	ds_read_b128 v[216:219], v151 offset:7168
	global_load_lds_dwordx4 v136, s[30:31]
	s_add_i32 m0, s29, 0xe000
	s_nop 0
	global_load_lds_dwordx4 v138, s[30:31]
	s_waitcnt vmcnt(8)
	s_waitcnt lgkmcnt(0)
	s_barrier
	v_mfma_f32_16x16x32_bf16 v[124:127], v[152:155], v[184:187], 0
	v_mfma_f32_16x16x32_bf16 v[120:123], v[160:163], v[184:187], 0
	v_mfma_f32_16x16x32_bf16 v[116:119], v[152:155], v[196:199], 0
	v_mfma_f32_16x16x32_bf16 v[108:111], v[160:163], v[196:199], 0
	v_mfma_f32_16x16x32_bf16 v[100:103], v[152:155], v[204:207], 0
	v_mfma_f32_16x16x32_bf16 v[92:95], v[160:163], v[204:207], 0
	v_mfma_f32_16x16x32_bf16 v[84:87], v[152:155], v[212:215], 0
	v_mfma_f32_16x16x32_bf16 v[76:79], v[160:163], v[212:215], 0
	v_mfma_f32_16x16x32_bf16 v[124:127], v[156:159], v[192:195], v[124:127]
	v_mfma_f32_16x16x32_bf16 v[120:123], v[164:167], v[192:195], v[120:123]
	v_mfma_f32_16x16x32_bf16 v[116:119], v[156:159], v[200:203], v[116:119]
	v_mfma_f32_16x16x32_bf16 v[108:111], v[164:167], v[200:203], v[108:111]
	v_mfma_f32_16x16x32_bf16 v[100:103], v[156:159], v[208:211], v[100:103]
	v_mfma_f32_16x16x32_bf16 v[92:95], v[164:167], v[208:211], v[92:95]
	v_mfma_f32_16x16x32_bf16 v[84:87], v[156:159], v[216:219], v[84:87]
	v_mfma_f32_16x16x32_bf16 v[76:79], v[164:167], v[216:219], v[76:79]
	v_mfma_f32_16x16x32_bf16 v[112:115], v[168:171], v[184:187], 0
	v_mfma_f32_16x16x32_bf16 v[104:107], v[176:179], v[184:187], 0
	v_mfma_f32_16x16x32_bf16 v[96:99], v[168:171], v[196:199], 0
	v_mfma_f32_16x16x32_bf16 v[88:91], v[176:179], v[196:199], 0
	v_mfma_f32_16x16x32_bf16 v[80:83], v[168:171], v[204:207], 0
	v_mfma_f32_16x16x32_bf16 v[72:75], v[176:179], v[204:207], 0
	v_mfma_f32_16x16x32_bf16 v[68:71], v[168:171], v[212:215], 0
	v_mfma_f32_16x16x32_bf16 v[64:67], v[176:179], v[212:215], 0
	v_mfma_f32_16x16x32_bf16 v[112:115], v[172:175], v[192:195], v[112:115]
	v_mfma_f32_16x16x32_bf16 v[104:107], v[180:183], v[192:195], v[104:107]
	v_mfma_f32_16x16x32_bf16 v[96:99], v[172:175], v[200:203], v[96:99]
	v_mfma_f32_16x16x32_bf16 v[88:91], v[180:183], v[200:203], v[88:91]
	v_mfma_f32_16x16x32_bf16 v[80:83], v[172:175], v[208:211], v[80:83]
	v_mfma_f32_16x16x32_bf16 v[72:75], v[180:183], v[208:211], v[72:75]
	v_mfma_f32_16x16x32_bf16 v[68:71], v[172:175], v[216:219], v[68:71]
	v_mfma_f32_16x16x32_bf16 v[64:67], v[180:183], v[216:219], v[64:67]
	s_barrier
	s_add_i32 s76, s66, s59
	v_lshl_add_u64 v[144:145], s[34:35], 0, v[130:131]
	s_mov_b32 m0, s76
	ds_read_b128 v[184:187], v151 offset:16384
	ds_read_b128 v[192:195], v151 offset:17408
	ds_read_b128 v[196:199], v151 offset:18432
	ds_read_b128 v[200:203], v151 offset:19456
	ds_read_b128 v[204:207], v151 offset:20480
	ds_read_b128 v[208:211], v151 offset:21504
	ds_read_b128 v[212:215], v151 offset:22528
	ds_read_b128 v[216:219], v151 offset:23552
	global_load_lds_dwordx4 v[144:145], off
	s_add_i32 m0, s76, 0x2000
	s_add_u32 s76, s34, 0x100000
	v_lshl_add_u64 v[188:189], s[34:35], 0, v[134:135]
	s_addc_u32 s77, s35, 0
	s_add_i32 s79, s67, s59
	global_load_lds_dwordx4 v[188:189], off
	s_mov_b32 m0, s79
	v_lshl_add_u64 v[222:223], s[42:43], 0, v[132:133]
	global_load_lds_dwordx4 v130, s[76:77]
	s_add_i32 m0, s79, 0x2000
	s_nop 0
	global_load_lds_dwordx4 v134, s[76:77]
	v_lshl_add_u64 v[220:221], s[42:43], 0, v[128:129]
	s_mov_b32 m0, s29
	s_nop 0
	global_load_lds_dwordx4 v[220:221], off
	s_mov_b32 m0, s33
	s_nop 0
	global_load_lds_dwordx4 v[222:223], off
	s_waitcnt vmcnt(8)
	s_waitcnt lgkmcnt(0)
	s_barrier
	v_mfma_f32_16x16x32_bf16 v[60:63], v[152:155], v[184:187], 0
	v_mfma_f32_16x16x32_bf16 v[56:59], v[160:163], v[184:187], 0
	v_mfma_f32_16x16x32_bf16 v[52:55], v[152:155], v[196:199], 0
	v_mfma_f32_16x16x32_bf16 v[44:47], v[160:163], v[196:199], 0
	v_mfma_f32_16x16x32_bf16 v[36:39], v[152:155], v[204:207], 0
	v_mfma_f32_16x16x32_bf16 v[28:31], v[160:163], v[204:207], 0
	v_mfma_f32_16x16x32_bf16 v[20:23], v[152:155], v[212:215], 0
	v_mfma_f32_16x16x32_bf16 v[12:15], v[160:163], v[212:215], 0
	v_mfma_f32_16x16x32_bf16 v[60:63], v[156:159], v[192:195], v[60:63]
	v_mfma_f32_16x16x32_bf16 v[56:59], v[164:167], v[192:195], v[56:59]
	v_mfma_f32_16x16x32_bf16 v[52:55], v[156:159], v[200:203], v[52:55]
	v_mfma_f32_16x16x32_bf16 v[44:47], v[164:167], v[200:203], v[44:47]
	v_mfma_f32_16x16x32_bf16 v[36:39], v[156:159], v[208:211], v[36:39]
	v_mfma_f32_16x16x32_bf16 v[28:31], v[164:167], v[208:211], v[28:31]
	v_mfma_f32_16x16x32_bf16 v[20:23], v[156:159], v[216:219], v[20:23]
	v_mfma_f32_16x16x32_bf16 v[12:15], v[164:167], v[216:219], v[12:15]
	v_mfma_f32_16x16x32_bf16 v[48:51], v[168:171], v[184:187], 0
	v_mfma_f32_16x16x32_bf16 v[40:43], v[176:179], v[184:187], 0
	v_mfma_f32_16x16x32_bf16 v[32:35], v[168:171], v[196:199], 0
	v_mfma_f32_16x16x32_bf16 v[24:27], v[176:179], v[196:199], 0
	v_mfma_f32_16x16x32_bf16 v[16:19], v[168:171], v[204:207], 0
	v_mfma_f32_16x16x32_bf16 v[8:11], v[176:179], v[204:207], 0
	v_mfma_f32_16x16x32_bf16 v[4:7], v[168:171], v[212:215], 0
	v_mfma_f32_16x16x32_bf16 v[0:3], v[176:179], v[212:215], 0
	v_mfma_f32_16x16x32_bf16 v[48:51], v[172:175], v[192:195], v[48:51]
	v_mfma_f32_16x16x32_bf16 v[40:43], v[180:183], v[192:195], v[40:43]
	v_mfma_f32_16x16x32_bf16 v[32:35], v[172:175], v[200:203], v[32:35]
	v_mfma_f32_16x16x32_bf16 v[24:27], v[180:183], v[200:203], v[24:27]
	v_mfma_f32_16x16x32_bf16 v[16:19], v[172:175], v[208:211], v[16:19]
	v_mfma_f32_16x16x32_bf16 v[8:11], v[180:183], v[208:211], v[8:11]
	v_mfma_f32_16x16x32_bf16 v[4:7], v[172:175], v[216:219], v[4:7]
	v_mfma_f32_16x16x32_bf16 v[0:3], v[180:183], v[216:219], v[0:3]
	s_barrier
	s_add_i32 s76, 0, 0x18000
	s_add_i32 s77, 0, 0x1c000
	v_add_u32_e32 v164, s76, v147
	v_add_u32_e32 v180, s77, v147
	ds_read_b128 v[152:155], v164
	ds_read_b128 v[156:159], v164 offset:1024
	ds_read_b128 v[160:163], v164 offset:2048
	ds_read_b128 v[164:167], v164 offset:3072
	ds_read_b128 v[168:171], v180
	ds_read_b128 v[172:175], v180 offset:1024
	ds_read_b128 v[176:179], v180 offset:2048
	ds_read_b128 v[180:183], v180 offset:3072
	s_add_u32 s42, s42, 0x100000
	s_addc_u32 s43, s43, 0
	s_mov_b32 m0, s60
	ds_read_b128 v[184:187], v151 offset:32768
	ds_read_b128 v[192:195], v151 offset:33792
	ds_read_b128 v[196:199], v151 offset:34816
	ds_read_b128 v[200:203], v151 offset:35840
	ds_read_b128 v[204:207], v151 offset:36864
	ds_read_b128 v[208:211], v151 offset:37888
	ds_read_b128 v[212:215], v151 offset:38912
	ds_read_b128 v[216:219], v151 offset:39936
	global_load_lds_dwordx4 v128, s[42:43]
	s_mov_b32 m0, s61
	s_nop 0
	global_load_lds_dwordx4 v132, s[42:43]
	s_waitcnt vmcnt(8)
	s_waitcnt lgkmcnt(0)
	s_barrier
	v_mfma_f32_16x16x32_bf16 v[124:127], v[152:155], v[184:187], v[124:127]
	v_mfma_f32_16x16x32_bf16 v[120:123], v[160:163], v[184:187], v[120:123]
	v_mfma_f32_16x16x32_bf16 v[116:119], v[152:155], v[196:199], v[116:119]
	v_mfma_f32_16x16x32_bf16 v[108:111], v[160:163], v[196:199], v[108:111]
	v_mfma_f32_16x16x32_bf16 v[100:103], v[152:155], v[204:207], v[100:103]
	v_mfma_f32_16x16x32_bf16 v[92:95], v[160:163], v[204:207], v[92:95]
	v_mfma_f32_16x16x32_bf16 v[84:87], v[152:155], v[212:215], v[84:87]
	v_mfma_f32_16x16x32_bf16 v[76:79], v[160:163], v[212:215], v[76:79]
	v_mfma_f32_16x16x32_bf16 v[124:127], v[156:159], v[192:195], v[124:127]
	v_mfma_f32_16x16x32_bf16 v[120:123], v[164:167], v[192:195], v[120:123]
	v_mfma_f32_16x16x32_bf16 v[116:119], v[156:159], v[200:203], v[116:119]
	v_mfma_f32_16x16x32_bf16 v[108:111], v[164:167], v[200:203], v[108:111]
	v_mfma_f32_16x16x32_bf16 v[100:103], v[156:159], v[208:211], v[100:103]
	v_mfma_f32_16x16x32_bf16 v[92:95], v[164:167], v[208:211], v[92:95]
	v_mfma_f32_16x16x32_bf16 v[84:87], v[156:159], v[216:219], v[84:87]
	v_mfma_f32_16x16x32_bf16 v[76:79], v[164:167], v[216:219], v[76:79]
	v_mfma_f32_16x16x32_bf16 v[112:115], v[168:171], v[184:187], v[112:115]
	v_mfma_f32_16x16x32_bf16 v[104:107], v[176:179], v[184:187], v[104:107]
	v_mfma_f32_16x16x32_bf16 v[96:99], v[168:171], v[196:199], v[96:99]
	v_mfma_f32_16x16x32_bf16 v[88:91], v[176:179], v[196:199], v[88:91]
	v_mfma_f32_16x16x32_bf16 v[80:83], v[168:171], v[204:207], v[80:83]
	v_mfma_f32_16x16x32_bf16 v[72:75], v[176:179], v[204:207], v[72:75]
	v_mfma_f32_16x16x32_bf16 v[68:71], v[168:171], v[212:215], v[68:71]
	v_mfma_f32_16x16x32_bf16 v[64:67], v[176:179], v[212:215], v[64:67]
	v_mfma_f32_16x16x32_bf16 v[112:115], v[172:175], v[192:195], v[112:115]
	v_mfma_f32_16x16x32_bf16 v[104:107], v[180:183], v[192:195], v[104:107]
	v_mfma_f32_16x16x32_bf16 v[96:99], v[172:175], v[200:203], v[96:99]
	v_mfma_f32_16x16x32_bf16 v[88:91], v[180:183], v[200:203], v[88:91]
	v_mfma_f32_16x16x32_bf16 v[80:83], v[172:175], v[208:211], v[80:83]
	v_mfma_f32_16x16x32_bf16 v[72:75], v[180:183], v[208:211], v[72:75]
	v_mfma_f32_16x16x32_bf16 v[68:71], v[172:175], v[216:219], v[68:71]
	v_mfma_f32_16x16x32_bf16 v[64:67], v[180:183], v[216:219], v[64:67]
	s_barrier
	s_add_i32 s42, s76, s59
	v_lshl_add_u64 v[144:145], v[144:145], 0, s[8:9]
	s_mov_b32 m0, s42
	ds_read_b128 v[184:187], v151 offset:49152
	ds_read_b128 v[192:195], v151 offset:50176
	ds_read_b128 v[196:199], v151 offset:51200
	ds_read_b128 v[200:203], v151 offset:52224
	ds_read_b128 v[204:207], v151 offset:53248
	ds_read_b128 v[208:211], v151 offset:54272
	ds_read_b128 v[212:215], v151 offset:55296
	ds_read_b128 v[216:219], v151 offset:56320
	global_load_lds_dwordx4 v[144:145], off
	s_add_i32 m0, s42, 0x2000
	s_add_u32 s34, s34, 0x100080
	v_lshl_add_u64 v[144:145], v[188:189], 0, s[8:9]
	s_addc_u32 s35, s35, 0
	s_add_i32 s42, s77, s59
	global_load_lds_dwordx4 v[144:145], off
	s_mov_b32 m0, s42
	s_nop 0
	global_load_lds_dwordx4 v130, s[34:35]
	s_add_i32 m0, s42, 0x2000
	s_nop 0
	global_load_lds_dwordx4 v134, s[34:35]
	v_lshl_add_u64 v[144:145], v[220:221], 0, s[8:9]
	s_mov_b32 m0, s63
	s_nop 0
	global_load_lds_dwordx4 v[144:145], off
	v_lshl_add_u64 v[144:145], v[222:223], 0, s[8:9]
	s_mov_b32 m0, s64
	s_nop 0
	global_load_lds_dwordx4 v[144:145], off
	s_waitcnt vmcnt(8)
	s_waitcnt lgkmcnt(0)
	s_barrier
	v_mfma_f32_16x16x32_bf16 v[60:63], v[152:155], v[184:187], v[60:63]
	v_mfma_f32_16x16x32_bf16 v[56:59], v[160:163], v[184:187], v[56:59]
	v_mfma_f32_16x16x32_bf16 v[52:55], v[152:155], v[196:199], v[52:55]
	v_mfma_f32_16x16x32_bf16 v[44:47], v[160:163], v[196:199], v[44:47]
	v_mfma_f32_16x16x32_bf16 v[36:39], v[152:155], v[204:207], v[36:39]
	v_mfma_f32_16x16x32_bf16 v[28:31], v[160:163], v[204:207], v[28:31]
	v_mfma_f32_16x16x32_bf16 v[20:23], v[152:155], v[212:215], v[20:23]
	v_mfma_f32_16x16x32_bf16 v[12:15], v[160:163], v[212:215], v[12:15]
	v_mfma_f32_16x16x32_bf16 v[60:63], v[156:159], v[192:195], v[60:63]
	v_mfma_f32_16x16x32_bf16 v[56:59], v[164:167], v[192:195], v[56:59]
	v_mfma_f32_16x16x32_bf16 v[52:55], v[156:159], v[200:203], v[52:55]
	v_mfma_f32_16x16x32_bf16 v[44:47], v[164:167], v[200:203], v[44:47]
	v_mfma_f32_16x16x32_bf16 v[36:39], v[156:159], v[208:211], v[36:39]
	v_mfma_f32_16x16x32_bf16 v[28:31], v[164:167], v[208:211], v[28:31]
	v_mfma_f32_16x16x32_bf16 v[20:23], v[156:159], v[216:219], v[20:23]
	v_mfma_f32_16x16x32_bf16 v[12:15], v[164:167], v[216:219], v[12:15]
	v_mfma_f32_16x16x32_bf16 v[48:51], v[168:171], v[184:187], v[48:51]
	v_mfma_f32_16x16x32_bf16 v[40:43], v[176:179], v[184:187], v[40:43]
	v_mfma_f32_16x16x32_bf16 v[32:35], v[168:171], v[196:199], v[32:35]
	v_mfma_f32_16x16x32_bf16 v[24:27], v[176:179], v[196:199], v[24:27]
	v_mfma_f32_16x16x32_bf16 v[16:19], v[168:171], v[204:207], v[16:19]
	v_mfma_f32_16x16x32_bf16 v[8:11], v[176:179], v[204:207], v[8:11]
	v_mfma_f32_16x16x32_bf16 v[4:7], v[168:171], v[212:215], v[4:7]
	v_mfma_f32_16x16x32_bf16 v[0:3], v[176:179], v[212:215], v[0:3]
	v_mfma_f32_16x16x32_bf16 v[48:51], v[172:175], v[192:195], v[48:51]
	v_mfma_f32_16x16x32_bf16 v[40:43], v[180:183], v[192:195], v[40:43]
	v_mfma_f32_16x16x32_bf16 v[32:35], v[172:175], v[200:203], v[32:35]
	v_mfma_f32_16x16x32_bf16 v[24:27], v[180:183], v[200:203], v[24:27]
	v_mfma_f32_16x16x32_bf16 v[16:19], v[172:175], v[208:211], v[16:19]
	v_mfma_f32_16x16x32_bf16 v[8:11], v[180:183], v[208:211], v[8:11]
	v_mfma_f32_16x16x32_bf16 v[4:7], v[172:175], v[216:219], v[4:7]
	v_mfma_f32_16x16x32_bf16 v[0:3], v[180:183], v[216:219], v[0:3]
	s_barrier
	s_add_i32 s75, s75, 2
	s_add_u32 s30, s30, 0x100
	s_addc_u32 s31, s31, 0
	s_add_u32 s73, s73, 0x100
	s_addc_u32 s74, s74, 0
	s_cmp_gt_u32 s75, 61
	s_cbranch_scc0 .LBB0_1650
	s_branch .Lpeel_exit12
.LBB0_1650:
	ds_read_b128 v[152:155], v149
	ds_read_b128 v[156:159], v149 offset:1024
	ds_read_b128 v[160:163], v149 offset:2048
	ds_read_b128 v[164:167], v149 offset:3072
	ds_read_b128 v[168:171], v150
	ds_read_b128 v[172:175], v150 offset:1024
	ds_read_b128 v[176:179], v150 offset:2048
	ds_read_b128 v[180:183], v150 offset:3072
	s_add_u32 s34, s30, 0xfff00080
	s_addc_u32 s35, s31, -1
	s_cmp_eq_u32 s75, 60
	s_cselect_b32 s43, s23, s35
	s_cselect_b32 s42, s55, s34
	s_cselect_b32 s35, s21, s74
	s_cselect_b32 s34, s72, s73
	s_add_i32 m0, s29, 0xc000
	ds_read_b128 v[184:187], v151
	ds_read_b128 v[192:195], v151 offset:1024
	ds_read_b128 v[196:199], v151 offset:2048
	ds_read_b128 v[200:203], v151 offset:3072
	ds_read_b128 v[204:207], v151 offset:4096
	ds_read_b128 v[208:211], v151 offset:5120
	ds_read_b128 v[212:215], v151 offset:6144
	ds_read_b128 v[216:219], v151 offset:7168
	global_load_lds_dwordx4 v136, s[30:31]
	s_add_i32 m0, s29, 0xe000
	s_nop 0
	global_load_lds_dwordx4 v138, s[30:31]
	s_waitcnt vmcnt(8)
	s_waitcnt lgkmcnt(0)
	s_barrier
	v_mfma_f32_16x16x32_bf16 v[124:127], v[152:155], v[184:187], v[124:127]
	v_mfma_f32_16x16x32_bf16 v[120:123], v[160:163], v[184:187], v[120:123]
	v_mfma_f32_16x16x32_bf16 v[116:119], v[152:155], v[196:199], v[116:119]
	v_mfma_f32_16x16x32_bf16 v[108:111], v[160:163], v[196:199], v[108:111]
	v_mfma_f32_16x16x32_bf16 v[100:103], v[152:155], v[204:207], v[100:103]
	v_mfma_f32_16x16x32_bf16 v[92:95], v[160:163], v[204:207], v[92:95]
	v_mfma_f32_16x16x32_bf16 v[84:87], v[152:155], v[212:215], v[84:87]
	v_mfma_f32_16x16x32_bf16 v[76:79], v[160:163], v[212:215], v[76:79]
	v_mfma_f32_16x16x32_bf16 v[124:127], v[156:159], v[192:195], v[124:127]
	v_mfma_f32_16x16x32_bf16 v[120:123], v[164:167], v[192:195], v[120:123]
	v_mfma_f32_16x16x32_bf16 v[116:119], v[156:159], v[200:203], v[116:119]
	v_mfma_f32_16x16x32_bf16 v[108:111], v[164:167], v[200:203], v[108:111]
	v_mfma_f32_16x16x32_bf16 v[100:103], v[156:159], v[208:211], v[100:103]
	v_mfma_f32_16x16x32_bf16 v[92:95], v[164:167], v[208:211], v[92:95]
	v_mfma_f32_16x16x32_bf16 v[84:87], v[156:159], v[216:219], v[84:87]
	v_mfma_f32_16x16x32_bf16 v[76:79], v[164:167], v[216:219], v[76:79]
	v_mfma_f32_16x16x32_bf16 v[112:115], v[168:171], v[184:187], v[112:115]
	v_mfma_f32_16x16x32_bf16 v[104:107], v[176:179], v[184:187], v[104:107]
	v_mfma_f32_16x16x32_bf16 v[96:99], v[168:171], v[196:199], v[96:99]
	v_mfma_f32_16x16x32_bf16 v[88:91], v[176:179], v[196:199], v[88:91]
	v_mfma_f32_16x16x32_bf16 v[80:83], v[168:171], v[204:207], v[80:83]
	v_mfma_f32_16x16x32_bf16 v[72:75], v[176:179], v[204:207], v[72:75]
	v_mfma_f32_16x16x32_bf16 v[68:71], v[168:171], v[212:215], v[68:71]
	v_mfma_f32_16x16x32_bf16 v[64:67], v[176:179], v[212:215], v[64:67]
	v_mfma_f32_16x16x32_bf16 v[112:115], v[172:175], v[192:195], v[112:115]
	v_mfma_f32_16x16x32_bf16 v[104:107], v[180:183], v[192:195], v[104:107]
	v_mfma_f32_16x16x32_bf16 v[96:99], v[172:175], v[200:203], v[96:99]
	v_mfma_f32_16x16x32_bf16 v[88:91], v[180:183], v[200:203], v[88:91]
	v_mfma_f32_16x16x32_bf16 v[80:83], v[172:175], v[208:211], v[80:83]
	v_mfma_f32_16x16x32_bf16 v[72:75], v[180:183], v[208:211], v[72:75]
	v_mfma_f32_16x16x32_bf16 v[68:71], v[172:175], v[216:219], v[68:71]
	v_mfma_f32_16x16x32_bf16 v[64:67], v[180:183], v[216:219], v[64:67]
	s_barrier
	s_add_i32 s76, s66, s59
	v_lshl_add_u64 v[144:145], s[34:35], 0, v[130:131]
	s_mov_b32 m0, s76
	ds_read_b128 v[184:187], v151 offset:16384
	ds_read_b128 v[192:195], v151 offset:17408
	ds_read_b128 v[196:199], v151 offset:18432
	ds_read_b128 v[200:203], v151 offset:19456
	ds_read_b128 v[204:207], v151 offset:20480
	ds_read_b128 v[208:211], v151 offset:21504
	ds_read_b128 v[212:215], v151 offset:22528
	ds_read_b128 v[216:219], v151 offset:23552
	global_load_lds_dwordx4 v[144:145], off
	s_add_i32 m0, s76, 0x2000
	s_add_u32 s76, s34, 0x100000
	v_lshl_add_u64 v[188:189], s[34:35], 0, v[134:135]
	s_addc_u32 s77, s35, 0
	s_add_i32 s79, s67, s59
	global_load_lds_dwordx4 v[188:189], off
	s_mov_b32 m0, s79
	v_lshl_add_u64 v[222:223], s[42:43], 0, v[132:133]
	global_load_lds_dwordx4 v130, s[76:77]
	s_add_i32 m0, s79, 0x2000
	s_nop 0
	global_load_lds_dwordx4 v134, s[76:77]
	v_lshl_add_u64 v[220:221], s[42:43], 0, v[128:129]
	s_mov_b32 m0, s29
	s_nop 0
	global_load_lds_dwordx4 v[220:221], off
	s_mov_b32 m0, s33
	s_nop 0
	global_load_lds_dwordx4 v[222:223], off
	s_waitcnt vmcnt(8)
	s_waitcnt lgkmcnt(0)
	s_barrier
	v_mfma_f32_16x16x32_bf16 v[60:63], v[152:155], v[184:187], v[60:63]
	v_mfma_f32_16x16x32_bf16 v[56:59], v[160:163], v[184:187], v[56:59]
	v_mfma_f32_16x16x32_bf16 v[52:55], v[152:155], v[196:199], v[52:55]
	v_mfma_f32_16x16x32_bf16 v[44:47], v[160:163], v[196:199], v[44:47]
	v_mfma_f32_16x16x32_bf16 v[36:39], v[152:155], v[204:207], v[36:39]
	v_mfma_f32_16x16x32_bf16 v[28:31], v[160:163], v[204:207], v[28:31]
	v_mfma_f32_16x16x32_bf16 v[20:23], v[152:155], v[212:215], v[20:23]
	v_mfma_f32_16x16x32_bf16 v[12:15], v[160:163], v[212:215], v[12:15]
	v_mfma_f32_16x16x32_bf16 v[60:63], v[156:159], v[192:195], v[60:63]
	v_mfma_f32_16x16x32_bf16 v[56:59], v[164:167], v[192:195], v[56:59]
	v_mfma_f32_16x16x32_bf16 v[52:55], v[156:159], v[200:203], v[52:55]
	v_mfma_f32_16x16x32_bf16 v[44:47], v[164:167], v[200:203], v[44:47]
	v_mfma_f32_16x16x32_bf16 v[36:39], v[156:159], v[208:211], v[36:39]
	v_mfma_f32_16x16x32_bf16 v[28:31], v[164:167], v[208:211], v[28:31]
	v_mfma_f32_16x16x32_bf16 v[20:23], v[156:159], v[216:219], v[20:23]
	v_mfma_f32_16x16x32_bf16 v[12:15], v[164:167], v[216:219], v[12:15]
	v_mfma_f32_16x16x32_bf16 v[48:51], v[168:171], v[184:187], v[48:51]
	v_mfma_f32_16x16x32_bf16 v[40:43], v[176:179], v[184:187], v[40:43]
	v_mfma_f32_16x16x32_bf16 v[32:35], v[168:171], v[196:199], v[32:35]
	v_mfma_f32_16x16x32_bf16 v[24:27], v[176:179], v[196:199], v[24:27]
	v_mfma_f32_16x16x32_bf16 v[16:19], v[168:171], v[204:207], v[16:19]
	v_mfma_f32_16x16x32_bf16 v[8:11], v[176:179], v[204:207], v[8:11]
	v_mfma_f32_16x16x32_bf16 v[4:7], v[168:171], v[212:215], v[4:7]
	v_mfma_f32_16x16x32_bf16 v[0:3], v[176:179], v[212:215], v[0:3]
	v_mfma_f32_16x16x32_bf16 v[48:51], v[172:175], v[192:195], v[48:51]
	v_mfma_f32_16x16x32_bf16 v[40:43], v[180:183], v[192:195], v[40:43]
	v_mfma_f32_16x16x32_bf16 v[32:35], v[172:175], v[200:203], v[32:35]
	v_mfma_f32_16x16x32_bf16 v[24:27], v[180:183], v[200:203], v[24:27]
	v_mfma_f32_16x16x32_bf16 v[16:19], v[172:175], v[208:211], v[16:19]
	v_mfma_f32_16x16x32_bf16 v[8:11], v[180:183], v[208:211], v[8:11]
	v_mfma_f32_16x16x32_bf16 v[4:7], v[172:175], v[216:219], v[4:7]
	v_mfma_f32_16x16x32_bf16 v[0:3], v[180:183], v[216:219], v[0:3]
	s_barrier
	s_add_i32 s76, 0, 0x18000
	s_add_i32 s77, 0, 0x1c000
	v_add_u32_e32 v164, s76, v147
	v_add_u32_e32 v180, s77, v147
	ds_read_b128 v[152:155], v164
	ds_read_b128 v[156:159], v164 offset:1024
	ds_read_b128 v[160:163], v164 offset:2048
	ds_read_b128 v[164:167], v164 offset:3072
	ds_read_b128 v[168:171], v180
	ds_read_b128 v[172:175], v180 offset:1024
	ds_read_b128 v[176:179], v180 offset:2048
	ds_read_b128 v[180:183], v180 offset:3072
	s_add_u32 s42, s42, 0x100000
	s_addc_u32 s43, s43, 0
	s_mov_b32 m0, s60
	ds_read_b128 v[184:187], v151 offset:32768
	ds_read_b128 v[192:195], v151 offset:33792
	ds_read_b128 v[196:199], v151 offset:34816
	ds_read_b128 v[200:203], v151 offset:35840
	ds_read_b128 v[204:207], v151 offset:36864
	ds_read_b128 v[208:211], v151 offset:37888
	ds_read_b128 v[212:215], v151 offset:38912
	ds_read_b128 v[216:219], v151 offset:39936
	global_load_lds_dwordx4 v128, s[42:43]
	s_mov_b32 m0, s61
	s_nop 0
	global_load_lds_dwordx4 v132, s[42:43]
	s_waitcnt vmcnt(8)
	s_waitcnt lgkmcnt(0)
	s_barrier
	v_mfma_f32_16x16x32_bf16 v[124:127], v[152:155], v[184:187], v[124:127]
	v_mfma_f32_16x16x32_bf16 v[120:123], v[160:163], v[184:187], v[120:123]
	v_mfma_f32_16x16x32_bf16 v[116:119], v[152:155], v[196:199], v[116:119]
	v_mfma_f32_16x16x32_bf16 v[108:111], v[160:163], v[196:199], v[108:111]
	v_mfma_f32_16x16x32_bf16 v[100:103], v[152:155], v[204:207], v[100:103]
	v_mfma_f32_16x16x32_bf16 v[92:95], v[160:163], v[204:207], v[92:95]
	v_mfma_f32_16x16x32_bf16 v[84:87], v[152:155], v[212:215], v[84:87]
	v_mfma_f32_16x16x32_bf16 v[76:79], v[160:163], v[212:215], v[76:79]
	v_mfma_f32_16x16x32_bf16 v[124:127], v[156:159], v[192:195], v[124:127]
	v_mfma_f32_16x16x32_bf16 v[120:123], v[164:167], v[192:195], v[120:123]
	v_mfma_f32_16x16x32_bf16 v[116:119], v[156:159], v[200:203], v[116:119]
	v_mfma_f32_16x16x32_bf16 v[108:111], v[164:167], v[200:203], v[108:111]
	v_mfma_f32_16x16x32_bf16 v[100:103], v[156:159], v[208:211], v[100:103]
	v_mfma_f32_16x16x32_bf16 v[92:95], v[164:167], v[208:211], v[92:95]
	v_mfma_f32_16x16x32_bf16 v[84:87], v[156:159], v[216:219], v[84:87]
	v_mfma_f32_16x16x32_bf16 v[76:79], v[164:167], v[216:219], v[76:79]
	v_mfma_f32_16x16x32_bf16 v[112:115], v[168:171], v[184:187], v[112:115]
	v_mfma_f32_16x16x32_bf16 v[104:107], v[176:179], v[184:187], v[104:107]
	v_mfma_f32_16x16x32_bf16 v[96:99], v[168:171], v[196:199], v[96:99]
	v_mfma_f32_16x16x32_bf16 v[88:91], v[176:179], v[196:199], v[88:91]
	v_mfma_f32_16x16x32_bf16 v[80:83], v[168:171], v[204:207], v[80:83]
	v_mfma_f32_16x16x32_bf16 v[72:75], v[176:179], v[204:207], v[72:75]
	v_mfma_f32_16x16x32_bf16 v[68:71], v[168:171], v[212:215], v[68:71]
	v_mfma_f32_16x16x32_bf16 v[64:67], v[176:179], v[212:215], v[64:67]
	v_mfma_f32_16x16x32_bf16 v[112:115], v[172:175], v[192:195], v[112:115]
	v_mfma_f32_16x16x32_bf16 v[104:107], v[180:183], v[192:195], v[104:107]
	v_mfma_f32_16x16x32_bf16 v[96:99], v[172:175], v[200:203], v[96:99]
	v_mfma_f32_16x16x32_bf16 v[88:91], v[180:183], v[200:203], v[88:91]
	v_mfma_f32_16x16x32_bf16 v[80:83], v[172:175], v[208:211], v[80:83]
	v_mfma_f32_16x16x32_bf16 v[72:75], v[180:183], v[208:211], v[72:75]
	v_mfma_f32_16x16x32_bf16 v[68:71], v[172:175], v[216:219], v[68:71]
	v_mfma_f32_16x16x32_bf16 v[64:67], v[180:183], v[216:219], v[64:67]
	s_barrier
	s_add_i32 s42, s76, s59
	v_lshl_add_u64 v[144:145], v[144:145], 0, s[8:9]
	s_mov_b32 m0, s42
	ds_read_b128 v[184:187], v151 offset:49152
	ds_read_b128 v[192:195], v151 offset:50176
	ds_read_b128 v[196:199], v151 offset:51200
	ds_read_b128 v[200:203], v151 offset:52224
	ds_read_b128 v[204:207], v151 offset:53248
	ds_read_b128 v[208:211], v151 offset:54272
	ds_read_b128 v[212:215], v151 offset:55296
	ds_read_b128 v[216:219], v151 offset:56320
	global_load_lds_dwordx4 v[144:145], off
	s_add_i32 m0, s42, 0x2000
	s_add_u32 s34, s34, 0x100080
	v_lshl_add_u64 v[144:145], v[188:189], 0, s[8:9]
	s_addc_u32 s35, s35, 0
	s_add_i32 s42, s77, s59
	global_load_lds_dwordx4 v[144:145], off
	s_mov_b32 m0, s42
	s_nop 0
	global_load_lds_dwordx4 v130, s[34:35]
	s_add_i32 m0, s42, 0x2000
	s_nop 0
	global_load_lds_dwordx4 v134, s[34:35]
	v_lshl_add_u64 v[144:145], v[220:221], 0, s[8:9]
	s_mov_b32 m0, s63
	s_nop 0
	global_load_lds_dwordx4 v[144:145], off
	v_lshl_add_u64 v[144:145], v[222:223], 0, s[8:9]
	s_mov_b32 m0, s64
	s_nop 0
	global_load_lds_dwordx4 v[144:145], off
	s_waitcnt vmcnt(8)
	s_waitcnt lgkmcnt(0)
	s_barrier
	v_mfma_f32_16x16x32_bf16 v[60:63], v[152:155], v[184:187], v[60:63]
	v_mfma_f32_16x16x32_bf16 v[56:59], v[160:163], v[184:187], v[56:59]
	v_mfma_f32_16x16x32_bf16 v[52:55], v[152:155], v[196:199], v[52:55]
	v_mfma_f32_16x16x32_bf16 v[44:47], v[160:163], v[196:199], v[44:47]
	v_mfma_f32_16x16x32_bf16 v[36:39], v[152:155], v[204:207], v[36:39]
	v_mfma_f32_16x16x32_bf16 v[28:31], v[160:163], v[204:207], v[28:31]
	v_mfma_f32_16x16x32_bf16 v[20:23], v[152:155], v[212:215], v[20:23]
	v_mfma_f32_16x16x32_bf16 v[12:15], v[160:163], v[212:215], v[12:15]
	v_mfma_f32_16x16x32_bf16 v[60:63], v[156:159], v[192:195], v[60:63]
	v_mfma_f32_16x16x32_bf16 v[56:59], v[164:167], v[192:195], v[56:59]
	v_mfma_f32_16x16x32_bf16 v[52:55], v[156:159], v[200:203], v[52:55]
	v_mfma_f32_16x16x32_bf16 v[44:47], v[164:167], v[200:203], v[44:47]
	v_mfma_f32_16x16x32_bf16 v[36:39], v[156:159], v[208:211], v[36:39]
	v_mfma_f32_16x16x32_bf16 v[28:31], v[164:167], v[208:211], v[28:31]
	v_mfma_f32_16x16x32_bf16 v[20:23], v[156:159], v[216:219], v[20:23]
	v_mfma_f32_16x16x32_bf16 v[12:15], v[164:167], v[216:219], v[12:15]
	v_mfma_f32_16x16x32_bf16 v[48:51], v[168:171], v[184:187], v[48:51]
	v_mfma_f32_16x16x32_bf16 v[40:43], v[176:179], v[184:187], v[40:43]
	v_mfma_f32_16x16x32_bf16 v[32:35], v[168:171], v[196:199], v[32:35]
	v_mfma_f32_16x16x32_bf16 v[24:27], v[176:179], v[196:199], v[24:27]
	v_mfma_f32_16x16x32_bf16 v[16:19], v[168:171], v[204:207], v[16:19]
	v_mfma_f32_16x16x32_bf16 v[8:11], v[176:179], v[204:207], v[8:11]
	v_mfma_f32_16x16x32_bf16 v[4:7], v[168:171], v[212:215], v[4:7]
	v_mfma_f32_16x16x32_bf16 v[0:3], v[176:179], v[212:215], v[0:3]
	v_mfma_f32_16x16x32_bf16 v[48:51], v[172:175], v[192:195], v[48:51]
	v_mfma_f32_16x16x32_bf16 v[40:43], v[180:183], v[192:195], v[40:43]
	v_mfma_f32_16x16x32_bf16 v[32:35], v[172:175], v[200:203], v[32:35]
	v_mfma_f32_16x16x32_bf16 v[24:27], v[180:183], v[200:203], v[24:27]
	v_mfma_f32_16x16x32_bf16 v[16:19], v[172:175], v[208:211], v[16:19]
	v_mfma_f32_16x16x32_bf16 v[8:11], v[180:183], v[208:211], v[8:11]
	v_mfma_f32_16x16x32_bf16 v[4:7], v[172:175], v[216:219], v[4:7]
	v_mfma_f32_16x16x32_bf16 v[0:3], v[180:183], v[216:219], v[0:3]
	s_barrier
	s_add_i32 s75, s75, 2
	s_add_u32 s30, s30, 0x100
	s_addc_u32 s31, s31, 0
	s_add_u32 s73, s73, 0x100
	s_addc_u32 s74, s74, 0
	s_cmp_gt_u32 s75, 61
	s_cbranch_scc0 .LBB0_1650
